# strategy 4 experiment on the 1.032x version: all per-phase s_setprio flips in the GEMM loops replaced by s_nop, one static s_setprio 1 for waves 4-7 at kernel entry
# speedup vs baseline: 1.0010x; 1.0010x over previous
; #define LAS __attribute__((address_space(3)))
; __global__ void __launch_bounds__(512, 2) mega_fwd(Params p) {
;     extern __shared__ __attribute__((aligned(16))) unsigned char smem[];
;     cg::grid_group grid = cg::this_grid();
;     volatile LAS unsigned* xst = (volatile LAS unsigned*)(LAS unsigned char*)(smem + 140 * 1024);
;     if (threadIdx.x == 0) { xst[0] = 0u; xst[1] = 0u; }
;     __syncthreads();
;     const XcdBarrier xb = xcd_barrier_post((unsigned*)(p.ws + WS_BAR), xst);
_Z8mega_fwd6Params:
	s_load_dwordx4 s[4:7], s[0:1], 0x110
	s_load_dwordx2 s[24:25], s[0:1], 0x120
	v_and_b32_e32 v238, 0x3ff, v0
	v_writelane_b32 v252, s2, 0
	v_readfirstlane_b32 s3, v238
	s_nop 3
	s_lshr_b32 s3, s3, 6
	s_cmp_ge_u32 s3, 4
	s_cbranch_scc0 .Lprio_done
	s_setprio 1
.Lprio_done:
	s_add_u32 s2, s0, 0x120
	s_waitcnt lgkmcnt(0)
	v_writelane_b32 v252, s4, 1
	s_nop 1
	v_writelane_b32 v252, s5, 2
	v_writelane_b32 v252, s6, 3
	v_writelane_b32 v252, s7, 4
	v_writelane_b32 v252, s0, 5
	s_addc_u32 s3, s1, 0
	s_nop 0
	v_writelane_b32 v252, s1, 6
	v_writelane_b32 v252, s2, 7
	s_nop 1
	v_writelane_b32 v252, s3, 8
	v_cmp_eq_u32_e64 s[2:3], 0, v238
	s_mov_b64 s[0:1], exec
	s_nop 0
	v_writelane_b32 v252, s2, 9
	s_nop 1
	v_writelane_b32 v252, s3, 10
	s_and_b64 s[2:3], s[0:1], s[2:3]
	s_mov_b64 exec, s[2:3]
	s_cbranch_execz .LBB0_2
	s_add_i32 s2, 0, 0x23000
	v_mov_b32_e32 v1, 0
	v_mov_b32_e32 v2, s2
	s_add_i32 s2, 0, 0x23004
	ds_write_b32 v2, v1
	v_mov_b32_e32 v2, s2
	ds_write_b32 v2, v1

; #define PG8_STAGE(bufoff, gbase, voff) do { _Pragma("unroll") for (int _i = 0; _i < 2; ++_i) \
;         __builtin_amdgcn_global_load_lds((const unsigned*)((const char*)(gbase) + (voff)[_i]), (LAS unsigned*)(lds + (bufoff) + ldsw + _i * 8192), 16, 0, 0); } while (0)
; #define PG8_LDA(dst, b, h) do { _Pragma("unroll") for (int m = 0; m < 4; ++m) _Pragma("unroll") for (int k = 0; k < 2; ++k) dst[m][k] = *(const LAS bf16x8*)(lds + PG8_SA(b, h) + aoff + m * 2048 + k * 1024); } while (0)
; #define PG8_LDB(dst, b, h) do { _Pragma("unroll") for (int n = 0; n < 2; ++n) _Pragma("unroll") for (int k = 0; k < 2; ++k) dst[n][k] = *(const LAS bf16x8*)(lds + PG8_SB(b, h) + boff + n * 2048 + k * 1024); } while (0)
; #define PG8_MMA(ai, bj, At, Bt) do { __builtin_amdgcn_s_setprio(1); _Pragma("unroll") for (int m = 0; m < 4; ++m) _Pragma("unroll") for (int n = 0; n < 2; ++n) _Pragma("unroll") for (int k = 0; k < 2; ++k) \
;         acc[ai][bj][m][n] = __builtin_amdgcn_mfma_f32_16x16x32_bf16(Bt[n][k], At[m][k], acc[ai][bj][m][n], 0, 0, 0); __builtin_amdgcn_s_setprio(0); } while (0)
; #define PG8_WAIT_L(n) asm volatile("s_waitcnt lgkmcnt(" #n ")" ::: "memory")
; #define PG8_BAR __builtin_amdgcn_s_barrier()
; template <class Epi>
; DI void gemm_phase(LAS unsigned char* lds, const Gemm g, const StaticOrder& S, const Epi& E) {
;     ...
;         const bool has_next = S.next(ui + 1, nxt);
;         const char* nA = has_next ? (const char*)g.A + (size_t)nxt.pm * tstepA : cA; const char* nB = has_next ? (const char*)g.Bt + (size_t)nxt.pn * tstepB : cB;
;         for (int t = 0; t < nt; t += 2) {
;             const bool last = (t == nt - 2);
;             const char* a1 = cA + (size_t)(t + 1) * kstep;
;             const char* a2 = last ? nA : cA + (size_t)(t + 2) * kstep; const char* b2 = last ? nB : cB + (size_t)(t + 2) * kstep;
;             const char* a3 = a2 + kstep; const char* b3 = b2 + kstep;
;             PG8_LDB(B0, 0, 0); PG8_SCHED; PG8_LDA(At, 0, 0); PG8_STAGE(PG8_SA(1, 1), a1 + hstepA, voffA);
;             PG8_WAIT_L(8); PG8_BAR; PG8_WAIT_L(0); PG8_MMA(0, 0, At, B0); PG8_BAR; PG8_SCHED;
;             PG8_LDB(B1, 0, 1); PG8_STAGE(PG8_SB(0, 0), b2, voffB);
;             PG8_BAR; PG8_WAIT_L(0); PG8_MMA(0, 1, At, B1); PG8_BAR;
;             PG8_LDA(At, 0, 1); PG8_STAGE(PG8_SA(0, 0), a2, voffA);
;             PG8_BAR; PG8_WAIT_L(0); PG8_MMA(1, 0, At, B0); PG8_BAR; PG8_SCHED;
.LBB0_362:
	s_ashr_i32 s19, s18, 31
	s_lshl_b64 s[20:21], s[18:19], 17
	s_add_u32 s20, s42, s20
	v_cmp_lt_i64_e32 vcc, s[4:5], v[198:199]
	s_addc_u32 s21, s43, s21
	s_and_b64 s[22:23], vcc, exec
	s_cselect_b32 s37, s21, s31
	s_cselect_b32 s36, s20, s30
	s_ashr_i32 s17, s16, 31
	s_lshl_b64 s[22:23], s[16:17], 17
	s_add_u32 s22, s39, s22
	s_addc_u32 s23, s40, s23
	s_and_b64 s[28:29], vcc, exec
	s_cselect_b32 s29, s23, s35
	s_cselect_b32 s28, s22, s34
	s_add_i32 s19, 0, 0x10000
	v_add_u32_e32 v200, s19, v16
	ds_read_b128 v[2:5], v200
	ds_read_b128 v[6:9], v200 offset:1024
	ds_read_b128 v[18:21], v200 offset:2048
	ds_read_b128 v[22:25], v200 offset:3072
	s_add_u32 s52, s30, 0x10080
	s_addc_u32 s53, s31, 0
	s_add_i32 s54, s15, 0xc000
	v_lshl_add_u64 v[58:59], s[52:53], 0, v[10:11]
	s_mov_b32 m0, s54
	s_add_i32 s17, s15, 0xe000
	ds_read_b128 v[26:29], v17
	ds_read_b128 v[30:33], v17 offset:1024
	ds_read_b128 v[34:37], v17 offset:2048
	ds_read_b128 v[38:41], v17 offset:3072
	ds_read_b128 v[42:45], v17 offset:4096
	ds_read_b128 v[46:49], v17 offset:5120
	ds_read_b128 v[50:53], v17 offset:6144
	ds_read_b128 v[54:57], v17 offset:7168
	global_load_lds_dwordx4 v[58:59], off
	v_lshl_add_u64 v[58:59], s[52:53], 0, v[12:13]
	s_mov_b32 m0, s17
	s_nop 0
	global_load_lds_dwordx4 v[58:59], off
	s_waitcnt lgkmcnt(8)
	s_barrier
	s_waitcnt lgkmcnt(0)
	s_nop 0
	s_waitcnt lgkmcnt(0)
	v_mfma_f32_16x16x32_bf16 v[58:61], v[2:5], v[26:29], 0
	v_mfma_f32_16x16x32_bf16 v[62:65], v[18:21], v[26:29], 0
	v_mfma_f32_16x16x32_bf16 v[66:69], v[2:5], v[34:37], 0
	v_mfma_f32_16x16x32_bf16 v[70:73], v[18:21], v[34:37], 0
	v_mfma_f32_16x16x32_bf16 v[74:77], v[2:5], v[42:45], 0
	v_mfma_f32_16x16x32_bf16 v[78:81], v[18:21], v[42:45], 0
	v_mfma_f32_16x16x32_bf16 v[82:85], v[2:5], v[50:53], 0
	v_mfma_f32_16x16x32_bf16 v[86:89], v[18:21], v[50:53], 0
	v_mfma_f32_16x16x32_bf16 v[58:61], v[6:9], v[30:33], v[58:61]
	v_mfma_f32_16x16x32_bf16 v[62:65], v[22:25], v[30:33], v[62:65]
	v_mfma_f32_16x16x32_bf16 v[66:69], v[6:9], v[38:41], v[66:69]
	v_mfma_f32_16x16x32_bf16 v[70:73], v[22:25], v[38:41], v[70:73]
	v_mfma_f32_16x16x32_bf16 v[74:77], v[6:9], v[46:49], v[74:77]
	v_mfma_f32_16x16x32_bf16 v[78:81], v[22:25], v[46:49], v[78:81]
	v_mfma_f32_16x16x32_bf16 v[82:85], v[6:9], v[54:57], v[82:85]
	v_mfma_f32_16x16x32_bf16 v[86:89], v[22:25], v[54:57], v[86:89]
	s_nop 0
	s_barrier
	s_add_i32 s55, 0, 0x14000
	v_lshl_add_u64 v[224:225], s[34:35], 0, v[0:1]
	s_mov_b64 s[56:57], 0x100
	s_add_i32 s53, s19, s41
	v_add_u32_e32 v201, s55, v16
	v_lshl_add_u64 v[106:107], v[224:225], 0, s[56:57]
	s_mov_b32 m0, s53
	v_lshl_add_u64 v[226:227], s[34:35], 0, v[14:15]
	s_add_i32 s19, s53, 0x2000
	ds_read_b128 v[90:93], v201
	ds_read_b128 v[94:97], v201 offset:1024
	ds_read_b128 v[98:101], v201 offset:2048
	ds_read_b128 v[102:105], v201 offset:3072
	global_load_lds_dwordx4 v[106:107], off
	v_lshl_add_u64 v[106:107], v[226:227], 0, s[56:57]
	s_mov_b32 m0, s19
	s_nop 0
	global_load_lds_dwordx4 v[106:107], off
	s_barrier
	s_waitcnt lgkmcnt(0)
	s_nop 0
	s_waitcnt lgkmcnt(0)
	v_mfma_f32_16x16x32_bf16 v[106:109], v[90:93], v[26:29], 0
	v_mfma_f32_16x16x32_bf16 v[26:29], v[98:101], v[26:29], 0
	v_mfma_f32_16x16x32_bf16 v[106:109], v[94:97], v[30:33], v[106:109]
	v_mfma_f32_16x16x32_bf16 v[26:29], v[102:105], v[30:33], v[26:29]
	v_mfma_f32_16x16x32_bf16 v[30:33], v[90:93], v[34:37], 0
	v_mfma_f32_16x16x32_bf16 v[34:37], v[98:101], v[34:37], 0
	v_mfma_f32_16x16x32_bf16 v[30:33], v[94:97], v[38:41], v[30:33]
	v_mfma_f32_16x16x32_bf16 v[34:37], v[102:105], v[38:41], v[34:37]
	v_mfma_f32_16x16x32_bf16 v[38:41], v[90:93], v[42:45], 0
	v_mfma_f32_16x16x32_bf16 v[42:45], v[98:101], v[42:45], 0
	v_mfma_f32_16x16x32_bf16 v[38:41], v[94:97], v[46:49], v[38:41]
	v_mfma_f32_16x16x32_bf16 v[42:45], v[102:105], v[46:49], v[42:45]
	v_mfma_f32_16x16x32_bf16 v[46:49], v[90:93], v[50:53], 0
	v_mfma_f32_16x16x32_bf16 v[50:53], v[98:101], v[50:53], 0
	v_mfma_f32_16x16x32_bf16 v[46:49], v[94:97], v[54:57], v[46:49]
	v_mfma_f32_16x16x32_bf16 v[50:53], v[102:105], v[54:57], v[50:53]
	s_nop 0
	v_lshl_add_u64 v[228:229], s[30:31], 0, v[10:11]
	s_mov_b32 m0, s15
	v_lshl_add_u64 v[138:139], v[228:229], 0, s[56:57]
	v_lshl_add_u64 v[230:231], s[30:31], 0, v[12:13]
	s_barrier
	ds_read_b128 v[54:57], v17 offset:16384
	ds_read_b128 v[110:113], v17 offset:17408
	ds_read_b128 v[114:117], v17 offset:18432
	ds_read_b128 v[118:121], v17 offset:19456
	ds_read_b128 v[122:125], v17 offset:20480
	ds_read_b128 v[126:129], v17 offset:21504
	ds_read_b128 v[130:133], v17 offset:22528
	ds_read_b128 v[134:137], v17 offset:23552
	global_load_lds_dwordx4 v[138:139], off
	v_lshl_add_u64 v[138:139], v[230:231], 0, s[56:57]
	s_mov_b32 m0, s44
	s_nop 0
	global_load_lds_dwordx4 v[138:139], off
	s_barrier
	s_waitcnt lgkmcnt(0)
	s_nop 0
	s_waitcnt lgkmcnt(0)
	v_mfma_f32_16x16x32_bf16 v[138:141], v[2:5], v[54:57], 0
	v_mfma_f32_16x16x32_bf16 v[146:149], v[2:5], v[114:117], 0
	v_mfma_f32_16x16x32_bf16 v[154:157], v[2:5], v[122:125], 0
	v_mfma_f32_16x16x32_bf16 v[2:5], v[2:5], v[130:133], 0
	v_mfma_f32_16x16x32_bf16 v[138:141], v[6:9], v[110:113], v[138:141]
	v_mfma_f32_16x16x32_bf16 v[142:145], v[18:21], v[54:57], 0
	v_mfma_f32_16x16x32_bf16 v[146:149], v[6:9], v[118:121], v[146:149]
	v_mfma_f32_16x16x32_bf16 v[150:153], v[18:21], v[114:117], 0
	v_mfma_f32_16x16x32_bf16 v[154:157], v[6:9], v[126:129], v[154:157]
	v_mfma_f32_16x16x32_bf16 v[158:161], v[18:21], v[122:125], 0
	v_mfma_f32_16x16x32_bf16 v[2:5], v[6:9], v[134:137], v[2:5]
	v_mfma_f32_16x16x32_bf16 v[6:9], v[18:21], v[130:133], 0
	v_mfma_f32_16x16x32_bf16 v[142:145], v[22:25], v[110:113], v[142:145]
	v_mfma_f32_16x16x32_bf16 v[150:153], v[22:25], v[118:121], v[150:153]
	v_mfma_f32_16x16x32_bf16 v[158:161], v[22:25], v[126:129], v[158:161]
	v_mfma_f32_16x16x32_bf16 v[6:9], v[22:25], v[134:137], v[6:9]
	s_nop 0
	s_barrier
; #define PG8_STAGE(bufoff, gbase, voff) do { _Pragma("unroll") for (int _i = 0; _i < 2; ++_i) \
;         __builtin_amdgcn_global_load_lds((const unsigned*)((const char*)(gbase) + (voff)[_i]), (LAS unsigned*)(lds + (bufoff) + ldsw + _i * 8192), 16, 0, 0); } while (0)
; #define PG8_LDA(dst, b, h) do { _Pragma("unroll") for (int m = 0; m < 4; ++m) _Pragma("unroll") for (int k = 0; k < 2; ++k) dst[m][k] = *(const LAS bf16x8*)(lds + PG8_SA(b, h) + aoff + m * 2048 + k * 1024); } while (0)
; #define PG8_LDB(dst, b, h) do { _Pragma("unroll") for (int n = 0; n < 2; ++n) _Pragma("unroll") for (int k = 0; k < 2; ++k) dst[n][k] = *(const LAS bf16x8*)(lds + PG8_SB(b, h) + boff + n * 2048 + k * 1024); } while (0)
; #define PG8_MMA(ai, bj, At, Bt) do { __builtin_amdgcn_s_setprio(1); _Pragma("unroll") for (int m = 0; m < 4; ++m) _Pragma("unroll") for (int n = 0; n < 2; ++n) _Pragma("unroll") for (int k = 0; k < 2; ++k) \
;         acc[ai][bj][m][n] = __builtin_amdgcn_mfma_f32_16x16x32_bf16(Bt[n][k], At[m][k], acc[ai][bj][m][n], 0, 0, 0); __builtin_amdgcn_s_setprio(0); } while (0)
; #define PG8_WAIT_V(n) asm volatile("s_waitcnt vmcnt(" #n ")" ::: "memory")
; #define PG8_WAIT_L(n) asm volatile("s_waitcnt lgkmcnt(" #n ")" ::: "memory")
; #define PG8_BAR __builtin_amdgcn_s_barrier()
; #define PG8_SCHED __builtin_amdgcn_sched_barrier(0)
; template <class Epi>
; DI void gemm_phase(LAS unsigned char* lds, const Gemm g, const StaticOrder& S, const Epi& E) {
;     ...
;             PG8_STAGE(PG8_SB(0, 1), b2 + hstepB, voffB);
;             PG8_WAIT_V(6); PG8_BAR; PG8_MMA(1, 1, At, B1); PG8_BAR;
;             PG8_LDB(B0, 1, 0); PG8_SCHED; PG8_LDA(At, 1, 0); PG8_STAGE(PG8_SA(0, 1), a2 + hstepA, voffA);
;             PG8_WAIT_L(8); PG8_BAR; PG8_WAIT_L(0); PG8_MMA(0, 0, At, B0); PG8_BAR; PG8_SCHED;
;             PG8_LDB(B1, 1, 1); PG8_STAGE(PG8_SB(1, 0), b3, voffB);
;             PG8_BAR; PG8_WAIT_L(0); PG8_MMA(0, 1, At, B1); PG8_BAR;
;             PG8_LDA(At, 1, 1); PG8_STAGE(PG8_SA(1, 0), a3, voffA);
;             PG8_BAR; PG8_WAIT_L(0); PG8_MMA(1, 0, At, B0); PG8_BAR; PG8_SCHED;
	s_add_u32 s56, s34, 0x10100
	s_addc_u32 s57, s35, 0
	s_add_i32 s55, s55, s41
	v_lshl_add_u64 v[18:19], s[56:57], 0, v[0:1]
	s_mov_b32 m0, s55
	s_add_i32 s52, s55, 0x2000
	global_load_lds_dwordx4 v[18:19], off
	v_lshl_add_u64 v[18:19], s[56:57], 0, v[14:15]
	s_mov_b32 m0, s52
	s_nop 0
	global_load_lds_dwordx4 v[18:19], off
	s_waitcnt vmcnt(6)
	s_barrier
	s_nop 0
	v_mfma_f32_16x16x32_bf16 v[18:21], v[90:93], v[54:57], 0
	v_mfma_f32_16x16x32_bf16 v[22:25], v[98:101], v[54:57], 0
	v_mfma_f32_16x16x32_bf16 v[18:21], v[94:97], v[110:113], v[18:21]
	v_mfma_f32_16x16x32_bf16 v[22:25], v[102:105], v[110:113], v[22:25]
	v_mfma_f32_16x16x32_bf16 v[54:57], v[90:93], v[114:117], 0
	v_mfma_f32_16x16x32_bf16 v[110:113], v[98:101], v[114:117], 0
	v_mfma_f32_16x16x32_bf16 v[114:117], v[90:93], v[122:125], 0
	v_mfma_f32_16x16x32_bf16 v[90:93], v[90:93], v[130:133], 0
	v_mfma_f32_16x16x32_bf16 v[54:57], v[94:97], v[118:121], v[54:57]
	v_mfma_f32_16x16x32_bf16 v[110:113], v[102:105], v[118:121], v[110:113]
	v_mfma_f32_16x16x32_bf16 v[114:117], v[94:97], v[126:129], v[114:117]
	v_mfma_f32_16x16x32_bf16 v[118:121], v[98:101], v[122:125], 0
	v_mfma_f32_16x16x32_bf16 v[90:93], v[94:97], v[134:137], v[90:93]
	v_mfma_f32_16x16x32_bf16 v[94:97], v[98:101], v[130:133], 0
	v_mfma_f32_16x16x32_bf16 v[118:121], v[102:105], v[126:129], v[118:121]
	v_mfma_f32_16x16x32_bf16 v[94:97], v[102:105], v[134:137], v[94:97]
	s_nop 0
	s_add_i32 s58, 0, 0x18000
	v_add_u32_e32 v232, s58, v16
	s_barrier
	ds_read_b128 v[98:101], v232
	ds_read_b128 v[102:105], v232 offset:1024
	ds_read_b128 v[122:125], v232 offset:2048
	ds_read_b128 v[126:129], v232 offset:3072
	s_add_u32 s56, s30, 0x10100
	s_addc_u32 s57, s31, 0
	s_mov_b32 m0, s46
	v_lshl_add_u64 v[186:187], s[56:57], 0, v[10:11]
	ds_read_b128 v[130:133], v17 offset:32768
	ds_read_b128 v[134:137], v17 offset:33792
	ds_read_b128 v[162:165], v17 offset:34816
	ds_read_b128 v[166:169], v17 offset:35840
	ds_read_b128 v[170:173], v17 offset:36864
	ds_read_b128 v[174:177], v17 offset:37888
	ds_read_b128 v[178:181], v17 offset:38912
	ds_read_b128 v[182:185], v17 offset:39936
	global_load_lds_dwordx4 v[186:187], off
	v_lshl_add_u64 v[186:187], s[56:57], 0, v[12:13]
	s_mov_b32 m0, s47
	s_nop 0
	global_load_lds_dwordx4 v[186:187], off
	s_waitcnt lgkmcnt(8)
	s_barrier
	s_waitcnt lgkmcnt(0)
	s_nop 0
	s_waitcnt lgkmcnt(0)
	v_mfma_f32_16x16x32_bf16 v[58:61], v[98:101], v[130:133], v[58:61]
	v_mfma_f32_16x16x32_bf16 v[62:65], v[122:125], v[130:133], v[62:65]
	v_mfma_f32_16x16x32_bf16 v[66:69], v[98:101], v[162:165], v[66:69]
	v_mfma_f32_16x16x32_bf16 v[70:73], v[122:125], v[162:165], v[70:73]
	v_mfma_f32_16x16x32_bf16 v[74:77], v[98:101], v[170:173], v[74:77]
	v_mfma_f32_16x16x32_bf16 v[78:81], v[122:125], v[170:173], v[78:81]
	v_mfma_f32_16x16x32_bf16 v[82:85], v[98:101], v[178:181], v[82:85]
	v_mfma_f32_16x16x32_bf16 v[86:89], v[122:125], v[178:181], v[86:89]
	v_mfma_f32_16x16x32_bf16 v[58:61], v[102:105], v[134:137], v[58:61]
	v_mfma_f32_16x16x32_bf16 v[62:65], v[126:129], v[134:137], v[62:65]
	v_mfma_f32_16x16x32_bf16 v[66:69], v[102:105], v[166:169], v[66:69]
	v_mfma_f32_16x16x32_bf16 v[70:73], v[126:129], v[166:169], v[70:73]
	v_mfma_f32_16x16x32_bf16 v[74:77], v[102:105], v[174:177], v[74:77]
	v_mfma_f32_16x16x32_bf16 v[78:81], v[126:129], v[174:177], v[78:81]
	v_mfma_f32_16x16x32_bf16 v[82:85], v[102:105], v[182:185], v[82:85]
	v_mfma_f32_16x16x32_bf16 v[86:89], v[126:129], v[182:185], v[86:89]
	s_nop 0
	s_barrier
	s_add_i32 s60, 0, 0x1c000
	s_mov_b64 s[62:63], 0x180
	s_add_i32 s57, s58, s41
	v_add_u32_e32 v233, s60, v16
	v_lshl_add_u64 v[224:225], v[224:225], 0, s[62:63]
	s_mov_b32 m0, s57
	s_add_i32 s56, s57, 0x2000
	ds_read_b128 v[186:189], v233
	ds_read_b128 v[190:193], v233 offset:1024
	ds_read_b128 v[216:219], v233 offset:2048
	ds_read_b128 v[220:223], v233 offset:3072
	global_load_lds_dwordx4 v[224:225], off
	v_lshl_add_u64 v[224:225], v[226:227], 0, s[62:63]
	s_mov_b32 m0, s56
	s_nop 0
	global_load_lds_dwordx4 v[224:225], off
	s_barrier
	s_waitcnt lgkmcnt(0)
	s_nop 0
	s_waitcnt lgkmcnt(0)
	v_mfma_f32_16x16x32_bf16 v[106:109], v[186:189], v[130:133], v[106:109]
	v_mfma_f32_16x16x32_bf16 v[26:29], v[216:219], v[130:133], v[26:29]
	v_mfma_f32_16x16x32_bf16 v[30:33], v[186:189], v[162:165], v[30:33]
	v_mfma_f32_16x16x32_bf16 v[34:37], v[216:219], v[162:165], v[34:37]
	v_mfma_f32_16x16x32_bf16 v[38:41], v[186:189], v[170:173], v[38:41]
	v_mfma_f32_16x16x32_bf16 v[42:45], v[216:219], v[170:173], v[42:45]
	v_mfma_f32_16x16x32_bf16 v[46:49], v[186:189], v[178:181], v[46:49]
	v_mfma_f32_16x16x32_bf16 v[50:53], v[216:219], v[178:181], v[50:53]
	v_mfma_f32_16x16x32_bf16 v[106:109], v[190:193], v[134:137], v[106:109]
	v_mfma_f32_16x16x32_bf16 v[26:29], v[220:223], v[134:137], v[26:29]
	v_mfma_f32_16x16x32_bf16 v[30:33], v[190:193], v[166:169], v[30:33]
	v_mfma_f32_16x16x32_bf16 v[34:37], v[220:223], v[166:169], v[34:37]
	v_mfma_f32_16x16x32_bf16 v[38:41], v[190:193], v[174:177], v[38:41]
	v_mfma_f32_16x16x32_bf16 v[42:45], v[220:223], v[174:177], v[42:45]
	v_mfma_f32_16x16x32_bf16 v[46:49], v[190:193], v[182:185], v[46:49]
	v_mfma_f32_16x16x32_bf16 v[50:53], v[220:223], v[182:185], v[50:53]
	s_nop 0
	s_mov_b32 m0, s48
	v_lshl_add_u64 v[224:225], v[228:229], 0, s[62:63]
	s_barrier
	ds_read_b128 v[130:133], v17 offset:49152
	ds_read_b128 v[134:137], v17 offset:50176
	ds_read_b128 v[162:165], v17 offset:51200
	ds_read_b128 v[166:169], v17 offset:52224
	ds_read_b128 v[170:173], v17 offset:53248
	ds_read_b128 v[174:177], v17 offset:54272
	ds_read_b128 v[178:181], v17 offset:55296
	ds_read_b128 v[182:185], v17 offset:56320
	global_load_lds_dwordx4 v[224:225], off
	v_lshl_add_u64 v[224:225], v[230:231], 0, s[62:63]
	s_mov_b32 m0, s49
	s_nop 0
	global_load_lds_dwordx4 v[224:225], off
	s_barrier
; #define PG8_STAGE(bufoff, gbase, voff) do { _Pragma("unroll") for (int _i = 0; _i < 2; ++_i) \
;         __builtin_amdgcn_global_load_lds((const unsigned*)((const char*)(gbase) + (voff)[_i]), (LAS unsigned*)(lds + (bufoff) + ldsw + _i * 8192), 16, 0, 0); } while (0)
; #define PG8_LDA(dst, b, h) do { _Pragma("unroll") for (int m = 0; m < 4; ++m) _Pragma("unroll") for (int k = 0; k < 2; ++k) dst[m][k] = *(const LAS bf16x8*)(lds + PG8_SA(b, h) + aoff + m * 2048 + k * 1024); } while (0)
; #define PG8_LDB(dst, b, h) do { _Pragma("unroll") for (int n = 0; n < 2; ++n) _Pragma("unroll") for (int k = 0; k < 2; ++k) dst[n][k] = *(const LAS bf16x8*)(lds + PG8_SB(b, h) + boff + n * 2048 + k * 1024); } while (0)
; #define PG8_MMA(ai, bj, At, Bt) do { __builtin_amdgcn_s_setprio(1); _Pragma("unroll") for (int m = 0; m < 4; ++m) _Pragma("unroll") for (int n = 0; n < 2; ++n) _Pragma("unroll") for (int k = 0; k < 2; ++k) \
;         acc[ai][bj][m][n] = __builtin_amdgcn_mfma_f32_16x16x32_bf16(Bt[n][k], At[m][k], acc[ai][bj][m][n], 0, 0, 0); __builtin_amdgcn_s_setprio(0); } while (0)
; #define PG8_WAIT_V(n) asm volatile("s_waitcnt vmcnt(" #n ")" ::: "memory")
; #define PG8_WAIT_L(n) asm volatile("s_waitcnt lgkmcnt(" #n ")" ::: "memory")
; #define PG8_BAR __builtin_amdgcn_s_barrier()
; #define PG8_SCHED __builtin_amdgcn_sched_barrier(0)
; template <class Epi>
; DI void gemm_phase(LAS unsigned char* lds, const Gemm g, const StaticOrder& S, const Epi& E) {
;     ...
;             PG8_WAIT_V(6); PG8_BAR; PG8_MMA(1, 1, At, B1); PG8_BAR;
;             PG8_LDB(B0, 1, 0); PG8_SCHED; PG8_LDA(At, 1, 0); PG8_STAGE(PG8_SA(0, 1), a2 + hstepA, voffA);
;             PG8_WAIT_L(8); PG8_BAR; PG8_WAIT_L(0); PG8_MMA(0, 0, At, B0); PG8_BAR; PG8_SCHED;
;             PG8_LDB(B1, 1, 1); PG8_STAGE(PG8_SB(1, 0), b3, voffB);
;             PG8_BAR; PG8_WAIT_L(0); PG8_MMA(0, 1, At, B1); PG8_BAR;
;             PG8_LDA(At, 1, 1); PG8_STAGE(PG8_SA(1, 0), a3, voffA);
;             PG8_BAR; PG8_WAIT_L(0); PG8_MMA(1, 0, At, B0); PG8_BAR; PG8_SCHED;
;             PG8_STAGE(PG8_SB(1, 1), b3 + hstepB, voffB);
;             PG8_WAIT_V(6); PG8_BAR; PG8_MMA(1, 1, At, B1); PG8_BAR;
	s_waitcnt lgkmcnt(0)
	s_nop 0
	s_waitcnt lgkmcnt(0)
	v_mfma_f32_16x16x32_bf16 v[138:141], v[98:101], v[130:133], v[138:141]
	v_mfma_f32_16x16x32_bf16 v[142:145], v[122:125], v[130:133], v[142:145]
	v_mfma_f32_16x16x32_bf16 v[146:149], v[98:101], v[162:165], v[146:149]
	v_mfma_f32_16x16x32_bf16 v[150:153], v[122:125], v[162:165], v[150:153]
	v_mfma_f32_16x16x32_bf16 v[154:157], v[98:101], v[170:173], v[154:157]
	v_mfma_f32_16x16x32_bf16 v[158:161], v[122:125], v[170:173], v[158:161]
	v_mfma_f32_16x16x32_bf16 v[2:5], v[98:101], v[178:181], v[2:5]
	v_mfma_f32_16x16x32_bf16 v[6:9], v[122:125], v[178:181], v[6:9]
	v_mfma_f32_16x16x32_bf16 v[138:141], v[102:105], v[134:137], v[138:141]
	v_mfma_f32_16x16x32_bf16 v[142:145], v[126:129], v[134:137], v[142:145]
	v_mfma_f32_16x16x32_bf16 v[146:149], v[102:105], v[166:169], v[146:149]
	v_mfma_f32_16x16x32_bf16 v[150:153], v[126:129], v[166:169], v[150:153]
	v_mfma_f32_16x16x32_bf16 v[154:157], v[102:105], v[174:177], v[154:157]
	v_mfma_f32_16x16x32_bf16 v[158:161], v[126:129], v[174:177], v[158:161]
	v_mfma_f32_16x16x32_bf16 v[2:5], v[102:105], v[182:185], v[2:5]
	v_mfma_f32_16x16x32_bf16 v[6:9], v[126:129], v[182:185], v[6:9]
	s_nop 0
	s_barrier
	s_add_u32 s58, s34, 0x10180
	s_addc_u32 s59, s35, 0
	s_add_i32 s35, s60, s41
	v_lshl_add_u64 v[98:99], s[58:59], 0, v[0:1]
	s_mov_b32 m0, s35
	s_add_i32 s34, s35, 0x2000
	global_load_lds_dwordx4 v[98:99], off
	v_lshl_add_u64 v[98:99], s[58:59], 0, v[14:15]
	s_mov_b32 m0, s34
	s_nop 0
	global_load_lds_dwordx4 v[98:99], off
	s_waitcnt vmcnt(6)
	s_barrier
	s_nop 0
	v_mfma_f32_16x16x32_bf16 v[18:21], v[186:189], v[130:133], v[18:21]
	v_mfma_f32_16x16x32_bf16 v[22:25], v[216:219], v[130:133], v[22:25]
	v_mfma_f32_16x16x32_bf16 v[54:57], v[186:189], v[162:165], v[54:57]
	v_mfma_f32_16x16x32_bf16 v[98:101], v[216:219], v[162:165], v[110:113]
	v_mfma_f32_16x16x32_bf16 v[102:105], v[186:189], v[170:173], v[114:117]
	v_mfma_f32_16x16x32_bf16 v[110:113], v[216:219], v[170:173], v[118:121]
	v_mfma_f32_16x16x32_bf16 v[90:93], v[186:189], v[178:181], v[90:93]
	v_mfma_f32_16x16x32_bf16 v[94:97], v[216:219], v[178:181], v[94:97]
	v_mfma_f32_16x16x32_bf16 v[18:21], v[190:193], v[134:137], v[18:21]
	v_mfma_f32_16x16x32_bf16 v[22:25], v[220:223], v[134:137], v[22:25]
	v_mfma_f32_16x16x32_bf16 v[54:57], v[190:193], v[166:169], v[54:57]
	v_mfma_f32_16x16x32_bf16 v[98:101], v[220:223], v[166:169], v[98:101]
	v_mfma_f32_16x16x32_bf16 v[102:105], v[190:193], v[174:177], v[102:105]
	v_mfma_f32_16x16x32_bf16 v[110:113], v[220:223], v[174:177], v[110:113]
	v_mfma_f32_16x16x32_bf16 v[90:93], v[190:193], v[182:185], v[90:93]
	v_mfma_f32_16x16x32_bf16 v[94:97], v[220:223], v[182:185], v[94:97]
	s_nop 0
	s_barrier
	ds_read_b128 v[114:117], v200
	ds_read_b128 v[118:121], v200 offset:1024
	ds_read_b128 v[122:125], v200 offset:2048
	ds_read_b128 v[126:129], v200 offset:3072
	s_add_u32 s30, s30, 0x10180
	s_addc_u32 s31, s31, 0
	s_mov_b32 m0, s54
	v_lshl_add_u64 v[186:187], s[30:31], 0, v[10:11]
	ds_read_b128 v[130:133], v17
	ds_read_b128 v[134:137], v17 offset:1024
	ds_read_b128 v[162:165], v17 offset:2048
	ds_read_b128 v[166:169], v17 offset:3072
	ds_read_b128 v[170:173], v17 offset:4096
	ds_read_b128 v[174:177], v17 offset:5120
	ds_read_b128 v[178:181], v17 offset:6144
	ds_read_b128 v[182:185], v17 offset:7168
	global_load_lds_dwordx4 v[186:187], off
	v_lshl_add_u64 v[186:187], s[30:31], 0, v[12:13]
	s_mov_b32 m0, s17
	s_nop 0
	global_load_lds_dwordx4 v[186:187], off
	s_waitcnt lgkmcnt(8)
	s_barrier
	s_waitcnt lgkmcnt(0)
	s_nop 0
	s_waitcnt lgkmcnt(0)
	v_mfma_f32_16x16x32_bf16 v[58:61], v[114:117], v[130:133], v[58:61]
	v_mfma_f32_16x16x32_bf16 v[62:65], v[122:125], v[130:133], v[62:65]
	v_mfma_f32_16x16x32_bf16 v[66:69], v[114:117], v[162:165], v[66:69]
	v_mfma_f32_16x16x32_bf16 v[70:73], v[122:125], v[162:165], v[70:73]
	v_mfma_f32_16x16x32_bf16 v[74:77], v[114:117], v[170:173], v[74:77]
	v_mfma_f32_16x16x32_bf16 v[78:81], v[122:125], v[170:173], v[78:81]
	v_mfma_f32_16x16x32_bf16 v[82:85], v[114:117], v[178:181], v[82:85]
	v_mfma_f32_16x16x32_bf16 v[86:89], v[122:125], v[178:181], v[86:89]
	v_mfma_f32_16x16x32_bf16 v[58:61], v[118:121], v[134:137], v[58:61]
	v_mfma_f32_16x16x32_bf16 v[62:65], v[126:129], v[134:137], v[62:65]
	v_mfma_f32_16x16x32_bf16 v[66:69], v[118:121], v[166:169], v[66:69]
	v_mfma_f32_16x16x32_bf16 v[70:73], v[126:129], v[166:169], v[70:73]
	v_mfma_f32_16x16x32_bf16 v[74:77], v[118:121], v[174:177], v[74:77]
	v_mfma_f32_16x16x32_bf16 v[78:81], v[126:129], v[174:177], v[78:81]
	v_mfma_f32_16x16x32_bf16 v[82:85], v[118:121], v[182:185], v[82:85]
	v_mfma_f32_16x16x32_bf16 v[86:89], v[126:129], v[182:185], v[86:89]
	s_nop 0
	s_barrier
	s_mov_b32 m0, s53
	v_lshl_add_u64 v[224:225], s[28:29], 0, v[0:1]
	ds_read_b128 v[186:189], v201
	ds_read_b128 v[190:193], v201 offset:1024
	ds_read_b128 v[216:219], v201 offset:2048
	ds_read_b128 v[220:223], v201 offset:3072
	global_load_lds_dwordx4 v[224:225], off
	v_lshl_add_u64 v[226:227], s[28:29], 0, v[14:15]
	s_mov_b32 m0, s19
	s_nop 0
	global_load_lds_dwordx4 v[226:227], off
	s_barrier
; #define PG8_STAGE(bufoff, gbase, voff) do { _Pragma("unroll") for (int _i = 0; _i < 2; ++_i) \
;         __builtin_amdgcn_global_load_lds((const unsigned*)((const char*)(gbase) + (voff)[_i]), (LAS unsigned*)(lds + (bufoff) + ldsw + _i * 8192), 16, 0, 0); } while (0)
; #define PG8_LDA(dst, b, h) do { _Pragma("unroll") for (int m = 0; m < 4; ++m) _Pragma("unroll") for (int k = 0; k < 2; ++k) dst[m][k] = *(const LAS bf16x8*)(lds + PG8_SA(b, h) + aoff + m * 2048 + k * 1024); } while (0)
; #define PG8_LDB(dst, b, h) do { _Pragma("unroll") for (int n = 0; n < 2; ++n) _Pragma("unroll") for (int k = 0; k < 2; ++k) dst[n][k] = *(const LAS bf16x8*)(lds + PG8_SB(b, h) + boff + n * 2048 + k * 1024); } while (0)
; #define PG8_MMA(ai, bj, At, Bt) do { __builtin_amdgcn_s_setprio(1); _Pragma("unroll") for (int m = 0; m < 4; ++m) _Pragma("unroll") for (int n = 0; n < 2; ++n) _Pragma("unroll") for (int k = 0; k < 2; ++k) \
;         acc[ai][bj][m][n] = __builtin_amdgcn_mfma_f32_16x16x32_bf16(Bt[n][k], At[m][k], acc[ai][bj][m][n], 0, 0, 0); __builtin_amdgcn_s_setprio(0); } while (0)
; #define PG8_WAIT_V(n) asm volatile("s_waitcnt vmcnt(" #n ")" ::: "memory")
; #define PG8_WAIT_L(n) asm volatile("s_waitcnt lgkmcnt(" #n ")" ::: "memory")
; #define PG8_BAR __builtin_amdgcn_s_barrier()
; #define PG8_SCHED __builtin_amdgcn_sched_barrier(0)
; template <class Epi>
; DI void gemm_phase(LAS unsigned char* lds, const Gemm g, const StaticOrder& S, const Epi& E) {
;     ...
;             PG8_LDB(B1, 1, 1); PG8_STAGE(PG8_SB(1, 0), b3, voffB);
;             PG8_BAR; PG8_WAIT_L(0); PG8_MMA(0, 1, At, B1); PG8_BAR;
;             PG8_LDA(At, 1, 1); PG8_STAGE(PG8_SA(1, 0), a3, voffA);
;             PG8_BAR; PG8_WAIT_L(0); PG8_MMA(1, 0, At, B0); PG8_BAR; PG8_SCHED;
;             PG8_STAGE(PG8_SB(1, 1), b3 + hstepB, voffB);
;             PG8_WAIT_V(6); PG8_BAR; PG8_MMA(1, 1, At, B1); PG8_BAR;
	s_waitcnt lgkmcnt(0)
	s_nop 0
	s_waitcnt lgkmcnt(0)
	v_mfma_f32_16x16x32_bf16 v[106:109], v[186:189], v[130:133], v[106:109]
	v_mfma_f32_16x16x32_bf16 v[26:29], v[216:219], v[130:133], v[26:29]
	v_mfma_f32_16x16x32_bf16 v[30:33], v[186:189], v[162:165], v[30:33]
	v_mfma_f32_16x16x32_bf16 v[34:37], v[216:219], v[162:165], v[34:37]
	v_mfma_f32_16x16x32_bf16 v[38:41], v[186:189], v[170:173], v[38:41]
	v_mfma_f32_16x16x32_bf16 v[42:45], v[216:219], v[170:173], v[42:45]
	v_mfma_f32_16x16x32_bf16 v[46:49], v[186:189], v[178:181], v[46:49]
	v_mfma_f32_16x16x32_bf16 v[50:53], v[216:219], v[178:181], v[50:53]
	v_mfma_f32_16x16x32_bf16 v[106:109], v[190:193], v[134:137], v[106:109]
	v_mfma_f32_16x16x32_bf16 v[26:29], v[220:223], v[134:137], v[26:29]
	v_mfma_f32_16x16x32_bf16 v[30:33], v[190:193], v[166:169], v[30:33]
	v_mfma_f32_16x16x32_bf16 v[34:37], v[220:223], v[166:169], v[34:37]
	v_mfma_f32_16x16x32_bf16 v[38:41], v[190:193], v[174:177], v[38:41]
	v_mfma_f32_16x16x32_bf16 v[42:45], v[220:223], v[174:177], v[42:45]
	v_mfma_f32_16x16x32_bf16 v[46:49], v[190:193], v[182:185], v[46:49]
	v_mfma_f32_16x16x32_bf16 v[50:53], v[220:223], v[182:185], v[50:53]
	s_nop 0
	s_mov_b32 m0, s15
	v_lshl_add_u64 v[228:229], s[36:37], 0, v[10:11]
	s_barrier
	ds_read_b128 v[130:133], v17 offset:16384
	ds_read_b128 v[134:137], v17 offset:17408
	ds_read_b128 v[162:165], v17 offset:18432
	ds_read_b128 v[166:169], v17 offset:19456
	ds_read_b128 v[170:173], v17 offset:20480
	ds_read_b128 v[174:177], v17 offset:21504
	ds_read_b128 v[178:181], v17 offset:22528
	ds_read_b128 v[182:185], v17 offset:23552
	global_load_lds_dwordx4 v[228:229], off
	v_lshl_add_u64 v[230:231], s[36:37], 0, v[12:13]
	s_mov_b32 m0, s44
	s_nop 0
	global_load_lds_dwordx4 v[230:231], off
	s_barrier
	s_waitcnt lgkmcnt(0)
	s_nop 0
	s_waitcnt lgkmcnt(0)
	v_mfma_f32_16x16x32_bf16 v[138:141], v[114:117], v[130:133], v[138:141]
	v_mfma_f32_16x16x32_bf16 v[142:145], v[122:125], v[130:133], v[142:145]
	v_mfma_f32_16x16x32_bf16 v[146:149], v[114:117], v[162:165], v[146:149]
	v_mfma_f32_16x16x32_bf16 v[150:153], v[122:125], v[162:165], v[150:153]
	v_mfma_f32_16x16x32_bf16 v[154:157], v[114:117], v[170:173], v[154:157]
	v_mfma_f32_16x16x32_bf16 v[158:161], v[122:125], v[170:173], v[158:161]
	v_mfma_f32_16x16x32_bf16 v[2:5], v[114:117], v[178:181], v[2:5]
	v_mfma_f32_16x16x32_bf16 v[6:9], v[122:125], v[178:181], v[6:9]
	v_mfma_f32_16x16x32_bf16 v[138:141], v[118:121], v[134:137], v[138:141]
	v_mfma_f32_16x16x32_bf16 v[142:145], v[126:129], v[134:137], v[142:145]
	v_mfma_f32_16x16x32_bf16 v[146:149], v[118:121], v[166:169], v[146:149]
	v_mfma_f32_16x16x32_bf16 v[150:153], v[126:129], v[166:169], v[150:153]
	v_mfma_f32_16x16x32_bf16 v[154:157], v[118:121], v[174:177], v[154:157]
	v_mfma_f32_16x16x32_bf16 v[158:161], v[126:129], v[174:177], v[158:161]
	v_mfma_f32_16x16x32_bf16 v[2:5], v[118:121], v[182:185], v[2:5]
	v_mfma_f32_16x16x32_bf16 v[6:9], v[126:129], v[182:185], v[6:9]
	s_nop 0
	s_barrier
	s_add_u32 s30, s28, 0x10000
	s_addc_u32 s31, s29, 0
	s_mov_b32 m0, s55
	v_lshl_add_u64 v[114:115], s[30:31], 0, v[0:1]
	global_load_lds_dwordx4 v[114:115], off
	v_lshl_add_u64 v[114:115], s[30:31], 0, v[14:15]
	s_mov_b32 m0, s52
	s_nop 0
	global_load_lds_dwordx4 v[114:115], off
	s_waitcnt vmcnt(6)
	s_barrier
	s_nop 0
	v_mfma_f32_16x16x32_bf16 v[18:21], v[186:189], v[130:133], v[18:21]
	v_mfma_f32_16x16x32_bf16 v[22:25], v[216:219], v[130:133], v[22:25]
	v_mfma_f32_16x16x32_bf16 v[54:57], v[186:189], v[162:165], v[54:57]
	v_mfma_f32_16x16x32_bf16 v[98:101], v[216:219], v[162:165], v[98:101]
	v_mfma_f32_16x16x32_bf16 v[102:105], v[186:189], v[170:173], v[102:105]
	v_mfma_f32_16x16x32_bf16 v[110:113], v[216:219], v[170:173], v[110:113]
	v_mfma_f32_16x16x32_bf16 v[90:93], v[186:189], v[178:181], v[90:93]
	v_mfma_f32_16x16x32_bf16 v[94:97], v[216:219], v[178:181], v[94:97]
	v_mfma_f32_16x16x32_bf16 v[18:21], v[190:193], v[134:137], v[18:21]
	v_mfma_f32_16x16x32_bf16 v[22:25], v[220:223], v[134:137], v[22:25]
	v_mfma_f32_16x16x32_bf16 v[54:57], v[190:193], v[166:169], v[54:57]
	v_mfma_f32_16x16x32_bf16 v[98:101], v[220:223], v[166:169], v[98:101]
	v_mfma_f32_16x16x32_bf16 v[102:105], v[190:193], v[174:177], v[102:105]
	v_mfma_f32_16x16x32_bf16 v[110:113], v[220:223], v[174:177], v[110:113]
	v_mfma_f32_16x16x32_bf16 v[90:93], v[190:193], v[182:185], v[90:93]
	v_mfma_f32_16x16x32_bf16 v[94:97], v[220:223], v[182:185], v[94:97]
	s_nop 0
	s_barrier
	ds_read_b128 v[114:117], v232
	ds_read_b128 v[118:121], v232 offset:1024
	ds_read_b128 v[122:125], v232 offset:2048
	ds_read_b128 v[126:129], v232 offset:3072
	s_add_u32 s30, s36, 0x10000
	s_addc_u32 s31, s37, 0
	s_mov_b32 m0, s46
	v_lshl_add_u64 v[186:187], s[30:31], 0, v[10:11]
	ds_read_b128 v[130:133], v17 offset:32768
	ds_read_b128 v[134:137], v17 offset:33792
	ds_read_b128 v[162:165], v17 offset:34816
	ds_read_b128 v[166:169], v17 offset:35840
	ds_read_b128 v[170:173], v17 offset:36864
	ds_read_b128 v[174:177], v17 offset:37888
	ds_read_b128 v[178:181], v17 offset:38912
	ds_read_b128 v[182:185], v17 offset:39936
	global_load_lds_dwordx4 v[186:187], off
	v_lshl_add_u64 v[186:187], s[30:31], 0, v[12:13]
	s_mov_b32 m0, s47
	s_nop 0
	global_load_lds_dwordx4 v[186:187], off
	s_waitcnt lgkmcnt(8)
	s_barrier
; #define PG8_STAGE(bufoff, gbase, voff) do { _Pragma("unroll") for (int _i = 0; _i < 2; ++_i) \
;         __builtin_amdgcn_global_load_lds((const unsigned*)((const char*)(gbase) + (voff)[_i]), (LAS unsigned*)(lds + (bufoff) + ldsw + _i * 8192), 16, 0, 0); } while (0)
; #define PG8_LDA(dst, b, h) do { _Pragma("unroll") for (int m = 0; m < 4; ++m) _Pragma("unroll") for (int k = 0; k < 2; ++k) dst[m][k] = *(const LAS bf16x8*)(lds + PG8_SA(b, h) + aoff + m * 2048 + k * 1024); } while (0)
; #define PG8_LDB(dst, b, h) do { _Pragma("unroll") for (int n = 0; n < 2; ++n) _Pragma("unroll") for (int k = 0; k < 2; ++k) dst[n][k] = *(const LAS bf16x8*)(lds + PG8_SB(b, h) + boff + n * 2048 + k * 1024); } while (0)
; #define PG8_MMA(ai, bj, At, Bt) do { __builtin_amdgcn_s_setprio(1); _Pragma("unroll") for (int m = 0; m < 4; ++m) _Pragma("unroll") for (int n = 0; n < 2; ++n) _Pragma("unroll") for (int k = 0; k < 2; ++k) \
;         acc[ai][bj][m][n] = __builtin_amdgcn_mfma_f32_16x16x32_bf16(Bt[n][k], At[m][k], acc[ai][bj][m][n], 0, 0, 0); __builtin_amdgcn_s_setprio(0); } while (0)
; #define PG8_WAIT_V(n) asm volatile("s_waitcnt vmcnt(" #n ")" ::: "memory")
; #define PG8_WAIT_L(n) asm volatile("s_waitcnt lgkmcnt(" #n ")" ::: "memory")
; #define PG8_BAR __builtin_amdgcn_s_barrier()
; #define PG8_SCHED __builtin_amdgcn_sched_barrier(0)
; template <class Epi>
; DI void gemm_phase(LAS unsigned char* lds, const Gemm g, const StaticOrder& S, const Epi& E) {
;     ...
;             PG8_LDB(B1, 1, 1); PG8_STAGE(PG8_SB(1, 0), b3, voffB);
;             PG8_BAR; PG8_WAIT_L(0); PG8_MMA(0, 1, At, B1); PG8_BAR;
;             PG8_LDA(At, 1, 1); PG8_STAGE(PG8_SA(1, 0), a3, voffA);
;             PG8_BAR; PG8_WAIT_L(0); PG8_MMA(1, 0, At, B0); PG8_BAR; PG8_SCHED;
;             PG8_STAGE(PG8_SB(1, 1), b3 + hstepB, voffB);
;             PG8_WAIT_V(6); PG8_BAR; PG8_MMA(1, 1, At, B1); PG8_BAR;
	s_waitcnt lgkmcnt(0)
	s_nop 0
	s_waitcnt lgkmcnt(0)
	v_mfma_f32_16x16x32_bf16 v[58:61], v[114:117], v[130:133], v[58:61]
	v_mfma_f32_16x16x32_bf16 v[62:65], v[122:125], v[130:133], v[62:65]
	v_mfma_f32_16x16x32_bf16 v[66:69], v[114:117], v[162:165], v[66:69]
	v_mfma_f32_16x16x32_bf16 v[70:73], v[122:125], v[162:165], v[70:73]
	v_mfma_f32_16x16x32_bf16 v[74:77], v[114:117], v[170:173], v[74:77]
	v_mfma_f32_16x16x32_bf16 v[78:81], v[122:125], v[170:173], v[78:81]
	v_mfma_f32_16x16x32_bf16 v[82:85], v[114:117], v[178:181], v[82:85]
	v_mfma_f32_16x16x32_bf16 v[86:89], v[122:125], v[178:181], v[86:89]
	v_mfma_f32_16x16x32_bf16 v[58:61], v[118:121], v[134:137], v[58:61]
	v_mfma_f32_16x16x32_bf16 v[62:65], v[126:129], v[134:137], v[62:65]
	v_mfma_f32_16x16x32_bf16 v[66:69], v[118:121], v[166:169], v[66:69]
	v_mfma_f32_16x16x32_bf16 v[70:73], v[126:129], v[166:169], v[70:73]
	v_mfma_f32_16x16x32_bf16 v[74:77], v[118:121], v[174:177], v[74:77]
	v_mfma_f32_16x16x32_bf16 v[78:81], v[126:129], v[174:177], v[78:81]
	v_mfma_f32_16x16x32_bf16 v[82:85], v[118:121], v[182:185], v[82:85]
	v_mfma_f32_16x16x32_bf16 v[86:89], v[126:129], v[182:185], v[86:89]
	s_nop 0
	s_barrier
	s_mov_b32 m0, s57
	v_lshl_add_u64 v[224:225], v[224:225], 0, s[2:3]
	ds_read_b128 v[186:189], v233
	ds_read_b128 v[190:193], v233 offset:1024
	ds_read_b128 v[216:219], v233 offset:2048
	ds_read_b128 v[220:223], v233 offset:3072
	global_load_lds_dwordx4 v[224:225], off
	v_lshl_add_u64 v[224:225], v[226:227], 0, s[2:3]
	s_mov_b32 m0, s56
	s_nop 0
	global_load_lds_dwordx4 v[224:225], off
	s_barrier
	s_waitcnt lgkmcnt(0)
	s_nop 0
	s_waitcnt lgkmcnt(0)
	v_mfma_f32_16x16x32_bf16 v[106:109], v[186:189], v[130:133], v[106:109]
	v_mfma_f32_16x16x32_bf16 v[26:29], v[216:219], v[130:133], v[26:29]
	v_mfma_f32_16x16x32_bf16 v[30:33], v[186:189], v[162:165], v[30:33]
	v_mfma_f32_16x16x32_bf16 v[34:37], v[216:219], v[162:165], v[34:37]
	v_mfma_f32_16x16x32_bf16 v[38:41], v[186:189], v[170:173], v[38:41]
	v_mfma_f32_16x16x32_bf16 v[42:45], v[216:219], v[170:173], v[42:45]
	v_mfma_f32_16x16x32_bf16 v[46:49], v[186:189], v[178:181], v[46:49]
	v_mfma_f32_16x16x32_bf16 v[50:53], v[216:219], v[178:181], v[50:53]
	v_mfma_f32_16x16x32_bf16 v[106:109], v[190:193], v[134:137], v[106:109]
	v_mfma_f32_16x16x32_bf16 v[26:29], v[220:223], v[134:137], v[26:29]
	v_mfma_f32_16x16x32_bf16 v[30:33], v[190:193], v[166:169], v[30:33]
	v_mfma_f32_16x16x32_bf16 v[34:37], v[220:223], v[166:169], v[34:37]
	v_mfma_f32_16x16x32_bf16 v[38:41], v[190:193], v[174:177], v[38:41]
	v_mfma_f32_16x16x32_bf16 v[42:45], v[220:223], v[174:177], v[42:45]
	v_mfma_f32_16x16x32_bf16 v[46:49], v[190:193], v[182:185], v[46:49]
	v_mfma_f32_16x16x32_bf16 v[50:53], v[220:223], v[182:185], v[50:53]
	s_nop 0
	s_mov_b32 m0, s48
	v_lshl_add_u64 v[224:225], v[228:229], 0, s[2:3]
	s_barrier
	ds_read_b128 v[130:133], v17 offset:49152
	ds_read_b128 v[134:137], v17 offset:50176
	ds_read_b128 v[162:165], v17 offset:51200
	ds_read_b128 v[166:169], v17 offset:52224
	ds_read_b128 v[170:173], v17 offset:53248
	ds_read_b128 v[174:177], v17 offset:54272
	ds_read_b128 v[178:181], v17 offset:55296
	ds_read_b128 v[182:185], v17 offset:56320
	global_load_lds_dwordx4 v[224:225], off
	v_lshl_add_u64 v[224:225], v[230:231], 0, s[2:3]
	s_mov_b32 m0, s49
	s_nop 0
	global_load_lds_dwordx4 v[224:225], off
	s_barrier
	s_waitcnt lgkmcnt(0)
	s_nop 0
	s_waitcnt lgkmcnt(0)
	v_mfma_f32_16x16x32_bf16 v[138:141], v[114:117], v[130:133], v[138:141]
	v_mfma_f32_16x16x32_bf16 v[142:145], v[122:125], v[130:133], v[142:145]
	v_mfma_f32_16x16x32_bf16 v[146:149], v[114:117], v[162:165], v[146:149]
	v_mfma_f32_16x16x32_bf16 v[150:153], v[122:125], v[162:165], v[150:153]
	v_mfma_f32_16x16x32_bf16 v[154:157], v[114:117], v[170:173], v[154:157]
	v_mfma_f32_16x16x32_bf16 v[158:161], v[122:125], v[170:173], v[158:161]
	v_mfma_f32_16x16x32_bf16 v[2:5], v[114:117], v[178:181], v[2:5]
	v_mfma_f32_16x16x32_bf16 v[6:9], v[122:125], v[178:181], v[6:9]
	v_mfma_f32_16x16x32_bf16 v[138:141], v[118:121], v[134:137], v[138:141]
	v_mfma_f32_16x16x32_bf16 v[142:145], v[126:129], v[134:137], v[142:145]
	v_mfma_f32_16x16x32_bf16 v[146:149], v[118:121], v[166:169], v[146:149]
	v_mfma_f32_16x16x32_bf16 v[150:153], v[126:129], v[166:169], v[150:153]
	v_mfma_f32_16x16x32_bf16 v[154:157], v[118:121], v[174:177], v[154:157]
	v_mfma_f32_16x16x32_bf16 v[158:161], v[126:129], v[174:177], v[158:161]
	v_mfma_f32_16x16x32_bf16 v[2:5], v[118:121], v[182:185], v[2:5]
	v_mfma_f32_16x16x32_bf16 v[6:9], v[126:129], v[182:185], v[6:9]
	s_nop 0
	s_barrier
	s_add_u32 s28, s28, 0x10080
	s_addc_u32 s29, s29, 0
	s_mov_b32 m0, s35
	v_lshl_add_u64 v[114:115], s[28:29], 0, v[0:1]
	global_load_lds_dwordx4 v[114:115], off
	v_lshl_add_u64 v[114:115], s[28:29], 0, v[14:15]
	s_mov_b32 m0, s34
	s_nop 0
	global_load_lds_dwordx4 v[114:115], off
	s_waitcnt vmcnt(6)
	s_barrier
	s_nop 0
	v_mfma_f32_16x16x32_bf16 v[18:21], v[186:189], v[130:133], v[18:21]
	v_mfma_f32_16x16x32_bf16 v[22:25], v[216:219], v[130:133], v[22:25]
	v_mfma_f32_16x16x32_bf16 v[54:57], v[186:189], v[162:165], v[54:57]
	v_mfma_f32_16x16x32_bf16 v[98:101], v[216:219], v[162:165], v[98:101]
	v_mfma_f32_16x16x32_bf16 v[102:105], v[186:189], v[170:173], v[102:105]
	v_mfma_f32_16x16x32_bf16 v[110:113], v[216:219], v[170:173], v[110:113]
	v_mfma_f32_16x16x32_bf16 v[90:93], v[186:189], v[178:181], v[90:93]
	v_mfma_f32_16x16x32_bf16 v[94:97], v[216:219], v[178:181], v[94:97]
	v_mfma_f32_16x16x32_bf16 v[18:21], v[190:193], v[134:137], v[18:21]
	v_mfma_f32_16x16x32_bf16 v[22:25], v[220:223], v[134:137], v[22:25]
	v_mfma_f32_16x16x32_bf16 v[54:57], v[190:193], v[166:169], v[54:57]
	v_mfma_f32_16x16x32_bf16 v[98:101], v[220:223], v[166:169], v[98:101]
	v_mfma_f32_16x16x32_bf16 v[102:105], v[190:193], v[174:177], v[102:105]
	v_mfma_f32_16x16x32_bf16 v[110:113], v[220:223], v[174:177], v[110:113]
	v_mfma_f32_16x16x32_bf16 v[90:93], v[190:193], v[182:185], v[90:93]
	v_mfma_f32_16x16x32_bf16 v[94:97], v[220:223], v[182:185], v[94:97]
	s_nop 0
	v_cvt_pk_bf16_f32 v66, v66, v67
	v_cvt_pk_bf16_f32 v67, v68, v69
	v_cvt_pk_bf16_f32 v68, v70, v71
	v_mov_b32_e32 v70, v238
	s_barrier
	s_lshl_b32 s14, s14, 8
	v_ashrrev_i32_e32 v71, 2, v70
	v_cvt_pk_bf16_f32 v69, v72, v73
	v_and_b32_e32 v71, 0xffffffc0, v71
	v_lshrrev_b32_e32 v72, 1, v70
	v_and_or_b32 v70, v70, 15, s14
	v_add_u32_e32 v70, v70, v71
	v_and_b32_e32 v72, 0x78, v72
	v_or_b32_e32 v114, 16, v70
	v_lshl_or_b32 v72, s51, 8, v72
	v_ashrrev_i32_e32 v115, 31, v114
	v_cvt_pk_bf16_f32 v30, v30, v31
	v_cvt_pk_bf16_f32 v31, v32, v33
	v_cvt_pk_bf16_f32 v32, v34, v35
	v_or_b32_e32 v34, 32, v70
	v_ashrrev_i32_e32 v73, 31, v72
	v_lshlrev_b64 v[114:115], 11, v[114:115]
	v_ashrrev_i32_e32 v35, 31, v34
	v_lshlrev_b64 v[72:73], 1, v[72:73]
	v_lshl_add_u64 v[114:115], s[6:7], 0, v[114:115]
	v_lshlrev_b64 v[34:35], 11, v[34:35]
	v_lshl_add_u64 v[114:115], v[114:115], 0, v[72:73]
	v_cvt_pk_bf16_f32 v33, v36, v37
	v_lshl_add_u64 v[34:35], s[6:7], 0, v[34:35]
	global_store_dwordx4 v[114:115], v[30:33], off offset:256
	v_lshl_add_u64 v[34:35], v[34:35], 0, v[72:73]
	v_ashrrev_i32_e32 v71, 31, v70
	v_cvt_pk_bf16_f32 v30, v74, v75
	v_cvt_pk_bf16_f32 v31, v76, v77
	v_cvt_pk_bf16_f32 v32, v78, v79
	v_cvt_pk_bf16_f32 v33, v80, v81
	global_store_dwordx4 v[34:35], v[30:33], off
	s_mov_b32 s14, 0x40000
	s_mov_b64 s[28:29], 0x40000
	v_cvt_pk_bf16_f32 v30, v38, v39
	v_cvt_pk_bf16_f32 v31, v40, v41
	v_cvt_pk_bf16_f32 v32, v42, v43
	v_cvt_pk_bf16_f32 v33, v44, v45
	global_store_dwordx4 v[34:35], v[30:33], off offset:256
	v_lshlrev_b64 v[34:35], 11, v[70:71]
	v_lshl_add_u64 v[34:35], s[6:7], 0, v[34:35]
	v_cvt_pk_bf16_f32 v30, v58, v59
	v_cvt_pk_bf16_f32 v31, v60, v61
	v_cvt_pk_bf16_f32 v32, v62, v63
	v_cvt_pk_bf16_f32 v33, v64, v65
	v_lshl_add_u64 v[34:35], v[34:35], 0, v[72:73]
	global_store_dwordx4 v[34:35], v[30:33], off
	v_cvt_pk_bf16_f32 v18, v18, v19
	v_cvt_pk_bf16_f32 v19, v20, v21
	v_cvt_pk_bf16_f32 v32, v26, v27
	v_or_b32_e32 v26, 48, v70
	v_cvt_pk_bf16_f32 v30, v106, v107
	v_cvt_pk_bf16_f32 v31, v108, v109
	v_cvt_pk_bf16_f32 v33, v28, v29
	v_ashrrev_i32_e32 v27, 31, v26
	global_store_dwordx4 v[34:35], v[30:33], off offset:256
	v_cvt_pk_bf16_f32 v28, v86, v87
	v_cvt_pk_bf16_f32 v29, v88, v89
	v_lshlrev_b64 v[30:31], 11, v[26:27]
	v_lshl_add_u64 v[30:31], s[6:7], 0, v[30:31]
	v_cvt_pk_bf16_f32 v26, v82, v83
	v_cvt_pk_bf16_f32 v27, v84, v85
	v_lshl_add_u64 v[30:31], v[30:31], 0, v[72:73]
	v_add_co_u32_e32 v32, vcc, s14, v34
	global_store_dwordx4 v[30:31], v[26:29], off
	s_nop 0
	v_addc_co_u32_e32 v33, vcc, 0, v35, vcc
	v_cvt_pk_bf16_f32 v26, v46, v47
	v_cvt_pk_bf16_f32 v27, v48, v49
	v_cvt_pk_bf16_f32 v28, v50, v51
	v_cvt_pk_bf16_f32 v29, v52, v53
	s_mov_b32 s14, 0x48000
	global_store_dwordx4 v[30:31], v[26:29], off offset:256
	v_lshl_add_u64 v[30:31], v[34:35], 0, s[28:29]
	v_cvt_pk_bf16_f32 v20, v22, v23
	v_cvt_pk_bf16_f32 v21, v24, v25
	v_add_co_u32_e32 v24, vcc, s14, v34
	global_store_dwordx4 v[30:31], v[18:21], off offset:256
	s_nop 0
	v_addc_co_u32_e32 v25, vcc, 0, v35, vcc
	v_cvt_pk_bf16_f32 v18, v146, v147
	v_cvt_pk_bf16_f32 v19, v148, v149
	v_cvt_pk_bf16_f32 v20, v150, v151
	v_cvt_pk_bf16_f32 v21, v152, v153
	s_mov_b32 s14, 0x50000
	global_store_dwordx4 v[24:25], v[18:21], off
	v_add_co_u32_e32 v24, vcc, s14, v34
	s_mov_b64 s[28:29], 0x48000
	s_nop 0
	v_addc_co_u32_e32 v25, vcc, 0, v35, vcc
	s_mov_b32 s14, 0x58000
	v_lshl_add_u64 v[22:23], v[34:35], 0, s[28:29]
	v_cvt_pk_bf16_f32 v18, v54, v55
	v_cvt_pk_bf16_f32 v19, v56, v57
	v_cvt_pk_bf16_f32 v20, v98, v99
	v_cvt_pk_bf16_f32 v21, v100, v101
	s_mov_b64 s[28:29], 0x50000
	v_cvt_pk_bf16_f32 v2, v2, v3
	v_cvt_pk_bf16_f32 v3, v4, v5
	v_cvt_pk_bf16_f32 v5, v8, v9
	v_add_co_u32_e32 v8, vcc, s14, v34
	global_store_dwordx4 v[22:23], v[18:21], off offset:256
	v_lshl_add_u64 v[22:23], v[34:35], 0, s[28:29]
	v_cvt_pk_bf16_f32 v4, v6, v7
	v_cvt_pk_bf16_f32 v18, v154, v155
	v_cvt_pk_bf16_f32 v19, v156, v157
	v_cvt_pk_bf16_f32 v20, v158, v159
	v_cvt_pk_bf16_f32 v21, v160, v161
	s_mov_b64 s[28:29], 0x58000
	v_addc_co_u32_e32 v9, vcc, 0, v35, vcc
	v_cvt_pk_bf16_f32 v26, v138, v139
	v_cvt_pk_bf16_f32 v27, v140, v141
	v_cvt_pk_bf16_f32 v28, v142, v143
	v_cvt_pk_bf16_f32 v29, v144, v145
	global_store_dwordx4 v[24:25], v[18:21], off
	v_lshl_add_u64 v[6:7], v[34:35], 0, s[28:29]
	global_store_dwordx4 v[8:9], v[2:5], off
	v_cvt_pk_bf16_f32 v18, v102, v103
	v_cvt_pk_bf16_f32 v19, v104, v105
	v_cvt_pk_bf16_f32 v20, v110, v111
	v_cvt_pk_bf16_f32 v21, v112, v113
	v_cvt_pk_bf16_f32 v2, v90, v91
	v_cvt_pk_bf16_f32 v3, v92, v93
	v_cvt_pk_bf16_f32 v4, v94, v95
	v_cvt_pk_bf16_f32 v5, v96, v97
	s_add_i32 s50, s50, s24
	s_andn2_b64 vcc, exec, s[0:1]
	s_mov_b32 s51, s16
	s_mov_b32 s14, s18
	s_mov_b64 s[34:35], s[22:23]
	s_mov_b64 s[30:31], s[20:21]
	global_store_dwordx4 v[114:115], v[66:69], off
	global_store_dwordx4 v[32:33], v[26:29], off
	global_store_dwordx4 v[22:23], v[18:21], off offset:256
	global_store_dwordx4 v[6:7], v[2:5], off offset:256
	s_cbranch_vccz .LBB0_368

; #define PG8_STAGE(bufoff, gbase, voff) do { _Pragma("unroll") for (int _i = 0; _i < 2; ++_i) \
;         __builtin_amdgcn_global_load_lds((const unsigned*)((const char*)(gbase) + (voff)[_i]), (LAS unsigned*)(lds + (bufoff) + ldsw + _i * 8192), 16, 0, 0); } while (0)
; #define PG8_LDA(dst, b, h) do { _Pragma("unroll") for (int m = 0; m < 4; ++m) _Pragma("unroll") for (int k = 0; k < 2; ++k) dst[m][k] = *(const LAS bf16x8*)(lds + PG8_SA(b, h) + aoff + m * 2048 + k * 1024); } while (0)
; #define PG8_LDB(dst, b, h) do { _Pragma("unroll") for (int n = 0; n < 2; ++n) _Pragma("unroll") for (int k = 0; k < 2; ++k) dst[n][k] = *(const LAS bf16x8*)(lds + PG8_SB(b, h) + boff + n * 2048 + k * 1024); } while (0)
; #define PG8_MMA(ai, bj, At, Bt) do { __builtin_amdgcn_s_setprio(1); _Pragma("unroll") for (int m = 0; m < 4; ++m) _Pragma("unroll") for (int n = 0; n < 2; ++n) _Pragma("unroll") for (int k = 0; k < 2; ++k) \
;         acc[ai][bj][m][n] = __builtin_amdgcn_mfma_f32_16x16x32_bf16(Bt[n][k], At[m][k], acc[ai][bj][m][n], 0, 0, 0); __builtin_amdgcn_s_setprio(0); } while (0)
; template <class Epi>
; DI void gemm_phase(LAS unsigned char* lds, const Gemm g, const StaticOrder& S, const Epi& E) {
;     ...
;         for (int t = 0; t < nt; t += 2) {
;             const bool last = (t == nt - 2);
;             const char* a1 = cA + (size_t)(t + 1) * kstep;
;             const char* a2 = last ? nA : cA + (size_t)(t + 2) * kstep; const char* b2 = last ? nB : cB + (size_t)(t + 2) * kstep;
;             const char* a3 = a2 + kstep; const char* b3 = b2 + kstep;
;             PG8_LDB(B0, 0, 0); PG8_SCHED; PG8_LDA(At, 0, 0); PG8_STAGE(PG8_SA(1, 1), a1 + hstepA, voffA);
;             PG8_WAIT_L(8); PG8_BAR; PG8_WAIT_L(0); PG8_MMA(0, 0, At, B0); PG8_BAR; PG8_SCHED;
;             PG8_LDB(B1, 0, 1); PG8_STAGE(PG8_SB(0, 0), b2, voffB);
;             PG8_BAR; PG8_WAIT_L(0); PG8_MMA(0, 1, At, B1); PG8_BAR;
;             PG8_LDA(At, 0, 1); PG8_STAGE(PG8_SA(0, 0), a2, voffA);
;             PG8_BAR; PG8_WAIT_L(0); PG8_MMA(1, 0, At, B0); PG8_BAR; PG8_SCHED;
;             PG8_STAGE(PG8_SB(0, 1), b2 + hstepB, voffB);
;             PG8_WAIT_V(6); PG8_BAR; PG8_MMA(1, 1, At, B1); PG8_BAR;
;             PG8_LDB(B0, 1, 0); PG8_SCHED; PG8_LDA(At, 1, 0); PG8_STAGE(PG8_SA(0, 1), a2 + hstepA, voffA);
;             PG8_WAIT_L(8); PG8_BAR; PG8_WAIT_L(0); PG8_MMA(0, 0, At, B0); PG8_BAR; PG8_SCHED;
.LBB0_407:
	s_add_u32 s38, s36, 0xfffc0080
	s_addc_u32 s39, s37, -1
	s_add_i32 s61, 0, 0x10000
	v_add_u32_e32 v0, s61, v146
	ds_read_b128 v[142:145], v0
	ds_read_b128 v[148:151], v0 offset:1024
	ds_read_b128 v[152:155], v0 offset:2048
	ds_read_b128 v[156:159], v0 offset:3072
	s_cmp_eq_u32 s60, 12
	s_cselect_b32 s43, s1, s39
	s_cselect_b32 s42, s5, s38
	s_cselect_b32 s39, s21, s59
	s_cselect_b32 s38, s29, s58
	v_lshl_add_u64 v[192:193], s[36:37], 0, v[140:141]
	s_add_i32 m0, s50, 0xc000
	ds_read_b128 v[160:163], v147
	ds_read_b128 v[164:167], v147 offset:1024
	ds_read_b128 v[168:171], v147 offset:2048
	ds_read_b128 v[172:175], v147 offset:3072
	ds_read_b128 v[176:179], v147 offset:4096
	ds_read_b128 v[180:183], v147 offset:5120
	ds_read_b128 v[184:187], v147 offset:6144
	ds_read_b128 v[188:191], v147 offset:7168
	global_load_lds_dwordx4 v[192:193], off
	v_lshl_add_u64 v[192:193], s[36:37], 0, v[138:139]
	s_add_i32 m0, s50, 0xe000
	s_nop 0
	global_load_lds_dwordx4 v[192:193], off
	s_waitcnt lgkmcnt(8)
	s_barrier
	s_waitcnt lgkmcnt(0)
	s_nop 0
	s_waitcnt lgkmcnt(0)
	v_mfma_f32_16x16x32_bf16 v[126:129], v[142:145], v[160:163], v[126:129]
	v_mfma_f32_16x16x32_bf16 v[122:125], v[152:155], v[160:163], v[122:125]
	v_mfma_f32_16x16x32_bf16 v[110:113], v[142:145], v[168:171], v[110:113]
	v_mfma_f32_16x16x32_bf16 v[106:109], v[152:155], v[168:171], v[106:109]
	v_mfma_f32_16x16x32_bf16 v[94:97], v[142:145], v[176:179], v[94:97]
	v_mfma_f32_16x16x32_bf16 v[90:93], v[152:155], v[176:179], v[90:93]
	v_mfma_f32_16x16x32_bf16 v[78:81], v[142:145], v[184:187], v[78:81]
	v_mfma_f32_16x16x32_bf16 v[74:77], v[152:155], v[184:187], v[74:77]
	v_mfma_f32_16x16x32_bf16 v[126:129], v[148:151], v[164:167], v[126:129]
	v_mfma_f32_16x16x32_bf16 v[122:125], v[156:159], v[164:167], v[122:125]
	v_mfma_f32_16x16x32_bf16 v[110:113], v[148:151], v[172:175], v[110:113]
	v_mfma_f32_16x16x32_bf16 v[106:109], v[156:159], v[172:175], v[106:109]
	v_mfma_f32_16x16x32_bf16 v[94:97], v[148:151], v[180:183], v[94:97]
	v_mfma_f32_16x16x32_bf16 v[90:93], v[156:159], v[180:183], v[90:93]
	v_mfma_f32_16x16x32_bf16 v[78:81], v[148:151], v[188:191], v[78:81]
	v_mfma_f32_16x16x32_bf16 v[74:77], v[156:159], v[188:191], v[74:77]
	s_nop 0
	s_barrier
	s_add_i32 s64, 0, 0x14000
	s_add_i32 s61, s61, s49
	v_add_u32_e32 v0, s64, v146
	v_lshl_add_u64 v[192:193], s[38:39], 0, v[132:133]
	s_mov_b32 m0, s61
	ds_read_b128 v[216:219], v0
	ds_read_b128 v[220:223], v0 offset:1024
	ds_read_b128 v[224:227], v0 offset:2048
	ds_read_b128 v[228:231], v0 offset:3072
	global_load_lds_dwordx4 v[192:193], off
	v_lshl_add_u64 v[232:233], s[38:39], 0, v[136:137]
	s_add_i32 m0, s61, 0x2000
	s_nop 0
	global_load_lds_dwordx4 v[232:233], off
	s_barrier
	s_waitcnt lgkmcnt(0)
	s_nop 0
	s_waitcnt lgkmcnt(0)
	v_mfma_f32_16x16x32_bf16 v[118:121], v[216:219], v[160:163], v[118:121]
	v_mfma_f32_16x16x32_bf16 v[114:117], v[224:227], v[160:163], v[114:117]
	v_mfma_f32_16x16x32_bf16 v[102:105], v[216:219], v[168:171], v[102:105]
	v_mfma_f32_16x16x32_bf16 v[98:101], v[224:227], v[168:171], v[98:101]
	v_mfma_f32_16x16x32_bf16 v[86:89], v[216:219], v[176:179], v[86:89]
	v_mfma_f32_16x16x32_bf16 v[82:85], v[224:227], v[176:179], v[82:85]
	v_mfma_f32_16x16x32_bf16 v[70:73], v[216:219], v[184:187], v[70:73]
	v_mfma_f32_16x16x32_bf16 v[66:69], v[224:227], v[184:187], v[66:69]
	v_mfma_f32_16x16x32_bf16 v[118:121], v[220:223], v[164:167], v[118:121]
	v_mfma_f32_16x16x32_bf16 v[114:117], v[228:231], v[164:167], v[114:117]
	v_mfma_f32_16x16x32_bf16 v[102:105], v[220:223], v[172:175], v[102:105]
	v_mfma_f32_16x16x32_bf16 v[98:101], v[228:231], v[172:175], v[98:101]
	v_mfma_f32_16x16x32_bf16 v[86:89], v[220:223], v[180:183], v[86:89]
	v_mfma_f32_16x16x32_bf16 v[82:85], v[228:231], v[180:183], v[82:85]
	v_mfma_f32_16x16x32_bf16 v[70:73], v[220:223], v[188:191], v[70:73]
	v_mfma_f32_16x16x32_bf16 v[66:69], v[228:231], v[188:191], v[66:69]
	s_nop 0
	s_mov_b32 m0, s50
	v_lshl_add_u64 v[234:235], s[42:43], 0, v[130:131]
	s_barrier
	ds_read_b128 v[160:163], v147 offset:16384
	ds_read_b128 v[164:167], v147 offset:17408
	ds_read_b128 v[168:171], v147 offset:18432
	ds_read_b128 v[172:175], v147 offset:19456
	ds_read_b128 v[176:179], v147 offset:20480
	ds_read_b128 v[180:183], v147 offset:21504
	ds_read_b128 v[184:187], v147 offset:22528
	ds_read_b128 v[188:191], v147 offset:23552
	global_load_lds_dwordx4 v[234:235], off
	v_lshl_add_u64 v[236:237], s[42:43], 0, v[134:135]
	s_mov_b32 m0, s51
	s_nop 0
	global_load_lds_dwordx4 v[236:237], off
	s_barrier
	s_waitcnt lgkmcnt(0)
	s_nop 0
	s_waitcnt lgkmcnt(0)
	v_mfma_f32_16x16x32_bf16 v[62:65], v[142:145], v[160:163], v[62:65]
	v_mfma_f32_16x16x32_bf16 v[58:61], v[152:155], v[160:163], v[58:61]
	v_mfma_f32_16x16x32_bf16 v[46:49], v[142:145], v[168:171], v[46:49]
	v_mfma_f32_16x16x32_bf16 v[42:45], v[152:155], v[168:171], v[42:45]
	v_mfma_f32_16x16x32_bf16 v[30:33], v[142:145], v[176:179], v[30:33]
	v_mfma_f32_16x16x32_bf16 v[26:29], v[152:155], v[176:179], v[26:29]
	v_mfma_f32_16x16x32_bf16 v[14:17], v[142:145], v[184:187], v[14:17]
	v_mfma_f32_16x16x32_bf16 v[10:13], v[152:155], v[184:187], v[10:13]
	v_mfma_f32_16x16x32_bf16 v[62:65], v[148:151], v[164:167], v[62:65]
	v_mfma_f32_16x16x32_bf16 v[58:61], v[156:159], v[164:167], v[58:61]
	v_mfma_f32_16x16x32_bf16 v[46:49], v[148:151], v[172:175], v[46:49]
	v_mfma_f32_16x16x32_bf16 v[42:45], v[156:159], v[172:175], v[42:45]
	v_mfma_f32_16x16x32_bf16 v[30:33], v[148:151], v[180:183], v[30:33]
	v_mfma_f32_16x16x32_bf16 v[26:29], v[156:159], v[180:183], v[26:29]
	v_mfma_f32_16x16x32_bf16 v[14:17], v[148:151], v[188:191], v[14:17]
	v_mfma_f32_16x16x32_bf16 v[10:13], v[156:159], v[188:191], v[10:13]
	s_nop 0
	s_barrier
; #define PG8_STAGE(bufoff, gbase, voff) do { _Pragma("unroll") for (int _i = 0; _i < 2; ++_i) \
;         __builtin_amdgcn_global_load_lds((const unsigned*)((const char*)(gbase) + (voff)[_i]), (LAS unsigned*)(lds + (bufoff) + ldsw + _i * 8192), 16, 0, 0); } while (0)
; #define PG8_LDA(dst, b, h) do { _Pragma("unroll") for (int m = 0; m < 4; ++m) _Pragma("unroll") for (int k = 0; k < 2; ++k) dst[m][k] = *(const LAS bf16x8*)(lds + PG8_SA(b, h) + aoff + m * 2048 + k * 1024); } while (0)
; #define PG8_LDB(dst, b, h) do { _Pragma("unroll") for (int n = 0; n < 2; ++n) _Pragma("unroll") for (int k = 0; k < 2; ++k) dst[n][k] = *(const LAS bf16x8*)(lds + PG8_SB(b, h) + boff + n * 2048 + k * 1024); } while (0)
; #define PG8_MMA(ai, bj, At, Bt) do { __builtin_amdgcn_s_setprio(1); _Pragma("unroll") for (int m = 0; m < 4; ++m) _Pragma("unroll") for (int n = 0; n < 2; ++n) _Pragma("unroll") for (int k = 0; k < 2; ++k) \
;         acc[ai][bj][m][n] = __builtin_amdgcn_mfma_f32_16x16x32_bf16(Bt[n][k], At[m][k], acc[ai][bj][m][n], 0, 0, 0); __builtin_amdgcn_s_setprio(0); } while (0)
; #define PG8_WAIT_V(n) asm volatile("s_waitcnt vmcnt(" #n ")" ::: "memory")
; #define PG8_WAIT_L(n) asm volatile("s_waitcnt lgkmcnt(" #n ")" ::: "memory")
; #define PG8_BAR __builtin_amdgcn_s_barrier()
; #define PG8_SCHED __builtin_amdgcn_sched_barrier(0)
; template <class Epi>
; DI void gemm_phase(LAS unsigned char* lds, const Gemm g, const StaticOrder& S, const Epi& E) {
;     ...
;             PG8_STAGE(PG8_SB(0, 1), b2 + hstepB, voffB);
;             PG8_WAIT_V(6); PG8_BAR; PG8_MMA(1, 1, At, B1); PG8_BAR;
;             PG8_LDB(B0, 1, 0); PG8_SCHED; PG8_LDA(At, 1, 0); PG8_STAGE(PG8_SA(0, 1), a2 + hstepA, voffA);
;             PG8_WAIT_L(8); PG8_BAR; PG8_WAIT_L(0); PG8_MMA(0, 0, At, B0); PG8_BAR; PG8_SCHED;
;             PG8_LDB(B1, 1, 1); PG8_STAGE(PG8_SB(1, 0), b3, voffB);
;             PG8_BAR; PG8_WAIT_L(0); PG8_MMA(0, 1, At, B1); PG8_BAR;
;             PG8_LDA(At, 1, 1); PG8_STAGE(PG8_SA(1, 0), a3, voffA);
;             PG8_BAR; PG8_WAIT_L(0); PG8_MMA(1, 0, At, B0); PG8_BAR; PG8_SCHED;
	s_add_u32 s62, s38, 0x40000
	s_addc_u32 s63, s39, 0
	s_add_i32 s61, s64, s49
	v_lshl_add_u64 v[142:143], s[62:63], 0, v[132:133]
	s_mov_b32 m0, s61
	s_nop 0
	global_load_lds_dwordx4 v[142:143], off
	v_lshl_add_u64 v[142:143], s[62:63], 0, v[136:137]
	s_add_i32 m0, s61, 0x2000
	s_nop 0
	global_load_lds_dwordx4 v[142:143], off
	s_waitcnt vmcnt(6)
	s_barrier
	s_nop 0
	v_mfma_f32_16x16x32_bf16 v[54:57], v[216:219], v[160:163], v[54:57]
	v_mfma_f32_16x16x32_bf16 v[50:53], v[224:227], v[160:163], v[50:53]
	v_mfma_f32_16x16x32_bf16 v[38:41], v[216:219], v[168:171], v[38:41]
	v_mfma_f32_16x16x32_bf16 v[34:37], v[224:227], v[168:171], v[34:37]
	v_mfma_f32_16x16x32_bf16 v[22:25], v[216:219], v[176:179], v[22:25]
	v_mfma_f32_16x16x32_bf16 v[18:21], v[224:227], v[176:179], v[18:21]
	v_mfma_f32_16x16x32_bf16 v[6:9], v[216:219], v[184:187], v[6:9]
	v_mfma_f32_16x16x32_bf16 v[2:5], v[224:227], v[184:187], v[2:5]
	v_mfma_f32_16x16x32_bf16 v[54:57], v[220:223], v[164:167], v[54:57]
	v_mfma_f32_16x16x32_bf16 v[50:53], v[228:231], v[164:167], v[50:53]
	v_mfma_f32_16x16x32_bf16 v[38:41], v[220:223], v[172:175], v[38:41]
	v_mfma_f32_16x16x32_bf16 v[34:37], v[228:231], v[172:175], v[34:37]
	v_mfma_f32_16x16x32_bf16 v[22:25], v[220:223], v[180:183], v[22:25]
	v_mfma_f32_16x16x32_bf16 v[18:21], v[228:231], v[180:183], v[18:21]
	v_mfma_f32_16x16x32_bf16 v[6:9], v[220:223], v[188:191], v[6:9]
	v_mfma_f32_16x16x32_bf16 v[2:5], v[228:231], v[188:191], v[2:5]
	s_nop 0
	s_add_i32 s61, 0, 0x18000
	v_add_u32_e32 v0, s61, v146
	s_barrier
	ds_read_b128 v[142:145], v0
	ds_read_b128 v[148:151], v0 offset:1024
	ds_read_b128 v[152:155], v0 offset:2048
	ds_read_b128 v[156:159], v0 offset:3072
	s_add_u32 s42, s42, 0x40000
	s_addc_u32 s43, s43, 0
	s_mov_b32 m0, s52
	v_lshl_add_u64 v[216:217], s[42:43], 0, v[130:131]
	ds_read_b128 v[160:163], v147 offset:32768
	ds_read_b128 v[164:167], v147 offset:33792
	ds_read_b128 v[168:171], v147 offset:34816
	ds_read_b128 v[172:175], v147 offset:35840
	ds_read_b128 v[176:179], v147 offset:36864
	ds_read_b128 v[180:183], v147 offset:37888
	ds_read_b128 v[184:187], v147 offset:38912
	ds_read_b128 v[188:191], v147 offset:39936
	global_load_lds_dwordx4 v[216:217], off
	v_lshl_add_u64 v[216:217], s[42:43], 0, v[134:135]
	s_mov_b32 m0, s53
	s_nop 0
	global_load_lds_dwordx4 v[216:217], off
	s_waitcnt lgkmcnt(8)
	s_barrier
	s_waitcnt lgkmcnt(0)
	s_nop 0
	s_waitcnt lgkmcnt(0)
	v_mfma_f32_16x16x32_bf16 v[126:129], v[142:145], v[160:163], v[126:129]
	v_mfma_f32_16x16x32_bf16 v[122:125], v[152:155], v[160:163], v[122:125]
	v_mfma_f32_16x16x32_bf16 v[110:113], v[142:145], v[168:171], v[110:113]
	v_mfma_f32_16x16x32_bf16 v[106:109], v[152:155], v[168:171], v[106:109]
	v_mfma_f32_16x16x32_bf16 v[94:97], v[142:145], v[176:179], v[94:97]
	v_mfma_f32_16x16x32_bf16 v[90:93], v[152:155], v[176:179], v[90:93]
	v_mfma_f32_16x16x32_bf16 v[78:81], v[142:145], v[184:187], v[78:81]
	v_mfma_f32_16x16x32_bf16 v[74:77], v[152:155], v[184:187], v[74:77]
	v_mfma_f32_16x16x32_bf16 v[126:129], v[148:151], v[164:167], v[126:129]
	v_mfma_f32_16x16x32_bf16 v[122:125], v[156:159], v[164:167], v[122:125]
	v_mfma_f32_16x16x32_bf16 v[110:113], v[148:151], v[172:175], v[110:113]
	v_mfma_f32_16x16x32_bf16 v[106:109], v[156:159], v[172:175], v[106:109]
	v_mfma_f32_16x16x32_bf16 v[94:97], v[148:151], v[180:183], v[94:97]
	v_mfma_f32_16x16x32_bf16 v[90:93], v[156:159], v[180:183], v[90:93]
	v_mfma_f32_16x16x32_bf16 v[78:81], v[148:151], v[188:191], v[78:81]
	v_mfma_f32_16x16x32_bf16 v[74:77], v[156:159], v[188:191], v[74:77]
	s_nop 0
	s_barrier
	s_add_i32 s42, 0, 0x1c000
	s_add_i32 s43, s61, s49
	v_add_u32_e32 v0, s42, v146
	v_lshl_add_u64 v[192:193], v[192:193], 0, s[2:3]
	s_mov_b32 m0, s43
	ds_read_b128 v[216:219], v0
	ds_read_b128 v[220:223], v0 offset:1024
	ds_read_b128 v[224:227], v0 offset:2048
	ds_read_b128 v[228:231], v0 offset:3072
	global_load_lds_dwordx4 v[192:193], off
	v_lshl_add_u64 v[192:193], v[232:233], 0, s[2:3]
	s_add_i32 m0, s43, 0x2000
	s_nop 0
	global_load_lds_dwordx4 v[192:193], off
	s_barrier
; #define PG8_STAGE(bufoff, gbase, voff) do { _Pragma("unroll") for (int _i = 0; _i < 2; ++_i) \
;         __builtin_amdgcn_global_load_lds((const unsigned*)((const char*)(gbase) + (voff)[_i]), (LAS unsigned*)(lds + (bufoff) + ldsw + _i * 8192), 16, 0, 0); } while (0)
; #define PG8_LDA(dst, b, h) do { _Pragma("unroll") for (int m = 0; m < 4; ++m) _Pragma("unroll") for (int k = 0; k < 2; ++k) dst[m][k] = *(const LAS bf16x8*)(lds + PG8_SA(b, h) + aoff + m * 2048 + k * 1024); } while (0)
; #define PG8_LDB(dst, b, h) do { _Pragma("unroll") for (int n = 0; n < 2; ++n) _Pragma("unroll") for (int k = 0; k < 2; ++k) dst[n][k] = *(const LAS bf16x8*)(lds + PG8_SB(b, h) + boff + n * 2048 + k * 1024); } while (0)
; #define PG8_MMA(ai, bj, At, Bt) do { __builtin_amdgcn_s_setprio(1); _Pragma("unroll") for (int m = 0; m < 4; ++m) _Pragma("unroll") for (int n = 0; n < 2; ++n) _Pragma("unroll") for (int k = 0; k < 2; ++k) \
;         acc[ai][bj][m][n] = __builtin_amdgcn_mfma_f32_16x16x32_bf16(Bt[n][k], At[m][k], acc[ai][bj][m][n], 0, 0, 0); __builtin_amdgcn_s_setprio(0); } while (0)
; #define PG8_WAIT_V(n) asm volatile("s_waitcnt vmcnt(" #n ")" ::: "memory")
; #define PG8_WAIT_L(n) asm volatile("s_waitcnt lgkmcnt(" #n ")" ::: "memory")
; #define PG8_BAR __builtin_amdgcn_s_barrier()
; #define PG8_SCHED __builtin_amdgcn_sched_barrier(0)
; template <class Epi>
; DI void gemm_phase(LAS unsigned char* lds, const Gemm g, const StaticOrder& S, const Epi& E) {
;     ...
;             PG8_LDB(B0, 1, 0); PG8_SCHED; PG8_LDA(At, 1, 0); PG8_STAGE(PG8_SA(0, 1), a2 + hstepA, voffA);
;             PG8_WAIT_L(8); PG8_BAR; PG8_WAIT_L(0); PG8_MMA(0, 0, At, B0); PG8_BAR; PG8_SCHED;
;             PG8_LDB(B1, 1, 1); PG8_STAGE(PG8_SB(1, 0), b3, voffB);
;             PG8_BAR; PG8_WAIT_L(0); PG8_MMA(0, 1, At, B1); PG8_BAR;
;             PG8_LDA(At, 1, 1); PG8_STAGE(PG8_SA(1, 0), a3, voffA);
;             PG8_BAR; PG8_WAIT_L(0); PG8_MMA(1, 0, At, B0); PG8_BAR; PG8_SCHED;
;             PG8_STAGE(PG8_SB(1, 1), b3 + hstepB, voffB);
;             PG8_WAIT_V(6); PG8_BAR; PG8_MMA(1, 1, At, B1); PG8_BAR;
;         }
	s_waitcnt lgkmcnt(0)
	s_nop 0
	s_waitcnt lgkmcnt(0)
	v_mfma_f32_16x16x32_bf16 v[118:121], v[216:219], v[160:163], v[118:121]
	v_mfma_f32_16x16x32_bf16 v[114:117], v[224:227], v[160:163], v[114:117]
	v_mfma_f32_16x16x32_bf16 v[102:105], v[216:219], v[168:171], v[102:105]
	v_mfma_f32_16x16x32_bf16 v[98:101], v[224:227], v[168:171], v[98:101]
	v_mfma_f32_16x16x32_bf16 v[86:89], v[216:219], v[176:179], v[86:89]
	v_mfma_f32_16x16x32_bf16 v[82:85], v[224:227], v[176:179], v[82:85]
	v_mfma_f32_16x16x32_bf16 v[70:73], v[216:219], v[184:187], v[70:73]
	v_mfma_f32_16x16x32_bf16 v[66:69], v[224:227], v[184:187], v[66:69]
	v_mfma_f32_16x16x32_bf16 v[118:121], v[220:223], v[164:167], v[118:121]
	v_mfma_f32_16x16x32_bf16 v[114:117], v[228:231], v[164:167], v[114:117]
	v_mfma_f32_16x16x32_bf16 v[102:105], v[220:223], v[172:175], v[102:105]
	v_mfma_f32_16x16x32_bf16 v[98:101], v[228:231], v[172:175], v[98:101]
	v_mfma_f32_16x16x32_bf16 v[86:89], v[220:223], v[180:183], v[86:89]
	v_mfma_f32_16x16x32_bf16 v[82:85], v[228:231], v[180:183], v[82:85]
	v_mfma_f32_16x16x32_bf16 v[70:73], v[220:223], v[188:191], v[70:73]
	v_mfma_f32_16x16x32_bf16 v[66:69], v[228:231], v[188:191], v[66:69]
	s_nop 0
	s_mov_b32 m0, s54
	v_lshl_add_u64 v[192:193], v[234:235], 0, s[2:3]
	s_barrier
	ds_read_b128 v[160:163], v147 offset:49152
	ds_read_b128 v[164:167], v147 offset:50176
	ds_read_b128 v[168:171], v147 offset:51200
	ds_read_b128 v[172:175], v147 offset:52224
	ds_read_b128 v[176:179], v147 offset:53248
	ds_read_b128 v[180:183], v147 offset:54272
	ds_read_b128 v[184:187], v147 offset:55296
	ds_read_b128 v[188:191], v147 offset:56320
	global_load_lds_dwordx4 v[192:193], off
	v_lshl_add_u64 v[192:193], v[236:237], 0, s[2:3]
	s_mov_b32 m0, s55
	s_nop 0
	global_load_lds_dwordx4 v[192:193], off
	s_barrier
	s_waitcnt lgkmcnt(0)
	s_nop 0
	s_waitcnt lgkmcnt(0)
	v_mfma_f32_16x16x32_bf16 v[62:65], v[142:145], v[160:163], v[62:65]
	v_mfma_f32_16x16x32_bf16 v[58:61], v[152:155], v[160:163], v[58:61]
	v_mfma_f32_16x16x32_bf16 v[46:49], v[142:145], v[168:171], v[46:49]
	v_mfma_f32_16x16x32_bf16 v[42:45], v[152:155], v[168:171], v[42:45]
	v_mfma_f32_16x16x32_bf16 v[30:33], v[142:145], v[176:179], v[30:33]
	v_mfma_f32_16x16x32_bf16 v[26:29], v[152:155], v[176:179], v[26:29]
	v_mfma_f32_16x16x32_bf16 v[14:17], v[142:145], v[184:187], v[14:17]
	v_mfma_f32_16x16x32_bf16 v[10:13], v[152:155], v[184:187], v[10:13]
	v_mfma_f32_16x16x32_bf16 v[62:65], v[148:151], v[164:167], v[62:65]
	v_mfma_f32_16x16x32_bf16 v[58:61], v[156:159], v[164:167], v[58:61]
	v_mfma_f32_16x16x32_bf16 v[46:49], v[148:151], v[172:175], v[46:49]
	v_mfma_f32_16x16x32_bf16 v[42:45], v[156:159], v[172:175], v[42:45]
	v_mfma_f32_16x16x32_bf16 v[30:33], v[148:151], v[180:183], v[30:33]
	v_mfma_f32_16x16x32_bf16 v[26:29], v[156:159], v[180:183], v[26:29]
	v_mfma_f32_16x16x32_bf16 v[14:17], v[148:151], v[188:191], v[14:17]
	v_mfma_f32_16x16x32_bf16 v[10:13], v[156:159], v[188:191], v[10:13]
	s_nop 0
	s_barrier
	s_add_u32 s38, s38, 0x40080
	s_addc_u32 s39, s39, 0
	s_add_i32 s42, s42, s49
	v_lshl_add_u64 v[142:143], s[38:39], 0, v[132:133]
	s_mov_b32 m0, s42
	s_nop 0
	global_load_lds_dwordx4 v[142:143], off
	v_lshl_add_u64 v[142:143], s[38:39], 0, v[136:137]
	s_add_i32 m0, s42, 0x2000
	s_nop 0
	global_load_lds_dwordx4 v[142:143], off
	s_waitcnt vmcnt(6)
	s_barrier
	s_nop 0
	v_mfma_f32_16x16x32_bf16 v[54:57], v[216:219], v[160:163], v[54:57]
	v_mfma_f32_16x16x32_bf16 v[50:53], v[224:227], v[160:163], v[50:53]
	v_mfma_f32_16x16x32_bf16 v[38:41], v[216:219], v[168:171], v[38:41]
	v_mfma_f32_16x16x32_bf16 v[34:37], v[224:227], v[168:171], v[34:37]
	v_mfma_f32_16x16x32_bf16 v[22:25], v[216:219], v[176:179], v[22:25]
	v_mfma_f32_16x16x32_bf16 v[18:21], v[224:227], v[176:179], v[18:21]
	v_mfma_f32_16x16x32_bf16 v[6:9], v[216:219], v[184:187], v[6:9]
	v_mfma_f32_16x16x32_bf16 v[2:5], v[224:227], v[184:187], v[2:5]
	v_mfma_f32_16x16x32_bf16 v[54:57], v[220:223], v[164:167], v[54:57]
	v_mfma_f32_16x16x32_bf16 v[50:53], v[228:231], v[164:167], v[50:53]
	v_mfma_f32_16x16x32_bf16 v[38:41], v[220:223], v[172:175], v[38:41]
	v_mfma_f32_16x16x32_bf16 v[34:37], v[228:231], v[172:175], v[34:37]
	v_mfma_f32_16x16x32_bf16 v[22:25], v[220:223], v[180:183], v[22:25]
	v_mfma_f32_16x16x32_bf16 v[18:21], v[228:231], v[180:183], v[18:21]
	v_mfma_f32_16x16x32_bf16 v[6:9], v[220:223], v[188:191], v[6:9]
	v_mfma_f32_16x16x32_bf16 v[2:5], v[228:231], v[188:191], v[2:5]
	s_nop 0
	s_add_i32 s60, s60, 2
	s_add_u32 s58, s58, 0x100
	s_addc_u32 s59, s59, 0
	s_add_u32 s36, s36, 0x100
	s_addc_u32 s37, s37, 0
	s_cmp_gt_u32 s60, 13
	s_barrier
	s_cbranch_scc0 .LBB0_407
	s_cmp_lt_i32 s0, 20
	s_cselect_b64 s[38:39], -1, 0
	s_cmp_gt_i32 s0, 19
	v_mov_b32_e32 v0, v238
	s_mov_b64 s[36:37], -1
	s_cbranch_scc1 .LBB0_410
	s_mov_b64 s[36:37], 0

; #define PG8_STAGE(bufoff, gbase, voff) do { _Pragma("unroll") for (int _i = 0; _i < 2; ++_i) \
;         __builtin_amdgcn_global_load_lds((const unsigned*)((const char*)(gbase) + (voff)[_i]), (LAS unsigned*)(lds + (bufoff) + ldsw + _i * 8192), 16, 0, 0); } while (0)
; #define PG8_LDA(dst, b, h) do { _Pragma("unroll") for (int m = 0; m < 4; ++m) _Pragma("unroll") for (int k = 0; k < 2; ++k) dst[m][k] = *(const LAS bf16x8*)(lds + PG8_SA(b, h) + aoff + m * 2048 + k * 1024); } while (0)
; #define PG8_LDB(dst, b, h) do { _Pragma("unroll") for (int n = 0; n < 2; ++n) _Pragma("unroll") for (int k = 0; k < 2; ++k) dst[n][k] = *(const LAS bf16x8*)(lds + PG8_SB(b, h) + boff + n * 2048 + k * 1024); } while (0)
; #define PG8_MMA(ai, bj, At, Bt) do { __builtin_amdgcn_s_setprio(1); _Pragma("unroll") for (int m = 0; m < 4; ++m) _Pragma("unroll") for (int n = 0; n < 2; ++n) _Pragma("unroll") for (int k = 0; k < 2; ++k) \
;         acc[ai][bj][m][n] = __builtin_amdgcn_mfma_f32_16x16x32_bf16(Bt[n][k], At[m][k], acc[ai][bj][m][n], 0, 0, 0); __builtin_amdgcn_s_setprio(0); } while (0)
; template <class Epi>
; DI void gemm_phase(LAS unsigned char* lds, const Gemm g, const StaticOrder& S, const Epi& E) {
;     ...
;         for (int t = 0; t < nt; t += 2) {
;             const bool last = (t == nt - 2);
;             const char* a1 = cA + (size_t)(t + 1) * kstep;
;             const char* a2 = last ? nA : cA + (size_t)(t + 2) * kstep; const char* b2 = last ? nB : cB + (size_t)(t + 2) * kstep;
;             const char* a3 = a2 + kstep; const char* b3 = b2 + kstep;
;             PG8_LDB(B0, 0, 0); PG8_SCHED; PG8_LDA(At, 0, 0); PG8_STAGE(PG8_SA(1, 1), a1 + hstepA, voffA);
;             PG8_WAIT_L(8); PG8_BAR; PG8_WAIT_L(0); PG8_MMA(0, 0, At, B0); PG8_BAR; PG8_SCHED;
;             PG8_LDB(B1, 0, 1); PG8_STAGE(PG8_SB(0, 0), b2, voffB);
;             PG8_BAR; PG8_WAIT_L(0); PG8_MMA(0, 1, At, B1); PG8_BAR;
;             PG8_LDA(At, 0, 1); PG8_STAGE(PG8_SA(0, 0), a2, voffA);
;             PG8_BAR; PG8_WAIT_L(0); PG8_MMA(1, 0, At, B0); PG8_BAR; PG8_SCHED;
;             PG8_STAGE(PG8_SB(0, 1), b2 + hstepB, voffB);
;             PG8_WAIT_V(6); PG8_BAR; PG8_MMA(1, 1, At, B1); PG8_BAR;
;             PG8_LDB(B0, 1, 0); PG8_SCHED; PG8_LDA(At, 1, 0); PG8_STAGE(PG8_SA(0, 1), a2 + hstepA, voffA);
;             PG8_WAIT_L(8); PG8_BAR; PG8_WAIT_L(0); PG8_MMA(0, 0, At, B0); PG8_BAR; PG8_SCHED;
.LBB0_533:
	s_add_i32 s62, s28, 2
	s_add_u32 s30, s22, 0x80
	s_addc_u32 s29, s23, 0
	s_add_i32 s63, 0, 0x10000
	v_add_u32_e32 v133, s63, v152
	ds_read_b128 v[140:143], v133
	ds_read_b128 v[144:147], v133 offset:1024
	ds_read_b128 v[148:151], v133 offset:2048
	ds_read_b128 v[154:157], v133 offset:3072
	s_cmp_eq_u32 s54, s28
	s_cselect_b32 s28, s0, s30
	s_cselect_b32 s29, s1, s29
	s_cselect_b32 s31, s5, s61
	s_cselect_b32 s30, s4, s60
	v_lshl_add_u64 v[190:191], s[22:23], 0, v[138:139]
	s_add_i32 m0, s47, 0xc000
	ds_read_b128 v[158:161], v153
	ds_read_b128 v[162:165], v153 offset:1024
	ds_read_b128 v[166:169], v153 offset:2048
	ds_read_b128 v[170:173], v153 offset:3072
	ds_read_b128 v[174:177], v153 offset:4096
	ds_read_b128 v[178:181], v153 offset:5120
	ds_read_b128 v[182:185], v153 offset:6144
	ds_read_b128 v[186:189], v153 offset:7168
	global_load_lds_dwordx4 v[190:191], off
	v_lshl_add_u64 v[190:191], s[22:23], 0, v[136:137]
	s_add_i32 m0, s47, 0xe000
	s_nop 0
	global_load_lds_dwordx4 v[190:191], off
	s_waitcnt lgkmcnt(8)
	s_barrier
	s_waitcnt lgkmcnt(0)
	s_nop 0
	s_waitcnt lgkmcnt(0)
	v_mfma_f32_16x16x32_bf16 v[126:129], v[140:143], v[158:161], v[126:129]
	v_mfma_f32_16x16x32_bf16 v[122:125], v[148:151], v[158:161], v[122:125]
	v_mfma_f32_16x16x32_bf16 v[118:121], v[140:143], v[166:169], v[118:121]
	v_mfma_f32_16x16x32_bf16 v[114:117], v[148:151], v[166:169], v[114:117]
	v_mfma_f32_16x16x32_bf16 v[106:109], v[140:143], v[174:177], v[106:109]
	v_mfma_f32_16x16x32_bf16 v[98:101], v[148:151], v[174:177], v[98:101]
	v_mfma_f32_16x16x32_bf16 v[90:93], v[140:143], v[182:185], v[90:93]
	v_mfma_f32_16x16x32_bf16 v[82:85], v[148:151], v[182:185], v[82:85]
	v_mfma_f32_16x16x32_bf16 v[126:129], v[144:147], v[162:165], v[126:129]
	v_mfma_f32_16x16x32_bf16 v[122:125], v[154:157], v[162:165], v[122:125]
	v_mfma_f32_16x16x32_bf16 v[118:121], v[144:147], v[170:173], v[118:121]
	v_mfma_f32_16x16x32_bf16 v[114:117], v[154:157], v[170:173], v[114:117]
	v_mfma_f32_16x16x32_bf16 v[106:109], v[144:147], v[178:181], v[106:109]
	v_mfma_f32_16x16x32_bf16 v[98:101], v[154:157], v[178:181], v[98:101]
	v_mfma_f32_16x16x32_bf16 v[90:93], v[144:147], v[186:189], v[90:93]
	v_mfma_f32_16x16x32_bf16 v[82:85], v[154:157], v[186:189], v[82:85]
	s_nop 0
	s_barrier
	s_add_i32 s64, 0, 0x14000
	s_add_i32 s63, s63, s46
	v_add_u32_e32 v133, s64, v152
	v_lshl_add_u64 v[228:229], s[30:31], 0, v[0:1]
	s_mov_b32 m0, s63
	ds_read_b128 v[190:193], v133
	ds_read_b128 v[216:219], v133 offset:1024
	ds_read_b128 v[220:223], v133 offset:2048
	ds_read_b128 v[224:227], v133 offset:3072
	global_load_lds_dwordx4 v[228:229], off
	v_lshl_add_u64 v[230:231], s[30:31], 0, v[130:131]
	s_add_i32 m0, s63, 0x2000
	s_nop 0
	global_load_lds_dwordx4 v[230:231], off
	s_barrier
	s_waitcnt lgkmcnt(0)
	s_nop 0
	s_waitcnt lgkmcnt(0)
	v_mfma_f32_16x16x32_bf16 v[110:113], v[190:193], v[158:161], v[110:113]
	v_mfma_f32_16x16x32_bf16 v[102:105], v[220:223], v[158:161], v[102:105]
	v_mfma_f32_16x16x32_bf16 v[94:97], v[190:193], v[166:169], v[94:97]
	v_mfma_f32_16x16x32_bf16 v[86:89], v[220:223], v[166:169], v[86:89]
	v_mfma_f32_16x16x32_bf16 v[78:81], v[190:193], v[174:177], v[78:81]
	v_mfma_f32_16x16x32_bf16 v[74:77], v[220:223], v[174:177], v[74:77]
	v_mfma_f32_16x16x32_bf16 v[70:73], v[190:193], v[182:185], v[70:73]
	v_mfma_f32_16x16x32_bf16 v[66:69], v[220:223], v[182:185], v[66:69]
	v_mfma_f32_16x16x32_bf16 v[110:113], v[216:219], v[162:165], v[110:113]
	v_mfma_f32_16x16x32_bf16 v[102:105], v[224:227], v[162:165], v[102:105]
	v_mfma_f32_16x16x32_bf16 v[94:97], v[216:219], v[170:173], v[94:97]
	v_mfma_f32_16x16x32_bf16 v[86:89], v[224:227], v[170:173], v[86:89]
	v_mfma_f32_16x16x32_bf16 v[78:81], v[216:219], v[178:181], v[78:81]
	v_mfma_f32_16x16x32_bf16 v[74:77], v[224:227], v[178:181], v[74:77]
	v_mfma_f32_16x16x32_bf16 v[70:73], v[216:219], v[186:189], v[70:73]
	v_mfma_f32_16x16x32_bf16 v[66:69], v[224:227], v[186:189], v[66:69]
	s_nop 0
	s_mov_b32 m0, s47
	v_lshl_add_u64 v[232:233], s[28:29], 0, v[0:1]
	s_barrier
	ds_read_b128 v[158:161], v153 offset:16384
	ds_read_b128 v[162:165], v153 offset:17408
	ds_read_b128 v[166:169], v153 offset:18432
	ds_read_b128 v[170:173], v153 offset:19456
	ds_read_b128 v[174:177], v153 offset:20480
	ds_read_b128 v[178:181], v153 offset:21504
	ds_read_b128 v[182:185], v153 offset:22528
	ds_read_b128 v[186:189], v153 offset:23552
	global_load_lds_dwordx4 v[232:233], off
	v_lshl_add_u64 v[234:235], s[28:29], 0, v[130:131]
	s_mov_b32 m0, s48
	s_nop 0
	global_load_lds_dwordx4 v[234:235], off
	s_barrier
	s_waitcnt lgkmcnt(0)
	s_nop 0
	s_waitcnt lgkmcnt(0)
	v_mfma_f32_16x16x32_bf16 v[62:65], v[140:143], v[158:161], v[62:65]
	v_mfma_f32_16x16x32_bf16 v[58:61], v[148:151], v[158:161], v[58:61]
	v_mfma_f32_16x16x32_bf16 v[54:57], v[140:143], v[166:169], v[54:57]
	v_mfma_f32_16x16x32_bf16 v[46:49], v[148:151], v[166:169], v[46:49]
	v_mfma_f32_16x16x32_bf16 v[38:41], v[140:143], v[174:177], v[38:41]
	v_mfma_f32_16x16x32_bf16 v[30:33], v[148:151], v[174:177], v[30:33]
	v_mfma_f32_16x16x32_bf16 v[22:25], v[140:143], v[182:185], v[22:25]
	v_mfma_f32_16x16x32_bf16 v[14:17], v[148:151], v[182:185], v[14:17]
	v_mfma_f32_16x16x32_bf16 v[62:65], v[144:147], v[162:165], v[62:65]
	v_mfma_f32_16x16x32_bf16 v[58:61], v[154:157], v[162:165], v[58:61]
	v_mfma_f32_16x16x32_bf16 v[54:57], v[144:147], v[170:173], v[54:57]
	v_mfma_f32_16x16x32_bf16 v[46:49], v[154:157], v[170:173], v[46:49]
	v_mfma_f32_16x16x32_bf16 v[38:41], v[144:147], v[178:181], v[38:41]
	v_mfma_f32_16x16x32_bf16 v[30:33], v[154:157], v[178:181], v[30:33]
	v_mfma_f32_16x16x32_bf16 v[22:25], v[144:147], v[186:189], v[22:25]
	v_mfma_f32_16x16x32_bf16 v[14:17], v[154:157], v[186:189], v[14:17]
	s_nop 0
	s_barrier
; #define PG8_STAGE(bufoff, gbase, voff) do { _Pragma("unroll") for (int _i = 0; _i < 2; ++_i) \
;         __builtin_amdgcn_global_load_lds((const unsigned*)((const char*)(gbase) + (voff)[_i]), (LAS unsigned*)(lds + (bufoff) + ldsw + _i * 8192), 16, 0, 0); } while (0)
; #define PG8_LDA(dst, b, h) do { _Pragma("unroll") for (int m = 0; m < 4; ++m) _Pragma("unroll") for (int k = 0; k < 2; ++k) dst[m][k] = *(const LAS bf16x8*)(lds + PG8_SA(b, h) + aoff + m * 2048 + k * 1024); } while (0)
; #define PG8_LDB(dst, b, h) do { _Pragma("unroll") for (int n = 0; n < 2; ++n) _Pragma("unroll") for (int k = 0; k < 2; ++k) dst[n][k] = *(const LAS bf16x8*)(lds + PG8_SB(b, h) + boff + n * 2048 + k * 1024); } while (0)
; #define PG8_MMA(ai, bj, At, Bt) do { __builtin_amdgcn_s_setprio(1); _Pragma("unroll") for (int m = 0; m < 4; ++m) _Pragma("unroll") for (int n = 0; n < 2; ++n) _Pragma("unroll") for (int k = 0; k < 2; ++k) \
;         acc[ai][bj][m][n] = __builtin_amdgcn_mfma_f32_16x16x32_bf16(Bt[n][k], At[m][k], acc[ai][bj][m][n], 0, 0, 0); __builtin_amdgcn_s_setprio(0); } while (0)
; #define PG8_WAIT_V(n) asm volatile("s_waitcnt vmcnt(" #n ")" ::: "memory")
; #define PG8_WAIT_L(n) asm volatile("s_waitcnt lgkmcnt(" #n ")" ::: "memory")
; #define PG8_BAR __builtin_amdgcn_s_barrier()
; #define PG8_SCHED __builtin_amdgcn_sched_barrier(0)
; template <class Epi>
; DI void gemm_phase(LAS unsigned char* lds, const Gemm g, const StaticOrder& S, const Epi& E) {
;     ...
;             PG8_STAGE(PG8_SB(0, 1), b2 + hstepB, voffB);
;             PG8_WAIT_V(6); PG8_BAR; PG8_MMA(1, 1, At, B1); PG8_BAR;
;             PG8_LDB(B0, 1, 0); PG8_SCHED; PG8_LDA(At, 1, 0); PG8_STAGE(PG8_SA(0, 1), a2 + hstepA, voffA);
;             PG8_WAIT_L(8); PG8_BAR; PG8_WAIT_L(0); PG8_MMA(0, 0, At, B0); PG8_BAR; PG8_SCHED;
;             PG8_LDB(B1, 1, 1); PG8_STAGE(PG8_SB(1, 0), b3, voffB);
;             PG8_BAR; PG8_WAIT_L(0); PG8_MMA(0, 1, At, B1); PG8_BAR;
;             PG8_LDA(At, 1, 1); PG8_STAGE(PG8_SA(1, 0), a3, voffA);
;             PG8_BAR; PG8_WAIT_L(0); PG8_MMA(1, 0, At, B0); PG8_BAR; PG8_SCHED;
	s_add_u32 s30, s30, s44
	s_addc_u32 s31, s31, 0
	s_add_i32 s63, s64, s46
	v_lshl_add_u64 v[236:237], s[30:31], 0, v[0:1]
	s_mov_b32 m0, s63
	v_lshl_add_u64 v[250:251], s[30:31], 0, v[130:131]
	global_load_lds_dwordx4 v[236:237], off
	s_add_i32 m0, s63, 0x2000
	s_nop 0
	global_load_lds_dwordx4 v[250:251], off
	s_waitcnt vmcnt(6)
	s_barrier
	s_nop 0
	v_mfma_f32_16x16x32_bf16 v[50:53], v[190:193], v[158:161], v[50:53]
	v_mfma_f32_16x16x32_bf16 v[42:45], v[220:223], v[158:161], v[42:45]
	v_mfma_f32_16x16x32_bf16 v[34:37], v[190:193], v[166:169], v[34:37]
	v_mfma_f32_16x16x32_bf16 v[26:29], v[220:223], v[166:169], v[26:29]
	v_mfma_f32_16x16x32_bf16 v[18:21], v[190:193], v[174:177], v[18:21]
	v_mfma_f32_16x16x32_bf16 v[10:13], v[220:223], v[174:177], v[10:13]
	v_mfma_f32_16x16x32_bf16 v[6:9], v[190:193], v[182:185], v[6:9]
	v_mfma_f32_16x16x32_bf16 v[2:5], v[220:223], v[182:185], v[2:5]
	v_mfma_f32_16x16x32_bf16 v[50:53], v[216:219], v[162:165], v[50:53]
	v_mfma_f32_16x16x32_bf16 v[42:45], v[224:227], v[162:165], v[42:45]
	v_mfma_f32_16x16x32_bf16 v[34:37], v[216:219], v[170:173], v[34:37]
	v_mfma_f32_16x16x32_bf16 v[26:29], v[224:227], v[170:173], v[26:29]
	v_mfma_f32_16x16x32_bf16 v[18:21], v[216:219], v[178:181], v[18:21]
	v_mfma_f32_16x16x32_bf16 v[10:13], v[224:227], v[178:181], v[10:13]
	v_mfma_f32_16x16x32_bf16 v[6:9], v[216:219], v[186:189], v[6:9]
	v_mfma_f32_16x16x32_bf16 v[2:5], v[224:227], v[186:189], v[2:5]
	s_nop 0
	s_add_i32 s30, 0, 0x18000
	v_add_u32_e32 v133, s30, v152
	s_barrier
	ds_read_b128 v[140:143], v133
	ds_read_b128 v[144:147], v133 offset:1024
	ds_read_b128 v[148:151], v133 offset:2048
	ds_read_b128 v[154:157], v133 offset:3072
	s_add_u32 s28, s28, s44
	s_addc_u32 s29, s29, 0
	s_mov_b32 m0, s49
	v_lshl_add_u64 v[190:191], s[28:29], 0, v[0:1]
	ds_read_b128 v[158:161], v153 offset:32768
	ds_read_b128 v[162:165], v153 offset:33792
	ds_read_b128 v[166:169], v153 offset:34816
	ds_read_b128 v[170:173], v153 offset:35840
	ds_read_b128 v[174:177], v153 offset:36864
	ds_read_b128 v[178:181], v153 offset:37888
	ds_read_b128 v[182:185], v153 offset:38912
	ds_read_b128 v[186:189], v153 offset:39936
	global_load_lds_dwordx4 v[190:191], off
	v_lshl_add_u64 v[190:191], s[28:29], 0, v[130:131]
	s_mov_b32 m0, s50
	s_nop 0
	global_load_lds_dwordx4 v[190:191], off
	s_waitcnt lgkmcnt(8)
	s_barrier
	s_waitcnt lgkmcnt(0)
	s_nop 0
	s_waitcnt lgkmcnt(0)
	v_mfma_f32_16x16x32_bf16 v[126:129], v[140:143], v[158:161], v[126:129]
	v_mfma_f32_16x16x32_bf16 v[122:125], v[148:151], v[158:161], v[122:125]
	v_mfma_f32_16x16x32_bf16 v[118:121], v[140:143], v[166:169], v[118:121]
	v_mfma_f32_16x16x32_bf16 v[114:117], v[148:151], v[166:169], v[114:117]
	v_mfma_f32_16x16x32_bf16 v[106:109], v[140:143], v[174:177], v[106:109]
	v_mfma_f32_16x16x32_bf16 v[98:101], v[148:151], v[174:177], v[98:101]
	v_mfma_f32_16x16x32_bf16 v[90:93], v[140:143], v[182:185], v[90:93]
	v_mfma_f32_16x16x32_bf16 v[82:85], v[148:151], v[182:185], v[82:85]
	v_mfma_f32_16x16x32_bf16 v[126:129], v[144:147], v[162:165], v[126:129]
	v_mfma_f32_16x16x32_bf16 v[122:125], v[154:157], v[162:165], v[122:125]
	v_mfma_f32_16x16x32_bf16 v[118:121], v[144:147], v[170:173], v[118:121]
	v_mfma_f32_16x16x32_bf16 v[114:117], v[154:157], v[170:173], v[114:117]
	v_mfma_f32_16x16x32_bf16 v[106:109], v[144:147], v[178:181], v[106:109]
	v_mfma_f32_16x16x32_bf16 v[98:101], v[154:157], v[178:181], v[98:101]
	v_mfma_f32_16x16x32_bf16 v[90:93], v[144:147], v[186:189], v[90:93]
	v_mfma_f32_16x16x32_bf16 v[82:85], v[154:157], v[186:189], v[82:85]
	s_nop 0
	s_barrier
	s_add_i32 s28, 0, 0x1c000
	s_add_i32 s29, s30, s46
	v_add_u32_e32 v133, s28, v152
	v_lshl_add_u64 v[228:229], v[228:229], 0, s[2:3]
	s_mov_b32 m0, s29
	ds_read_b128 v[190:193], v133
	ds_read_b128 v[216:219], v133 offset:1024
	ds_read_b128 v[220:223], v133 offset:2048
	ds_read_b128 v[224:227], v133 offset:3072
	global_load_lds_dwordx4 v[228:229], off
	v_lshl_add_u64 v[228:229], v[230:231], 0, s[2:3]
	s_add_i32 m0, s29, 0x2000
	s_nop 0
	global_load_lds_dwordx4 v[228:229], off
	s_barrier
	s_waitcnt lgkmcnt(0)
	s_nop 0
	s_waitcnt lgkmcnt(0)
	v_mfma_f32_16x16x32_bf16 v[110:113], v[190:193], v[158:161], v[110:113]
	v_mfma_f32_16x16x32_bf16 v[102:105], v[220:223], v[158:161], v[102:105]
	v_mfma_f32_16x16x32_bf16 v[94:97], v[190:193], v[166:169], v[94:97]
	v_mfma_f32_16x16x32_bf16 v[86:89], v[220:223], v[166:169], v[86:89]
	v_mfma_f32_16x16x32_bf16 v[78:81], v[190:193], v[174:177], v[78:81]
	v_mfma_f32_16x16x32_bf16 v[74:77], v[220:223], v[174:177], v[74:77]
	v_mfma_f32_16x16x32_bf16 v[70:73], v[190:193], v[182:185], v[70:73]
	v_mfma_f32_16x16x32_bf16 v[66:69], v[220:223], v[182:185], v[66:69]
	v_mfma_f32_16x16x32_bf16 v[110:113], v[216:219], v[162:165], v[110:113]
	v_mfma_f32_16x16x32_bf16 v[102:105], v[224:227], v[162:165], v[102:105]
	v_mfma_f32_16x16x32_bf16 v[94:97], v[216:219], v[170:173], v[94:97]
	v_mfma_f32_16x16x32_bf16 v[86:89], v[224:227], v[170:173], v[86:89]
	v_mfma_f32_16x16x32_bf16 v[78:81], v[216:219], v[178:181], v[78:81]
	v_mfma_f32_16x16x32_bf16 v[74:77], v[224:227], v[178:181], v[74:77]
	v_mfma_f32_16x16x32_bf16 v[70:73], v[216:219], v[186:189], v[70:73]
	v_mfma_f32_16x16x32_bf16 v[66:69], v[224:227], v[186:189], v[66:69]
	s_nop 0
	s_mov_b32 m0, s51
	v_lshl_add_u64 v[228:229], v[232:233], 0, s[2:3]
	s_barrier
	ds_read_b128 v[158:161], v153 offset:49152
	ds_read_b128 v[162:165], v153 offset:50176
	ds_read_b128 v[166:169], v153 offset:51200
	ds_read_b128 v[170:173], v153 offset:52224
	ds_read_b128 v[174:177], v153 offset:53248
	ds_read_b128 v[178:181], v153 offset:54272
	ds_read_b128 v[182:185], v153 offset:55296
	ds_read_b128 v[186:189], v153 offset:56320
	global_load_lds_dwordx4 v[228:229], off
	v_lshl_add_u64 v[228:229], v[234:235], 0, s[2:3]
	s_mov_b32 m0, s52
	s_nop 0
	global_load_lds_dwordx4 v[228:229], off
	s_barrier
; #define PG8_STAGE(bufoff, gbase, voff) do { _Pragma("unroll") for (int _i = 0; _i < 2; ++_i) \
;         __builtin_amdgcn_global_load_lds((const unsigned*)((const char*)(gbase) + (voff)[_i]), (LAS unsigned*)(lds + (bufoff) + ldsw + _i * 8192), 16, 0, 0); } while (0)
; #define PG8_LDA(dst, b, h) do { _Pragma("unroll") for (int m = 0; m < 4; ++m) _Pragma("unroll") for (int k = 0; k < 2; ++k) dst[m][k] = *(const LAS bf16x8*)(lds + PG8_SA(b, h) + aoff + m * 2048 + k * 1024); } while (0)
; #define PG8_MMA(ai, bj, At, Bt) do { __builtin_amdgcn_s_setprio(1); _Pragma("unroll") for (int m = 0; m < 4; ++m) _Pragma("unroll") for (int n = 0; n < 2; ++n) _Pragma("unroll") for (int k = 0; k < 2; ++k) \
;         acc[ai][bj][m][n] = __builtin_amdgcn_mfma_f32_16x16x32_bf16(Bt[n][k], At[m][k], acc[ai][bj][m][n], 0, 0, 0); __builtin_amdgcn_s_setprio(0); } while (0)
; #define PG8_WAIT_V(n) asm volatile("s_waitcnt vmcnt(" #n ")" ::: "memory")
; #define PG8_WAIT_L(n) asm volatile("s_waitcnt lgkmcnt(" #n ")" ::: "memory")
; #define PG8_BAR __builtin_amdgcn_s_barrier()
; #define PG8_SCHED __builtin_amdgcn_sched_barrier(0)
; template <class Epi>
; DI void gemm_phase(LAS unsigned char* lds, const Gemm g, const StaticOrder& S, const Epi& E) {
;     ...
;             PG8_BAR; PG8_WAIT_L(0); PG8_MMA(0, 1, At, B1); PG8_BAR;
;             PG8_LDA(At, 1, 1); PG8_STAGE(PG8_SA(1, 0), a3, voffA);
;             PG8_BAR; PG8_WAIT_L(0); PG8_MMA(1, 0, At, B0); PG8_BAR; PG8_SCHED;
;             PG8_STAGE(PG8_SB(1, 1), b3 + hstepB, voffB);
;             PG8_WAIT_V(6); PG8_BAR; PG8_MMA(1, 1, At, B1); PG8_BAR;
;         }
	s_waitcnt lgkmcnt(0)
	s_nop 0
	s_waitcnt lgkmcnt(0)
	v_mfma_f32_16x16x32_bf16 v[62:65], v[140:143], v[158:161], v[62:65]
	v_mfma_f32_16x16x32_bf16 v[58:61], v[148:151], v[158:161], v[58:61]
	v_mfma_f32_16x16x32_bf16 v[54:57], v[140:143], v[166:169], v[54:57]
	v_mfma_f32_16x16x32_bf16 v[46:49], v[148:151], v[166:169], v[46:49]
	v_mfma_f32_16x16x32_bf16 v[38:41], v[140:143], v[174:177], v[38:41]
	v_mfma_f32_16x16x32_bf16 v[30:33], v[148:151], v[174:177], v[30:33]
	v_mfma_f32_16x16x32_bf16 v[22:25], v[140:143], v[182:185], v[22:25]
	v_mfma_f32_16x16x32_bf16 v[14:17], v[148:151], v[182:185], v[14:17]
	v_mfma_f32_16x16x32_bf16 v[62:65], v[144:147], v[162:165], v[62:65]
	v_mfma_f32_16x16x32_bf16 v[58:61], v[154:157], v[162:165], v[58:61]
	v_mfma_f32_16x16x32_bf16 v[54:57], v[144:147], v[170:173], v[54:57]
	v_mfma_f32_16x16x32_bf16 v[46:49], v[154:157], v[170:173], v[46:49]
	v_mfma_f32_16x16x32_bf16 v[38:41], v[144:147], v[178:181], v[38:41]
	v_mfma_f32_16x16x32_bf16 v[30:33], v[154:157], v[178:181], v[30:33]
	v_mfma_f32_16x16x32_bf16 v[22:25], v[144:147], v[186:189], v[22:25]
	v_mfma_f32_16x16x32_bf16 v[14:17], v[154:157], v[186:189], v[14:17]
	s_nop 0
	s_barrier
	s_add_i32 s28, s28, s46
	v_lshl_add_u64 v[140:141], v[236:237], 0, s[2:3]
	s_mov_b32 m0, s28
	s_nop 0
	global_load_lds_dwordx4 v[140:141], off
	v_lshl_add_u64 v[140:141], v[250:251], 0, s[2:3]
	s_add_i32 m0, s28, 0x2000
	s_nop 0
	global_load_lds_dwordx4 v[140:141], off
	s_waitcnt vmcnt(6)
	s_barrier
	s_nop 0
	v_mfma_f32_16x16x32_bf16 v[50:53], v[190:193], v[158:161], v[50:53]
	v_mfma_f32_16x16x32_bf16 v[42:45], v[220:223], v[158:161], v[42:45]
	v_mfma_f32_16x16x32_bf16 v[34:37], v[190:193], v[166:169], v[34:37]
	v_mfma_f32_16x16x32_bf16 v[26:29], v[220:223], v[166:169], v[26:29]
	v_mfma_f32_16x16x32_bf16 v[18:21], v[190:193], v[174:177], v[18:21]
	v_mfma_f32_16x16x32_bf16 v[10:13], v[220:223], v[174:177], v[10:13]
	v_mfma_f32_16x16x32_bf16 v[6:9], v[190:193], v[182:185], v[6:9]
	v_mfma_f32_16x16x32_bf16 v[2:5], v[220:223], v[182:185], v[2:5]
	v_mfma_f32_16x16x32_bf16 v[50:53], v[216:219], v[162:165], v[50:53]
	v_mfma_f32_16x16x32_bf16 v[42:45], v[224:227], v[162:165], v[42:45]
	v_mfma_f32_16x16x32_bf16 v[34:37], v[216:219], v[170:173], v[34:37]
	v_mfma_f32_16x16x32_bf16 v[26:29], v[224:227], v[170:173], v[26:29]
	v_mfma_f32_16x16x32_bf16 v[18:21], v[216:219], v[178:181], v[18:21]
	v_mfma_f32_16x16x32_bf16 v[10:13], v[224:227], v[178:181], v[10:13]
	v_mfma_f32_16x16x32_bf16 v[6:9], v[216:219], v[186:189], v[6:9]
	v_mfma_f32_16x16x32_bf16 v[2:5], v[224:227], v[186:189], v[2:5]
	s_nop 0
	s_add_u32 s60, s60, 0x100
	s_addc_u32 s61, s61, 0
	s_add_u32 s22, s22, 0x100
	s_addc_u32 s23, s23, 0
	s_cmp_ge_u32 s62, s53
	s_mov_b32 s28, s62
	s_barrier
	s_cbranch_scc0 .LBB0_533
	v_mov_b32_e32 v133, v238
	s_lshl_b32 s22, s59, 8
	v_ashrrev_i32_e32 v140, 2, v133
	v_and_b32_e32 v140, 0xffffffc0, v140
	v_lshl_add_u32 v140, s58, 8, v140
	v_and_or_b32 v142, v133, 15, v140
	v_lshrrev_b32_e32 v140, 1, v133
	v_lshrrev_b32_e32 v133, 2, v133
	v_and_b32_e32 v140, 0x60, v140
	v_and_b32_e32 v133, 12, v133
	v_or3_b32 v140, v140, s22, v133
	v_ashrrev_i32_e32 v141, 31, v140
	v_lshlrev_b64 v[140:141], 2, v[140:141]
	v_ashrrev_i32_e32 v143, 31, v142
	v_lshl_add_u64 v[144:145], s[68:69], 0, v[140:141]
	v_lshlrev_b64 v[146:147], 12, v[142:143]
	v_or_b32_e32 v166, 16, v142
	v_lshl_add_u64 v[162:163], v[144:145], 0, v[146:147]
	v_ashrrev_i32_e32 v167, 31, v166
	global_load_dwordx4 v[148:151], v[162:163], off
	global_load_dwordx4 v[154:157], v[162:163], off offset:64
	global_load_dwordx4 v[158:161], v[162:163], off offset:512
	s_nop 0
	global_load_dwordx4 v[162:165], v[162:163], off offset:576
	v_lshlrev_b64 v[236:237], 12, v[166:167]
	v_or_b32_e32 v182, 32, v142
	v_lshl_add_u64 v[178:179], v[144:145], 0, v[236:237]
	v_ashrrev_i32_e32 v183, 31, v182
	global_load_dwordx4 v[166:169], v[178:179], off
	global_load_dwordx4 v[170:173], v[178:179], off offset:64
	global_load_dwordx4 v[174:177], v[178:179], off offset:512
	s_nop 0
	global_load_dwordx4 v[178:181], v[178:179], off offset:576
	v_lshlrev_b64 v[250:251], 12, v[182:183]
	v_or_b32_e32 v142, 48, v142
	v_lshl_add_u64 v[216:217], v[144:145], 0, v[250:251]
	v_ashrrev_i32_e32 v143, 31, v142
	global_load_dwordx4 v[182:185], v[216:217], off
	global_load_dwordx4 v[186:189], v[216:217], off offset:64
	global_load_dwordx4 v[190:193], v[216:217], off offset:512
	s_nop 0
	global_load_dwordx4 v[216:219], v[216:217], off offset:576
	v_lshlrev_b64 v[142:143], 12, v[142:143]
	v_lshl_add_u64 v[232:233], v[144:145], 0, v[142:143]
	global_load_dwordx4 v[220:223], v[232:233], off
	global_load_dwordx4 v[224:227], v[232:233], off offset:64
	global_load_dwordx4 v[228:231], v[232:233], off offset:512
	s_nop 0
	global_load_dwordx4 v[232:235], v[232:233], off offset:576
	v_mov_b32_e32 v133, v132
	s_mov_b64 s[22:23], 0x80000
	s_and_b64 vcc, exec, s[40:41]
	s_mov_b32 s59, s56
	s_mov_b32 s58, s57
	s_mov_b64 s[28:29], s[0:1]
	s_waitcnt vmcnt(0)
	v_pk_fma_f32 v[126:127], v[134:135], v[126:127], v[148:149]
	v_lshl_add_u64 v[148:149], s[68:69], 0, v[146:147]
	v_lshl_add_u64 v[148:149], v[148:149], 0, v[140:141]
	v_pk_fma_f32 v[112:113], v[132:133], v[112:113], v[160:161]
	v_pk_fma_f32 v[110:111], v[134:135], v[110:111], v[158:159]
	global_store_dwordx4 v[148:149], v[110:113], off offset:512
	v_pk_fma_f32 v[104:105], v[132:133], v[104:105], v[164:165]
	v_pk_fma_f32 v[96:97], v[132:133], v[96:97], v[176:177]
	v_lshl_add_u64 v[110:111], s[68:69], 0, v[236:237]
	v_lshl_add_u64 v[110:111], v[110:111], 0, v[140:141]
	v_pk_fma_f32 v[94:95], v[134:135], v[94:95], v[174:175]
	global_store_dwordx4 v[110:111], v[94:97], off offset:512
	v_pk_fma_f32 v[80:81], v[132:133], v[80:81], v[192:193]
	v_pk_fma_f32 v[78:79], v[134:135], v[78:79], v[190:191]
	v_lshl_add_u64 v[94:95], s[68:69], 0, v[250:251]
	v_lshl_add_u64 v[94:95], v[94:95], 0, v[140:141]
	v_pk_fma_f32 v[102:103], v[134:135], v[102:103], v[162:163]
	v_pk_fma_f32 v[88:89], v[132:133], v[88:89], v[180:181]
	v_pk_fma_f32 v[86:87], v[134:135], v[86:87], v[178:179]
	global_store_dwordx4 v[94:95], v[78:81], off offset:512
	v_pk_fma_f32 v[76:77], v[132:133], v[76:77], v[218:219]
	v_pk_fma_f32 v[74:75], v[134:135], v[74:75], v[216:217]
	v_lshl_add_u64 v[78:79], s[68:69], 0, v[142:143]
	global_store_dwordx4 v[148:149], v[102:105], off offset:576
	global_store_dwordx4 v[110:111], v[86:89], off offset:576
	global_store_dwordx4 v[94:95], v[74:77], off offset:576
	v_pk_fma_f32 v[104:105], v[132:133], v[120:121], v[168:169]
	v_pk_fma_f32 v[102:103], v[134:135], v[118:119], v[166:167]
	v_pk_fma_f32 v[88:89], v[132:133], v[108:109], v[184:185]
	v_pk_fma_f32 v[86:87], v[134:135], v[106:107], v[182:183]
	v_pk_fma_f32 v[76:77], v[132:133], v[92:93], v[222:223]
	v_pk_fma_f32 v[74:75], v[134:135], v[90:91], v[220:221]
	v_lshl_add_u64 v[78:79], v[78:79], 0, v[140:141]
	v_pk_fma_f32 v[128:129], v[132:133], v[128:129], v[150:151]
	v_pk_fma_f32 v[124:125], v[132:133], v[124:125], v[156:157]
	v_pk_fma_f32 v[122:123], v[134:135], v[122:123], v[154:155]
	global_store_dwordx4 v[110:111], v[102:105], off
	global_store_dwordx4 v[94:95], v[86:89], off
	global_store_dwordx4 v[78:79], v[74:77], off
	v_pk_fma_f32 v[104:105], v[132:133], v[116:117], v[172:173]
	v_pk_fma_f32 v[102:103], v[134:135], v[114:115], v[170:171]
	v_pk_fma_f32 v[88:89], v[132:133], v[100:101], v[188:189]
	v_pk_fma_f32 v[86:87], v[134:135], v[98:99], v[186:187]
	v_pk_fma_f32 v[76:77], v[132:133], v[84:85], v[226:227]
	v_pk_fma_f32 v[74:75], v[134:135], v[82:83], v[224:225]
	v_pk_fma_f32 v[72:73], v[132:133], v[72:73], v[230:231]
	v_pk_fma_f32 v[70:71], v[134:135], v[70:71], v[228:229]
	v_pk_fma_f32 v[68:69], v[132:133], v[68:69], v[234:235]
	v_pk_fma_f32 v[66:67], v[134:135], v[66:67], v[232:233]
	v_lshl_add_u64 v[142:143], v[146:147], 0, s[22:23]
	global_store_dwordx4 v[148:149], v[126:129], off
	global_store_dwordx4 v[148:149], v[122:125], off offset:64
	global_store_dwordx4 v[110:111], v[102:105], off offset:64
	global_store_dwordx4 v[94:95], v[86:89], off offset:64
	global_store_dwordx4 v[78:79], v[74:77], off offset:64
	global_store_dwordx4 v[78:79], v[70:73], off offset:512
	global_store_dwordx4 v[78:79], v[66:69], off offset:576
	s_mov_b64 s[22:23], 0x90000
	v_lshl_add_u64 v[148:149], v[146:147], 0, s[22:23]
	v_lshl_add_u64 v[66:67], v[144:145], 0, v[142:143]
	global_load_dwordx4 v[78:81], v[66:67], off
	global_load_dwordx4 v[74:77], v[66:67], off offset:64
	global_load_dwordx4 v[70:73], v[66:67], off offset:512
	s_nop 0
	global_load_dwordx4 v[66:69], v[66:67], off offset:576
	v_lshl_add_u64 v[82:83], v[144:145], 0, v[148:149]
	s_mov_b64 s[22:23], 0xa0000
	global_load_dwordx4 v[94:97], v[82:83], off
	global_load_dwordx4 v[90:93], v[82:83], off offset:64
	global_load_dwordx4 v[86:89], v[82:83], off offset:512
	s_nop 0
	global_load_dwordx4 v[82:85], v[82:83], off offset:576
	v_lshl_add_u64 v[150:151], v[146:147], 0, s[22:23]
	v_lshl_add_u64 v[98:99], v[144:145], 0, v[150:151]
	s_mov_b64 s[22:23], 0xb0000
	global_load_dwordx4 v[110:113], v[98:99], off
	global_load_dwordx4 v[102:105], v[98:99], off offset:64
	global_load_dwordx4 v[106:109], v[98:99], off offset:512
	s_nop 0
	global_load_dwordx4 v[98:101], v[98:99], off offset:576
	v_lshl_add_u64 v[146:147], v[146:147], 0, s[22:23]
	v_lshl_add_u64 v[118:119], v[144:145], 0, v[146:147]
	global_load_dwordx4 v[114:117], v[118:119], off
	global_load_dwordx4 v[126:129], v[118:119], off offset:64
	global_load_dwordx4 v[122:125], v[118:119], off offset:512
	s_nop 0
	global_load_dwordx4 v[118:121], v[118:119], off offset:576
	s_mov_b64 s[22:23], s[4:5]
	s_waitcnt vmcnt(0)
; template <class Epi>
; DI void gemm_phase(LAS unsigned char* lds, const Gemm g, const StaticOrder& S, const Epi& E) {
;     ...
;         E(acc, cur, wr, wc, fr, fq);
;         if (!has_next) break;
	v_pk_fma_f32 v[62:63], v[134:135], v[62:63], v[78:79]
	v_lshl_add_u64 v[78:79], s[68:69], 0, v[142:143]
	v_lshl_add_u64 v[78:79], v[78:79], 0, v[140:141]
	v_pk_fma_f32 v[52:53], v[132:133], v[52:53], v[72:73]
	v_pk_fma_f32 v[50:51], v[134:135], v[50:51], v[70:71]
	global_store_dwordx4 v[78:79], v[50:53], off offset:512
	v_pk_fma_f32 v[36:37], v[132:133], v[36:37], v[88:89]
	v_pk_fma_f32 v[34:35], v[134:135], v[34:35], v[86:87]
	v_lshl_add_u64 v[50:51], s[68:69], 0, v[148:149]
	v_lshl_add_u64 v[50:51], v[50:51], 0, v[140:141]
	global_store_dwordx4 v[50:51], v[34:37], off offset:512
	v_pk_fma_f32 v[20:21], v[132:133], v[20:21], v[108:109]
	v_pk_fma_f32 v[18:19], v[134:135], v[18:19], v[106:107]
	v_lshl_add_u64 v[34:35], s[68:69], 0, v[150:151]
	v_lshl_add_u64 v[34:35], v[34:35], 0, v[140:141]
	v_pk_fma_f32 v[44:45], v[132:133], v[44:45], v[68:69]
	v_pk_fma_f32 v[42:43], v[134:135], v[42:43], v[66:67]
	v_pk_fma_f32 v[28:29], v[132:133], v[28:29], v[84:85]
	v_pk_fma_f32 v[26:27], v[134:135], v[26:27], v[82:83]
	global_store_dwordx4 v[34:35], v[18:21], off offset:512
	v_pk_fma_f32 v[12:13], v[132:133], v[12:13], v[100:101]
	v_pk_fma_f32 v[10:11], v[134:135], v[10:11], v[98:99]
	v_lshl_add_u64 v[18:19], s[68:69], 0, v[146:147]
	global_store_dwordx4 v[78:79], v[42:45], off offset:576
	global_store_dwordx4 v[50:51], v[26:29], off offset:576
	global_store_dwordx4 v[34:35], v[10:13], off offset:576
	v_pk_fma_f32 v[44:45], v[132:133], v[56:57], v[96:97]
	v_pk_fma_f32 v[42:43], v[134:135], v[54:55], v[94:95]
	v_pk_fma_f32 v[28:29], v[132:133], v[40:41], v[112:113]
	v_pk_fma_f32 v[26:27], v[134:135], v[38:39], v[110:111]
	v_pk_fma_f32 v[12:13], v[132:133], v[24:25], v[116:117]
	v_pk_fma_f32 v[10:11], v[134:135], v[22:23], v[114:115]
	v_lshl_add_u64 v[18:19], v[18:19], 0, v[140:141]
	v_pk_fma_f32 v[64:65], v[132:133], v[64:65], v[80:81]
	v_pk_fma_f32 v[60:61], v[132:133], v[60:61], v[76:77]
	v_pk_fma_f32 v[58:59], v[134:135], v[58:59], v[74:75]
	global_store_dwordx4 v[50:51], v[42:45], off
	global_store_dwordx4 v[34:35], v[26:29], off
	global_store_dwordx4 v[18:19], v[10:13], off
	v_pk_fma_f32 v[44:45], v[132:133], v[48:49], v[92:93]
	v_pk_fma_f32 v[42:43], v[134:135], v[46:47], v[90:91]
	v_pk_fma_f32 v[28:29], v[132:133], v[32:33], v[104:105]
	v_pk_fma_f32 v[26:27], v[134:135], v[30:31], v[102:103]
	v_pk_fma_f32 v[12:13], v[132:133], v[16:17], v[128:129]
	v_pk_fma_f32 v[10:11], v[134:135], v[14:15], v[126:127]
	v_pk_fma_f32 v[8:9], v[132:133], v[8:9], v[124:125]
	v_pk_fma_f32 v[6:7], v[134:135], v[6:7], v[122:123]
	v_pk_fma_f32 v[4:5], v[132:133], v[4:5], v[120:121]
	v_pk_fma_f32 v[2:3], v[134:135], v[2:3], v[118:119]
	global_store_dwordx4 v[78:79], v[62:65], off
	global_store_dwordx4 v[78:79], v[58:61], off offset:64
	global_store_dwordx4 v[50:51], v[42:45], off offset:64
	global_store_dwordx4 v[34:35], v[26:29], off offset:64
	global_store_dwordx4 v[18:19], v[10:13], off offset:64
	global_store_dwordx4 v[18:19], v[6:9], off offset:512
	global_store_dwordx4 v[18:19], v[2:5], off offset:576
	s_cbranch_vccz .LBB0_522
	s_waitcnt vmcnt(0)
	s_cmpk_gt_u32 s35, 0xff
	s_cbranch_scc1 .LBB0_537
	s_barrier

; #define PG8_STAGE(bufoff, gbase, voff) do { _Pragma("unroll") for (int _i = 0; _i < 2; ++_i) \
;         __builtin_amdgcn_global_load_lds((const unsigned*)((const char*)(gbase) + (voff)[_i]), (LAS unsigned*)(lds + (bufoff) + ldsw + _i * 8192), 16, 0, 0); } while (0)
; #define PG8_LDA(dst, b, h) do { _Pragma("unroll") for (int m = 0; m < 4; ++m) _Pragma("unroll") for (int k = 0; k < 2; ++k) dst[m][k] = *(const LAS bf16x8*)(lds + PG8_SA(b, h) + aoff + m * 2048 + k * 1024); } while (0)
; #define PG8_LDB(dst, b, h) do { _Pragma("unroll") for (int n = 0; n < 2; ++n) _Pragma("unroll") for (int k = 0; k < 2; ++k) dst[n][k] = *(const LAS bf16x8*)(lds + PG8_SB(b, h) + boff + n * 2048 + k * 1024); } while (0)
; #define PG8_MMA(ai, bj, At, Bt) do { __builtin_amdgcn_s_setprio(1); _Pragma("unroll") for (int m = 0; m < 4; ++m) _Pragma("unroll") for (int n = 0; n < 2; ++n) _Pragma("unroll") for (int k = 0; k < 2; ++k) \
;         acc[ai][bj][m][n] = __builtin_amdgcn_mfma_f32_16x16x32_bf16(Bt[n][k], At[m][k], acc[ai][bj][m][n], 0, 0, 0); __builtin_amdgcn_s_setprio(0); } while (0)
; template <class Epi>
; DI void gemm_phase(LAS unsigned char* lds, const Gemm g, const StaticOrder& S, const Epi& E) {
;     ...
;         for (int t = 0; t < nt; t += 2) {
;             const bool last = (t == nt - 2);
;             const char* a1 = cA + (size_t)(t + 1) * kstep;
;             const char* a2 = last ? nA : cA + (size_t)(t + 2) * kstep; const char* b2 = last ? nB : cB + (size_t)(t + 2) * kstep;
;             const char* a3 = a2 + kstep; const char* b3 = b2 + kstep;
;             PG8_LDB(B0, 0, 0); PG8_SCHED; PG8_LDA(At, 0, 0); PG8_STAGE(PG8_SA(1, 1), a1 + hstepA, voffA);
;             PG8_WAIT_L(8); PG8_BAR; PG8_WAIT_L(0); PG8_MMA(0, 0, At, B0); PG8_BAR; PG8_SCHED;
;             PG8_LDB(B1, 0, 1); PG8_STAGE(PG8_SB(0, 0), b2, voffB);
;             PG8_BAR; PG8_WAIT_L(0); PG8_MMA(0, 1, At, B1); PG8_BAR;
;             PG8_LDA(At, 0, 1); PG8_STAGE(PG8_SA(0, 0), a2, voffA);
;             PG8_BAR; PG8_WAIT_L(0); PG8_MMA(1, 0, At, B0); PG8_BAR; PG8_SCHED;
;             PG8_STAGE(PG8_SB(0, 1), b2 + hstepB, voffB);
;             PG8_WAIT_V(6); PG8_BAR; PG8_MMA(1, 1, At, B1); PG8_BAR;
;             PG8_LDB(B0, 1, 0); PG8_SCHED; PG8_LDA(At, 1, 0); PG8_STAGE(PG8_SA(0, 1), a2 + hstepA, voffA);
;             PG8_WAIT_L(8); PG8_BAR; PG8_WAIT_L(0); PG8_MMA(0, 0, At, B0); PG8_BAR; PG8_SCHED;
.LBB0_547:
	s_add_u32 s28, s22, 0xfffc0080
	s_addc_u32 s29, s23, -1
	s_add_i32 s53, 0, 0x10000
	v_add_u32_e32 v154, s53, v140
	ds_read_b128 v[142:145], v154
	ds_read_b128 v[146:149], v154 offset:1024
	ds_read_b128 v[150:153], v154 offset:2048
	ds_read_b128 v[154:157], v154 offset:3072
	s_cmp_eq_u32 s52, 12
	s_cselect_b32 s31, s5, s29
	s_cselect_b32 s30, s48, s28
	s_cselect_b32 s29, s1, s51
	s_cselect_b32 s28, s49, s50
	v_lshl_add_u64 v[190:191], s[22:23], 0, v[138:139]
	s_add_i32 m0, s19, 0xc000
	ds_read_b128 v[158:161], v141
	ds_read_b128 v[162:165], v141 offset:1024
	ds_read_b128 v[166:169], v141 offset:2048
	ds_read_b128 v[170:173], v141 offset:3072
	ds_read_b128 v[174:177], v141 offset:4096
	ds_read_b128 v[178:181], v141 offset:5120
	ds_read_b128 v[182:185], v141 offset:6144
	ds_read_b128 v[186:189], v141 offset:7168
	global_load_lds_dwordx4 v[190:191], off
	v_lshl_add_u64 v[190:191], s[22:23], 0, v[136:137]
	s_add_i32 m0, s19, 0xe000
	s_nop 0
	global_load_lds_dwordx4 v[190:191], off
	s_waitcnt lgkmcnt(8)
	s_barrier
	s_waitcnt lgkmcnt(0)
	s_nop 0
	s_waitcnt lgkmcnt(0)
	v_mfma_f32_16x16x32_bf16 v[126:129], v[142:145], v[158:161], v[126:129]
	v_mfma_f32_16x16x32_bf16 v[122:125], v[150:153], v[158:161], v[122:125]
	v_mfma_f32_16x16x32_bf16 v[110:113], v[142:145], v[166:169], v[110:113]
	v_mfma_f32_16x16x32_bf16 v[106:109], v[150:153], v[166:169], v[106:109]
	v_mfma_f32_16x16x32_bf16 v[94:97], v[142:145], v[174:177], v[94:97]
	v_mfma_f32_16x16x32_bf16 v[90:93], v[150:153], v[174:177], v[90:93]
	v_mfma_f32_16x16x32_bf16 v[78:81], v[142:145], v[182:185], v[78:81]
	v_mfma_f32_16x16x32_bf16 v[74:77], v[150:153], v[182:185], v[74:77]
	v_mfma_f32_16x16x32_bf16 v[126:129], v[146:149], v[162:165], v[126:129]
	v_mfma_f32_16x16x32_bf16 v[122:125], v[154:157], v[162:165], v[122:125]
	v_mfma_f32_16x16x32_bf16 v[110:113], v[146:149], v[170:173], v[110:113]
	v_mfma_f32_16x16x32_bf16 v[106:109], v[154:157], v[170:173], v[106:109]
	v_mfma_f32_16x16x32_bf16 v[94:97], v[146:149], v[178:181], v[94:97]
	v_mfma_f32_16x16x32_bf16 v[90:93], v[154:157], v[178:181], v[90:93]
	v_mfma_f32_16x16x32_bf16 v[78:81], v[146:149], v[186:189], v[78:81]
	v_mfma_f32_16x16x32_bf16 v[74:77], v[154:157], v[186:189], v[74:77]
	s_nop 0
	s_barrier
	s_add_i32 s56, 0, 0x14000
	s_add_i32 s53, s53, s36
	v_add_u32_e32 v200, s56, v140
	v_lshl_add_u64 v[228:229], s[28:29], 0, v[0:1]
	s_mov_b32 m0, s53
	ds_read_b128 v[190:193], v200
	ds_read_b128 v[216:219], v200 offset:1024
	ds_read_b128 v[220:223], v200 offset:2048
	ds_read_b128 v[224:227], v200 offset:3072
	global_load_lds_dwordx4 v[228:229], off
	v_lshl_add_u64 v[230:231], s[28:29], 0, v[130:131]
	s_add_i32 m0, s53, 0x2000
	s_nop 0
	global_load_lds_dwordx4 v[230:231], off
	s_barrier
	s_waitcnt lgkmcnt(0)
	s_nop 0
	s_waitcnt lgkmcnt(0)
	v_mfma_f32_16x16x32_bf16 v[118:121], v[190:193], v[158:161], v[118:121]
	v_mfma_f32_16x16x32_bf16 v[114:117], v[220:223], v[158:161], v[114:117]
	v_mfma_f32_16x16x32_bf16 v[102:105], v[190:193], v[166:169], v[102:105]
	v_mfma_f32_16x16x32_bf16 v[98:101], v[220:223], v[166:169], v[98:101]
	v_mfma_f32_16x16x32_bf16 v[86:89], v[190:193], v[174:177], v[86:89]
	v_mfma_f32_16x16x32_bf16 v[82:85], v[220:223], v[174:177], v[82:85]
	v_mfma_f32_16x16x32_bf16 v[70:73], v[190:193], v[182:185], v[70:73]
	v_mfma_f32_16x16x32_bf16 v[66:69], v[220:223], v[182:185], v[66:69]
	v_mfma_f32_16x16x32_bf16 v[118:121], v[216:219], v[162:165], v[118:121]
	v_mfma_f32_16x16x32_bf16 v[114:117], v[224:227], v[162:165], v[114:117]
	v_mfma_f32_16x16x32_bf16 v[102:105], v[216:219], v[170:173], v[102:105]
	v_mfma_f32_16x16x32_bf16 v[98:101], v[224:227], v[170:173], v[98:101]
	v_mfma_f32_16x16x32_bf16 v[86:89], v[216:219], v[178:181], v[86:89]
	v_mfma_f32_16x16x32_bf16 v[82:85], v[224:227], v[178:181], v[82:85]
	v_mfma_f32_16x16x32_bf16 v[70:73], v[216:219], v[186:189], v[70:73]
	v_mfma_f32_16x16x32_bf16 v[66:69], v[224:227], v[186:189], v[66:69]
	s_nop 0
	s_mov_b32 m0, s19
	v_lshl_add_u64 v[232:233], s[30:31], 0, v[134:135]
	s_barrier
	ds_read_b128 v[158:161], v141 offset:16384
	ds_read_b128 v[162:165], v141 offset:17408
	ds_read_b128 v[166:169], v141 offset:18432
	ds_read_b128 v[170:173], v141 offset:19456
	ds_read_b128 v[174:177], v141 offset:20480
	ds_read_b128 v[178:181], v141 offset:21504
	ds_read_b128 v[182:185], v141 offset:22528
	ds_read_b128 v[186:189], v141 offset:23552
	global_load_lds_dwordx4 v[232:233], off
	v_lshl_add_u64 v[234:235], s[30:31], 0, v[132:133]
	s_mov_b32 m0, s38
	s_nop 0
	global_load_lds_dwordx4 v[234:235], off
	s_barrier
	s_waitcnt lgkmcnt(0)
	s_nop 0
	s_waitcnt lgkmcnt(0)
	v_mfma_f32_16x16x32_bf16 v[62:65], v[142:145], v[158:161], v[62:65]
	v_mfma_f32_16x16x32_bf16 v[58:61], v[150:153], v[158:161], v[58:61]
	v_mfma_f32_16x16x32_bf16 v[46:49], v[142:145], v[166:169], v[46:49]
	v_mfma_f32_16x16x32_bf16 v[42:45], v[150:153], v[166:169], v[42:45]
	v_mfma_f32_16x16x32_bf16 v[30:33], v[142:145], v[174:177], v[30:33]
	v_mfma_f32_16x16x32_bf16 v[26:29], v[150:153], v[174:177], v[26:29]
	v_mfma_f32_16x16x32_bf16 v[14:17], v[142:145], v[182:185], v[14:17]
	v_mfma_f32_16x16x32_bf16 v[10:13], v[150:153], v[182:185], v[10:13]
	v_mfma_f32_16x16x32_bf16 v[62:65], v[146:149], v[162:165], v[62:65]
	v_mfma_f32_16x16x32_bf16 v[58:61], v[154:157], v[162:165], v[58:61]
	v_mfma_f32_16x16x32_bf16 v[46:49], v[146:149], v[170:173], v[46:49]
	v_mfma_f32_16x16x32_bf16 v[42:45], v[154:157], v[170:173], v[42:45]
	v_mfma_f32_16x16x32_bf16 v[30:33], v[146:149], v[178:181], v[30:33]
	v_mfma_f32_16x16x32_bf16 v[26:29], v[154:157], v[178:181], v[26:29]
	v_mfma_f32_16x16x32_bf16 v[14:17], v[146:149], v[186:189], v[14:17]
	v_mfma_f32_16x16x32_bf16 v[10:13], v[154:157], v[186:189], v[10:13]
	s_nop 0
	s_barrier
; #define PG8_STAGE(bufoff, gbase, voff) do { _Pragma("unroll") for (int _i = 0; _i < 2; ++_i) \
;         __builtin_amdgcn_global_load_lds((const unsigned*)((const char*)(gbase) + (voff)[_i]), (LAS unsigned*)(lds + (bufoff) + ldsw + _i * 8192), 16, 0, 0); } while (0)
; #define PG8_LDA(dst, b, h) do { _Pragma("unroll") for (int m = 0; m < 4; ++m) _Pragma("unroll") for (int k = 0; k < 2; ++k) dst[m][k] = *(const LAS bf16x8*)(lds + PG8_SA(b, h) + aoff + m * 2048 + k * 1024); } while (0)
; #define PG8_LDB(dst, b, h) do { _Pragma("unroll") for (int n = 0; n < 2; ++n) _Pragma("unroll") for (int k = 0; k < 2; ++k) dst[n][k] = *(const LAS bf16x8*)(lds + PG8_SB(b, h) + boff + n * 2048 + k * 1024); } while (0)
; #define PG8_MMA(ai, bj, At, Bt) do { __builtin_amdgcn_s_setprio(1); _Pragma("unroll") for (int m = 0; m < 4; ++m) _Pragma("unroll") for (int n = 0; n < 2; ++n) _Pragma("unroll") for (int k = 0; k < 2; ++k) \
;         acc[ai][bj][m][n] = __builtin_amdgcn_mfma_f32_16x16x32_bf16(Bt[n][k], At[m][k], acc[ai][bj][m][n], 0, 0, 0); __builtin_amdgcn_s_setprio(0); } while (0)
; #define PG8_WAIT_V(n) asm volatile("s_waitcnt vmcnt(" #n ")" ::: "memory")
; #define PG8_WAIT_L(n) asm volatile("s_waitcnt lgkmcnt(" #n ")" ::: "memory")
; #define PG8_BAR __builtin_amdgcn_s_barrier()
; #define PG8_SCHED __builtin_amdgcn_sched_barrier(0)
; template <class Epi>
; DI void gemm_phase(LAS unsigned char* lds, const Gemm g, const StaticOrder& S, const Epi& E) {
;     ...
;             PG8_STAGE(PG8_SB(0, 1), b2 + hstepB, voffB);
;             PG8_WAIT_V(6); PG8_BAR; PG8_MMA(1, 1, At, B1); PG8_BAR;
;             PG8_LDB(B0, 1, 0); PG8_SCHED; PG8_LDA(At, 1, 0); PG8_STAGE(PG8_SA(0, 1), a2 + hstepA, voffA);
;             PG8_WAIT_L(8); PG8_BAR; PG8_WAIT_L(0); PG8_MMA(0, 0, At, B0); PG8_BAR; PG8_SCHED;
;             PG8_LDB(B1, 1, 1); PG8_STAGE(PG8_SB(1, 0), b3, voffB);
;             PG8_BAR; PG8_WAIT_L(0); PG8_MMA(0, 1, At, B1); PG8_BAR;
;             PG8_LDA(At, 1, 1); PG8_STAGE(PG8_SA(1, 0), a3, voffA);
;             PG8_BAR; PG8_WAIT_L(0); PG8_MMA(1, 0, At, B0); PG8_BAR; PG8_SCHED;
	s_add_u32 s54, s28, 0x40000
	s_addc_u32 s55, s29, 0
	s_add_i32 s53, s56, s36
	v_lshl_add_u64 v[142:143], s[54:55], 0, v[0:1]
	s_mov_b32 m0, s53
	s_nop 0
	global_load_lds_dwordx4 v[142:143], off
	v_lshl_add_u64 v[142:143], s[54:55], 0, v[130:131]
	s_add_i32 m0, s53, 0x2000
	s_nop 0
	global_load_lds_dwordx4 v[142:143], off
	s_waitcnt vmcnt(6)
	s_barrier
	s_nop 0
	v_mfma_f32_16x16x32_bf16 v[54:57], v[190:193], v[158:161], v[54:57]
	v_mfma_f32_16x16x32_bf16 v[50:53], v[220:223], v[158:161], v[50:53]
	v_mfma_f32_16x16x32_bf16 v[38:41], v[190:193], v[166:169], v[38:41]
	v_mfma_f32_16x16x32_bf16 v[34:37], v[220:223], v[166:169], v[34:37]
	v_mfma_f32_16x16x32_bf16 v[22:25], v[190:193], v[174:177], v[22:25]
	v_mfma_f32_16x16x32_bf16 v[18:21], v[220:223], v[174:177], v[18:21]
	v_mfma_f32_16x16x32_bf16 v[6:9], v[190:193], v[182:185], v[6:9]
	v_mfma_f32_16x16x32_bf16 v[2:5], v[220:223], v[182:185], v[2:5]
	v_mfma_f32_16x16x32_bf16 v[54:57], v[216:219], v[162:165], v[54:57]
	v_mfma_f32_16x16x32_bf16 v[50:53], v[224:227], v[162:165], v[50:53]
	v_mfma_f32_16x16x32_bf16 v[38:41], v[216:219], v[170:173], v[38:41]
	v_mfma_f32_16x16x32_bf16 v[34:37], v[224:227], v[170:173], v[34:37]
	v_mfma_f32_16x16x32_bf16 v[22:25], v[216:219], v[178:181], v[22:25]
	v_mfma_f32_16x16x32_bf16 v[18:21], v[224:227], v[178:181], v[18:21]
	v_mfma_f32_16x16x32_bf16 v[6:9], v[216:219], v[186:189], v[6:9]
	v_mfma_f32_16x16x32_bf16 v[2:5], v[224:227], v[186:189], v[2:5]
	s_nop 0
	s_add_i32 s53, 0, 0x18000
	v_add_u32_e32 v154, s53, v140
	s_barrier
	ds_read_b128 v[142:145], v154
	ds_read_b128 v[146:149], v154 offset:1024
	ds_read_b128 v[150:153], v154 offset:2048
	ds_read_b128 v[154:157], v154 offset:3072
	s_add_u32 s30, s30, 0x40000
	s_addc_u32 s31, s31, 0
	s_mov_b32 m0, s39
	v_lshl_add_u64 v[190:191], s[30:31], 0, v[134:135]
	ds_read_b128 v[158:161], v141 offset:32768
	ds_read_b128 v[162:165], v141 offset:33792
	ds_read_b128 v[166:169], v141 offset:34816
	ds_read_b128 v[170:173], v141 offset:35840
	ds_read_b128 v[174:177], v141 offset:36864
	ds_read_b128 v[178:181], v141 offset:37888
	ds_read_b128 v[182:185], v141 offset:38912
	ds_read_b128 v[186:189], v141 offset:39936
	global_load_lds_dwordx4 v[190:191], off
	v_lshl_add_u64 v[190:191], s[30:31], 0, v[132:133]
	s_mov_b32 m0, s42
	s_nop 0
	global_load_lds_dwordx4 v[190:191], off
	s_waitcnt lgkmcnt(8)
	s_barrier
	s_waitcnt lgkmcnt(0)
	s_nop 0
	s_waitcnt lgkmcnt(0)
	v_mfma_f32_16x16x32_bf16 v[126:129], v[142:145], v[158:161], v[126:129]
	v_mfma_f32_16x16x32_bf16 v[122:125], v[150:153], v[158:161], v[122:125]
	v_mfma_f32_16x16x32_bf16 v[110:113], v[142:145], v[166:169], v[110:113]
	v_mfma_f32_16x16x32_bf16 v[106:109], v[150:153], v[166:169], v[106:109]
	v_mfma_f32_16x16x32_bf16 v[94:97], v[142:145], v[174:177], v[94:97]
	v_mfma_f32_16x16x32_bf16 v[90:93], v[150:153], v[174:177], v[90:93]
	v_mfma_f32_16x16x32_bf16 v[78:81], v[142:145], v[182:185], v[78:81]
	v_mfma_f32_16x16x32_bf16 v[74:77], v[150:153], v[182:185], v[74:77]
	v_mfma_f32_16x16x32_bf16 v[126:129], v[146:149], v[162:165], v[126:129]
	v_mfma_f32_16x16x32_bf16 v[122:125], v[154:157], v[162:165], v[122:125]
	v_mfma_f32_16x16x32_bf16 v[110:113], v[146:149], v[170:173], v[110:113]
	v_mfma_f32_16x16x32_bf16 v[106:109], v[154:157], v[170:173], v[106:109]
	v_mfma_f32_16x16x32_bf16 v[94:97], v[146:149], v[178:181], v[94:97]
	v_mfma_f32_16x16x32_bf16 v[90:93], v[154:157], v[178:181], v[90:93]
	v_mfma_f32_16x16x32_bf16 v[78:81], v[146:149], v[186:189], v[78:81]
	v_mfma_f32_16x16x32_bf16 v[74:77], v[154:157], v[186:189], v[74:77]
	s_nop 0
	s_barrier
	s_add_i32 s30, 0, 0x1c000
	s_add_i32 s31, s53, s36
	v_add_u32_e32 v200, s30, v140
	v_lshl_add_u64 v[228:229], v[228:229], 0, s[2:3]
	s_mov_b32 m0, s31
	ds_read_b128 v[190:193], v200
	ds_read_b128 v[216:219], v200 offset:1024
	ds_read_b128 v[220:223], v200 offset:2048
	ds_read_b128 v[224:227], v200 offset:3072
	global_load_lds_dwordx4 v[228:229], off
	v_lshl_add_u64 v[228:229], v[230:231], 0, s[2:3]
	s_add_i32 m0, s31, 0x2000
	s_nop 0
	global_load_lds_dwordx4 v[228:229], off
	s_barrier
	s_waitcnt lgkmcnt(0)
	s_nop 0
	s_waitcnt lgkmcnt(0)
	v_mfma_f32_16x16x32_bf16 v[118:121], v[190:193], v[158:161], v[118:121]
	v_mfma_f32_16x16x32_bf16 v[114:117], v[220:223], v[158:161], v[114:117]
	v_mfma_f32_16x16x32_bf16 v[102:105], v[190:193], v[166:169], v[102:105]
	v_mfma_f32_16x16x32_bf16 v[98:101], v[220:223], v[166:169], v[98:101]
	v_mfma_f32_16x16x32_bf16 v[86:89], v[190:193], v[174:177], v[86:89]
	v_mfma_f32_16x16x32_bf16 v[82:85], v[220:223], v[174:177], v[82:85]
	v_mfma_f32_16x16x32_bf16 v[70:73], v[190:193], v[182:185], v[70:73]
	v_mfma_f32_16x16x32_bf16 v[66:69], v[220:223], v[182:185], v[66:69]
	v_mfma_f32_16x16x32_bf16 v[118:121], v[216:219], v[162:165], v[118:121]
	v_mfma_f32_16x16x32_bf16 v[114:117], v[224:227], v[162:165], v[114:117]
	v_mfma_f32_16x16x32_bf16 v[102:105], v[216:219], v[170:173], v[102:105]
	v_mfma_f32_16x16x32_bf16 v[98:101], v[224:227], v[170:173], v[98:101]
	v_mfma_f32_16x16x32_bf16 v[86:89], v[216:219], v[178:181], v[86:89]
	v_mfma_f32_16x16x32_bf16 v[82:85], v[224:227], v[178:181], v[82:85]
	v_mfma_f32_16x16x32_bf16 v[70:73], v[216:219], v[186:189], v[70:73]
	v_mfma_f32_16x16x32_bf16 v[66:69], v[224:227], v[186:189], v[66:69]
	s_nop 0
	s_mov_b32 m0, s43
	v_lshl_add_u64 v[228:229], v[232:233], 0, s[2:3]
	s_barrier
	ds_read_b128 v[158:161], v141 offset:49152
	ds_read_b128 v[162:165], v141 offset:50176
	ds_read_b128 v[166:169], v141 offset:51200
	ds_read_b128 v[170:173], v141 offset:52224
	ds_read_b128 v[174:177], v141 offset:53248
	ds_read_b128 v[178:181], v141 offset:54272
	ds_read_b128 v[182:185], v141 offset:55296
	ds_read_b128 v[186:189], v141 offset:56320
	global_load_lds_dwordx4 v[228:229], off
	v_lshl_add_u64 v[228:229], v[234:235], 0, s[2:3]
	s_mov_b32 m0, s44
	s_nop 0
	global_load_lds_dwordx4 v[228:229], off
	s_barrier
; #define PG8_STAGE(bufoff, gbase, voff) do { _Pragma("unroll") for (int _i = 0; _i < 2; ++_i) \
;         __builtin_amdgcn_global_load_lds((const unsigned*)((const char*)(gbase) + (voff)[_i]), (LAS unsigned*)(lds + (bufoff) + ldsw + _i * 8192), 16, 0, 0); } while (0)
; #define PG8_LDA(dst, b, h) do { _Pragma("unroll") for (int m = 0; m < 4; ++m) _Pragma("unroll") for (int k = 0; k < 2; ++k) dst[m][k] = *(const LAS bf16x8*)(lds + PG8_SA(b, h) + aoff + m * 2048 + k * 1024); } while (0)
; #define PG8_MMA(ai, bj, At, Bt) do { __builtin_amdgcn_s_setprio(1); _Pragma("unroll") for (int m = 0; m < 4; ++m) _Pragma("unroll") for (int n = 0; n < 2; ++n) _Pragma("unroll") for (int k = 0; k < 2; ++k) \
;         acc[ai][bj][m][n] = __builtin_amdgcn_mfma_f32_16x16x32_bf16(Bt[n][k], At[m][k], acc[ai][bj][m][n], 0, 0, 0); __builtin_amdgcn_s_setprio(0); } while (0)
; #define PG8_WAIT_V(n) asm volatile("s_waitcnt vmcnt(" #n ")" ::: "memory")
; #define PG8_WAIT_L(n) asm volatile("s_waitcnt lgkmcnt(" #n ")" ::: "memory")
; #define PG8_BAR __builtin_amdgcn_s_barrier()
; #define PG8_SCHED __builtin_amdgcn_sched_barrier(0)
; DI float siluf_(float x) { return x * __builtin_amdgcn_rcpf(1.0f + __builtin_amdgcn_exp2f(-1.4426950408889634f * x)); }
; template <class Epi>
; DI void gemm_phase(LAS unsigned char* lds, const Gemm g, const StaticOrder& S, const Epi& E) {
;     ...
;             PG8_LDA(At, 1, 1); PG8_STAGE(PG8_SA(1, 0), a3, voffA);
;             PG8_BAR; PG8_WAIT_L(0); PG8_MMA(1, 0, At, B0); PG8_BAR; PG8_SCHED;
;             PG8_STAGE(PG8_SB(1, 1), b3 + hstepB, voffB);
;             PG8_WAIT_V(6); PG8_BAR; PG8_MMA(1, 1, At, B1); PG8_BAR;
;         }
	s_waitcnt lgkmcnt(0)
	s_nop 0
	s_waitcnt lgkmcnt(0)
	v_mfma_f32_16x16x32_bf16 v[62:65], v[142:145], v[158:161], v[62:65]
	v_mfma_f32_16x16x32_bf16 v[58:61], v[150:153], v[158:161], v[58:61]
	v_mfma_f32_16x16x32_bf16 v[46:49], v[142:145], v[166:169], v[46:49]
	v_mfma_f32_16x16x32_bf16 v[42:45], v[150:153], v[166:169], v[42:45]
	v_mfma_f32_16x16x32_bf16 v[30:33], v[142:145], v[174:177], v[30:33]
	v_mfma_f32_16x16x32_bf16 v[26:29], v[150:153], v[174:177], v[26:29]
	v_mfma_f32_16x16x32_bf16 v[14:17], v[142:145], v[182:185], v[14:17]
	v_mfma_f32_16x16x32_bf16 v[10:13], v[150:153], v[182:185], v[10:13]
	v_mfma_f32_16x16x32_bf16 v[62:65], v[146:149], v[162:165], v[62:65]
	v_mfma_f32_16x16x32_bf16 v[58:61], v[154:157], v[162:165], v[58:61]
	v_mfma_f32_16x16x32_bf16 v[46:49], v[146:149], v[170:173], v[46:49]
	v_mfma_f32_16x16x32_bf16 v[42:45], v[154:157], v[170:173], v[42:45]
	v_mfma_f32_16x16x32_bf16 v[30:33], v[146:149], v[178:181], v[30:33]
	v_mfma_f32_16x16x32_bf16 v[26:29], v[154:157], v[178:181], v[26:29]
	v_mfma_f32_16x16x32_bf16 v[14:17], v[146:149], v[186:189], v[14:17]
	v_mfma_f32_16x16x32_bf16 v[10:13], v[154:157], v[186:189], v[10:13]
	s_nop 0
	s_barrier
	s_add_u32 s28, s28, 0x40080
	s_addc_u32 s29, s29, 0
	s_add_i32 s30, s30, s36
	v_lshl_add_u64 v[142:143], s[28:29], 0, v[0:1]
	s_mov_b32 m0, s30
	s_nop 0
	global_load_lds_dwordx4 v[142:143], off
	v_lshl_add_u64 v[142:143], s[28:29], 0, v[130:131]
	s_add_i32 m0, s30, 0x2000
	s_nop 0
	global_load_lds_dwordx4 v[142:143], off
	s_waitcnt vmcnt(6)
	s_barrier
	s_nop 0
	v_mfma_f32_16x16x32_bf16 v[54:57], v[190:193], v[158:161], v[54:57]
	v_mfma_f32_16x16x32_bf16 v[50:53], v[220:223], v[158:161], v[50:53]
	v_mfma_f32_16x16x32_bf16 v[38:41], v[190:193], v[166:169], v[38:41]
	v_mfma_f32_16x16x32_bf16 v[34:37], v[220:223], v[166:169], v[34:37]
	v_mfma_f32_16x16x32_bf16 v[22:25], v[190:193], v[174:177], v[22:25]
	v_mfma_f32_16x16x32_bf16 v[18:21], v[220:223], v[174:177], v[18:21]
	v_mfma_f32_16x16x32_bf16 v[6:9], v[190:193], v[182:185], v[6:9]
	v_mfma_f32_16x16x32_bf16 v[2:5], v[220:223], v[182:185], v[2:5]
	v_mfma_f32_16x16x32_bf16 v[54:57], v[216:219], v[162:165], v[54:57]
	v_mfma_f32_16x16x32_bf16 v[50:53], v[224:227], v[162:165], v[50:53]
	v_mfma_f32_16x16x32_bf16 v[38:41], v[216:219], v[170:173], v[38:41]
	v_mfma_f32_16x16x32_bf16 v[34:37], v[224:227], v[170:173], v[34:37]
	v_mfma_f32_16x16x32_bf16 v[22:25], v[216:219], v[178:181], v[22:25]
	v_mfma_f32_16x16x32_bf16 v[18:21], v[224:227], v[178:181], v[18:21]
	v_mfma_f32_16x16x32_bf16 v[6:9], v[216:219], v[186:189], v[6:9]
	v_mfma_f32_16x16x32_bf16 v[2:5], v[224:227], v[186:189], v[2:5]
	s_nop 0
	s_add_i32 s52, s52, 2
	s_add_u32 s50, s50, 0x100
	s_addc_u32 s51, s51, 0
	s_add_u32 s22, s22, 0x100
	s_addc_u32 s23, s23, 0
	s_cmp_gt_u32 s52, 13
	s_barrier
	s_cbranch_scc0 .LBB0_547
	v_mov_b32_e32 v142, v238
	s_lshl_b32 s1, s18, 8
	v_ashrrev_i32_e32 v143, 2, v142
	v_and_b32_e32 v143, 0xffffffc0, v143
	v_lshrrev_b32_e32 v144, 1, v142
	v_and_or_b32 v142, v142, 15, s1
	v_add_u32_e32 v142, v142, v143
	v_mul_f32_e32 v143, 0xbfb8aa3b, v126
	v_exp_f32_e32 v143, v143
	v_and_b32_e32 v144, 0x78, v144
	v_lshl_or_b32 v146, s47, 8, v144
	v_readlane_b32 s22, v254, 54
	v_add_f32_e32 v143, 1.0, v143
	v_rcp_f32_e32 v144, v143
	v_mul_f32_e32 v143, 0xbfb8aa3b, v127
	v_exp_f32_e32 v143, v143
	v_readlane_b32 s23, v254, 55
	s_movk_i32 s1, 0x1600
	s_and_b64 vcc, exec, s[40:41]
	v_add_f32_e32 v143, 1.0, v143
	v_rcp_f32_e32 v145, v143
	s_mov_b32 s47, s0
	s_mov_b32 s18, s4
	s_mov_b64 s[28:29], s[14:15]
	v_pk_mul_f32 v[126:127], v[126:127], v[144:145]
	s_nop 0
	v_pk_mul_f32 v[122:123], v[122:123], v[126:127]
	s_nop 0
	v_cvt_pk_bf16_f32 v126, v122, v123
	v_mul_f32_e32 v122, 0xbfb8aa3b, v128
	v_mul_f32_e32 v123, 0xbfb8aa3b, v129
	v_exp_f32_e32 v122, v122
	v_exp_f32_e32 v123, v123
	v_add_f32_e32 v122, 1.0, v122
	v_add_f32_e32 v123, 1.0, v123
	v_rcp_f32_e32 v122, v122
	v_rcp_f32_e32 v123, v123
	s_nop 0
	v_pk_mul_f32 v[122:123], v[128:129], v[122:123]
	s_nop 0
	v_pk_mul_f32 v[122:123], v[124:125], v[122:123]
	v_ashrrev_i32_e32 v124, 1, v146
	v_cvt_pk_bf16_f32 v127, v122, v123
	v_mov_b64_e32 v[122:123], s[22:23]
	v_ashrrev_i32_e32 v125, 31, v124
	v_mad_i64_i32 v[128:129], s[22:23], v142, s1, v[122:123]
	v_lshlrev_b64 v[124:125], 1, v[124:125]
	v_lshl_add_u64 v[128:129], v[128:129], 0, v[124:125]
	global_store_dwordx2 v[128:129], v[126:127], off
	v_mul_f32_e32 v126, 0xbfb8aa3b, v118
	v_mul_f32_e32 v127, 0xbfb8aa3b, v119
	v_exp_f32_e32 v126, v126
	v_exp_f32_e32 v127, v127
	v_add_f32_e32 v126, 1.0, v126
	v_add_f32_e32 v127, 1.0, v127
	v_rcp_f32_e32 v126, v126
	v_rcp_f32_e32 v127, v127
	s_nop 0
	v_pk_mul_f32 v[118:119], v[118:119], v[126:127]
	s_nop 0
	v_pk_mul_f32 v[114:115], v[114:115], v[118:119]
	s_nop 0
	v_cvt_pk_bf16_f32 v114, v114, v115
	v_mul_f32_e32 v115, 0xbfb8aa3b, v120
	v_exp_f32_e32 v115, v115
	s_nop 0
	v_add_f32_e32 v115, 1.0, v115
	v_rcp_f32_e32 v118, v115
	v_mul_f32_e32 v115, 0xbfb8aa3b, v121
	v_exp_f32_e32 v115, v115
	s_nop 0
	v_add_f32_e32 v115, 1.0, v115
	v_rcp_f32_e32 v119, v115
	s_nop 0
	v_pk_mul_f32 v[118:119], v[120:121], v[118:119]
	s_nop 0
	v_pk_mul_f32 v[116:117], v[116:117], v[118:119]
	s_nop 0
	v_cvt_pk_bf16_f32 v115, v116, v117
	global_store_dwordx2 v[128:129], v[114:115], off offset:128
	v_mul_f32_e32 v114, 0xbfb8aa3b, v110
	v_mul_f32_e32 v115, 0xbfb8aa3b, v111
	v_exp_f32_e32 v114, v114
	v_exp_f32_e32 v115, v115
	v_or_b32_e32 v116, 16, v142
	v_add_f32_e32 v114, 1.0, v114
	v_add_f32_e32 v115, 1.0, v115
	v_rcp_f32_e32 v114, v114
	v_rcp_f32_e32 v115, v115
	s_nop 0
	v_pk_mul_f32 v[110:111], v[110:111], v[114:115]
	s_nop 0
	v_pk_mul_f32 v[106:107], v[106:107], v[110:111]
	s_nop 0
	v_cvt_pk_bf16_f32 v106, v106, v107
	v_mul_f32_e32 v107, 0xbfb8aa3b, v112
	v_exp_f32_e32 v107, v107
	s_nop 0
	v_add_f32_e32 v107, 1.0, v107
	v_rcp_f32_e32 v110, v107
	v_mul_f32_e32 v107, 0xbfb8aa3b, v113
	v_exp_f32_e32 v107, v107
	s_nop 0
	v_add_f32_e32 v107, 1.0, v107
	v_rcp_f32_e32 v111, v107
	s_nop 0
	v_pk_mul_f32 v[110:111], v[112:113], v[110:111]
	s_nop 0
	v_pk_mul_f32 v[108:109], v[108:109], v[110:111]
	s_nop 0
	v_cvt_pk_bf16_f32 v107, v108, v109
	v_mad_i64_i32 v[108:109], s[22:23], v116, s1, v[122:123]
	v_lshl_add_u64 v[108:109], v[108:109], 0, v[124:125]
	global_store_dwordx2 v[108:109], v[106:107], off
	v_mul_f32_e32 v106, 0xbfb8aa3b, v102
	v_mul_f32_e32 v107, 0xbfb8aa3b, v103
	v_exp_f32_e32 v106, v106
	v_exp_f32_e32 v107, v107
	v_add_f32_e32 v106, 1.0, v106
	v_add_f32_e32 v107, 1.0, v107
	v_rcp_f32_e32 v106, v106
	v_rcp_f32_e32 v107, v107
	s_nop 0
	v_pk_mul_f32 v[102:103], v[102:103], v[106:107]
	s_nop 0
	v_pk_mul_f32 v[98:99], v[98:99], v[102:103]
	s_nop 0
	v_cvt_pk_bf16_f32 v98, v98, v99
	v_mul_f32_e32 v99, 0xbfb8aa3b, v104
	v_exp_f32_e32 v99, v99
	s_nop 0
	v_add_f32_e32 v99, 1.0, v99
	v_rcp_f32_e32 v102, v99
	v_mul_f32_e32 v99, 0xbfb8aa3b, v105
	v_exp_f32_e32 v99, v99
	s_nop 0
	v_add_f32_e32 v99, 1.0, v99
	v_rcp_f32_e32 v103, v99
	s_nop 0
	v_pk_mul_f32 v[102:103], v[104:105], v[102:103]
	s_nop 0
	v_pk_mul_f32 v[100:101], v[100:101], v[102:103]
	s_nop 0
	v_cvt_pk_bf16_f32 v99, v100, v101
	global_store_dwordx2 v[108:109], v[98:99], off offset:128
	v_mul_f32_e32 v98, 0xbfb8aa3b, v94
	v_mul_f32_e32 v99, 0xbfb8aa3b, v95
	v_exp_f32_e32 v98, v98
	v_exp_f32_e32 v99, v99
	v_or_b32_e32 v100, 32, v142
	v_add_f32_e32 v98, 1.0, v98
	v_add_f32_e32 v99, 1.0, v99
	v_rcp_f32_e32 v98, v98
	v_rcp_f32_e32 v99, v99
	s_nop 0
	v_pk_mul_f32 v[94:95], v[94:95], v[98:99]
	s_nop 0
	v_pk_mul_f32 v[90:91], v[90:91], v[94:95]
	s_nop 0
	v_cvt_pk_bf16_f32 v90, v90, v91
	v_mul_f32_e32 v91, 0xbfb8aa3b, v96
	v_exp_f32_e32 v91, v91
	s_nop 0
	v_add_f32_e32 v91, 1.0, v91
	v_rcp_f32_e32 v94, v91
	v_mul_f32_e32 v91, 0xbfb8aa3b, v97
	v_exp_f32_e32 v91, v91
	s_nop 0
	v_add_f32_e32 v91, 1.0, v91
	v_rcp_f32_e32 v95, v91
	s_nop 0
	v_pk_mul_f32 v[94:95], v[96:97], v[94:95]
	s_nop 0
	v_pk_mul_f32 v[92:93], v[92:93], v[94:95]
	s_nop 0
	v_cvt_pk_bf16_f32 v91, v92, v93
	v_mad_i64_i32 v[92:93], s[22:23], v100, s1, v[122:123]
	v_lshl_add_u64 v[92:93], v[92:93], 0, v[124:125]
	global_store_dwordx2 v[92:93], v[90:91], off
	v_mul_f32_e32 v90, 0xbfb8aa3b, v86
	v_mul_f32_e32 v91, 0xbfb8aa3b, v87
	v_exp_f32_e32 v90, v90
	v_exp_f32_e32 v91, v91
	v_add_f32_e32 v90, 1.0, v90
	v_add_f32_e32 v91, 1.0, v91
	v_rcp_f32_e32 v90, v90
	v_rcp_f32_e32 v91, v91
	s_nop 0
	v_pk_mul_f32 v[86:87], v[86:87], v[90:91]
	s_nop 0
	v_pk_mul_f32 v[82:83], v[82:83], v[86:87]
	s_nop 0
	v_cvt_pk_bf16_f32 v82, v82, v83
	v_mul_f32_e32 v83, 0xbfb8aa3b, v88
	v_exp_f32_e32 v83, v83
	s_nop 0
	v_add_f32_e32 v83, 1.0, v83
	v_rcp_f32_e32 v86, v83
	v_mul_f32_e32 v83, 0xbfb8aa3b, v89
	v_exp_f32_e32 v83, v83
	s_nop 0
	v_add_f32_e32 v83, 1.0, v83
	v_rcp_f32_e32 v87, v83
	s_nop 0
	v_pk_mul_f32 v[86:87], v[88:89], v[86:87]
	s_nop 0
	v_pk_mul_f32 v[84:85], v[84:85], v[86:87]
	s_nop 0
	v_cvt_pk_bf16_f32 v83, v84, v85
	global_store_dwordx2 v[92:93], v[82:83], off offset:128
	v_mul_f32_e32 v82, 0xbfb8aa3b, v78
	v_mul_f32_e32 v83, 0xbfb8aa3b, v79
	v_exp_f32_e32 v82, v82
	v_exp_f32_e32 v83, v83
	v_or_b32_e32 v84, 48, v142
	v_add_f32_e32 v82, 1.0, v82
	v_add_f32_e32 v83, 1.0, v83
	v_rcp_f32_e32 v82, v82
	v_rcp_f32_e32 v83, v83
	s_nop 0
	v_pk_mul_f32 v[78:79], v[78:79], v[82:83]
	s_nop 0
	v_pk_mul_f32 v[74:75], v[74:75], v[78:79]
	s_nop 0
	v_cvt_pk_bf16_f32 v74, v74, v75
	v_mul_f32_e32 v75, 0xbfb8aa3b, v80
	v_exp_f32_e32 v75, v75
	s_nop 0
	v_add_f32_e32 v75, 1.0, v75
	v_rcp_f32_e32 v78, v75
	v_mul_f32_e32 v75, 0xbfb8aa3b, v81
	v_exp_f32_e32 v75, v75
	s_nop 0
	v_add_f32_e32 v75, 1.0, v75
	v_rcp_f32_e32 v79, v75
	s_nop 0
	v_pk_mul_f32 v[78:79], v[80:81], v[78:79]
	s_nop 0
	v_pk_mul_f32 v[76:77], v[76:77], v[78:79]
	s_nop 0
	v_cvt_pk_bf16_f32 v75, v76, v77
	v_mad_i64_i32 v[76:77], s[22:23], v84, s1, v[122:123]
	v_lshl_add_u64 v[76:77], v[76:77], 0, v[124:125]
	global_store_dwordx2 v[76:77], v[74:75], off
	v_mul_f32_e32 v74, 0xbfb8aa3b, v70
	v_mul_f32_e32 v75, 0xbfb8aa3b, v71
	v_exp_f32_e32 v74, v74
	v_exp_f32_e32 v75, v75
	v_add_f32_e32 v74, 1.0, v74
	v_add_f32_e32 v75, 1.0, v75
	v_rcp_f32_e32 v74, v74
	v_rcp_f32_e32 v75, v75
	s_nop 0
	v_pk_mul_f32 v[70:71], v[70:71], v[74:75]
	s_nop 0
	v_pk_mul_f32 v[66:67], v[66:67], v[70:71]
	s_nop 0
	v_cvt_pk_bf16_f32 v66, v66, v67
	v_mul_f32_e32 v67, 0xbfb8aa3b, v72
	v_exp_f32_e32 v67, v67
	s_nop 0
	v_add_f32_e32 v67, 1.0, v67
	v_rcp_f32_e32 v70, v67
	v_mul_f32_e32 v67, 0xbfb8aa3b, v73
	v_exp_f32_e32 v67, v67
	s_nop 0
	v_add_f32_e32 v67, 1.0, v67
	v_rcp_f32_e32 v71, v67
	s_nop 0
	v_pk_mul_f32 v[70:71], v[72:73], v[70:71]
	s_nop 0
	v_pk_mul_f32 v[68:69], v[68:69], v[70:71]
	s_nop 0
	v_cvt_pk_bf16_f32 v67, v68, v69
	global_store_dwordx2 v[76:77], v[66:67], off offset:128
	v_mul_f32_e32 v66, 0xbfb8aa3b, v62
	v_mul_f32_e32 v67, 0xbfb8aa3b, v63
	v_exp_f32_e32 v66, v66
	v_exp_f32_e32 v67, v67
	v_add_u32_e32 v68, 0x80, v142
	v_add_f32_e32 v66, 1.0, v66
	v_add_f32_e32 v67, 1.0, v67
	v_rcp_f32_e32 v66, v66
	v_rcp_f32_e32 v67, v67
	s_nop 0
	v_pk_mul_f32 v[62:63], v[62:63], v[66:67]
	s_nop 0
	v_pk_mul_f32 v[58:59], v[58:59], v[62:63]
	s_nop 0
	v_cvt_pk_bf16_f32 v58, v58, v59
	v_mul_f32_e32 v59, 0xbfb8aa3b, v64
	v_exp_f32_e32 v59, v59
	s_nop 0
	v_add_f32_e32 v59, 1.0, v59
	v_rcp_f32_e32 v62, v59
	v_mul_f32_e32 v59, 0xbfb8aa3b, v65
	v_exp_f32_e32 v59, v59
	s_nop 0
	v_add_f32_e32 v59, 1.0, v59
; template <class Epi>
; DI void gemm_phase(LAS unsigned char* lds, const Gemm g, const StaticOrder& S, const Epi& E) {
;     ...
;         E(acc, cur, wr, wc, fr, fq);
;         if (!has_next) break;
	v_rcp_f32_e32 v63, v59
	s_nop 0
	v_pk_mul_f32 v[62:63], v[64:65], v[62:63]
	s_nop 0
	v_pk_mul_f32 v[60:61], v[60:61], v[62:63]
	s_nop 0
	v_cvt_pk_bf16_f32 v59, v60, v61
	v_mad_i64_i32 v[60:61], s[22:23], v68, s1, v[122:123]
	v_lshl_add_u64 v[60:61], v[60:61], 0, v[124:125]
	global_store_dwordx2 v[60:61], v[58:59], off
	v_mul_f32_e32 v58, 0xbfb8aa3b, v54
	v_mul_f32_e32 v59, 0xbfb8aa3b, v55
	v_exp_f32_e32 v58, v58
	v_exp_f32_e32 v59, v59
	v_add_f32_e32 v58, 1.0, v58
	v_add_f32_e32 v59, 1.0, v59
	v_rcp_f32_e32 v58, v58
	v_rcp_f32_e32 v59, v59
	s_nop 0
	v_pk_mul_f32 v[54:55], v[54:55], v[58:59]
	s_nop 0
	v_pk_mul_f32 v[50:51], v[50:51], v[54:55]
	s_nop 0
	v_cvt_pk_bf16_f32 v50, v50, v51
	v_mul_f32_e32 v51, 0xbfb8aa3b, v56
	v_exp_f32_e32 v51, v51
	s_nop 0
	v_add_f32_e32 v51, 1.0, v51
	v_rcp_f32_e32 v54, v51
	v_mul_f32_e32 v51, 0xbfb8aa3b, v57
	v_exp_f32_e32 v51, v51
	s_nop 0
	v_add_f32_e32 v51, 1.0, v51
	v_rcp_f32_e32 v55, v51
	s_nop 0
	v_pk_mul_f32 v[54:55], v[56:57], v[54:55]
	s_nop 0
	v_pk_mul_f32 v[52:53], v[52:53], v[54:55]
	s_nop 0
	v_cvt_pk_bf16_f32 v51, v52, v53
	global_store_dwordx2 v[60:61], v[50:51], off offset:128
	v_mul_f32_e32 v50, 0xbfb8aa3b, v46
	v_mul_f32_e32 v51, 0xbfb8aa3b, v47
	v_exp_f32_e32 v50, v50
	v_exp_f32_e32 v51, v51
	v_add_u32_e32 v52, 0x90, v142
	v_add_f32_e32 v50, 1.0, v50
	v_add_f32_e32 v51, 1.0, v51
	v_rcp_f32_e32 v50, v50
	v_rcp_f32_e32 v51, v51
	s_nop 0
	v_pk_mul_f32 v[46:47], v[46:47], v[50:51]
	s_nop 0
	v_pk_mul_f32 v[42:43], v[42:43], v[46:47]
	s_nop 0
	v_cvt_pk_bf16_f32 v42, v42, v43
	v_mul_f32_e32 v43, 0xbfb8aa3b, v48
	v_exp_f32_e32 v43, v43
	s_nop 0
	v_add_f32_e32 v43, 1.0, v43
	v_rcp_f32_e32 v46, v43
	v_mul_f32_e32 v43, 0xbfb8aa3b, v49
	v_exp_f32_e32 v43, v43
	s_nop 0
	v_add_f32_e32 v43, 1.0, v43
	v_rcp_f32_e32 v47, v43
	s_nop 0
	v_pk_mul_f32 v[46:47], v[48:49], v[46:47]
	s_nop 0
	v_pk_mul_f32 v[44:45], v[44:45], v[46:47]
	s_nop 0
	v_cvt_pk_bf16_f32 v43, v44, v45
	v_mad_i64_i32 v[44:45], s[22:23], v52, s1, v[122:123]
	v_lshl_add_u64 v[44:45], v[44:45], 0, v[124:125]
	global_store_dwordx2 v[44:45], v[42:43], off
	v_mul_f32_e32 v42, 0xbfb8aa3b, v38
	v_mul_f32_e32 v43, 0xbfb8aa3b, v39
	v_exp_f32_e32 v42, v42
	v_exp_f32_e32 v43, v43
	v_add_f32_e32 v42, 1.0, v42
	v_add_f32_e32 v43, 1.0, v43
	v_rcp_f32_e32 v42, v42
	v_rcp_f32_e32 v43, v43
	s_nop 0
	v_pk_mul_f32 v[38:39], v[38:39], v[42:43]
	s_nop 0
	v_pk_mul_f32 v[34:35], v[34:35], v[38:39]
	s_nop 0
	v_cvt_pk_bf16_f32 v34, v34, v35
	v_mul_f32_e32 v35, 0xbfb8aa3b, v40
	v_exp_f32_e32 v35, v35
	s_nop 0
	v_add_f32_e32 v35, 1.0, v35
	v_rcp_f32_e32 v38, v35
	v_mul_f32_e32 v35, 0xbfb8aa3b, v41
	v_exp_f32_e32 v35, v35
	s_nop 0
	v_add_f32_e32 v35, 1.0, v35
	v_rcp_f32_e32 v39, v35
	s_nop 0
	v_pk_mul_f32 v[38:39], v[40:41], v[38:39]
	s_nop 0
	v_pk_mul_f32 v[36:37], v[36:37], v[38:39]
	s_nop 0
	v_cvt_pk_bf16_f32 v35, v36, v37
	global_store_dwordx2 v[44:45], v[34:35], off offset:128
	v_mul_f32_e32 v34, 0xbfb8aa3b, v30
	v_mul_f32_e32 v35, 0xbfb8aa3b, v31
	v_exp_f32_e32 v34, v34
	v_exp_f32_e32 v35, v35
	v_add_u32_e32 v36, 0xa0, v142
	v_add_f32_e32 v34, 1.0, v34
	v_add_f32_e32 v35, 1.0, v35
	v_rcp_f32_e32 v34, v34
	v_rcp_f32_e32 v35, v35
	s_nop 0
	v_pk_mul_f32 v[30:31], v[30:31], v[34:35]
	s_nop 0
	v_pk_mul_f32 v[26:27], v[26:27], v[30:31]
	s_nop 0
	v_cvt_pk_bf16_f32 v26, v26, v27
	v_mul_f32_e32 v27, 0xbfb8aa3b, v32
	v_exp_f32_e32 v27, v27
	s_nop 0
	v_add_f32_e32 v27, 1.0, v27
	v_rcp_f32_e32 v30, v27
	v_mul_f32_e32 v27, 0xbfb8aa3b, v33
	v_exp_f32_e32 v27, v27
	s_nop 0
	v_add_f32_e32 v27, 1.0, v27
	v_rcp_f32_e32 v31, v27
	s_nop 0
	v_pk_mul_f32 v[30:31], v[32:33], v[30:31]
	s_nop 0
	v_pk_mul_f32 v[28:29], v[28:29], v[30:31]
	s_nop 0
	v_cvt_pk_bf16_f32 v27, v28, v29
	v_mad_i64_i32 v[28:29], s[22:23], v36, s1, v[122:123]
	v_lshl_add_u64 v[28:29], v[28:29], 0, v[124:125]
	global_store_dwordx2 v[28:29], v[26:27], off
	v_mul_f32_e32 v26, 0xbfb8aa3b, v22
	v_mul_f32_e32 v27, 0xbfb8aa3b, v23
	v_exp_f32_e32 v26, v26
	v_exp_f32_e32 v27, v27
	v_add_f32_e32 v26, 1.0, v26
	v_add_f32_e32 v27, 1.0, v27
	v_rcp_f32_e32 v26, v26
	v_rcp_f32_e32 v27, v27
	s_nop 0
	v_pk_mul_f32 v[22:23], v[22:23], v[26:27]
	s_nop 0
	v_pk_mul_f32 v[18:19], v[18:19], v[22:23]
	s_nop 0
	v_cvt_pk_bf16_f32 v18, v18, v19
	v_mul_f32_e32 v19, 0xbfb8aa3b, v24
	v_exp_f32_e32 v19, v19
	s_nop 0
	v_add_f32_e32 v19, 1.0, v19
	v_rcp_f32_e32 v22, v19
	v_mul_f32_e32 v19, 0xbfb8aa3b, v25
	v_exp_f32_e32 v19, v19
	s_nop 0
	v_add_f32_e32 v19, 1.0, v19
	v_rcp_f32_e32 v23, v19
	s_nop 0
	v_pk_mul_f32 v[22:23], v[24:25], v[22:23]
	s_nop 0
	v_pk_mul_f32 v[20:21], v[20:21], v[22:23]
	s_nop 0
	v_cvt_pk_bf16_f32 v19, v20, v21
	global_store_dwordx2 v[28:29], v[18:19], off offset:128
	v_mul_f32_e32 v18, 0xbfb8aa3b, v14
	v_mul_f32_e32 v19, 0xbfb8aa3b, v15
	v_exp_f32_e32 v18, v18
	v_exp_f32_e32 v19, v19
	v_add_u32_e32 v20, 0xb0, v142
	v_add_f32_e32 v18, 1.0, v18
	v_add_f32_e32 v19, 1.0, v19
	v_rcp_f32_e32 v18, v18
	v_rcp_f32_e32 v19, v19
	s_nop 0
	v_pk_mul_f32 v[14:15], v[14:15], v[18:19]
	s_nop 0
	v_pk_mul_f32 v[10:11], v[10:11], v[14:15]
	s_nop 0
	v_cvt_pk_bf16_f32 v10, v10, v11
	v_mul_f32_e32 v11, 0xbfb8aa3b, v16
	v_exp_f32_e32 v11, v11
	s_nop 0
	v_add_f32_e32 v11, 1.0, v11
	v_rcp_f32_e32 v14, v11
	v_mul_f32_e32 v11, 0xbfb8aa3b, v17
	v_exp_f32_e32 v11, v11
	s_nop 0
	v_add_f32_e32 v11, 1.0, v11
	v_rcp_f32_e32 v15, v11
	s_nop 0
	v_pk_mul_f32 v[14:15], v[16:17], v[14:15]
	s_nop 0
	v_pk_mul_f32 v[12:13], v[12:13], v[14:15]
	s_nop 0
	v_cvt_pk_bf16_f32 v11, v12, v13
	v_mad_i64_i32 v[12:13], s[22:23], v20, s1, v[122:123]
	v_lshl_add_u64 v[12:13], v[12:13], 0, v[124:125]
	global_store_dwordx2 v[12:13], v[10:11], off
	v_mul_f32_e32 v10, 0xbfb8aa3b, v6
	v_mul_f32_e32 v11, 0xbfb8aa3b, v7
	v_exp_f32_e32 v10, v10
	v_exp_f32_e32 v11, v11
	s_mov_b64 s[22:23], s[16:17]
	v_add_f32_e32 v10, 1.0, v10
	v_add_f32_e32 v11, 1.0, v11
	v_rcp_f32_e32 v10, v10
	v_rcp_f32_e32 v11, v11
	s_nop 0
	v_pk_mul_f32 v[6:7], v[6:7], v[10:11]
	s_nop 0
	v_pk_mul_f32 v[2:3], v[2:3], v[6:7]
	s_nop 0
	v_cvt_pk_bf16_f32 v2, v2, v3
	v_mul_f32_e32 v3, 0xbfb8aa3b, v8
	v_exp_f32_e32 v3, v3
	s_nop 0
	v_add_f32_e32 v3, 1.0, v3
	v_rcp_f32_e32 v6, v3
	v_mul_f32_e32 v3, 0xbfb8aa3b, v9
	v_exp_f32_e32 v3, v3
	s_nop 0
	v_add_f32_e32 v3, 1.0, v3
	v_rcp_f32_e32 v7, v3
	s_nop 0
	v_pk_mul_f32 v[6:7], v[8:9], v[6:7]
	s_nop 0
	v_pk_mul_f32 v[4:5], v[4:5], v[6:7]
	s_nop 0
	v_cvt_pk_bf16_f32 v3, v4, v5
	global_store_dwordx2 v[12:13], v[2:3], off offset:128
	s_cbranch_vccz .LBB0_544
	s_waitcnt vmcnt(0)
	s_cmpk_gt_u32 s35, 0xff
	s_cbranch_scc1 .LBB0_551
	s_barrier

; #define PG8_STAGE(bufoff, gbase, voff) do { _Pragma("unroll") for (int _i = 0; _i < 2; ++_i) \
;         __builtin_amdgcn_global_load_lds((const unsigned*)((const char*)(gbase) + (voff)[_i]), (LAS unsigned*)(lds + (bufoff) + ldsw + _i * 8192), 16, 0, 0); } while (0)
; #define PG8_LDA(dst, b, h) do { _Pragma("unroll") for (int m = 0; m < 4; ++m) _Pragma("unroll") for (int k = 0; k < 2; ++k) dst[m][k] = *(const LAS bf16x8*)(lds + PG8_SA(b, h) + aoff + m * 2048 + k * 1024); } while (0)
; #define PG8_LDB(dst, b, h) do { _Pragma("unroll") for (int n = 0; n < 2; ++n) _Pragma("unroll") for (int k = 0; k < 2; ++k) dst[n][k] = *(const LAS bf16x8*)(lds + PG8_SB(b, h) + boff + n * 2048 + k * 1024); } while (0)
; #define PG8_MMA(ai, bj, At, Bt) do { __builtin_amdgcn_s_setprio(1); _Pragma("unroll") for (int m = 0; m < 4; ++m) _Pragma("unroll") for (int n = 0; n < 2; ++n) _Pragma("unroll") for (int k = 0; k < 2; ++k) \
;         acc[ai][bj][m][n] = __builtin_amdgcn_mfma_f32_16x16x32_bf16(Bt[n][k], At[m][k], acc[ai][bj][m][n], 0, 0, 0); __builtin_amdgcn_s_setprio(0); } while (0)
; template <class Epi>
; DI void gemm_phase(LAS unsigned char* lds, const Gemm g, const StaticOrder& S, const Epi& E) {
;     ...
;         for (int t = 0; t < nt; t += 2) {
;             const bool last = (t == nt - 2);
;             const char* a1 = cA + (size_t)(t + 1) * kstep;
;             const char* a2 = last ? nA : cA + (size_t)(t + 2) * kstep; const char* b2 = last ? nB : cB + (size_t)(t + 2) * kstep;
;             const char* a3 = a2 + kstep; const char* b3 = b2 + kstep;
;             PG8_LDB(B0, 0, 0); PG8_SCHED; PG8_LDA(At, 0, 0); PG8_STAGE(PG8_SA(1, 1), a1 + hstepA, voffA);
;             PG8_WAIT_L(8); PG8_BAR; PG8_WAIT_L(0); PG8_MMA(0, 0, At, B0); PG8_BAR; PG8_SCHED;
;             PG8_LDB(B1, 0, 1); PG8_STAGE(PG8_SB(0, 0), b2, voffB);
;             PG8_BAR; PG8_WAIT_L(0); PG8_MMA(0, 1, At, B1); PG8_BAR;
;             PG8_LDA(At, 0, 1); PG8_STAGE(PG8_SA(0, 0), a2, voffA);
;             PG8_BAR; PG8_WAIT_L(0); PG8_MMA(1, 0, At, B0); PG8_BAR; PG8_SCHED;
;             PG8_STAGE(PG8_SB(0, 1), b2 + hstepB, voffB);
;             PG8_WAIT_V(6); PG8_BAR; PG8_MMA(1, 1, At, B1); PG8_BAR;
;             PG8_LDB(B0, 1, 0); PG8_SCHED; PG8_LDA(At, 1, 0); PG8_STAGE(PG8_SA(0, 1), a2 + hstepA, voffA);
;             PG8_WAIT_L(8); PG8_BAR; PG8_WAIT_L(0); PG8_MMA(0, 0, At, B0); PG8_BAR; PG8_SCHED;
.LBB0_574:
	s_add_u32 s16, s14, 0xfffc0080
	s_addc_u32 s17, s15, -1
	s_add_i32 s47, 0, 0x10000
	v_add_u32_e32 v142, s47, v190
	ds_read_b128 v[126:129], v142
	ds_read_b128 v[130:133], v142 offset:1024
	ds_read_b128 v[138:141], v142 offset:2048
	ds_read_b128 v[142:145], v142 offset:3072
	s_cmp_eq_u32 s46, 12
	s_cselect_b32 s19, s5, s17
	s_cselect_b32 s18, s39, s16
	s_cselect_b32 s17, s1, s44
	s_cselect_b32 s16, s42, s43
	v_lshl_add_u64 v[184:185], s[14:15], 0, v[166:167]
	s_add_i32 m0, s13, 0xc000
	ds_read_b128 v[146:149], v191
	ds_read_b128 v[150:153], v191 offset:1024
	ds_read_b128 v[154:157], v191 offset:2048
	ds_read_b128 v[158:161], v191 offset:3072
	ds_read_b128 v[168:171], v191 offset:4096
	ds_read_b128 v[172:175], v191 offset:5120
	ds_read_b128 v[176:179], v191 offset:6144
	ds_read_b128 v[180:183], v191 offset:7168
	global_load_lds_dwordx4 v[184:185], off
	v_lshl_add_u64 v[184:185], s[14:15], 0, v[164:165]
	s_add_i32 m0, s13, 0xe000
	s_nop 0
	global_load_lds_dwordx4 v[184:185], off
	s_waitcnt lgkmcnt(8)
	s_barrier
	s_waitcnt lgkmcnt(0)
	s_nop 0
	s_waitcnt lgkmcnt(0)
	v_mfma_f32_16x16x32_bf16 v[134:137], v[126:129], v[146:149], v[134:137]
	v_mfma_f32_16x16x32_bf16 v[122:125], v[138:141], v[146:149], v[122:125]
	v_mfma_f32_16x16x32_bf16 v[110:113], v[126:129], v[154:157], v[110:113]
	v_mfma_f32_16x16x32_bf16 v[106:109], v[138:141], v[154:157], v[106:109]
	v_mfma_f32_16x16x32_bf16 v[94:97], v[126:129], v[168:171], v[94:97]
	v_mfma_f32_16x16x32_bf16 v[90:93], v[138:141], v[168:171], v[90:93]
	v_mfma_f32_16x16x32_bf16 v[78:81], v[126:129], v[176:179], v[78:81]
	v_mfma_f32_16x16x32_bf16 v[74:77], v[138:141], v[176:179], v[74:77]
	v_mfma_f32_16x16x32_bf16 v[134:137], v[130:133], v[150:153], v[134:137]
	v_mfma_f32_16x16x32_bf16 v[122:125], v[142:145], v[150:153], v[122:125]
	v_mfma_f32_16x16x32_bf16 v[110:113], v[130:133], v[158:161], v[110:113]
	v_mfma_f32_16x16x32_bf16 v[106:109], v[142:145], v[158:161], v[106:109]
	v_mfma_f32_16x16x32_bf16 v[94:97], v[130:133], v[172:175], v[94:97]
	v_mfma_f32_16x16x32_bf16 v[90:93], v[142:145], v[172:175], v[90:93]
	v_mfma_f32_16x16x32_bf16 v[78:81], v[130:133], v[180:183], v[78:81]
	v_mfma_f32_16x16x32_bf16 v[74:77], v[142:145], v[180:183], v[74:77]
	s_nop 0
	s_barrier
	s_add_i32 s50, 0, 0x14000
	v_add_u32_e32 v188, s50, v190
	s_add_i32 s47, s47, s29
	ds_read_b128 v[184:187], v188
	ds_read_b128 v[216:219], v188 offset:1024
	ds_read_b128 v[220:223], v188 offset:2048
	ds_read_b128 v[224:227], v188 offset:3072
	v_lshl_add_u64 v[188:189], s[16:17], 0, v[0:1]
	s_mov_b32 m0, s47
	v_lshl_add_u64 v[192:193], s[16:17], 0, v[162:163]
	global_load_lds_dwordx4 v[188:189], off
	s_add_i32 m0, s47, 0x2000
	s_nop 0
	global_load_lds_dwordx4 v[192:193], off
	s_barrier
	s_waitcnt lgkmcnt(0)
	s_nop 0
	s_waitcnt lgkmcnt(0)
	v_mfma_f32_16x16x32_bf16 v[118:121], v[184:187], v[146:149], v[118:121]
	v_mfma_f32_16x16x32_bf16 v[114:117], v[220:223], v[146:149], v[114:117]
	v_mfma_f32_16x16x32_bf16 v[102:105], v[184:187], v[154:157], v[102:105]
	v_mfma_f32_16x16x32_bf16 v[98:101], v[220:223], v[154:157], v[98:101]
	v_mfma_f32_16x16x32_bf16 v[86:89], v[184:187], v[168:171], v[86:89]
	v_mfma_f32_16x16x32_bf16 v[82:85], v[220:223], v[168:171], v[82:85]
	v_mfma_f32_16x16x32_bf16 v[70:73], v[184:187], v[176:179], v[70:73]
	v_mfma_f32_16x16x32_bf16 v[66:69], v[220:223], v[176:179], v[66:69]
	v_mfma_f32_16x16x32_bf16 v[118:121], v[216:219], v[150:153], v[118:121]
	v_mfma_f32_16x16x32_bf16 v[114:117], v[224:227], v[150:153], v[114:117]
	v_mfma_f32_16x16x32_bf16 v[102:105], v[216:219], v[158:161], v[102:105]
	v_mfma_f32_16x16x32_bf16 v[98:101], v[224:227], v[158:161], v[98:101]
	v_mfma_f32_16x16x32_bf16 v[86:89], v[216:219], v[172:175], v[86:89]
	v_mfma_f32_16x16x32_bf16 v[82:85], v[224:227], v[172:175], v[82:85]
	v_mfma_f32_16x16x32_bf16 v[70:73], v[216:219], v[180:183], v[70:73]
	v_mfma_f32_16x16x32_bf16 v[66:69], v[224:227], v[180:183], v[66:69]
	s_nop 0
	s_mov_b32 m0, s13
	v_lshl_add_u64 v[200:201], s[18:19], 0, v[0:1]
	s_barrier
	ds_read_b128 v[146:149], v191 offset:16384
	ds_read_b128 v[150:153], v191 offset:17408
	ds_read_b128 v[154:157], v191 offset:18432
	ds_read_b128 v[158:161], v191 offset:19456
	ds_read_b128 v[168:171], v191 offset:20480
	ds_read_b128 v[172:175], v191 offset:21504
	ds_read_b128 v[176:179], v191 offset:22528
	ds_read_b128 v[180:183], v191 offset:23552
	global_load_lds_dwordx4 v[200:201], off
	v_lshl_add_u64 v[228:229], s[18:19], 0, v[162:163]
	s_mov_b32 m0, s30
	s_nop 0
	global_load_lds_dwordx4 v[228:229], off
	s_barrier
	s_waitcnt lgkmcnt(0)
	s_nop 0
	s_waitcnt lgkmcnt(0)
	v_mfma_f32_16x16x32_bf16 v[62:65], v[126:129], v[146:149], v[62:65]
	v_mfma_f32_16x16x32_bf16 v[58:61], v[138:141], v[146:149], v[58:61]
	v_mfma_f32_16x16x32_bf16 v[46:49], v[126:129], v[154:157], v[46:49]
	v_mfma_f32_16x16x32_bf16 v[42:45], v[138:141], v[154:157], v[42:45]
	v_mfma_f32_16x16x32_bf16 v[30:33], v[126:129], v[168:171], v[30:33]
	v_mfma_f32_16x16x32_bf16 v[26:29], v[138:141], v[168:171], v[26:29]
	v_mfma_f32_16x16x32_bf16 v[14:17], v[126:129], v[176:179], v[14:17]
	v_mfma_f32_16x16x32_bf16 v[10:13], v[138:141], v[176:179], v[10:13]
	v_mfma_f32_16x16x32_bf16 v[62:65], v[130:133], v[150:153], v[62:65]
	v_mfma_f32_16x16x32_bf16 v[58:61], v[142:145], v[150:153], v[58:61]
	v_mfma_f32_16x16x32_bf16 v[46:49], v[130:133], v[158:161], v[46:49]
	v_mfma_f32_16x16x32_bf16 v[42:45], v[142:145], v[158:161], v[42:45]
	v_mfma_f32_16x16x32_bf16 v[30:33], v[130:133], v[172:175], v[30:33]
	v_mfma_f32_16x16x32_bf16 v[26:29], v[142:145], v[172:175], v[26:29]
	v_mfma_f32_16x16x32_bf16 v[14:17], v[130:133], v[180:183], v[14:17]
	v_mfma_f32_16x16x32_bf16 v[10:13], v[142:145], v[180:183], v[10:13]
	s_nop 0
	s_barrier
; #define PG8_STAGE(bufoff, gbase, voff) do { _Pragma("unroll") for (int _i = 0; _i < 2; ++_i) \
;         __builtin_amdgcn_global_load_lds((const unsigned*)((const char*)(gbase) + (voff)[_i]), (LAS unsigned*)(lds + (bufoff) + ldsw + _i * 8192), 16, 0, 0); } while (0)
; #define PG8_LDA(dst, b, h) do { _Pragma("unroll") for (int m = 0; m < 4; ++m) _Pragma("unroll") for (int k = 0; k < 2; ++k) dst[m][k] = *(const LAS bf16x8*)(lds + PG8_SA(b, h) + aoff + m * 2048 + k * 1024); } while (0)
; #define PG8_LDB(dst, b, h) do { _Pragma("unroll") for (int n = 0; n < 2; ++n) _Pragma("unroll") for (int k = 0; k < 2; ++k) dst[n][k] = *(const LAS bf16x8*)(lds + PG8_SB(b, h) + boff + n * 2048 + k * 1024); } while (0)
; #define PG8_MMA(ai, bj, At, Bt) do { __builtin_amdgcn_s_setprio(1); _Pragma("unroll") for (int m = 0; m < 4; ++m) _Pragma("unroll") for (int n = 0; n < 2; ++n) _Pragma("unroll") for (int k = 0; k < 2; ++k) \
;         acc[ai][bj][m][n] = __builtin_amdgcn_mfma_f32_16x16x32_bf16(Bt[n][k], At[m][k], acc[ai][bj][m][n], 0, 0, 0); __builtin_amdgcn_s_setprio(0); } while (0)
; #define PG8_WAIT_V(n) asm volatile("s_waitcnt vmcnt(" #n ")" ::: "memory")
; #define PG8_WAIT_L(n) asm volatile("s_waitcnt lgkmcnt(" #n ")" ::: "memory")
; #define PG8_BAR __builtin_amdgcn_s_barrier()
; #define PG8_SCHED __builtin_amdgcn_sched_barrier(0)
; template <class Epi>
; DI void gemm_phase(LAS unsigned char* lds, const Gemm g, const StaticOrder& S, const Epi& E) {
;     ...
;             PG8_STAGE(PG8_SB(0, 1), b2 + hstepB, voffB);
;             PG8_WAIT_V(6); PG8_BAR; PG8_MMA(1, 1, At, B1); PG8_BAR;
;             PG8_LDB(B0, 1, 0); PG8_SCHED; PG8_LDA(At, 1, 0); PG8_STAGE(PG8_SA(0, 1), a2 + hstepA, voffA);
;             PG8_WAIT_L(8); PG8_BAR; PG8_WAIT_L(0); PG8_MMA(0, 0, At, B0); PG8_BAR; PG8_SCHED;
;             PG8_LDB(B1, 1, 1); PG8_STAGE(PG8_SB(1, 0), b3, voffB);
;             PG8_BAR; PG8_WAIT_L(0); PG8_MMA(0, 1, At, B1); PG8_BAR;
;             PG8_LDA(At, 1, 1); PG8_STAGE(PG8_SA(1, 0), a3, voffA);
;             PG8_BAR; PG8_WAIT_L(0); PG8_MMA(1, 0, At, B0); PG8_BAR; PG8_SCHED;
	s_add_u32 s48, s16, 0x40000
	s_addc_u32 s49, s17, 0
	s_add_i32 s47, s50, s29
	v_lshl_add_u64 v[126:127], s[48:49], 0, v[0:1]
	s_mov_b32 m0, s47
	s_nop 0
	global_load_lds_dwordx4 v[126:127], off
	v_lshl_add_u64 v[126:127], s[48:49], 0, v[162:163]
	s_add_i32 m0, s47, 0x2000
	s_nop 0
	global_load_lds_dwordx4 v[126:127], off
	s_waitcnt vmcnt(6)
	s_barrier
	s_nop 0
	v_mfma_f32_16x16x32_bf16 v[54:57], v[184:187], v[146:149], v[54:57]
	v_mfma_f32_16x16x32_bf16 v[50:53], v[220:223], v[146:149], v[50:53]
	v_mfma_f32_16x16x32_bf16 v[38:41], v[184:187], v[154:157], v[38:41]
	v_mfma_f32_16x16x32_bf16 v[34:37], v[220:223], v[154:157], v[34:37]
	v_mfma_f32_16x16x32_bf16 v[22:25], v[184:187], v[168:171], v[22:25]
	v_mfma_f32_16x16x32_bf16 v[18:21], v[220:223], v[168:171], v[18:21]
	v_mfma_f32_16x16x32_bf16 v[6:9], v[184:187], v[176:179], v[6:9]
	v_mfma_f32_16x16x32_bf16 v[2:5], v[220:223], v[176:179], v[2:5]
	v_mfma_f32_16x16x32_bf16 v[54:57], v[216:219], v[150:153], v[54:57]
	v_mfma_f32_16x16x32_bf16 v[50:53], v[224:227], v[150:153], v[50:53]
	v_mfma_f32_16x16x32_bf16 v[38:41], v[216:219], v[158:161], v[38:41]
	v_mfma_f32_16x16x32_bf16 v[34:37], v[224:227], v[158:161], v[34:37]
	v_mfma_f32_16x16x32_bf16 v[22:25], v[216:219], v[172:175], v[22:25]
	v_mfma_f32_16x16x32_bf16 v[18:21], v[224:227], v[172:175], v[18:21]
	v_mfma_f32_16x16x32_bf16 v[6:9], v[216:219], v[180:183], v[6:9]
	v_mfma_f32_16x16x32_bf16 v[2:5], v[224:227], v[180:183], v[2:5]
	s_nop 0
	s_add_i32 s47, 0, 0x18000
	v_add_u32_e32 v142, s47, v190
	s_barrier
	ds_read_b128 v[126:129], v142
	ds_read_b128 v[130:133], v142 offset:1024
	ds_read_b128 v[138:141], v142 offset:2048
	ds_read_b128 v[142:145], v142 offset:3072
	s_add_u32 s18, s18, 0x40000
	s_addc_u32 s19, s19, 0
	s_mov_b32 m0, s31
	v_lshl_add_u64 v[184:185], s[18:19], 0, v[0:1]
	ds_read_b128 v[146:149], v191 offset:32768
	ds_read_b128 v[150:153], v191 offset:33792
	ds_read_b128 v[154:157], v191 offset:34816
	ds_read_b128 v[158:161], v191 offset:35840
	ds_read_b128 v[168:171], v191 offset:36864
	ds_read_b128 v[172:175], v191 offset:37888
	ds_read_b128 v[176:179], v191 offset:38912
	ds_read_b128 v[180:183], v191 offset:39936
	global_load_lds_dwordx4 v[184:185], off
	v_lshl_add_u64 v[184:185], s[18:19], 0, v[162:163]
	s_mov_b32 m0, s34
	s_nop 0
	global_load_lds_dwordx4 v[184:185], off
	s_waitcnt lgkmcnt(8)
	s_barrier
	s_waitcnt lgkmcnt(0)
	s_nop 0
	s_waitcnt lgkmcnt(0)
	v_mfma_f32_16x16x32_bf16 v[134:137], v[126:129], v[146:149], v[134:137]
	v_mfma_f32_16x16x32_bf16 v[122:125], v[138:141], v[146:149], v[122:125]
	v_mfma_f32_16x16x32_bf16 v[110:113], v[126:129], v[154:157], v[110:113]
	v_mfma_f32_16x16x32_bf16 v[106:109], v[138:141], v[154:157], v[106:109]
	v_mfma_f32_16x16x32_bf16 v[94:97], v[126:129], v[168:171], v[94:97]
	v_mfma_f32_16x16x32_bf16 v[90:93], v[138:141], v[168:171], v[90:93]
	v_mfma_f32_16x16x32_bf16 v[78:81], v[126:129], v[176:179], v[78:81]
	v_mfma_f32_16x16x32_bf16 v[74:77], v[138:141], v[176:179], v[74:77]
	v_mfma_f32_16x16x32_bf16 v[134:137], v[130:133], v[150:153], v[134:137]
	v_mfma_f32_16x16x32_bf16 v[122:125], v[142:145], v[150:153], v[122:125]
	v_mfma_f32_16x16x32_bf16 v[110:113], v[130:133], v[158:161], v[110:113]
	v_mfma_f32_16x16x32_bf16 v[106:109], v[142:145], v[158:161], v[106:109]
	v_mfma_f32_16x16x32_bf16 v[94:97], v[130:133], v[172:175], v[94:97]
	v_mfma_f32_16x16x32_bf16 v[90:93], v[142:145], v[172:175], v[90:93]
	v_mfma_f32_16x16x32_bf16 v[78:81], v[130:133], v[180:183], v[78:81]
	v_mfma_f32_16x16x32_bf16 v[74:77], v[142:145], v[180:183], v[74:77]
	s_nop 0
	s_barrier
	s_add_i32 s18, 0, 0x1c000
	s_add_i32 s19, s47, s29
	v_add_u32_e32 v224, s18, v190
	v_lshl_add_u64 v[188:189], v[188:189], 0, s[2:3]
	s_mov_b32 m0, s19
	ds_read_b128 v[184:187], v224
	ds_read_b128 v[216:219], v224 offset:1024
	ds_read_b128 v[220:223], v224 offset:2048
	ds_read_b128 v[224:227], v224 offset:3072
	global_load_lds_dwordx4 v[188:189], off
	v_lshl_add_u64 v[188:189], v[192:193], 0, s[2:3]
	s_add_i32 m0, s19, 0x2000
	s_nop 0
	global_load_lds_dwordx4 v[188:189], off
	s_barrier
	s_waitcnt lgkmcnt(0)
	s_nop 0
	s_waitcnt lgkmcnt(0)
	v_mfma_f32_16x16x32_bf16 v[118:121], v[184:187], v[146:149], v[118:121]
	v_mfma_f32_16x16x32_bf16 v[114:117], v[220:223], v[146:149], v[114:117]
	v_mfma_f32_16x16x32_bf16 v[102:105], v[184:187], v[154:157], v[102:105]
	v_mfma_f32_16x16x32_bf16 v[98:101], v[220:223], v[154:157], v[98:101]
	v_mfma_f32_16x16x32_bf16 v[86:89], v[184:187], v[168:171], v[86:89]
	v_mfma_f32_16x16x32_bf16 v[82:85], v[220:223], v[168:171], v[82:85]
	v_mfma_f32_16x16x32_bf16 v[70:73], v[184:187], v[176:179], v[70:73]
	v_mfma_f32_16x16x32_bf16 v[66:69], v[220:223], v[176:179], v[66:69]
	v_mfma_f32_16x16x32_bf16 v[118:121], v[216:219], v[150:153], v[118:121]
	v_mfma_f32_16x16x32_bf16 v[114:117], v[224:227], v[150:153], v[114:117]
	v_mfma_f32_16x16x32_bf16 v[102:105], v[216:219], v[158:161], v[102:105]
	v_mfma_f32_16x16x32_bf16 v[98:101], v[224:227], v[158:161], v[98:101]
	v_mfma_f32_16x16x32_bf16 v[86:89], v[216:219], v[172:175], v[86:89]
	v_mfma_f32_16x16x32_bf16 v[82:85], v[224:227], v[172:175], v[82:85]
	v_mfma_f32_16x16x32_bf16 v[70:73], v[216:219], v[180:183], v[70:73]
	v_mfma_f32_16x16x32_bf16 v[66:69], v[224:227], v[180:183], v[66:69]
	s_nop 0
	s_mov_b32 m0, s35
	v_lshl_add_u64 v[188:189], v[200:201], 0, s[2:3]
	s_barrier
	ds_read_b128 v[146:149], v191 offset:49152
	ds_read_b128 v[150:153], v191 offset:50176
	ds_read_b128 v[154:157], v191 offset:51200
	ds_read_b128 v[158:161], v191 offset:52224
	ds_read_b128 v[168:171], v191 offset:53248
	ds_read_b128 v[172:175], v191 offset:54272
	ds_read_b128 v[176:179], v191 offset:55296
	ds_read_b128 v[180:183], v191 offset:56320
	global_load_lds_dwordx4 v[188:189], off
	v_lshl_add_u64 v[188:189], v[228:229], 0, s[2:3]
	s_mov_b32 m0, s36
	s_nop 0
	global_load_lds_dwordx4 v[188:189], off
	s_barrier
; #define PG8_STAGE(bufoff, gbase, voff) do { _Pragma("unroll") for (int _i = 0; _i < 2; ++_i) \
;         __builtin_amdgcn_global_load_lds((const unsigned*)((const char*)(gbase) + (voff)[_i]), (LAS unsigned*)(lds + (bufoff) + ldsw + _i * 8192), 16, 0, 0); } while (0)
; #define PG8_LDA(dst, b, h) do { _Pragma("unroll") for (int m = 0; m < 4; ++m) _Pragma("unroll") for (int k = 0; k < 2; ++k) dst[m][k] = *(const LAS bf16x8*)(lds + PG8_SA(b, h) + aoff + m * 2048 + k * 1024); } while (0)
; #define PG8_MMA(ai, bj, At, Bt) do { __builtin_amdgcn_s_setprio(1); _Pragma("unroll") for (int m = 0; m < 4; ++m) _Pragma("unroll") for (int n = 0; n < 2; ++n) _Pragma("unroll") for (int k = 0; k < 2; ++k) \
;         acc[ai][bj][m][n] = __builtin_amdgcn_mfma_f32_16x16x32_bf16(Bt[n][k], At[m][k], acc[ai][bj][m][n], 0, 0, 0); __builtin_amdgcn_s_setprio(0); } while (0)
; #define PG8_WAIT_V(n) asm volatile("s_waitcnt vmcnt(" #n ")" ::: "memory")
; #define PG8_WAIT_L(n) asm volatile("s_waitcnt lgkmcnt(" #n ")" ::: "memory")
; #define PG8_BAR __builtin_amdgcn_s_barrier()
; #define PG8_SCHED __builtin_amdgcn_sched_barrier(0)
; template <class Epi>
; DI void gemm_phase(LAS unsigned char* lds, const Gemm g, const StaticOrder& S, const Epi& E) {
;     ...
;             PG8_LDA(At, 1, 1); PG8_STAGE(PG8_SA(1, 0), a3, voffA);
;             PG8_BAR; PG8_WAIT_L(0); PG8_MMA(1, 0, At, B0); PG8_BAR; PG8_SCHED;
;             PG8_STAGE(PG8_SB(1, 1), b3 + hstepB, voffB);
;             PG8_WAIT_V(6); PG8_BAR; PG8_MMA(1, 1, At, B1); PG8_BAR;
;         }
	s_waitcnt lgkmcnt(0)
	s_nop 0
	s_waitcnt lgkmcnt(0)
	v_mfma_f32_16x16x32_bf16 v[62:65], v[126:129], v[146:149], v[62:65]
	v_mfma_f32_16x16x32_bf16 v[58:61], v[138:141], v[146:149], v[58:61]
	v_mfma_f32_16x16x32_bf16 v[46:49], v[126:129], v[154:157], v[46:49]
	v_mfma_f32_16x16x32_bf16 v[42:45], v[138:141], v[154:157], v[42:45]
	v_mfma_f32_16x16x32_bf16 v[30:33], v[126:129], v[168:171], v[30:33]
	v_mfma_f32_16x16x32_bf16 v[26:29], v[138:141], v[168:171], v[26:29]
	v_mfma_f32_16x16x32_bf16 v[14:17], v[126:129], v[176:179], v[14:17]
	v_mfma_f32_16x16x32_bf16 v[10:13], v[138:141], v[176:179], v[10:13]
	v_mfma_f32_16x16x32_bf16 v[62:65], v[130:133], v[150:153], v[62:65]
	v_mfma_f32_16x16x32_bf16 v[58:61], v[142:145], v[150:153], v[58:61]
	v_mfma_f32_16x16x32_bf16 v[46:49], v[130:133], v[158:161], v[46:49]
	v_mfma_f32_16x16x32_bf16 v[42:45], v[142:145], v[158:161], v[42:45]
	v_mfma_f32_16x16x32_bf16 v[30:33], v[130:133], v[172:175], v[30:33]
	v_mfma_f32_16x16x32_bf16 v[26:29], v[142:145], v[172:175], v[26:29]
	v_mfma_f32_16x16x32_bf16 v[14:17], v[130:133], v[180:183], v[14:17]
	v_mfma_f32_16x16x32_bf16 v[10:13], v[142:145], v[180:183], v[10:13]
	s_nop 0
	s_barrier
	s_add_u32 s16, s16, 0x40080
	s_addc_u32 s17, s17, 0
	s_add_i32 s18, s18, s29
	v_lshl_add_u64 v[126:127], s[16:17], 0, v[0:1]
	s_mov_b32 m0, s18
	s_nop 0
	global_load_lds_dwordx4 v[126:127], off
	v_lshl_add_u64 v[126:127], s[16:17], 0, v[162:163]
	s_add_i32 m0, s18, 0x2000
	s_nop 0
	global_load_lds_dwordx4 v[126:127], off
	s_waitcnt vmcnt(6)
	s_barrier
	s_nop 0
	v_mfma_f32_16x16x32_bf16 v[54:57], v[184:187], v[146:149], v[54:57]
	v_mfma_f32_16x16x32_bf16 v[50:53], v[220:223], v[146:149], v[50:53]
	v_mfma_f32_16x16x32_bf16 v[38:41], v[184:187], v[154:157], v[38:41]
	v_mfma_f32_16x16x32_bf16 v[34:37], v[220:223], v[154:157], v[34:37]
	v_mfma_f32_16x16x32_bf16 v[22:25], v[184:187], v[168:171], v[22:25]
	v_mfma_f32_16x16x32_bf16 v[18:21], v[220:223], v[168:171], v[18:21]
	v_mfma_f32_16x16x32_bf16 v[6:9], v[184:187], v[176:179], v[6:9]
	v_mfma_f32_16x16x32_bf16 v[2:5], v[220:223], v[176:179], v[2:5]
	v_mfma_f32_16x16x32_bf16 v[54:57], v[216:219], v[150:153], v[54:57]
	v_mfma_f32_16x16x32_bf16 v[50:53], v[224:227], v[150:153], v[50:53]
	v_mfma_f32_16x16x32_bf16 v[38:41], v[216:219], v[158:161], v[38:41]
	v_mfma_f32_16x16x32_bf16 v[34:37], v[224:227], v[158:161], v[34:37]
	v_mfma_f32_16x16x32_bf16 v[22:25], v[216:219], v[172:175], v[22:25]
	v_mfma_f32_16x16x32_bf16 v[18:21], v[224:227], v[172:175], v[18:21]
	v_mfma_f32_16x16x32_bf16 v[6:9], v[216:219], v[180:183], v[6:9]
	v_mfma_f32_16x16x32_bf16 v[2:5], v[224:227], v[180:183], v[2:5]
	s_nop 0
	s_add_i32 s46, s46, 2
	s_add_u32 s43, s43, 0x100
	s_addc_u32 s44, s44, 0
	s_add_u32 s14, s14, 0x100
	s_addc_u32 s15, s15, 0
	s_cmp_gt_u32 s46, 13
	s_barrier
	s_cbranch_scc0 .LBB0_574
	v_mov_b32_e32 v126, v238
	s_lshl_b32 s1, s38, 8
	v_ashrrev_i32_e32 v127, 2, v126
	v_and_b32_e32 v127, 0xffffffc0, v127
	v_lshl_add_u32 v127, s12, 8, v127
	v_and_or_b32 v168, v126, 15, v127
	v_lshrrev_b32_e32 v127, 1, v126
	v_lshrrev_b32_e32 v126, 2, v126
	v_and_b32_e32 v127, 0x60, v127
	v_and_b32_e32 v126, 12, v126
	v_or3_b32 v170, v127, s1, v126
	v_ashrrev_i32_e32 v169, 31, v168
	v_ashrrev_i32_e32 v171, 31, v170
	v_lshlrev_b64 v[126:127], 10, v[168:169]
	v_lshl_add_u64 v[126:127], v[126:127], 0, v[170:171]
	v_lshl_add_u64 v[128:129], v[126:127], 2, s[68:69]
	v_lshlrev_b64 v[126:127], 1, v[126:127]
	v_lshl_add_u64 v[130:131], s[6:7], 0, v[126:127]
	global_load_dwordx4 v[158:161], v[128:129], off
	global_load_dwordx2 v[188:189], v[130:131], off
	global_load_dwordx4 v[154:157], v[128:129], off offset:64
	v_or_b32_e32 v130, 32, v126
	v_mov_b32_e32 v131, v127
	v_lshl_add_u64 v[130:131], s[6:7], 0, v[130:131]
	global_load_dwordx2 v[186:187], v[130:131], off
	global_load_dwordx4 v[150:153], v[128:129], off offset:512
	v_or_b32_e32 v130, 0x100, v126
	v_mov_b32_e32 v131, v127
	v_lshl_add_u64 v[130:131], s[6:7], 0, v[130:131]
	global_load_dwordx2 v[184:185], v[130:131], off
	global_load_dwordx4 v[146:149], v[128:129], off offset:576
	v_or_b32_e32 v126, 0x120, v126
	v_or_b32_e32 v180, 16, v168
	v_lshl_add_u64 v[126:127], s[6:7], 0, v[126:127]
	v_ashrrev_i32_e32 v181, 31, v180
	global_load_dwordx2 v[182:183], v[126:127], off
	v_lshlrev_b64 v[126:127], 10, v[180:181]
	v_lshl_add_u64 v[126:127], v[126:127], 0, v[170:171]
	v_lshlrev_b64 v[172:173], 1, v[126:127]
	v_lshl_add_u64 v[128:129], v[126:127], 2, s[68:69]
	v_lshl_add_u64 v[126:127], s[6:7], 0, v[172:173]
	global_load_dwordx4 v[142:145], v[128:129], off
	global_load_dwordx2 v[178:179], v[126:127], off
	global_load_dwordx4 v[138:141], v[128:129], off offset:64
	v_or_b32_e32 v126, 32, v172
	v_mov_b32_e32 v127, v173
	v_lshl_add_u64 v[126:127], s[6:7], 0, v[126:127]
	global_load_dwordx2 v[176:177], v[126:127], off
	global_load_dwordx4 v[130:133], v[128:129], off offset:512
	v_or_b32_e32 v126, 0x100, v172
	v_mov_b32_e32 v127, v173
	v_lshl_add_u64 v[126:127], s[6:7], 0, v[126:127]
	global_load_dwordx2 v[174:175], v[126:127], off
	s_nop 0
	global_load_dwordx4 v[126:129], v[128:129], off offset:576
	v_or_b32_e32 v172, 0x120, v172
	v_lshl_add_u64 v[172:173], s[6:7], 0, v[172:173]
	global_load_dwordx2 v[172:173], v[172:173], off
	v_mul_f32_e32 v134, 0xbfb8aa3b, v134
	v_mul_f32_e32 v135, 0xbfb8aa3b, v135
	v_exp_f32_e32 v134, v134
	v_exp_f32_e32 v135, v135
	v_mul_f32_e32 v122, 0xbfb8aa3b, v122
	v_mul_f32_e32 v123, 0xbfb8aa3b, v123
	v_add_f32_e32 v134, 1.0, v134
	v_add_f32_e32 v135, 1.0, v135
	v_rcp_f32_e32 v134, v134
	v_rcp_f32_e32 v135, v135
	v_exp_f32_e32 v122, v122
	v_exp_f32_e32 v123, v123
	v_mul_f32_e32 v124, 0xbfb8aa3b, v124
	v_mul_f32_e32 v125, 0xbfb8aa3b, v125
	v_exp_f32_e32 v124, v124
	v_exp_f32_e32 v125, v125
	v_mul_f32_e32 v118, 0xbfb8aa3b, v118
	v_mul_f32_e32 v119, 0xbfb8aa3b, v119
	v_exp_f32_e32 v118, v118
	v_exp_f32_e32 v119, v119
	v_mul_f32_e32 v120, 0xbfb8aa3b, v120
	v_mul_f32_e32 v121, 0xbfb8aa3b, v121
	v_add_f32_e32 v122, 1.0, v122
	v_add_f32_e32 v123, 1.0, v123
	v_exp_f32_e32 v120, v120
	v_exp_f32_e32 v121, v121
	v_lshlrev_b64 v[192:193], 12, v[168:169]
	v_rcp_f32_e32 v122, v122
	v_rcp_f32_e32 v123, v123
	v_add_f32_e32 v124, 1.0, v124
	v_add_f32_e32 v125, 1.0, v125
	v_mul_f32_e32 v114, 0xbfb8aa3b, v114
	v_mul_f32_e32 v115, 0xbfb8aa3b, v115
	v_rcp_f32_e32 v124, v124
	v_rcp_f32_e32 v125, v125
	v_exp_f32_e32 v114, v114
	v_exp_f32_e32 v115, v115
	v_mul_f32_e32 v116, 0xbfb8aa3b, v116
	v_mul_f32_e32 v117, 0xbfb8aa3b, v117
	v_add_f32_e32 v118, 1.0, v118
	v_add_f32_e32 v119, 1.0, v119
	v_exp_f32_e32 v116, v116
	v_exp_f32_e32 v117, v117
	v_rcp_f32_e32 v118, v118
	v_rcp_f32_e32 v119, v119
	v_add_f32_e32 v120, 1.0, v120
	s_waitcnt vmcnt(0)
	v_lshlrev_b32_e32 v200, 16, v188
	v_and_b32_e32 v201, 0xffff0000, v188
	v_pk_fma_f32 v[158:159], v[134:135], v[200:201], v[158:159]
	v_mul_f32_e32 v134, 0xbfb8aa3b, v136
	v_mul_f32_e32 v135, 0xbfb8aa3b, v137
	v_exp_f32_e32 v134, v134
	v_exp_f32_e32 v135, v135
	v_lshlrev_b32_e32 v136, 16, v189
	v_and_b32_e32 v137, 0xffff0000, v189
	v_add_f32_e32 v134, 1.0, v134
	v_add_f32_e32 v135, 1.0, v135
	v_rcp_f32_e32 v134, v134
	v_rcp_f32_e32 v135, v135
	v_add_f32_e32 v121, 1.0, v121
	v_mul_f32_e32 v110, 0xbfb8aa3b, v110
	v_mul_f32_e32 v111, 0xbfb8aa3b, v111
	v_pk_fma_f32 v[160:161], v[134:135], v[136:137], v[160:161]
	v_lshl_add_u64 v[136:137], s[68:69], 0, v[192:193]
	v_lshlrev_b64 v[134:135], 2, v[170:171]
	v_lshl_add_u64 v[136:137], v[136:137], 0, v[134:135]
	global_store_dwordx4 v[136:137], v[158:161], off
	v_rcp_f32_e32 v120, v120
	v_rcp_f32_e32 v121, v121
	v_lshlrev_b32_e32 v158, 16, v186
	v_and_b32_e32 v159, 0xffff0000, v186
	v_pk_fma_f32 v[122:123], v[122:123], v[158:159], v[154:155]
	v_lshlrev_b32_e32 v154, 16, v187
	v_and_b32_e32 v155, 0xffff0000, v187
	v_exp_f32_e32 v110, v110
	v_exp_f32_e32 v111, v111
	v_pk_fma_f32 v[124:125], v[124:125], v[154:155], v[156:157]
	v_add_f32_e32 v114, 1.0, v114
	v_add_f32_e32 v115, 1.0, v115
	global_store_dwordx4 v[136:137], v[122:125], off offset:64
	v_rcp_f32_e32 v114, v114
	v_rcp_f32_e32 v115, v115
	v_lshlrev_b32_e32 v122, 16, v184
	v_and_b32_e32 v123, 0xffff0000, v184
	v_add_f32_e32 v116, 1.0, v116
	v_add_f32_e32 v117, 1.0, v117
	v_pk_fma_f32 v[118:119], v[118:119], v[122:123], v[150:151]
	v_lshlrev_b32_e32 v122, 16, v185
	v_and_b32_e32 v123, 0xffff0000, v185
	v_rcp_f32_e32 v116, v116
	v_rcp_f32_e32 v117, v117
	v_pk_fma_f32 v[120:121], v[120:121], v[122:123], v[152:153]
	v_add_f32_e32 v110, 1.0, v110
	v_add_f32_e32 v111, 1.0, v111
	global_store_dwordx4 v[136:137], v[118:121], off offset:512
	v_rcp_f32_e32 v110, v110
	v_rcp_f32_e32 v111, v111
	v_lshlrev_b32_e32 v118, 16, v182
	v_and_b32_e32 v119, 0xffff0000, v182
	v_pk_fma_f32 v[114:115], v[114:115], v[118:119], v[146:147]
	v_lshlrev_b32_e32 v118, 16, v183
	v_and_b32_e32 v119, 0xffff0000, v183
	v_pk_fma_f32 v[116:117], v[116:117], v[118:119], v[148:149]
	global_store_dwordx4 v[136:137], v[114:117], off offset:576
	v_mul_f32_e32 v106, 0xbfb8aa3b, v106
	v_mul_f32_e32 v107, 0xbfb8aa3b, v107
	v_lshlrev_b32_e32 v114, 16, v178
	v_and_b32_e32 v115, 0xffff0000, v178
	v_pk_fma_f32 v[114:115], v[110:111], v[114:115], v[142:143]
	v_mul_f32_e32 v110, 0xbfb8aa3b, v112
	v_mul_f32_e32 v111, 0xbfb8aa3b, v113
	v_exp_f32_e32 v110, v110
	v_exp_f32_e32 v111, v111
	v_exp_f32_e32 v106, v106
	v_exp_f32_e32 v107, v107
	v_mul_f32_e32 v108, 0xbfb8aa3b, v108
	v_mul_f32_e32 v109, 0xbfb8aa3b, v109
	v_exp_f32_e32 v108, v108
	v_exp_f32_e32 v109, v109
	v_mul_f32_e32 v102, 0xbfb8aa3b, v102
	v_mul_f32_e32 v103, 0xbfb8aa3b, v103
	v_add_f32_e32 v110, 1.0, v110
	v_add_f32_e32 v111, 1.0, v111
	v_exp_f32_e32 v102, v102
	v_exp_f32_e32 v103, v103
	v_mul_f32_e32 v104, 0xbfb8aa3b, v104
	v_mul_f32_e32 v105, 0xbfb8aa3b, v105
	v_rcp_f32_e32 v110, v110
	v_rcp_f32_e32 v111, v111
	v_add_f32_e32 v106, 1.0, v106
	v_add_f32_e32 v107, 1.0, v107
	v_exp_f32_e32 v104, v104
	v_exp_f32_e32 v105, v105
	v_rcp_f32_e32 v106, v106
	v_rcp_f32_e32 v107, v107
	v_add_f32_e32 v108, 1.0, v108
	v_add_f32_e32 v109, 1.0, v109
	v_mul_f32_e32 v98, 0xbfb8aa3b, v98
	v_mul_f32_e32 v99, 0xbfb8aa3b, v99
	v_rcp_f32_e32 v108, v108
	v_rcp_f32_e32 v109, v109
	v_exp_f32_e32 v98, v98
	v_exp_f32_e32 v99, v99
	v_mul_f32_e32 v100, 0xbfb8aa3b, v100
	v_mul_f32_e32 v101, 0xbfb8aa3b, v101
	v_lshlrev_b32_e32 v112, 16, v179
	v_and_b32_e32 v113, 0xffff0000, v179
	v_add_f32_e32 v102, 1.0, v102
	v_add_f32_e32 v103, 1.0, v103
	v_exp_f32_e32 v100, v100
	v_exp_f32_e32 v101, v101
	v_lshlrev_b64 v[118:119], 12, v[180:181]
	v_pk_fma_f32 v[116:117], v[110:111], v[112:113], v[144:145]
	v_lshlrev_b32_e32 v112, 16, v176
	v_and_b32_e32 v113, 0xffff0000, v176
	v_rcp_f32_e32 v102, v102
	v_rcp_f32_e32 v103, v103
	v_add_f32_e32 v104, 1.0, v104
	v_add_f32_e32 v105, 1.0, v105
	v_lshl_add_u64 v[110:111], s[68:69], 0, v[118:119]
	v_pk_fma_f32 v[106:107], v[106:107], v[112:113], v[138:139]
	v_lshlrev_b32_e32 v112, 16, v177
	v_and_b32_e32 v113, 0xffff0000, v177
	v_rcp_f32_e32 v104, v104
	v_rcp_f32_e32 v105, v105
	v_lshl_add_u64 v[110:111], v[110:111], 0, v[134:135]
	v_pk_fma_f32 v[108:109], v[108:109], v[112:113], v[140:141]
	v_add_f32_e32 v98, 1.0, v98
	v_add_f32_e32 v99, 1.0, v99
	global_store_dwordx4 v[110:111], v[106:109], off offset:64
	v_rcp_f32_e32 v98, v98
	v_rcp_f32_e32 v99, v99
	v_lshlrev_b32_e32 v106, 16, v174
	v_and_b32_e32 v107, 0xffff0000, v174
	v_add_f32_e32 v100, 1.0, v100
	v_add_f32_e32 v101, 1.0, v101
	v_pk_fma_f32 v[102:103], v[102:103], v[106:107], v[130:131]
	v_lshlrev_b32_e32 v106, 16, v175
	v_and_b32_e32 v107, 0xffff0000, v175
	v_rcp_f32_e32 v100, v100
	v_rcp_f32_e32 v101, v101
	v_pk_fma_f32 v[104:105], v[104:105], v[106:107], v[132:133]
	global_store_dwordx4 v[110:111], v[102:105], off offset:512
	v_or_b32_e32 v148, 32, v168
	v_ashrrev_i32_e32 v149, 31, v148
	v_lshlrev_b32_e32 v102, 16, v172
	v_and_b32_e32 v103, 0xffff0000, v172
	v_pk_fma_f32 v[98:99], v[98:99], v[102:103], v[126:127]
	v_lshlrev_b32_e32 v102, 16, v173
	v_and_b32_e32 v103, 0xffff0000, v173
	v_pk_fma_f32 v[100:101], v[100:101], v[102:103], v[128:129]
	global_store_dwordx4 v[110:111], v[98:101], off offset:576
	global_store_dwordx4 v[110:111], v[114:117], off
	v_or_b32_e32 v136, 48, v168
	v_lshlrev_b64 v[98:99], 10, v[148:149]
	v_lshl_add_u64 v[98:99], v[98:99], 0, v[170:171]
	v_lshl_add_u64 v[100:101], v[98:99], 2, s[68:69]
	v_lshlrev_b64 v[98:99], 1, v[98:99]
	v_lshl_add_u64 v[102:103], s[6:7], 0, v[98:99]
	global_load_dwordx4 v[144:147], v[100:101], off
	global_load_dwordx2 v[150:151], v[102:103], off
	global_load_dwordx4 v[122:125], v[100:101], off offset:64
	v_or_b32_e32 v102, 32, v98
	v_mov_b32_e32 v103, v99
	v_lshl_add_u64 v[102:103], s[6:7], 0, v[102:103]
	global_load_dwordx2 v[142:143], v[102:103], off
	global_load_dwordx4 v[118:121], v[100:101], off offset:512
	v_or_b32_e32 v102, 0x100, v98
	v_mov_b32_e32 v103, v99
	v_lshl_add_u64 v[102:103], s[6:7], 0, v[102:103]
	global_load_dwordx2 v[140:141], v[102:103], off
	global_load_dwordx4 v[114:117], v[100:101], off offset:576
	v_or_b32_e32 v98, 0x120, v98
	v_lshl_add_u64 v[98:99], s[6:7], 0, v[98:99]
	v_ashrrev_i32_e32 v137, 31, v136
	global_load_dwordx2 v[138:139], v[98:99], off
	v_lshlrev_b64 v[98:99], 10, v[136:137]
	v_lshl_add_u64 v[98:99], v[98:99], 0, v[170:171]
	v_lshlrev_b64 v[126:127], 1, v[98:99]
	v_lshl_add_u64 v[100:101], v[98:99], 2, s[68:69]
	v_lshl_add_u64 v[98:99], s[6:7], 0, v[126:127]
	global_load_dwordx4 v[110:113], v[100:101], off
	global_load_dwordx2 v[132:133], v[98:99], off
	global_load_dwordx4 v[106:109], v[100:101], off offset:64
	v_or_b32_e32 v98, 32, v126
	v_mov_b32_e32 v99, v127
	v_lshl_add_u64 v[98:99], s[6:7], 0, v[98:99]
	global_load_dwordx2 v[130:131], v[98:99], off
	global_load_dwordx4 v[102:105], v[100:101], off offset:512
	v_or_b32_e32 v98, 0x100, v126
	v_mov_b32_e32 v99, v127
	v_lshl_add_u64 v[98:99], s[6:7], 0, v[98:99]
	global_load_dwordx2 v[128:129], v[98:99], off
	s_nop 0
	global_load_dwordx4 v[98:101], v[100:101], off offset:576
	v_or_b32_e32 v126, 0x120, v126
	v_lshl_add_u64 v[126:127], s[6:7], 0, v[126:127]
	global_load_dwordx2 v[126:127], v[126:127], off
	v_mul_f32_e32 v94, 0xbfb8aa3b, v94
	v_mul_f32_e32 v95, 0xbfb8aa3b, v95
	v_exp_f32_e32 v94, v94
	v_exp_f32_e32 v95, v95
	v_mul_f32_e32 v90, 0xbfb8aa3b, v90
	v_mul_f32_e32 v91, 0xbfb8aa3b, v91
	v_add_f32_e32 v94, 1.0, v94
	v_add_f32_e32 v95, 1.0, v95
	v_rcp_f32_e32 v94, v94
	v_rcp_f32_e32 v95, v95
	v_exp_f32_e32 v90, v90
	v_exp_f32_e32 v91, v91
	v_mul_f32_e32 v92, 0xbfb8aa3b, v92
	v_mul_f32_e32 v93, 0xbfb8aa3b, v93
	v_exp_f32_e32 v92, v92
	v_exp_f32_e32 v93, v93
	v_mul_f32_e32 v86, 0xbfb8aa3b, v86
	v_mul_f32_e32 v87, 0xbfb8aa3b, v87
	v_exp_f32_e32 v86, v86
	v_exp_f32_e32 v87, v87
	v_mul_f32_e32 v88, 0xbfb8aa3b, v88
	v_mul_f32_e32 v89, 0xbfb8aa3b, v89
	v_add_f32_e32 v90, 1.0, v90
	v_add_f32_e32 v91, 1.0, v91
	v_exp_f32_e32 v88, v88
	v_exp_f32_e32 v89, v89
	v_rcp_f32_e32 v90, v90
	v_rcp_f32_e32 v91, v91
	v_add_f32_e32 v92, 1.0, v92
	v_add_f32_e32 v93, 1.0, v93
	v_mul_f32_e32 v82, 0xbfb8aa3b, v82
	v_mul_f32_e32 v83, 0xbfb8aa3b, v83
	v_rcp_f32_e32 v92, v92
	v_rcp_f32_e32 v93, v93
	v_exp_f32_e32 v82, v82
	v_exp_f32_e32 v83, v83
	v_mul_f32_e32 v84, 0xbfb8aa3b, v84
	v_mul_f32_e32 v85, 0xbfb8aa3b, v85
	v_add_f32_e32 v86, 1.0, v86
	v_add_f32_e32 v87, 1.0, v87
	v_exp_f32_e32 v84, v84
	v_exp_f32_e32 v85, v85
	v_lshlrev_b64 v[148:149], 12, v[148:149]
	v_rcp_f32_e32 v86, v86
	v_rcp_f32_e32 v87, v87
	v_add_f32_e32 v88, 1.0, v88
	v_add_f32_e32 v89, 1.0, v89
	v_mul_f32_e32 v78, 0xbfb8aa3b, v78
	s_waitcnt vmcnt(0)
	v_lshlrev_b32_e32 v152, 16, v150
	v_and_b32_e32 v153, 0xffff0000, v150
	v_pk_fma_f32 v[144:145], v[94:95], v[152:153], v[144:145]
	v_mul_f32_e32 v94, 0xbfb8aa3b, v96
	v_mul_f32_e32 v95, 0xbfb8aa3b, v97
	v_exp_f32_e32 v94, v94
	v_exp_f32_e32 v95, v95
	v_lshlrev_b32_e32 v96, 16, v151
	v_and_b32_e32 v97, 0xffff0000, v151
	v_add_f32_e32 v94, 1.0, v94
	v_add_f32_e32 v95, 1.0, v95
	v_rcp_f32_e32 v94, v94
	v_rcp_f32_e32 v95, v95
	v_mul_f32_e32 v79, 0xbfb8aa3b, v79
	v_rcp_f32_e32 v88, v88
	v_rcp_f32_e32 v89, v89
	v_pk_fma_f32 v[146:147], v[94:95], v[96:97], v[146:147]
	v_lshlrev_b32_e32 v96, 16, v142
	v_and_b32_e32 v97, 0xffff0000, v142
	v_lshl_add_u64 v[94:95], s[68:69], 0, v[148:149]
	v_pk_fma_f32 v[90:91], v[90:91], v[96:97], v[122:123]
	v_lshlrev_b32_e32 v96, 16, v143
	v_and_b32_e32 v97, 0xffff0000, v143
	v_exp_f32_e32 v78, v78
	v_exp_f32_e32 v79, v79
	v_lshl_add_u64 v[94:95], v[94:95], 0, v[134:135]
	v_pk_fma_f32 v[92:93], v[92:93], v[96:97], v[124:125]
	v_add_f32_e32 v82, 1.0, v82
	v_add_f32_e32 v83, 1.0, v83
	global_store_dwordx4 v[94:95], v[90:93], off offset:64
	v_rcp_f32_e32 v82, v82
	v_rcp_f32_e32 v83, v83
	v_lshlrev_b32_e32 v90, 16, v140
	v_and_b32_e32 v91, 0xffff0000, v140
	v_add_f32_e32 v84, 1.0, v84
	v_add_f32_e32 v85, 1.0, v85
	v_pk_fma_f32 v[86:87], v[86:87], v[90:91], v[118:119]
	v_lshlrev_b32_e32 v90, 16, v141
	v_and_b32_e32 v91, 0xffff0000, v141
	v_rcp_f32_e32 v84, v84
	v_rcp_f32_e32 v85, v85
	v_pk_fma_f32 v[88:89], v[88:89], v[90:91], v[120:121]
	v_add_f32_e32 v78, 1.0, v78
	v_add_f32_e32 v79, 1.0, v79
	global_store_dwordx4 v[94:95], v[86:89], off offset:512
	v_rcp_f32_e32 v78, v78
	v_rcp_f32_e32 v79, v79
	v_lshlrev_b32_e32 v86, 16, v138
	v_and_b32_e32 v87, 0xffff0000, v138
	v_pk_fma_f32 v[82:83], v[82:83], v[86:87], v[114:115]
	v_lshlrev_b32_e32 v86, 16, v139
	v_and_b32_e32 v87, 0xffff0000, v139
	v_pk_fma_f32 v[84:85], v[84:85], v[86:87], v[116:117]
	global_store_dwordx4 v[94:95], v[82:85], off offset:576
	v_mul_f32_e32 v74, 0xbfb8aa3b, v74
	v_mul_f32_e32 v75, 0xbfb8aa3b, v75
	v_lshlrev_b32_e32 v82, 16, v132
	v_and_b32_e32 v83, 0xffff0000, v132
	v_pk_fma_f32 v[82:83], v[78:79], v[82:83], v[110:111]
	v_mul_f32_e32 v78, 0xbfb8aa3b, v80
	v_mul_f32_e32 v79, 0xbfb8aa3b, v81
	v_exp_f32_e32 v78, v78
	v_exp_f32_e32 v79, v79
	v_exp_f32_e32 v74, v74
	v_exp_f32_e32 v75, v75
	v_mul_f32_e32 v76, 0xbfb8aa3b, v76
	v_mul_f32_e32 v77, 0xbfb8aa3b, v77
	v_exp_f32_e32 v76, v76
	v_exp_f32_e32 v77, v77
	v_mul_f32_e32 v70, 0xbfb8aa3b, v70
	v_mul_f32_e32 v71, 0xbfb8aa3b, v71
	v_add_f32_e32 v78, 1.0, v78
	v_add_f32_e32 v79, 1.0, v79
	v_exp_f32_e32 v70, v70
	v_exp_f32_e32 v71, v71
	v_mul_f32_e32 v72, 0xbfb8aa3b, v72
	v_mul_f32_e32 v73, 0xbfb8aa3b, v73
	v_rcp_f32_e32 v78, v78
	v_rcp_f32_e32 v79, v79
	v_add_f32_e32 v74, 1.0, v74
	v_add_f32_e32 v75, 1.0, v75
	v_exp_f32_e32 v72, v72
	v_exp_f32_e32 v73, v73
	v_rcp_f32_e32 v74, v74
	v_rcp_f32_e32 v75, v75
	v_add_f32_e32 v76, 1.0, v76
	v_add_f32_e32 v77, 1.0, v77
	v_mul_f32_e32 v66, 0xbfb8aa3b, v66
	v_mul_f32_e32 v67, 0xbfb8aa3b, v67
	v_rcp_f32_e32 v76, v76
	v_rcp_f32_e32 v77, v77
	v_exp_f32_e32 v66, v66
	v_exp_f32_e32 v67, v67
	v_mul_f32_e32 v68, 0xbfb8aa3b, v68
	v_mul_f32_e32 v69, 0xbfb8aa3b, v69
	v_lshlrev_b32_e32 v80, 16, v133
	v_and_b32_e32 v81, 0xffff0000, v133
	v_add_f32_e32 v70, 1.0, v70
	v_add_f32_e32 v71, 1.0, v71
	v_exp_f32_e32 v68, v68
	v_exp_f32_e32 v69, v69
	v_lshlrev_b64 v[86:87], 12, v[136:137]
	v_pk_fma_f32 v[84:85], v[78:79], v[80:81], v[112:113]
	v_lshlrev_b32_e32 v80, 16, v130
	v_and_b32_e32 v81, 0xffff0000, v130
	v_rcp_f32_e32 v70, v70
	v_rcp_f32_e32 v71, v71
	v_add_f32_e32 v72, 1.0, v72
	v_add_f32_e32 v73, 1.0, v73
	v_lshl_add_u64 v[78:79], s[68:69], 0, v[86:87]
	v_pk_fma_f32 v[74:75], v[74:75], v[80:81], v[106:107]
	v_lshlrev_b32_e32 v80, 16, v131
	v_and_b32_e32 v81, 0xffff0000, v131
	v_rcp_f32_e32 v72, v72
	v_rcp_f32_e32 v73, v73
	v_lshl_add_u64 v[78:79], v[78:79], 0, v[134:135]
	v_pk_fma_f32 v[76:77], v[76:77], v[80:81], v[108:109]
	v_add_f32_e32 v66, 1.0, v66
	v_add_f32_e32 v67, 1.0, v67
	global_store_dwordx4 v[78:79], v[74:77], off offset:64
	v_rcp_f32_e32 v66, v66
	v_rcp_f32_e32 v67, v67
	v_lshlrev_b32_e32 v74, 16, v128
	v_and_b32_e32 v75, 0xffff0000, v128
	v_add_f32_e32 v68, 1.0, v68
	v_add_f32_e32 v69, 1.0, v69
	v_pk_fma_f32 v[70:71], v[70:71], v[74:75], v[102:103]
	v_lshlrev_b32_e32 v74, 16, v129
	v_and_b32_e32 v75, 0xffff0000, v129
	v_rcp_f32_e32 v68, v68
	v_rcp_f32_e32 v69, v69
	v_pk_fma_f32 v[72:73], v[72:73], v[74:75], v[104:105]
	global_store_dwordx4 v[78:79], v[70:73], off offset:512
	v_add_u32_e32 v114, 0x80, v168
	v_ashrrev_i32_e32 v115, 31, v114
	v_lshlrev_b32_e32 v70, 16, v126
	v_and_b32_e32 v71, 0xffff0000, v126
	v_pk_fma_f32 v[66:67], v[66:67], v[70:71], v[98:99]
	v_lshlrev_b32_e32 v70, 16, v127
	v_and_b32_e32 v71, 0xffff0000, v127
	v_pk_fma_f32 v[68:69], v[68:69], v[70:71], v[100:101]
	global_store_dwordx4 v[78:79], v[66:69], off offset:576
	global_store_dwordx4 v[94:95], v[144:147], off
	global_store_dwordx4 v[78:79], v[82:85], off
	v_lshlrev_b64 v[66:67], 10, v[114:115]
	v_lshl_add_u64 v[66:67], v[66:67], 0, v[170:171]
	v_lshl_add_u64 v[68:69], v[66:67], 2, s[68:69]
	v_lshlrev_b64 v[66:67], 1, v[66:67]
	v_lshl_add_u64 v[70:71], s[6:7], 0, v[66:67]
	global_load_dwordx4 v[110:113], v[68:69], off
	global_load_dwordx2 v[116:117], v[70:71], off
	global_load_dwordx4 v[90:93], v[68:69], off offset:64
	v_or_b32_e32 v70, 32, v66
	v_mov_b32_e32 v71, v67
	v_lshl_add_u64 v[70:71], s[6:7], 0, v[70:71]
	global_load_dwordx2 v[108:109], v[70:71], off
	global_load_dwordx4 v[86:89], v[68:69], off offset:512
	v_or_b32_e32 v70, 0x100, v66
	v_mov_b32_e32 v71, v67
	v_lshl_add_u64 v[70:71], s[6:7], 0, v[70:71]
	global_load_dwordx2 v[106:107], v[70:71], off
	global_load_dwordx4 v[82:85], v[68:69], off offset:576
	v_or_b32_e32 v66, 0x120, v66
	v_add_u32_e32 v102, 0x90, v168
	v_lshl_add_u64 v[66:67], s[6:7], 0, v[66:67]
	v_ashrrev_i32_e32 v103, 31, v102
	global_load_dwordx2 v[104:105], v[66:67], off
	v_lshlrev_b64 v[66:67], 10, v[102:103]
	v_lshl_add_u64 v[66:67], v[66:67], 0, v[170:171]
	v_lshlrev_b64 v[94:95], 1, v[66:67]
	v_lshl_add_u64 v[68:69], v[66:67], 2, s[68:69]
	v_lshl_add_u64 v[66:67], s[6:7], 0, v[94:95]
	global_load_dwordx4 v[78:81], v[68:69], off
	global_load_dwordx2 v[100:101], v[66:67], off
	global_load_dwordx4 v[74:77], v[68:69], off offset:64
	v_or_b32_e32 v66, 32, v94
	v_mov_b32_e32 v67, v95
	v_lshl_add_u64 v[66:67], s[6:7], 0, v[66:67]
	global_load_dwordx2 v[98:99], v[66:67], off
	global_load_dwordx4 v[70:73], v[68:69], off offset:512
	v_or_b32_e32 v66, 0x100, v94
	v_mov_b32_e32 v67, v95
	v_lshl_add_u64 v[66:67], s[6:7], 0, v[66:67]
	global_load_dwordx2 v[96:97], v[66:67], off
	s_nop 0
	global_load_dwordx4 v[66:69], v[68:69], off offset:576
	v_or_b32_e32 v94, 0x120, v94
	v_lshl_add_u64 v[94:95], s[6:7], 0, v[94:95]
	global_load_dwordx2 v[94:95], v[94:95], off
	v_mul_f32_e32 v62, 0xbfb8aa3b, v62
	v_mul_f32_e32 v63, 0xbfb8aa3b, v63
	v_exp_f32_e32 v62, v62
	v_exp_f32_e32 v63, v63
	v_mul_f32_e32 v58, 0xbfb8aa3b, v58
	v_mul_f32_e32 v59, 0xbfb8aa3b, v59
	v_add_f32_e32 v62, 1.0, v62
	v_add_f32_e32 v63, 1.0, v63
	v_rcp_f32_e32 v62, v62
	v_rcp_f32_e32 v63, v63
	v_exp_f32_e32 v58, v58
	v_exp_f32_e32 v59, v59
	v_mul_f32_e32 v60, 0xbfb8aa3b, v60
	v_mul_f32_e32 v61, 0xbfb8aa3b, v61
	v_exp_f32_e32 v60, v60
	v_exp_f32_e32 v61, v61
	v_mul_f32_e32 v54, 0xbfb8aa3b, v54
	v_mul_f32_e32 v55, 0xbfb8aa3b, v55
	v_exp_f32_e32 v54, v54
	v_exp_f32_e32 v55, v55
	v_mul_f32_e32 v56, 0xbfb8aa3b, v56
	v_mul_f32_e32 v57, 0xbfb8aa3b, v57
	v_add_f32_e32 v58, 1.0, v58
	v_add_f32_e32 v59, 1.0, v59
	v_exp_f32_e32 v56, v56
	v_exp_f32_e32 v57, v57
	v_rcp_f32_e32 v58, v58
	v_rcp_f32_e32 v59, v59
	v_add_f32_e32 v60, 1.0, v60
	v_add_f32_e32 v61, 1.0, v61
	v_mul_f32_e32 v50, 0xbfb8aa3b, v50
	v_mul_f32_e32 v51, 0xbfb8aa3b, v51
	v_rcp_f32_e32 v60, v60
	v_rcp_f32_e32 v61, v61
	v_exp_f32_e32 v50, v50
	v_exp_f32_e32 v51, v51
	v_mul_f32_e32 v52, 0xbfb8aa3b, v52
	v_mul_f32_e32 v53, 0xbfb8aa3b, v53
	v_add_f32_e32 v54, 1.0, v54
	v_add_f32_e32 v55, 1.0, v55
	v_exp_f32_e32 v52, v52
	v_exp_f32_e32 v53, v53
	v_lshlrev_b64 v[114:115], 12, v[114:115]
	v_rcp_f32_e32 v54, v54
	v_rcp_f32_e32 v55, v55
	v_add_f32_e32 v56, 1.0, v56
	v_add_f32_e32 v57, 1.0, v57
	s_waitcnt vmcnt(0)
	v_lshlrev_b32_e32 v118, 16, v116
	v_and_b32_e32 v119, 0xffff0000, v116
	v_pk_fma_f32 v[110:111], v[62:63], v[118:119], v[110:111]
	v_mul_f32_e32 v62, 0xbfb8aa3b, v64
	v_mul_f32_e32 v63, 0xbfb8aa3b, v65
	v_exp_f32_e32 v62, v62
	v_exp_f32_e32 v63, v63
	v_lshlrev_b32_e32 v64, 16, v117
	v_and_b32_e32 v65, 0xffff0000, v117
	v_add_f32_e32 v62, 1.0, v62
	v_add_f32_e32 v63, 1.0, v63
	v_rcp_f32_e32 v62, v62
	v_rcp_f32_e32 v63, v63
	v_mul_f32_e32 v46, 0xbfb8aa3b, v46
	v_mul_f32_e32 v47, 0xbfb8aa3b, v47
	v_rcp_f32_e32 v56, v56
	v_pk_fma_f32 v[112:113], v[62:63], v[64:65], v[112:113]
	v_lshlrev_b32_e32 v64, 16, v108
	v_and_b32_e32 v65, 0xffff0000, v108
	v_lshl_add_u64 v[62:63], s[68:69], 0, v[114:115]
	v_pk_fma_f32 v[58:59], v[58:59], v[64:65], v[90:91]
	v_lshlrev_b32_e32 v64, 16, v109
	v_and_b32_e32 v65, 0xffff0000, v109
	v_rcp_f32_e32 v57, v57
	v_exp_f32_e32 v46, v46
	v_exp_f32_e32 v47, v47
	v_lshl_add_u64 v[62:63], v[62:63], 0, v[134:135]
	v_pk_fma_f32 v[60:61], v[60:61], v[64:65], v[92:93]
	v_add_f32_e32 v50, 1.0, v50
	v_add_f32_e32 v51, 1.0, v51
	global_store_dwordx4 v[62:63], v[58:61], off offset:64
	v_rcp_f32_e32 v50, v50
	v_rcp_f32_e32 v51, v51
	v_lshlrev_b32_e32 v58, 16, v106
	v_and_b32_e32 v59, 0xffff0000, v106
	v_add_f32_e32 v52, 1.0, v52
	v_add_f32_e32 v53, 1.0, v53
	v_pk_fma_f32 v[54:55], v[54:55], v[58:59], v[86:87]
	v_lshlrev_b32_e32 v58, 16, v107
	v_and_b32_e32 v59, 0xffff0000, v107
	v_rcp_f32_e32 v52, v52
	v_rcp_f32_e32 v53, v53
	v_pk_fma_f32 v[56:57], v[56:57], v[58:59], v[88:89]
	v_add_f32_e32 v46, 1.0, v46
	v_add_f32_e32 v47, 1.0, v47
	global_store_dwordx4 v[62:63], v[54:57], off offset:512
	v_rcp_f32_e32 v46, v46
	v_rcp_f32_e32 v47, v47
	v_lshlrev_b32_e32 v54, 16, v104
	v_and_b32_e32 v55, 0xffff0000, v104
	v_pk_fma_f32 v[50:51], v[50:51], v[54:55], v[82:83]
	v_lshlrev_b32_e32 v54, 16, v105
	v_and_b32_e32 v55, 0xffff0000, v105
	v_pk_fma_f32 v[52:53], v[52:53], v[54:55], v[84:85]
	global_store_dwordx4 v[62:63], v[50:53], off offset:576
	v_mul_f32_e32 v42, 0xbfb8aa3b, v42
	v_mul_f32_e32 v43, 0xbfb8aa3b, v43
	v_lshlrev_b32_e32 v50, 16, v100
	v_and_b32_e32 v51, 0xffff0000, v100
	v_pk_fma_f32 v[50:51], v[46:47], v[50:51], v[78:79]
	v_mul_f32_e32 v46, 0xbfb8aa3b, v48
	v_mul_f32_e32 v47, 0xbfb8aa3b, v49
	v_exp_f32_e32 v46, v46
	v_exp_f32_e32 v47, v47
	v_exp_f32_e32 v42, v42
	v_exp_f32_e32 v43, v43
	v_mul_f32_e32 v44, 0xbfb8aa3b, v44
	v_mul_f32_e32 v45, 0xbfb8aa3b, v45
	v_exp_f32_e32 v44, v44
	v_exp_f32_e32 v45, v45
	v_mul_f32_e32 v38, 0xbfb8aa3b, v38
	v_mul_f32_e32 v39, 0xbfb8aa3b, v39
	v_add_f32_e32 v46, 1.0, v46
	v_add_f32_e32 v47, 1.0, v47
	v_exp_f32_e32 v38, v38
	v_exp_f32_e32 v39, v39
	v_mul_f32_e32 v40, 0xbfb8aa3b, v40
	v_mul_f32_e32 v41, 0xbfb8aa3b, v41
	v_rcp_f32_e32 v46, v46
	v_rcp_f32_e32 v47, v47
	v_add_f32_e32 v42, 1.0, v42
	v_add_f32_e32 v43, 1.0, v43
	v_exp_f32_e32 v40, v40
	v_exp_f32_e32 v41, v41
	v_rcp_f32_e32 v42, v42
	v_rcp_f32_e32 v43, v43
	v_add_f32_e32 v44, 1.0, v44
	v_add_f32_e32 v45, 1.0, v45
	v_mul_f32_e32 v34, 0xbfb8aa3b, v34
	v_mul_f32_e32 v35, 0xbfb8aa3b, v35
	v_rcp_f32_e32 v44, v44
	v_rcp_f32_e32 v45, v45
	v_exp_f32_e32 v34, v34
	v_exp_f32_e32 v35, v35
	v_mul_f32_e32 v36, 0xbfb8aa3b, v36
	v_mul_f32_e32 v37, 0xbfb8aa3b, v37
	v_lshlrev_b32_e32 v48, 16, v101
	v_and_b32_e32 v49, 0xffff0000, v101
	v_add_f32_e32 v38, 1.0, v38
	v_add_f32_e32 v39, 1.0, v39
	v_exp_f32_e32 v36, v36
	v_exp_f32_e32 v37, v37
	v_lshlrev_b64 v[54:55], 12, v[102:103]
	v_pk_fma_f32 v[52:53], v[46:47], v[48:49], v[80:81]
	v_lshlrev_b32_e32 v48, 16, v98
	v_and_b32_e32 v49, 0xffff0000, v98
	v_rcp_f32_e32 v38, v38
	v_rcp_f32_e32 v39, v39
	v_add_f32_e32 v40, 1.0, v40
	v_add_f32_e32 v41, 1.0, v41
	v_lshl_add_u64 v[46:47], s[68:69], 0, v[54:55]
	v_pk_fma_f32 v[42:43], v[42:43], v[48:49], v[74:75]
	v_lshlrev_b32_e32 v48, 16, v99
	v_and_b32_e32 v49, 0xffff0000, v99
	v_rcp_f32_e32 v40, v40
	v_rcp_f32_e32 v41, v41
	v_lshl_add_u64 v[46:47], v[46:47], 0, v[134:135]
	v_pk_fma_f32 v[44:45], v[44:45], v[48:49], v[76:77]
	v_add_f32_e32 v34, 1.0, v34
	v_add_f32_e32 v35, 1.0, v35
	global_store_dwordx4 v[46:47], v[42:45], off offset:64
	v_rcp_f32_e32 v34, v34
	v_rcp_f32_e32 v35, v35
	v_lshlrev_b32_e32 v42, 16, v96
	v_and_b32_e32 v43, 0xffff0000, v96
	v_add_f32_e32 v36, 1.0, v36
	v_add_f32_e32 v37, 1.0, v37
	v_pk_fma_f32 v[38:39], v[38:39], v[42:43], v[70:71]
	v_lshlrev_b32_e32 v42, 16, v97
	v_and_b32_e32 v43, 0xffff0000, v97
	v_rcp_f32_e32 v36, v36
	v_rcp_f32_e32 v37, v37
	v_pk_fma_f32 v[40:41], v[40:41], v[42:43], v[72:73]
	global_store_dwordx4 v[46:47], v[38:41], off offset:512
	v_add_u32_e32 v82, 0xa0, v168
	v_ashrrev_i32_e32 v83, 31, v82
	v_lshlrev_b32_e32 v38, 16, v94
	v_and_b32_e32 v39, 0xffff0000, v94
	v_pk_fma_f32 v[34:35], v[34:35], v[38:39], v[66:67]
	v_lshlrev_b32_e32 v38, 16, v95
	v_and_b32_e32 v39, 0xffff0000, v95
	v_pk_fma_f32 v[36:37], v[36:37], v[38:39], v[68:69]
	global_store_dwordx4 v[46:47], v[34:37], off offset:576
	global_store_dwordx4 v[62:63], v[110:113], off
	global_store_dwordx4 v[46:47], v[50:53], off
	v_lshlrev_b64 v[34:35], 10, v[82:83]
	v_lshl_add_u64 v[34:35], v[34:35], 0, v[170:171]
	v_lshl_add_u64 v[36:37], v[34:35], 2, s[68:69]
	v_lshlrev_b64 v[34:35], 1, v[34:35]
	v_lshl_add_u64 v[38:39], s[6:7], 0, v[34:35]
	global_load_dwordx4 v[78:81], v[36:37], off
	global_load_dwordx2 v[84:85], v[38:39], off
	global_load_dwordx4 v[58:61], v[36:37], off offset:64
	v_or_b32_e32 v38, 32, v34
	v_mov_b32_e32 v39, v35
	v_lshl_add_u64 v[38:39], s[6:7], 0, v[38:39]
	global_load_dwordx2 v[76:77], v[38:39], off
	global_load_dwordx4 v[54:57], v[36:37], off offset:512
	v_or_b32_e32 v38, 0x100, v34
	v_mov_b32_e32 v39, v35
	v_lshl_add_u64 v[38:39], s[6:7], 0, v[38:39]
	global_load_dwordx2 v[74:75], v[38:39], off
	global_load_dwordx4 v[50:53], v[36:37], off offset:576
	v_or_b32_e32 v34, 0x120, v34
	v_add_u32_e32 v70, 0xb0, v168
	v_lshl_add_u64 v[34:35], s[6:7], 0, v[34:35]
	v_ashrrev_i32_e32 v71, 31, v70
	global_load_dwordx2 v[72:73], v[34:35], off
	v_lshlrev_b64 v[34:35], 10, v[70:71]
	v_lshl_add_u64 v[34:35], v[34:35], 0, v[170:171]
	v_lshlrev_b64 v[62:63], 1, v[34:35]
	v_lshl_add_u64 v[36:37], v[34:35], 2, s[68:69]
	v_lshl_add_u64 v[34:35], s[6:7], 0, v[62:63]
	global_load_dwordx4 v[46:49], v[36:37], off
	global_load_dwordx2 v[68:69], v[34:35], off
	global_load_dwordx4 v[42:45], v[36:37], off offset:64
	v_or_b32_e32 v34, 32, v62
	v_mov_b32_e32 v35, v63
	v_lshl_add_u64 v[34:35], s[6:7], 0, v[34:35]
	global_load_dwordx2 v[66:67], v[34:35], off
	global_load_dwordx4 v[38:41], v[36:37], off offset:512
	v_or_b32_e32 v34, 0x100, v62
	v_mov_b32_e32 v35, v63
	v_lshl_add_u64 v[34:35], s[6:7], 0, v[34:35]
	global_load_dwordx2 v[64:65], v[34:35], off
	s_nop 0
	global_load_dwordx4 v[34:37], v[36:37], off offset:576
	v_or_b32_e32 v62, 0x120, v62
	v_lshl_add_u64 v[62:63], s[6:7], 0, v[62:63]
	global_load_dwordx2 v[62:63], v[62:63], off
	v_mul_f32_e32 v30, 0xbfb8aa3b, v30
	v_mul_f32_e32 v31, 0xbfb8aa3b, v31
	v_exp_f32_e32 v30, v30
	v_exp_f32_e32 v31, v31
	v_mul_f32_e32 v26, 0xbfb8aa3b, v26
	v_mul_f32_e32 v27, 0xbfb8aa3b, v27
	v_add_f32_e32 v30, 1.0, v30
	v_add_f32_e32 v31, 1.0, v31
	v_rcp_f32_e32 v30, v30
	v_rcp_f32_e32 v31, v31
	v_exp_f32_e32 v26, v26
	v_exp_f32_e32 v27, v27
	v_mul_f32_e32 v28, 0xbfb8aa3b, v28
	v_mul_f32_e32 v29, 0xbfb8aa3b, v29
	v_exp_f32_e32 v28, v28
	v_exp_f32_e32 v29, v29
	v_mul_f32_e32 v22, 0xbfb8aa3b, v22
	v_mul_f32_e32 v23, 0xbfb8aa3b, v23
	v_exp_f32_e32 v22, v22
	v_exp_f32_e32 v23, v23
	v_mul_f32_e32 v24, 0xbfb8aa3b, v24
	v_mul_f32_e32 v25, 0xbfb8aa3b, v25
	v_add_f32_e32 v26, 1.0, v26
	v_add_f32_e32 v27, 1.0, v27
	v_exp_f32_e32 v24, v24
	v_exp_f32_e32 v25, v25
	v_rcp_f32_e32 v26, v26
	v_rcp_f32_e32 v27, v27
	v_add_f32_e32 v28, 1.0, v28
	v_add_f32_e32 v29, 1.0, v29
	v_mul_f32_e32 v18, 0xbfb8aa3b, v18
	v_mul_f32_e32 v19, 0xbfb8aa3b, v19
	v_rcp_f32_e32 v28, v28
	v_rcp_f32_e32 v29, v29
	v_exp_f32_e32 v18, v18
	v_exp_f32_e32 v19, v19
	v_mul_f32_e32 v20, 0xbfb8aa3b, v20
	v_mul_f32_e32 v21, 0xbfb8aa3b, v21
	v_add_f32_e32 v22, 1.0, v22
	v_add_f32_e32 v23, 1.0, v23
	v_exp_f32_e32 v20, v20
	v_exp_f32_e32 v21, v21
	v_lshlrev_b64 v[82:83], 12, v[82:83]
	v_rcp_f32_e32 v22, v22
	v_rcp_f32_e32 v23, v23
	v_add_f32_e32 v24, 1.0, v24
	v_add_f32_e32 v25, 1.0, v25
	s_waitcnt vmcnt(0)
; #define PG8_WAIT_V(n) asm volatile("s_waitcnt vmcnt(" #n ")" ::: "memory")
; #define PG8_BAR __builtin_amdgcn_s_barrier()
; template <class Epi>
; DI void gemm_phase(LAS unsigned char* lds, const Gemm g, const StaticOrder& S, const Epi& E) {
;     ...
;         E(acc, cur, wr, wc, fr, fq);
;         if (!has_next) break;
; #pragma unroll
;         for (int a = 0; a < 2; ++a)
; #pragma unroll
;             for (int b = 0; b < 2; ++b)
; #pragma unroll
;                 for (int m = 0; m < 4; ++m)
; #pragma unroll
;                     for (int n = 0; n < 2; ++n) acc[a][b][m][n] = (f32x4){0.f, 0.f, 0.f, 0.f};
;         cur = nxt; cA = nA; cB = nB; ++ui;
;     }
;     PG8_WAIT_V(0);
;     if (wr == 0) PG8_BAR;
;     PG8_BAR;
	v_lshlrev_b32_e32 v86, 16, v84
	v_and_b32_e32 v87, 0xffff0000, v84
	v_pk_fma_f32 v[78:79], v[30:31], v[86:87], v[78:79]
	v_mul_f32_e32 v30, 0xbfb8aa3b, v32
	v_mul_f32_e32 v31, 0xbfb8aa3b, v33
	v_exp_f32_e32 v30, v30
	v_exp_f32_e32 v31, v31
	v_lshlrev_b32_e32 v32, 16, v85
	v_and_b32_e32 v33, 0xffff0000, v85
	v_add_f32_e32 v30, 1.0, v30
	v_add_f32_e32 v31, 1.0, v31
	v_rcp_f32_e32 v30, v30
	v_rcp_f32_e32 v31, v31
	v_mul_f32_e32 v14, 0xbfb8aa3b, v14
	v_mul_f32_e32 v15, 0xbfb8aa3b, v15
	v_rcp_f32_e32 v24, v24
	v_pk_fma_f32 v[80:81], v[30:31], v[32:33], v[80:81]
	v_lshlrev_b32_e32 v32, 16, v76
	v_and_b32_e32 v33, 0xffff0000, v76
	v_lshl_add_u64 v[30:31], s[68:69], 0, v[82:83]
	v_pk_fma_f32 v[26:27], v[26:27], v[32:33], v[58:59]
	v_lshlrev_b32_e32 v32, 16, v77
	v_and_b32_e32 v33, 0xffff0000, v77
	v_rcp_f32_e32 v25, v25
	v_exp_f32_e32 v14, v14
	v_exp_f32_e32 v15, v15
	v_lshl_add_u64 v[30:31], v[30:31], 0, v[134:135]
	v_pk_fma_f32 v[28:29], v[28:29], v[32:33], v[60:61]
	v_add_f32_e32 v18, 1.0, v18
	v_add_f32_e32 v19, 1.0, v19
	global_store_dwordx4 v[30:31], v[26:29], off offset:64
	v_rcp_f32_e32 v18, v18
	v_rcp_f32_e32 v19, v19
	v_lshlrev_b32_e32 v26, 16, v74
	v_and_b32_e32 v27, 0xffff0000, v74
	v_add_f32_e32 v20, 1.0, v20
	v_add_f32_e32 v21, 1.0, v21
	v_pk_fma_f32 v[22:23], v[22:23], v[26:27], v[54:55]
	v_lshlrev_b32_e32 v26, 16, v75
	v_and_b32_e32 v27, 0xffff0000, v75
	v_rcp_f32_e32 v20, v20
	v_rcp_f32_e32 v21, v21
	v_pk_fma_f32 v[24:25], v[24:25], v[26:27], v[56:57]
	v_add_f32_e32 v14, 1.0, v14
	v_add_f32_e32 v15, 1.0, v15
	global_store_dwordx4 v[30:31], v[22:25], off offset:512
	v_rcp_f32_e32 v14, v14
	v_rcp_f32_e32 v15, v15
	v_lshlrev_b32_e32 v22, 16, v72
	v_and_b32_e32 v23, 0xffff0000, v72
	v_pk_fma_f32 v[18:19], v[18:19], v[22:23], v[50:51]
	v_lshlrev_b32_e32 v22, 16, v73
	v_and_b32_e32 v23, 0xffff0000, v73
	v_pk_fma_f32 v[20:21], v[20:21], v[22:23], v[52:53]
	global_store_dwordx4 v[30:31], v[18:21], off offset:576
	v_mul_f32_e32 v10, 0xbfb8aa3b, v10
	v_mul_f32_e32 v11, 0xbfb8aa3b, v11
	v_lshlrev_b32_e32 v18, 16, v68
	v_and_b32_e32 v19, 0xffff0000, v68
	v_pk_fma_f32 v[18:19], v[14:15], v[18:19], v[46:47]
	v_mul_f32_e32 v14, 0xbfb8aa3b, v16
	v_mul_f32_e32 v15, 0xbfb8aa3b, v17
	v_exp_f32_e32 v14, v14
	v_exp_f32_e32 v15, v15
	v_exp_f32_e32 v10, v10
	v_exp_f32_e32 v11, v11
	v_mul_f32_e32 v12, 0xbfb8aa3b, v12
	v_mul_f32_e32 v13, 0xbfb8aa3b, v13
	v_exp_f32_e32 v12, v12
	v_exp_f32_e32 v13, v13
	v_mul_f32_e32 v6, 0xbfb8aa3b, v6
	v_mul_f32_e32 v7, 0xbfb8aa3b, v7
	v_add_f32_e32 v14, 1.0, v14
	v_add_f32_e32 v15, 1.0, v15
	v_exp_f32_e32 v6, v6
	v_exp_f32_e32 v7, v7
	v_mul_f32_e32 v8, 0xbfb8aa3b, v8
	v_mul_f32_e32 v9, 0xbfb8aa3b, v9
	v_rcp_f32_e32 v14, v14
	v_rcp_f32_e32 v15, v15
	v_add_f32_e32 v10, 1.0, v10
	v_add_f32_e32 v11, 1.0, v11
	v_exp_f32_e32 v8, v8
	v_exp_f32_e32 v9, v9
	v_rcp_f32_e32 v10, v10
	v_rcp_f32_e32 v11, v11
	v_add_f32_e32 v12, 1.0, v12
	v_add_f32_e32 v13, 1.0, v13
	v_mul_f32_e32 v2, 0xbfb8aa3b, v2
	v_mul_f32_e32 v3, 0xbfb8aa3b, v3
	v_rcp_f32_e32 v12, v12
	v_rcp_f32_e32 v13, v13
	v_exp_f32_e32 v2, v2
	v_exp_f32_e32 v3, v3
	v_mul_f32_e32 v4, 0xbfb8aa3b, v4
	v_mul_f32_e32 v5, 0xbfb8aa3b, v5
	v_lshlrev_b32_e32 v16, 16, v69
	v_and_b32_e32 v17, 0xffff0000, v69
	v_add_f32_e32 v6, 1.0, v6
	v_add_f32_e32 v7, 1.0, v7
	v_exp_f32_e32 v4, v4
	v_exp_f32_e32 v5, v5
	v_lshlrev_b64 v[22:23], 12, v[70:71]
	v_pk_fma_f32 v[20:21], v[14:15], v[16:17], v[48:49]
	v_lshlrev_b32_e32 v16, 16, v66
	v_and_b32_e32 v17, 0xffff0000, v66
	v_rcp_f32_e32 v6, v6
	v_rcp_f32_e32 v7, v7
	v_add_f32_e32 v8, 1.0, v8
	v_add_f32_e32 v9, 1.0, v9
	v_lshl_add_u64 v[14:15], s[68:69], 0, v[22:23]
	v_pk_fma_f32 v[10:11], v[10:11], v[16:17], v[42:43]
	v_lshlrev_b32_e32 v16, 16, v67
	v_and_b32_e32 v17, 0xffff0000, v67
	v_rcp_f32_e32 v8, v8
	v_rcp_f32_e32 v9, v9
	v_lshl_add_u64 v[14:15], v[14:15], 0, v[134:135]
	v_pk_fma_f32 v[12:13], v[12:13], v[16:17], v[44:45]
	v_add_f32_e32 v2, 1.0, v2
	v_add_f32_e32 v3, 1.0, v3
	global_store_dwordx4 v[14:15], v[10:13], off offset:64
	v_rcp_f32_e32 v2, v2
	v_rcp_f32_e32 v3, v3
	v_lshlrev_b32_e32 v10, 16, v64
	v_and_b32_e32 v11, 0xffff0000, v64
	v_add_f32_e32 v4, 1.0, v4
	v_add_f32_e32 v5, 1.0, v5
	v_pk_fma_f32 v[6:7], v[6:7], v[10:11], v[38:39]
	v_lshlrev_b32_e32 v10, 16, v65
	v_and_b32_e32 v11, 0xffff0000, v65
	v_rcp_f32_e32 v4, v4
	v_rcp_f32_e32 v5, v5
	v_pk_fma_f32 v[8:9], v[8:9], v[10:11], v[40:41]
	global_store_dwordx4 v[14:15], v[6:9], off offset:512
	s_and_b64 vcc, exec, s[40:41]
	s_mov_b32 s38, s0
	v_lshlrev_b32_e32 v6, 16, v62
	v_and_b32_e32 v7, 0xffff0000, v62
	v_pk_fma_f32 v[2:3], v[2:3], v[6:7], v[34:35]
	v_lshlrev_b32_e32 v6, 16, v63
	v_and_b32_e32 v7, 0xffff0000, v63
	v_pk_fma_f32 v[4:5], v[4:5], v[6:7], v[36:37]
	s_mov_b32 s12, s4
	s_mov_b64 s[14:15], s[10:11]
	s_mov_b64 s[16:17], s[8:9]
	global_store_dwordx4 v[30:31], v[78:81], off
	global_store_dwordx4 v[14:15], v[18:21], off
	global_store_dwordx4 v[14:15], v[2:5], off offset:576
	s_cbranch_vccz .LBB0_567
	s_waitcnt vmcnt(0)
	s_cmpk_gt_u32 s21, 0xff
	s_cbranch_scc1 .LBB0_578
	s_barrier

; #define PG8_STAGE(bufoff, gbase, voff) do { _Pragma("unroll") for (int _i = 0; _i < 2; ++_i) \
;         __builtin_amdgcn_global_load_lds((const unsigned*)((const char*)(gbase) + (voff)[_i]), (LAS unsigned*)(lds + (bufoff) + ldsw + _i * 8192), 16, 0, 0); } while (0)
; #define PG8_LDA(dst, b, h) do { _Pragma("unroll") for (int m = 0; m < 4; ++m) _Pragma("unroll") for (int k = 0; k < 2; ++k) dst[m][k] = *(const LAS bf16x8*)(lds + PG8_SA(b, h) + aoff + m * 2048 + k * 1024); } while (0)
; #define PG8_WAIT_V(n) asm volatile("s_waitcnt vmcnt(" #n ")" ::: "memory")
; #define PG8_WAIT_L(n) asm volatile("s_waitcnt lgkmcnt(" #n ")" ::: "memory")
; template <class Epi>
; DI void gemm_phase(LAS unsigned char* lds, const Gemm g, const StaticOrder& S, const Epi& E) {
;     ...
;         for (int t = 0; t < nt; t += 2) {
;             const bool last = (t == nt - 2);
;             const char* a1 = cA + (size_t)(t + 1) * kstep;
;             const char* a2 = last ? nA : cA + (size_t)(t + 2) * kstep; const char* b2 = last ? nB : cB + (size_t)(t + 2) * kstep;
;             const char* a3 = a2 + kstep; const char* b3 = b2 + kstep;
;             PG8_LDB(B0, 0, 0); PG8_SCHED; PG8_LDA(At, 0, 0); PG8_STAGE(PG8_SA(1, 1), a1 + hstepA, voffA);
;             PG8_WAIT_L(8); PG8_BAR; PG8_WAIT_L(0); PG8_MMA(0, 0, At, B0); PG8_BAR; PG8_SCHED;
;             PG8_LDB(B1, 0, 1); PG8_STAGE(PG8_SB(0, 0), b2, voffB);
;             PG8_BAR; PG8_WAIT_L(0); PG8_MMA(0, 1, At, B1); PG8_BAR;
;             PG8_LDA(At, 0, 1); PG8_STAGE(PG8_SA(0, 0), a2, voffA);
;             PG8_BAR; PG8_WAIT_L(0); PG8_MMA(1, 0, At, B0); PG8_BAR; PG8_SCHED;
;             PG8_STAGE(PG8_SB(0, 1), b2 + hstepB, voffB);
;             PG8_WAIT_V(6); PG8_BAR; PG8_MMA(1, 1, At, B1); PG8_BAR;
;             PG8_LDB(B0, 1, 0); PG8_SCHED; PG8_LDA(At, 1, 0); PG8_STAGE(PG8_SA(0, 1), a2 + hstepA, voffA);
;             PG8_WAIT_L(8); PG8_BAR; PG8_WAIT_L(0); PG8_MMA(0, 0, At, B0); PG8_BAR; PG8_SCHED;
;             PG8_LDB(B1, 1, 1); PG8_STAGE(PG8_SB(1, 0), b3, voffB);
;             PG8_BAR; PG8_WAIT_L(0); PG8_MMA(0, 1, At, B1); PG8_BAR;
;             PG8_LDA(At, 1, 1); PG8_STAGE(PG8_SA(1, 0), a3, voffA);
;             PG8_BAR; PG8_WAIT_L(0); PG8_MMA(1, 0, At, B0); PG8_BAR; PG8_SCHED;
;             PG8_STAGE(PG8_SB(1, 1), b3 + hstepB, voffB);
;             PG8_WAIT_V(6); PG8_BAR; PG8_MMA(1, 1, At, B1); PG8_BAR;
;         }
.LBB0_606:
	s_add_u32 s18, s16, s0
	s_addc_u32 s19, s17, s1
	s_add_u32 s18, s18, 0x100
	s_addc_u32 s19, s19, 0
	s_add_u32 s57, s54, s0
	s_addc_u32 s58, s55, s1
	s_add_i32 s59, 0, 0x10000
	v_add_u32_e32 v146, s59, v249
	ds_read_b128 v[134:137], v146
	ds_read_b128 v[138:141], v146 offset:1024
	ds_read_b128 v[142:145], v146 offset:2048
	ds_read_b128 v[146:149], v146 offset:3072
	s_cmpk_eq_i32 s0, 0x300
	s_cselect_b32 s21, s11, s19
	s_cselect_b32 s20, s10, s18
	s_cselect_b32 s19, s9, s58
	s_cselect_b32 s18, s53, s57
	v_lshl_add_u64 v[182:183], v[132:133], 0, s[0:1]
	s_add_i32 m0, s15, 0xc000
	ds_read_b128 v[150:153], v250
	ds_read_b128 v[154:157], v250 offset:1024
	ds_read_b128 v[158:161], v250 offset:2048
	ds_read_b128 v[162:165], v250 offset:3072
	ds_read_b128 v[166:169], v250 offset:4096
	ds_read_b128 v[170:173], v250 offset:5120
	ds_read_b128 v[174:177], v250 offset:6144
	ds_read_b128 v[178:181], v250 offset:7168
	global_load_lds_dwordx4 v[182:183], off
	v_lshl_add_u64 v[182:183], v[130:131], 0, s[0:1]
	s_add_i32 m0, s15, 0xe000
	s_nop 0
	global_load_lds_dwordx4 v[182:183], off
	s_waitcnt lgkmcnt(8)
	s_barrier
	s_waitcnt lgkmcnt(0)
	s_nop 0
	s_waitcnt lgkmcnt(0)
	v_mfma_f32_16x16x32_bf16 v[126:129], v[134:137], v[150:153], v[126:129]
	v_mfma_f32_16x16x32_bf16 v[122:125], v[142:145], v[150:153], v[122:125]
	v_mfma_f32_16x16x32_bf16 v[118:121], v[134:137], v[158:161], v[118:121]
	v_mfma_f32_16x16x32_bf16 v[114:117], v[142:145], v[158:161], v[114:117]
	v_mfma_f32_16x16x32_bf16 v[110:113], v[134:137], v[166:169], v[110:113]
	v_mfma_f32_16x16x32_bf16 v[106:109], v[142:145], v[166:169], v[106:109]
	v_mfma_f32_16x16x32_bf16 v[102:105], v[134:137], v[174:177], v[102:105]
	v_mfma_f32_16x16x32_bf16 v[98:101], v[142:145], v[174:177], v[98:101]
	v_mfma_f32_16x16x32_bf16 v[126:129], v[138:141], v[154:157], v[126:129]
	v_mfma_f32_16x16x32_bf16 v[122:125], v[146:149], v[154:157], v[122:125]
	v_mfma_f32_16x16x32_bf16 v[118:121], v[138:141], v[162:165], v[118:121]
	v_mfma_f32_16x16x32_bf16 v[114:117], v[146:149], v[162:165], v[114:117]
	v_mfma_f32_16x16x32_bf16 v[110:113], v[138:141], v[170:173], v[110:113]
	v_mfma_f32_16x16x32_bf16 v[106:109], v[146:149], v[170:173], v[106:109]
	v_mfma_f32_16x16x32_bf16 v[102:105], v[138:141], v[178:181], v[102:105]
	v_mfma_f32_16x16x32_bf16 v[98:101], v[146:149], v[178:181], v[98:101]
	s_nop 0
	s_barrier
	s_add_i32 s57, 0, 0x14000
	v_add_u32_e32 v200, s57, v249
	s_add_i32 s58, s59, s42
	ds_read_b128 v[182:185], v200
	ds_read_b128 v[186:189], v200 offset:1024
	ds_read_b128 v[190:193], v200 offset:2048
	ds_read_b128 v[226:229], v200 offset:3072
	v_lshl_add_u64 v[200:201], s[18:19], 0, v[0:1]
	s_mov_b32 m0, s58
	v_lshl_add_u64 v[230:231], s[18:19], 0, v[220:221]
	global_load_lds_dwordx4 v[200:201], off
	s_add_i32 m0, s58, 0x2000
	s_nop 0
	global_load_lds_dwordx4 v[230:231], off
	s_barrier
	s_waitcnt lgkmcnt(0)
	s_nop 0
	s_waitcnt lgkmcnt(0)
	v_mfma_f32_16x16x32_bf16 v[94:97], v[182:185], v[150:153], v[94:97]
	v_mfma_f32_16x16x32_bf16 v[90:93], v[190:193], v[150:153], v[90:93]
	v_mfma_f32_16x16x32_bf16 v[86:89], v[182:185], v[158:161], v[86:89]
	v_mfma_f32_16x16x32_bf16 v[82:85], v[190:193], v[158:161], v[82:85]
	v_mfma_f32_16x16x32_bf16 v[78:81], v[182:185], v[166:169], v[78:81]
	v_mfma_f32_16x16x32_bf16 v[74:77], v[190:193], v[166:169], v[74:77]
	v_mfma_f32_16x16x32_bf16 v[70:73], v[182:185], v[174:177], v[70:73]
	v_mfma_f32_16x16x32_bf16 v[66:69], v[190:193], v[174:177], v[66:69]
	v_mfma_f32_16x16x32_bf16 v[94:97], v[186:189], v[154:157], v[94:97]
	v_mfma_f32_16x16x32_bf16 v[90:93], v[226:229], v[154:157], v[90:93]
	v_mfma_f32_16x16x32_bf16 v[86:89], v[186:189], v[162:165], v[86:89]
	v_mfma_f32_16x16x32_bf16 v[82:85], v[226:229], v[162:165], v[82:85]
	v_mfma_f32_16x16x32_bf16 v[78:81], v[186:189], v[170:173], v[78:81]
	v_mfma_f32_16x16x32_bf16 v[74:77], v[226:229], v[170:173], v[74:77]
	v_mfma_f32_16x16x32_bf16 v[70:73], v[186:189], v[178:181], v[70:73]
	v_mfma_f32_16x16x32_bf16 v[66:69], v[226:229], v[178:181], v[66:69]
	s_nop 0
	s_mov_b32 m0, s15
	v_lshl_add_u64 v[232:233], s[20:21], 0, v[216:217]
	s_barrier
	ds_read_b128 v[150:153], v250 offset:16384
	ds_read_b128 v[154:157], v250 offset:17408
	ds_read_b128 v[158:161], v250 offset:18432
	ds_read_b128 v[162:165], v250 offset:19456
	ds_read_b128 v[166:169], v250 offset:20480
	ds_read_b128 v[170:173], v250 offset:21504
	ds_read_b128 v[174:177], v250 offset:22528
	ds_read_b128 v[178:181], v250 offset:23552
	global_load_lds_dwordx4 v[232:233], off
	v_lshl_add_u64 v[234:235], s[20:21], 0, v[218:219]
	s_mov_b32 m0, s43
	s_nop 0
	global_load_lds_dwordx4 v[234:235], off
	s_barrier
	s_waitcnt lgkmcnt(0)
	s_nop 0
	s_waitcnt lgkmcnt(0)
	v_mfma_f32_16x16x32_bf16 v[62:65], v[134:137], v[150:153], v[62:65]
	v_mfma_f32_16x16x32_bf16 v[58:61], v[142:145], v[150:153], v[58:61]
	v_mfma_f32_16x16x32_bf16 v[54:57], v[134:137], v[158:161], v[54:57]
	v_mfma_f32_16x16x32_bf16 v[50:53], v[142:145], v[158:161], v[50:53]
	v_mfma_f32_16x16x32_bf16 v[46:49], v[134:137], v[166:169], v[46:49]
	v_mfma_f32_16x16x32_bf16 v[42:45], v[142:145], v[166:169], v[42:45]
	v_mfma_f32_16x16x32_bf16 v[38:41], v[134:137], v[174:177], v[38:41]
	v_mfma_f32_16x16x32_bf16 v[34:37], v[142:145], v[174:177], v[34:37]
	v_mfma_f32_16x16x32_bf16 v[62:65], v[138:141], v[154:157], v[62:65]
	v_mfma_f32_16x16x32_bf16 v[58:61], v[146:149], v[154:157], v[58:61]
	v_mfma_f32_16x16x32_bf16 v[54:57], v[138:141], v[162:165], v[54:57]
	v_mfma_f32_16x16x32_bf16 v[50:53], v[146:149], v[162:165], v[50:53]
	v_mfma_f32_16x16x32_bf16 v[46:49], v[138:141], v[170:173], v[46:49]
	v_mfma_f32_16x16x32_bf16 v[42:45], v[146:149], v[170:173], v[42:45]
	v_mfma_f32_16x16x32_bf16 v[38:41], v[138:141], v[178:181], v[38:41]
	v_mfma_f32_16x16x32_bf16 v[34:37], v[146:149], v[178:181], v[34:37]
	s_nop 0
	s_barrier
; #define PG8_STAGE(bufoff, gbase, voff) do { _Pragma("unroll") for (int _i = 0; _i < 2; ++_i) \
;         __builtin_amdgcn_global_load_lds((const unsigned*)((const char*)(gbase) + (voff)[_i]), (LAS unsigned*)(lds + (bufoff) + ldsw + _i * 8192), 16, 0, 0); } while (0)
; #define PG8_LDA(dst, b, h) do { _Pragma("unroll") for (int m = 0; m < 4; ++m) _Pragma("unroll") for (int k = 0; k < 2; ++k) dst[m][k] = *(const LAS bf16x8*)(lds + PG8_SA(b, h) + aoff + m * 2048 + k * 1024); } while (0)
; #define PG8_LDB(dst, b, h) do { _Pragma("unroll") for (int n = 0; n < 2; ++n) _Pragma("unroll") for (int k = 0; k < 2; ++k) dst[n][k] = *(const LAS bf16x8*)(lds + PG8_SB(b, h) + boff + n * 2048 + k * 1024); } while (0)
; #define PG8_MMA(ai, bj, At, Bt) do { __builtin_amdgcn_s_setprio(1); _Pragma("unroll") for (int m = 0; m < 4; ++m) _Pragma("unroll") for (int n = 0; n < 2; ++n) _Pragma("unroll") for (int k = 0; k < 2; ++k) \
;         acc[ai][bj][m][n] = __builtin_amdgcn_mfma_f32_16x16x32_bf16(Bt[n][k], At[m][k], acc[ai][bj][m][n], 0, 0, 0); __builtin_amdgcn_s_setprio(0); } while (0)
; #define PG8_WAIT_V(n) asm volatile("s_waitcnt vmcnt(" #n ")" ::: "memory")
; #define PG8_WAIT_L(n) asm volatile("s_waitcnt lgkmcnt(" #n ")" ::: "memory")
; #define PG8_BAR __builtin_amdgcn_s_barrier()
; template <class Epi>
; DI void gemm_phase(LAS unsigned char* lds, const Gemm g, const StaticOrder& S, const Epi& E) {
;     ...
;             PG8_BAR; PG8_WAIT_L(0); PG8_MMA(0, 1, At, B1); PG8_BAR;
;             PG8_LDA(At, 0, 1); PG8_STAGE(PG8_SA(0, 0), a2, voffA);
;             PG8_BAR; PG8_WAIT_L(0); PG8_MMA(1, 0, At, B0); PG8_BAR; PG8_SCHED;
;             PG8_STAGE(PG8_SB(0, 1), b2 + hstepB, voffB);
;             PG8_WAIT_V(6); PG8_BAR; PG8_MMA(1, 1, At, B1); PG8_BAR;
;             PG8_LDB(B0, 1, 0); PG8_SCHED; PG8_LDA(At, 1, 0); PG8_STAGE(PG8_SA(0, 1), a2 + hstepA, voffA);
;             PG8_WAIT_L(8); PG8_BAR; PG8_WAIT_L(0); PG8_MMA(0, 0, At, B0); PG8_BAR; PG8_SCHED;
;             PG8_LDB(B1, 1, 1); PG8_STAGE(PG8_SB(1, 0), b3, voffB);
;             PG8_BAR; PG8_WAIT_L(0); PG8_MMA(0, 1, At, B1); PG8_BAR;
;             PG8_LDA(At, 1, 1); PG8_STAGE(PG8_SA(1, 0), a3, voffA);
;             PG8_BAR; PG8_WAIT_L(0); PG8_MMA(1, 0, At, B0); PG8_BAR; PG8_SCHED;
;             PG8_STAGE(PG8_SB(1, 1), b3 + hstepB, voffB);
;             PG8_WAIT_V(6); PG8_BAR; PG8_MMA(1, 1, At, B1); PG8_BAR;
;         }
	s_add_u32 s58, s18, 0x20000
	s_addc_u32 s59, s19, 0
	s_add_i32 s57, s57, s42
	v_lshl_add_u64 v[134:135], s[58:59], 0, v[0:1]
	s_mov_b32 m0, s57
	s_nop 0
	global_load_lds_dwordx4 v[134:135], off
	v_lshl_add_u64 v[134:135], s[58:59], 0, v[220:221]
	s_add_i32 m0, s57, 0x2000
	s_nop 0
	global_load_lds_dwordx4 v[134:135], off
	s_waitcnt vmcnt(6)
	s_barrier
	s_nop 0
	v_mfma_f32_16x16x32_bf16 v[30:33], v[182:185], v[150:153], v[30:33]
	v_mfma_f32_16x16x32_bf16 v[26:29], v[190:193], v[150:153], v[26:29]
	v_mfma_f32_16x16x32_bf16 v[22:25], v[182:185], v[158:161], v[22:25]
	v_mfma_f32_16x16x32_bf16 v[18:21], v[190:193], v[158:161], v[18:21]
	v_mfma_f32_16x16x32_bf16 v[14:17], v[182:185], v[166:169], v[14:17]
	v_mfma_f32_16x16x32_bf16 v[10:13], v[190:193], v[166:169], v[10:13]
	v_mfma_f32_16x16x32_bf16 v[6:9], v[182:185], v[174:177], v[6:9]
	v_mfma_f32_16x16x32_bf16 v[2:5], v[190:193], v[174:177], v[2:5]
	v_mfma_f32_16x16x32_bf16 v[30:33], v[186:189], v[154:157], v[30:33]
	v_mfma_f32_16x16x32_bf16 v[26:29], v[226:229], v[154:157], v[26:29]
	v_mfma_f32_16x16x32_bf16 v[22:25], v[186:189], v[162:165], v[22:25]
	v_mfma_f32_16x16x32_bf16 v[18:21], v[226:229], v[162:165], v[18:21]
	v_mfma_f32_16x16x32_bf16 v[14:17], v[186:189], v[170:173], v[14:17]
	v_mfma_f32_16x16x32_bf16 v[10:13], v[226:229], v[170:173], v[10:13]
	v_mfma_f32_16x16x32_bf16 v[6:9], v[186:189], v[178:181], v[6:9]
	v_mfma_f32_16x16x32_bf16 v[2:5], v[226:229], v[178:181], v[2:5]
	s_nop 0
	s_add_i32 s57, 0, 0x18000
	v_add_u32_e32 v146, s57, v249
	s_barrier
	ds_read_b128 v[134:137], v146
	ds_read_b128 v[138:141], v146 offset:1024
	ds_read_b128 v[142:145], v146 offset:2048
	ds_read_b128 v[146:149], v146 offset:3072
	s_add_u32 s20, s20, s6
	s_addc_u32 s21, s21, 0
	s_mov_b32 m0, s46
	v_lshl_add_u64 v[182:183], s[20:21], 0, v[216:217]
	ds_read_b128 v[150:153], v250 offset:32768
	ds_read_b128 v[154:157], v250 offset:33792
	ds_read_b128 v[158:161], v250 offset:34816
	ds_read_b128 v[162:165], v250 offset:35840
	ds_read_b128 v[166:169], v250 offset:36864
	ds_read_b128 v[170:173], v250 offset:37888
	ds_read_b128 v[174:177], v250 offset:38912
	ds_read_b128 v[178:181], v250 offset:39936
	global_load_lds_dwordx4 v[182:183], off
	v_lshl_add_u64 v[182:183], s[20:21], 0, v[218:219]
	s_mov_b32 m0, s47
	s_nop 0
	global_load_lds_dwordx4 v[182:183], off
	s_waitcnt lgkmcnt(8)
	s_barrier
	s_waitcnt lgkmcnt(0)
	s_nop 0
	s_waitcnt lgkmcnt(0)
	v_mfma_f32_16x16x32_bf16 v[126:129], v[134:137], v[150:153], v[126:129]
	v_mfma_f32_16x16x32_bf16 v[122:125], v[142:145], v[150:153], v[122:125]
	v_mfma_f32_16x16x32_bf16 v[118:121], v[134:137], v[158:161], v[118:121]
	v_mfma_f32_16x16x32_bf16 v[114:117], v[142:145], v[158:161], v[114:117]
	v_mfma_f32_16x16x32_bf16 v[110:113], v[134:137], v[166:169], v[110:113]
	v_mfma_f32_16x16x32_bf16 v[106:109], v[142:145], v[166:169], v[106:109]
	v_mfma_f32_16x16x32_bf16 v[102:105], v[134:137], v[174:177], v[102:105]
	v_mfma_f32_16x16x32_bf16 v[98:101], v[142:145], v[174:177], v[98:101]
	v_mfma_f32_16x16x32_bf16 v[126:129], v[138:141], v[154:157], v[126:129]
	v_mfma_f32_16x16x32_bf16 v[122:125], v[146:149], v[154:157], v[122:125]
	v_mfma_f32_16x16x32_bf16 v[118:121], v[138:141], v[162:165], v[118:121]
	v_mfma_f32_16x16x32_bf16 v[114:117], v[146:149], v[162:165], v[114:117]
	v_mfma_f32_16x16x32_bf16 v[110:113], v[138:141], v[170:173], v[110:113]
	v_mfma_f32_16x16x32_bf16 v[106:109], v[146:149], v[170:173], v[106:109]
	v_mfma_f32_16x16x32_bf16 v[102:105], v[138:141], v[178:181], v[102:105]
	v_mfma_f32_16x16x32_bf16 v[98:101], v[146:149], v[178:181], v[98:101]
	s_nop 0
	s_barrier
	s_add_i32 s20, 0, 0x1c000
	s_add_i32 s21, s57, s42
	v_add_u32_e32 v226, s20, v249
	v_lshl_add_u64 v[200:201], v[200:201], 0, s[2:3]
	s_mov_b32 m0, s21
	ds_read_b128 v[182:185], v226
	ds_read_b128 v[186:189], v226 offset:1024
	ds_read_b128 v[190:193], v226 offset:2048
	ds_read_b128 v[226:229], v226 offset:3072
	global_load_lds_dwordx4 v[200:201], off
	v_lshl_add_u64 v[200:201], v[230:231], 0, s[2:3]
	s_add_i32 m0, s21, 0x2000
	s_nop 0
	global_load_lds_dwordx4 v[200:201], off
	s_barrier
	s_waitcnt lgkmcnt(0)
	s_nop 0
	s_waitcnt lgkmcnt(0)
	v_mfma_f32_16x16x32_bf16 v[94:97], v[182:185], v[150:153], v[94:97]
	v_mfma_f32_16x16x32_bf16 v[90:93], v[190:193], v[150:153], v[90:93]
	v_mfma_f32_16x16x32_bf16 v[86:89], v[182:185], v[158:161], v[86:89]
	v_mfma_f32_16x16x32_bf16 v[82:85], v[190:193], v[158:161], v[82:85]
	v_mfma_f32_16x16x32_bf16 v[78:81], v[182:185], v[166:169], v[78:81]
	v_mfma_f32_16x16x32_bf16 v[74:77], v[190:193], v[166:169], v[74:77]
	v_mfma_f32_16x16x32_bf16 v[70:73], v[182:185], v[174:177], v[70:73]
	v_mfma_f32_16x16x32_bf16 v[66:69], v[190:193], v[174:177], v[66:69]
	v_mfma_f32_16x16x32_bf16 v[94:97], v[186:189], v[154:157], v[94:97]
	v_mfma_f32_16x16x32_bf16 v[90:93], v[226:229], v[154:157], v[90:93]
	v_mfma_f32_16x16x32_bf16 v[86:89], v[186:189], v[162:165], v[86:89]
	v_mfma_f32_16x16x32_bf16 v[82:85], v[226:229], v[162:165], v[82:85]
	v_mfma_f32_16x16x32_bf16 v[78:81], v[186:189], v[170:173], v[78:81]
	v_mfma_f32_16x16x32_bf16 v[74:77], v[226:229], v[170:173], v[74:77]
	v_mfma_f32_16x16x32_bf16 v[70:73], v[186:189], v[178:181], v[70:73]
	v_mfma_f32_16x16x32_bf16 v[66:69], v[226:229], v[178:181], v[66:69]
	s_nop 0
	s_mov_b32 m0, s48
	v_lshl_add_u64 v[200:201], v[232:233], 0, s[2:3]
	s_barrier
; #define PG8_STAGE(bufoff, gbase, voff) do { _Pragma("unroll") for (int _i = 0; _i < 2; ++_i) \
;         __builtin_amdgcn_global_load_lds((const unsigned*)((const char*)(gbase) + (voff)[_i]), (LAS unsigned*)(lds + (bufoff) + ldsw + _i * 8192), 16, 0, 0); } while (0)
; #define PG8_LDA(dst, b, h) do { _Pragma("unroll") for (int m = 0; m < 4; ++m) _Pragma("unroll") for (int k = 0; k < 2; ++k) dst[m][k] = *(const LAS bf16x8*)(lds + PG8_SA(b, h) + aoff + m * 2048 + k * 1024); } while (0)
; #define PG8_MMA(ai, bj, At, Bt) do { __builtin_amdgcn_s_setprio(1); _Pragma("unroll") for (int m = 0; m < 4; ++m) _Pragma("unroll") for (int n = 0; n < 2; ++n) _Pragma("unroll") for (int k = 0; k < 2; ++k) \
;         acc[ai][bj][m][n] = __builtin_amdgcn_mfma_f32_16x16x32_bf16(Bt[n][k], At[m][k], acc[ai][bj][m][n], 0, 0, 0); __builtin_amdgcn_s_setprio(0); } while (0)
; #define PG8_WAIT_V(n) asm volatile("s_waitcnt vmcnt(" #n ")" ::: "memory")
; #define PG8_WAIT_L(n) asm volatile("s_waitcnt lgkmcnt(" #n ")" ::: "memory")
; #define PG8_BAR __builtin_amdgcn_s_barrier()
; #define PG8_SCHED __builtin_amdgcn_sched_barrier(0)
; template <class Epi>
; DI void gemm_phase(LAS unsigned char* lds, const Gemm g, const StaticOrder& S, const Epi& E) {
;     ...
;             PG8_BAR; PG8_WAIT_L(0); PG8_MMA(0, 1, At, B1); PG8_BAR;
;             PG8_LDA(At, 1, 1); PG8_STAGE(PG8_SA(1, 0), a3, voffA);
;             PG8_BAR; PG8_WAIT_L(0); PG8_MMA(1, 0, At, B0); PG8_BAR; PG8_SCHED;
;             PG8_STAGE(PG8_SB(1, 1), b3 + hstepB, voffB);
;             PG8_WAIT_V(6); PG8_BAR; PG8_MMA(1, 1, At, B1); PG8_BAR;
;         }
	ds_read_b128 v[150:153], v250 offset:49152
	ds_read_b128 v[154:157], v250 offset:50176
	ds_read_b128 v[158:161], v250 offset:51200
	ds_read_b128 v[162:165], v250 offset:52224
	ds_read_b128 v[166:169], v250 offset:53248
	ds_read_b128 v[170:173], v250 offset:54272
	ds_read_b128 v[174:177], v250 offset:55296
	ds_read_b128 v[178:181], v250 offset:56320
	global_load_lds_dwordx4 v[200:201], off
	v_lshl_add_u64 v[200:201], v[234:235], 0, s[2:3]
	s_mov_b32 m0, s49
	s_nop 0
	global_load_lds_dwordx4 v[200:201], off
	s_barrier
	s_waitcnt lgkmcnt(0)
	s_nop 0
	s_waitcnt lgkmcnt(0)
	v_mfma_f32_16x16x32_bf16 v[62:65], v[134:137], v[150:153], v[62:65]
	v_mfma_f32_16x16x32_bf16 v[58:61], v[142:145], v[150:153], v[58:61]
	v_mfma_f32_16x16x32_bf16 v[54:57], v[134:137], v[158:161], v[54:57]
	v_mfma_f32_16x16x32_bf16 v[50:53], v[142:145], v[158:161], v[50:53]
	v_mfma_f32_16x16x32_bf16 v[46:49], v[134:137], v[166:169], v[46:49]
	v_mfma_f32_16x16x32_bf16 v[42:45], v[142:145], v[166:169], v[42:45]
	v_mfma_f32_16x16x32_bf16 v[38:41], v[134:137], v[174:177], v[38:41]
	v_mfma_f32_16x16x32_bf16 v[34:37], v[142:145], v[174:177], v[34:37]
	v_mfma_f32_16x16x32_bf16 v[62:65], v[138:141], v[154:157], v[62:65]
	v_mfma_f32_16x16x32_bf16 v[58:61], v[146:149], v[154:157], v[58:61]
	v_mfma_f32_16x16x32_bf16 v[54:57], v[138:141], v[162:165], v[54:57]
	v_mfma_f32_16x16x32_bf16 v[50:53], v[146:149], v[162:165], v[50:53]
	v_mfma_f32_16x16x32_bf16 v[46:49], v[138:141], v[170:173], v[46:49]
	v_mfma_f32_16x16x32_bf16 v[42:45], v[146:149], v[170:173], v[42:45]
	v_mfma_f32_16x16x32_bf16 v[38:41], v[138:141], v[178:181], v[38:41]
	v_mfma_f32_16x16x32_bf16 v[34:37], v[146:149], v[178:181], v[34:37]
	s_nop 0
	s_barrier
	s_add_u32 s18, s18, 0x20080
	s_addc_u32 s19, s19, 0
	s_add_i32 s20, s20, s42
	v_lshl_add_u64 v[134:135], s[18:19], 0, v[0:1]
	s_mov_b32 m0, s20
	s_nop 0
	global_load_lds_dwordx4 v[134:135], off
	v_lshl_add_u64 v[134:135], s[18:19], 0, v[220:221]
	s_add_i32 m0, s20, 0x2000
	s_nop 0
	global_load_lds_dwordx4 v[134:135], off
	s_waitcnt vmcnt(6)
	s_barrier
	s_nop 0
	v_mfma_f32_16x16x32_bf16 v[30:33], v[182:185], v[150:153], v[30:33]
	v_mfma_f32_16x16x32_bf16 v[26:29], v[190:193], v[150:153], v[26:29]
	v_mfma_f32_16x16x32_bf16 v[22:25], v[182:185], v[158:161], v[22:25]
	v_mfma_f32_16x16x32_bf16 v[18:21], v[190:193], v[158:161], v[18:21]
	v_mfma_f32_16x16x32_bf16 v[14:17], v[182:185], v[166:169], v[14:17]
	v_mfma_f32_16x16x32_bf16 v[10:13], v[190:193], v[166:169], v[10:13]
	v_mfma_f32_16x16x32_bf16 v[6:9], v[182:185], v[174:177], v[6:9]
	v_mfma_f32_16x16x32_bf16 v[2:5], v[190:193], v[174:177], v[2:5]
	v_mfma_f32_16x16x32_bf16 v[30:33], v[186:189], v[154:157], v[30:33]
	v_mfma_f32_16x16x32_bf16 v[26:29], v[226:229], v[154:157], v[26:29]
	v_mfma_f32_16x16x32_bf16 v[22:25], v[186:189], v[162:165], v[22:25]
	v_mfma_f32_16x16x32_bf16 v[18:21], v[226:229], v[162:165], v[18:21]
	v_mfma_f32_16x16x32_bf16 v[14:17], v[186:189], v[170:173], v[14:17]
	v_mfma_f32_16x16x32_bf16 v[10:13], v[226:229], v[170:173], v[10:13]
	v_mfma_f32_16x16x32_bf16 v[6:9], v[186:189], v[178:181], v[6:9]
	v_mfma_f32_16x16x32_bf16 v[2:5], v[226:229], v[178:181], v[2:5]
	s_nop 0
	s_add_i32 s56, s56, 2
	s_add_u32 s0, s0, 0x100
	s_addc_u32 s1, s1, 0
	s_cmp_gt_u32 s56, 5
	s_barrier
	s_cbranch_scc0 .LBB0_606
	v_mov_b32_e32 v130, v238
	v_readlane_b32 s0, v254, 54
	v_ashrrev_i32_e32 v131, 2, v130
	v_and_b32_e32 v131, 0xffffffc0, v131
	v_lshl_add_u32 v131, s44, 8, v131
	v_and_or_b32 v228, v130, 15, v131
	v_lshrrev_b32_e32 v130, 1, v130
	v_and_b32_e32 v130, 0x78, v130
	v_readlane_b32 s1, v254, 55
	v_lshl_or_b32 v226, s14, 8, v130
	s_lshl_b32 s44, s51, 1
	v_mov_b64_e32 v[130:131], s[0:1]
	v_mad_i64_i32 v[130:131], s[0:1], v228, s65, v[130:131]
	v_lshl_add_u64 v[130:131], v[130:131], 0, s[44:45]
	v_ashrrev_i32_e32 v227, 31, v226
	v_lshl_add_u64 v[130:131], v[226:227], 1, v[130:131]
	v_add_co_u32_e32 v132, vcc, 0x2000, v130
	v_ashrrev_i32_e32 v229, 31, v228
	s_nop 0
	v_addc_co_u32_e32 v133, vcc, 0, v131, vcc
	global_load_dwordx4 v[182:185], v[132:133], off offset:2048
	v_cndmask_b32_e64 v132, 0, 1, s[4:5]
	v_readlane_b32 s16, v254, 52
	v_cmp_ne_u32_e64 s[0:1], 1, v132
	v_lshlrev_b64 v[132:133], 11, v[228:229]
	v_readlane_b32 s17, v254, 53
	v_mov_b32_e32 v158, 0
	s_andn2_b64 vcc, exec, s[4:5]
	v_lshl_add_u64 v[236:237], s[16:17], 0, v[132:133]
	v_mov_b32_e32 v190, 0
	v_mov_b32_e32 v191, 0
	v_mov_b32_e32 v192, 0
	v_mov_b32_e32 v193, 0
	s_cbranch_vccnz .LBB0_609
	v_lshl_add_u64 v[132:133], v[226:227], 1, v[236:237]
	global_load_dwordx4 v[190:193], v[132:133], off

; #define PG8_STAGE(bufoff, gbase, voff) do { _Pragma("unroll") for (int _i = 0; _i < 2; ++_i) \
;         __builtin_amdgcn_global_load_lds((const unsigned*)((const char*)(gbase) + (voff)[_i]), (LAS unsigned*)(lds + (bufoff) + ldsw + _i * 8192), 16, 0, 0); } while (0)
; #define PG8_LDA(dst, b, h) do { _Pragma("unroll") for (int m = 0; m < 4; ++m) _Pragma("unroll") for (int k = 0; k < 2; ++k) dst[m][k] = *(const LAS bf16x8*)(lds + PG8_SA(b, h) + aoff + m * 2048 + k * 1024); } while (0)
; #define PG8_LDB(dst, b, h) do { _Pragma("unroll") for (int n = 0; n < 2; ++n) _Pragma("unroll") for (int k = 0; k < 2; ++k) dst[n][k] = *(const LAS bf16x8*)(lds + PG8_SB(b, h) + boff + n * 2048 + k * 1024); } while (0)
; #define PG8_MMA(ai, bj, At, Bt) do { __builtin_amdgcn_s_setprio(1); _Pragma("unroll") for (int m = 0; m < 4; ++m) _Pragma("unroll") for (int n = 0; n < 2; ++n) _Pragma("unroll") for (int k = 0; k < 2; ++k) \
;         acc[ai][bj][m][n] = __builtin_amdgcn_mfma_f32_16x16x32_bf16(Bt[n][k], At[m][k], acc[ai][bj][m][n], 0, 0, 0); __builtin_amdgcn_s_setprio(0); } while (0)
; template <class Epi>
; DI void gemm_phase(LAS unsigned char* lds, const Gemm g, const StaticOrder& S, const Epi& E) {
;     ...
;         for (int t = 0; t < nt; t += 2) {
;             const bool last = (t == nt - 2);
;             const char* a1 = cA + (size_t)(t + 1) * kstep;
;             const char* a2 = last ? nA : cA + (size_t)(t + 2) * kstep; const char* b2 = last ? nB : cB + (size_t)(t + 2) * kstep;
;             const char* a3 = a2 + kstep; const char* b3 = b2 + kstep;
;             PG8_LDB(B0, 0, 0); PG8_SCHED; PG8_LDA(At, 0, 0); PG8_STAGE(PG8_SA(1, 1), a1 + hstepA, voffA);
;             PG8_WAIT_L(8); PG8_BAR; PG8_WAIT_L(0); PG8_MMA(0, 0, At, B0); PG8_BAR; PG8_SCHED;
;             PG8_LDB(B1, 0, 1); PG8_STAGE(PG8_SB(0, 0), b2, voffB);
;             PG8_BAR; PG8_WAIT_L(0); PG8_MMA(0, 1, At, B1); PG8_BAR;
;             PG8_LDA(At, 0, 1); PG8_STAGE(PG8_SA(0, 0), a2, voffA);
;             PG8_BAR; PG8_WAIT_L(0); PG8_MMA(1, 0, At, B0); PG8_BAR; PG8_SCHED;
;             PG8_STAGE(PG8_SB(0, 1), b2 + hstepB, voffB);
;             PG8_WAIT_V(6); PG8_BAR; PG8_MMA(1, 1, At, B1); PG8_BAR;
;             PG8_LDB(B0, 1, 0); PG8_SCHED; PG8_LDA(At, 1, 0); PG8_STAGE(PG8_SA(0, 1), a2 + hstepA, voffA);
;             PG8_WAIT_L(8); PG8_BAR; PG8_WAIT_L(0); PG8_MMA(0, 0, At, B0); PG8_BAR; PG8_SCHED;
.LBB0_814:
	s_ashr_i32 s13, s12, 31
	s_lshl_b64 s[14:15], s[12:13], 17
	s_add_u32 s14, s29, s14
	s_addc_u32 s15, s30, s15
	s_and_b64 s[16:17], s[4:5], exec
	s_cselect_b32 s23, s15, s19
	s_cselect_b32 s22, s14, s18
	s_ashr_i32 s11, s10, 31
	s_lshl_b64 s[16:17], s[10:11], 17
	s_add_u32 s16, s31, s16
	s_addc_u32 s17, s34, s17
	s_and_b64 s[4:5], s[4:5], exec
	s_cselect_b32 s5, s17, s21
	s_cselect_b32 s4, s16, s20
	s_add_i32 s13, 0, 0x10000
	v_add_u32_e32 v9, s13, v16
	ds_read_b128 v[10:13], v9
	ds_read_b128 v[18:21], v9 offset:1024
	ds_read_b128 v[22:25], v9 offset:2048
	ds_read_b128 v[26:29], v9 offset:3072
	s_add_u32 s46, s18, 0x10080
	s_addc_u32 s47, s19, 0
	s_add_i32 s48, s9, 0xc000
	v_lshl_add_u64 v[14:15], s[46:47], 0, v[6:7]
	s_mov_b32 m0, s48
	s_add_i32 s11, s9, 0xe000
	ds_read_b128 v[30:33], v8
	ds_read_b128 v[34:37], v8 offset:1024
	ds_read_b128 v[38:41], v8 offset:2048
	ds_read_b128 v[42:45], v8 offset:3072
	ds_read_b128 v[46:49], v8 offset:4096
	ds_read_b128 v[50:53], v8 offset:5120
	ds_read_b128 v[54:57], v8 offset:6144
	ds_read_b128 v[58:61], v8 offset:7168
	global_load_lds_dwordx4 v[14:15], off
	v_lshl_add_u64 v[14:15], s[46:47], 0, v[4:5]
	s_mov_b32 m0, s11
	s_nop 0
	global_load_lds_dwordx4 v[14:15], off
	s_waitcnt lgkmcnt(8)
	s_barrier
	s_waitcnt lgkmcnt(0)
	s_nop 0
	s_waitcnt lgkmcnt(0)
	v_mfma_f32_16x16x32_bf16 v[62:65], v[10:13], v[30:33], 0
	v_mfma_f32_16x16x32_bf16 v[66:69], v[22:25], v[30:33], 0
	v_mfma_f32_16x16x32_bf16 v[70:73], v[10:13], v[38:41], 0
	v_mfma_f32_16x16x32_bf16 v[74:77], v[22:25], v[38:41], 0
	v_mfma_f32_16x16x32_bf16 v[78:81], v[10:13], v[46:49], 0
	v_mfma_f32_16x16x32_bf16 v[82:85], v[22:25], v[46:49], 0
	v_mfma_f32_16x16x32_bf16 v[86:89], v[10:13], v[54:57], 0
	v_mfma_f32_16x16x32_bf16 v[90:93], v[22:25], v[54:57], 0
	v_mfma_f32_16x16x32_bf16 v[62:65], v[18:21], v[34:37], v[62:65]
	v_mfma_f32_16x16x32_bf16 v[66:69], v[26:29], v[34:37], v[66:69]
	v_mfma_f32_16x16x32_bf16 v[70:73], v[18:21], v[42:45], v[70:73]
	v_mfma_f32_16x16x32_bf16 v[74:77], v[26:29], v[42:45], v[74:77]
	v_mfma_f32_16x16x32_bf16 v[78:81], v[18:21], v[50:53], v[78:81]
	v_mfma_f32_16x16x32_bf16 v[82:85], v[26:29], v[50:53], v[82:85]
	v_mfma_f32_16x16x32_bf16 v[86:89], v[18:21], v[58:61], v[86:89]
	v_mfma_f32_16x16x32_bf16 v[90:93], v[26:29], v[58:61], v[90:93]
	s_nop 0
	s_barrier
	s_add_i32 s49, 0, 0x14000
	v_lshl_add_u64 v[14:15], s[20:21], 0, v[0:1]
	s_mov_b64 s[50:51], 0x100
	s_add_i32 s47, s13, s35
	v_add_u32_e32 v17, s49, v16
	v_lshl_add_u64 v[110:111], v[14:15], 0, s[50:51]
	s_mov_b32 m0, s47
	v_lshl_add_u64 v[228:229], s[20:21], 0, v[2:3]
	s_add_i32 s13, s47, 0x2000
	ds_read_b128 v[94:97], v17
	ds_read_b128 v[98:101], v17 offset:1024
	ds_read_b128 v[102:105], v17 offset:2048
	ds_read_b128 v[106:109], v17 offset:3072
	global_load_lds_dwordx4 v[110:111], off
	v_lshl_add_u64 v[110:111], v[228:229], 0, s[50:51]
	s_mov_b32 m0, s13
	s_nop 0
	global_load_lds_dwordx4 v[110:111], off
	s_barrier
	s_waitcnt lgkmcnt(0)
	s_nop 0
	s_waitcnt lgkmcnt(0)
	v_mfma_f32_16x16x32_bf16 v[110:113], v[94:97], v[30:33], 0
	v_mfma_f32_16x16x32_bf16 v[30:33], v[102:105], v[30:33], 0
	v_mfma_f32_16x16x32_bf16 v[110:113], v[98:101], v[34:37], v[110:113]
	v_mfma_f32_16x16x32_bf16 v[30:33], v[106:109], v[34:37], v[30:33]
	v_mfma_f32_16x16x32_bf16 v[34:37], v[94:97], v[38:41], 0
	v_mfma_f32_16x16x32_bf16 v[38:41], v[102:105], v[38:41], 0
	v_mfma_f32_16x16x32_bf16 v[34:37], v[98:101], v[42:45], v[34:37]
	v_mfma_f32_16x16x32_bf16 v[38:41], v[106:109], v[42:45], v[38:41]
	v_mfma_f32_16x16x32_bf16 v[42:45], v[94:97], v[46:49], 0
	v_mfma_f32_16x16x32_bf16 v[46:49], v[102:105], v[46:49], 0
	v_mfma_f32_16x16x32_bf16 v[42:45], v[98:101], v[50:53], v[42:45]
	v_mfma_f32_16x16x32_bf16 v[46:49], v[106:109], v[50:53], v[46:49]
	v_mfma_f32_16x16x32_bf16 v[50:53], v[94:97], v[54:57], 0
	v_mfma_f32_16x16x32_bf16 v[54:57], v[102:105], v[54:57], 0
	v_mfma_f32_16x16x32_bf16 v[50:53], v[98:101], v[58:61], v[50:53]
	v_mfma_f32_16x16x32_bf16 v[54:57], v[106:109], v[58:61], v[54:57]
	s_nop 0
	v_lshl_add_u64 v[230:231], s[18:19], 0, v[6:7]
	s_mov_b32 m0, s9
	v_lshl_add_u64 v[142:143], v[230:231], 0, s[50:51]
	v_lshl_add_u64 v[232:233], s[18:19], 0, v[4:5]
	s_barrier
	ds_read_b128 v[58:61], v8 offset:16384
	ds_read_b128 v[114:117], v8 offset:17408
	ds_read_b128 v[118:121], v8 offset:18432
	ds_read_b128 v[122:125], v8 offset:19456
	ds_read_b128 v[126:129], v8 offset:20480
	ds_read_b128 v[130:133], v8 offset:21504
	ds_read_b128 v[134:137], v8 offset:22528
	ds_read_b128 v[138:141], v8 offset:23552
	global_load_lds_dwordx4 v[142:143], off
	v_lshl_add_u64 v[142:143], v[232:233], 0, s[50:51]
	s_mov_b32 m0, s36
	s_nop 0
	global_load_lds_dwordx4 v[142:143], off
	s_barrier
	s_waitcnt lgkmcnt(0)
	s_nop 0
	s_waitcnt lgkmcnt(0)
	v_mfma_f32_16x16x32_bf16 v[142:145], v[10:13], v[58:61], 0
	v_mfma_f32_16x16x32_bf16 v[150:153], v[10:13], v[118:121], 0
	v_mfma_f32_16x16x32_bf16 v[158:161], v[10:13], v[126:129], 0
	v_mfma_f32_16x16x32_bf16 v[10:13], v[10:13], v[134:137], 0
	v_mfma_f32_16x16x32_bf16 v[142:145], v[18:21], v[114:117], v[142:145]
	v_mfma_f32_16x16x32_bf16 v[146:149], v[22:25], v[58:61], 0
	v_mfma_f32_16x16x32_bf16 v[150:153], v[18:21], v[122:125], v[150:153]
	v_mfma_f32_16x16x32_bf16 v[154:157], v[22:25], v[118:121], 0
	v_mfma_f32_16x16x32_bf16 v[158:161], v[18:21], v[130:133], v[158:161]
	v_mfma_f32_16x16x32_bf16 v[162:165], v[22:25], v[126:129], 0
	v_mfma_f32_16x16x32_bf16 v[10:13], v[18:21], v[138:141], v[10:13]
	v_mfma_f32_16x16x32_bf16 v[18:21], v[22:25], v[134:137], 0
	v_mfma_f32_16x16x32_bf16 v[146:149], v[26:29], v[114:117], v[146:149]
	v_mfma_f32_16x16x32_bf16 v[154:157], v[26:29], v[122:125], v[154:157]
	v_mfma_f32_16x16x32_bf16 v[162:165], v[26:29], v[130:133], v[162:165]
	v_mfma_f32_16x16x32_bf16 v[18:21], v[26:29], v[138:141], v[18:21]
	s_nop 0
	s_barrier
; #define PG8_STAGE(bufoff, gbase, voff) do { _Pragma("unroll") for (int _i = 0; _i < 2; ++_i) \
;         __builtin_amdgcn_global_load_lds((const unsigned*)((const char*)(gbase) + (voff)[_i]), (LAS unsigned*)(lds + (bufoff) + ldsw + _i * 8192), 16, 0, 0); } while (0)
; #define PG8_LDA(dst, b, h) do { _Pragma("unroll") for (int m = 0; m < 4; ++m) _Pragma("unroll") for (int k = 0; k < 2; ++k) dst[m][k] = *(const LAS bf16x8*)(lds + PG8_SA(b, h) + aoff + m * 2048 + k * 1024); } while (0)
; #define PG8_LDB(dst, b, h) do { _Pragma("unroll") for (int n = 0; n < 2; ++n) _Pragma("unroll") for (int k = 0; k < 2; ++k) dst[n][k] = *(const LAS bf16x8*)(lds + PG8_SB(b, h) + boff + n * 2048 + k * 1024); } while (0)
; #define PG8_MMA(ai, bj, At, Bt) do { __builtin_amdgcn_s_setprio(1); _Pragma("unroll") for (int m = 0; m < 4; ++m) _Pragma("unroll") for (int n = 0; n < 2; ++n) _Pragma("unroll") for (int k = 0; k < 2; ++k) \
;         acc[ai][bj][m][n] = __builtin_amdgcn_mfma_f32_16x16x32_bf16(Bt[n][k], At[m][k], acc[ai][bj][m][n], 0, 0, 0); __builtin_amdgcn_s_setprio(0); } while (0)
; #define PG8_WAIT_V(n) asm volatile("s_waitcnt vmcnt(" #n ")" ::: "memory")
; #define PG8_WAIT_L(n) asm volatile("s_waitcnt lgkmcnt(" #n ")" ::: "memory")
; #define PG8_BAR __builtin_amdgcn_s_barrier()
; #define PG8_SCHED __builtin_amdgcn_sched_barrier(0)
; template <class Epi>
; DI void gemm_phase(LAS unsigned char* lds, const Gemm g, const StaticOrder& S, const Epi& E) {
;     ...
;             PG8_BAR; PG8_WAIT_L(0); PG8_MMA(0, 1, At, B1); PG8_BAR;
;             PG8_LDA(At, 0, 1); PG8_STAGE(PG8_SA(0, 0), a2, voffA);
;             PG8_BAR; PG8_WAIT_L(0); PG8_MMA(1, 0, At, B0); PG8_BAR; PG8_SCHED;
;             PG8_STAGE(PG8_SB(0, 1), b2 + hstepB, voffB);
;             PG8_WAIT_V(6); PG8_BAR; PG8_MMA(1, 1, At, B1); PG8_BAR;
;             PG8_LDB(B0, 1, 0); PG8_SCHED; PG8_LDA(At, 1, 0); PG8_STAGE(PG8_SA(0, 1), a2 + hstepA, voffA);
;             PG8_WAIT_L(8); PG8_BAR; PG8_WAIT_L(0); PG8_MMA(0, 0, At, B0); PG8_BAR; PG8_SCHED;
;             PG8_LDB(B1, 1, 1); PG8_STAGE(PG8_SB(1, 0), b3, voffB);
;             PG8_BAR; PG8_WAIT_L(0); PG8_MMA(0, 1, At, B1); PG8_BAR;
;             PG8_LDA(At, 1, 1); PG8_STAGE(PG8_SA(1, 0), a3, voffA);
;             PG8_BAR; PG8_WAIT_L(0); PG8_MMA(1, 0, At, B0); PG8_BAR; PG8_SCHED;
	s_add_u32 s50, s20, 0x10100
	s_addc_u32 s51, s21, 0
	s_add_i32 s49, s49, s35
	v_lshl_add_u64 v[22:23], s[50:51], 0, v[0:1]
	s_mov_b32 m0, s49
	s_add_i32 s46, s49, 0x2000
	global_load_lds_dwordx4 v[22:23], off
	v_lshl_add_u64 v[22:23], s[50:51], 0, v[2:3]
	s_mov_b32 m0, s46
	s_nop 0
	global_load_lds_dwordx4 v[22:23], off
	s_waitcnt vmcnt(6)
	s_barrier
	s_nop 0
	v_mfma_f32_16x16x32_bf16 v[22:25], v[94:97], v[58:61], 0
	v_mfma_f32_16x16x32_bf16 v[26:29], v[102:105], v[58:61], 0
	v_mfma_f32_16x16x32_bf16 v[22:25], v[98:101], v[114:117], v[22:25]
	v_mfma_f32_16x16x32_bf16 v[26:29], v[106:109], v[114:117], v[26:29]
	v_mfma_f32_16x16x32_bf16 v[58:61], v[94:97], v[118:121], 0
	v_mfma_f32_16x16x32_bf16 v[114:117], v[102:105], v[118:121], 0
	v_mfma_f32_16x16x32_bf16 v[118:121], v[94:97], v[126:129], 0
	v_mfma_f32_16x16x32_bf16 v[94:97], v[94:97], v[134:137], 0
	v_mfma_f32_16x16x32_bf16 v[58:61], v[98:101], v[122:125], v[58:61]
	v_mfma_f32_16x16x32_bf16 v[114:117], v[106:109], v[122:125], v[114:117]
	v_mfma_f32_16x16x32_bf16 v[118:121], v[98:101], v[130:133], v[118:121]
	v_mfma_f32_16x16x32_bf16 v[122:125], v[102:105], v[126:129], 0
	v_mfma_f32_16x16x32_bf16 v[94:97], v[98:101], v[138:141], v[94:97]
	v_mfma_f32_16x16x32_bf16 v[98:101], v[102:105], v[134:137], 0
	v_mfma_f32_16x16x32_bf16 v[122:125], v[106:109], v[130:133], v[122:125]
	v_mfma_f32_16x16x32_bf16 v[98:101], v[106:109], v[138:141], v[98:101]
	s_nop 0
	s_add_i32 s52, 0, 0x18000
	v_add_u32_e32 v200, s52, v16
	s_barrier
	ds_read_b128 v[102:105], v200
	ds_read_b128 v[106:109], v200 offset:1024
	ds_read_b128 v[126:129], v200 offset:2048
	ds_read_b128 v[130:133], v200 offset:3072
	s_add_u32 s50, s18, 0x10100
	s_addc_u32 s51, s19, 0
	s_mov_b32 m0, s37
	v_lshl_add_u64 v[190:191], s[50:51], 0, v[6:7]
	ds_read_b128 v[134:137], v8 offset:32768
	ds_read_b128 v[138:141], v8 offset:33792
	ds_read_b128 v[166:169], v8 offset:34816
	ds_read_b128 v[170:173], v8 offset:35840
	ds_read_b128 v[174:177], v8 offset:36864
	ds_read_b128 v[178:181], v8 offset:37888
	ds_read_b128 v[182:185], v8 offset:38912
	ds_read_b128 v[186:189], v8 offset:39936
	global_load_lds_dwordx4 v[190:191], off
	v_lshl_add_u64 v[190:191], s[50:51], 0, v[4:5]
	s_mov_b32 m0, s38
	s_nop 0
	global_load_lds_dwordx4 v[190:191], off
	s_waitcnt lgkmcnt(8)
	s_barrier
	s_waitcnt lgkmcnt(0)
	s_nop 0
	s_waitcnt lgkmcnt(0)
	v_mfma_f32_16x16x32_bf16 v[62:65], v[102:105], v[134:137], v[62:65]
	v_mfma_f32_16x16x32_bf16 v[66:69], v[126:129], v[134:137], v[66:69]
	v_mfma_f32_16x16x32_bf16 v[70:73], v[102:105], v[166:169], v[70:73]
	v_mfma_f32_16x16x32_bf16 v[74:77], v[126:129], v[166:169], v[74:77]
	v_mfma_f32_16x16x32_bf16 v[78:81], v[102:105], v[174:177], v[78:81]
	v_mfma_f32_16x16x32_bf16 v[82:85], v[126:129], v[174:177], v[82:85]
	v_mfma_f32_16x16x32_bf16 v[86:89], v[102:105], v[182:185], v[86:89]
	v_mfma_f32_16x16x32_bf16 v[90:93], v[126:129], v[182:185], v[90:93]
	v_mfma_f32_16x16x32_bf16 v[62:65], v[106:109], v[138:141], v[62:65]
	v_mfma_f32_16x16x32_bf16 v[66:69], v[130:133], v[138:141], v[66:69]
	v_mfma_f32_16x16x32_bf16 v[70:73], v[106:109], v[170:173], v[70:73]
	v_mfma_f32_16x16x32_bf16 v[74:77], v[130:133], v[170:173], v[74:77]
	v_mfma_f32_16x16x32_bf16 v[78:81], v[106:109], v[178:181], v[78:81]
	v_mfma_f32_16x16x32_bf16 v[82:85], v[130:133], v[178:181], v[82:85]
	v_mfma_f32_16x16x32_bf16 v[86:89], v[106:109], v[186:189], v[86:89]
	v_mfma_f32_16x16x32_bf16 v[90:93], v[130:133], v[186:189], v[90:93]
	s_nop 0
	s_barrier
	s_add_i32 s54, 0, 0x1c000
	s_mov_b64 s[56:57], 0x180
	s_add_i32 s51, s52, s35
	v_add_u32_e32 v201, s54, v16
	v_lshl_add_u64 v[14:15], v[14:15], 0, s[56:57]
	s_mov_b32 m0, s51
	s_add_i32 s50, s51, 0x2000
	ds_read_b128 v[190:193], v201
	ds_read_b128 v[216:219], v201 offset:1024
	ds_read_b128 v[220:223], v201 offset:2048
	ds_read_b128 v[224:227], v201 offset:3072
	global_load_lds_dwordx4 v[14:15], off
	v_lshl_add_u64 v[14:15], v[228:229], 0, s[56:57]
	s_mov_b32 m0, s50
	s_nop 0
	global_load_lds_dwordx4 v[14:15], off
	s_barrier
	s_waitcnt lgkmcnt(0)
	s_nop 0
	s_waitcnt lgkmcnt(0)
	v_mfma_f32_16x16x32_bf16 v[110:113], v[190:193], v[134:137], v[110:113]
	v_mfma_f32_16x16x32_bf16 v[30:33], v[220:223], v[134:137], v[30:33]
	v_mfma_f32_16x16x32_bf16 v[34:37], v[190:193], v[166:169], v[34:37]
	v_mfma_f32_16x16x32_bf16 v[38:41], v[220:223], v[166:169], v[38:41]
	v_mfma_f32_16x16x32_bf16 v[42:45], v[190:193], v[174:177], v[42:45]
	v_mfma_f32_16x16x32_bf16 v[46:49], v[220:223], v[174:177], v[46:49]
	v_mfma_f32_16x16x32_bf16 v[50:53], v[190:193], v[182:185], v[50:53]
	v_mfma_f32_16x16x32_bf16 v[54:57], v[220:223], v[182:185], v[54:57]
	v_mfma_f32_16x16x32_bf16 v[110:113], v[216:219], v[138:141], v[110:113]
	v_mfma_f32_16x16x32_bf16 v[30:33], v[224:227], v[138:141], v[30:33]
	v_mfma_f32_16x16x32_bf16 v[34:37], v[216:219], v[170:173], v[34:37]
	v_mfma_f32_16x16x32_bf16 v[38:41], v[224:227], v[170:173], v[38:41]
	v_mfma_f32_16x16x32_bf16 v[42:45], v[216:219], v[178:181], v[42:45]
	v_mfma_f32_16x16x32_bf16 v[46:49], v[224:227], v[178:181], v[46:49]
	v_mfma_f32_16x16x32_bf16 v[50:53], v[216:219], v[186:189], v[50:53]
	v_mfma_f32_16x16x32_bf16 v[54:57], v[224:227], v[186:189], v[54:57]
	s_nop 0
	s_mov_b32 m0, s39
	v_lshl_add_u64 v[14:15], v[230:231], 0, s[56:57]
	s_barrier
	ds_read_b128 v[134:137], v8 offset:49152
	ds_read_b128 v[138:141], v8 offset:50176
	ds_read_b128 v[166:169], v8 offset:51200
	ds_read_b128 v[170:173], v8 offset:52224
	ds_read_b128 v[174:177], v8 offset:53248
	ds_read_b128 v[178:181], v8 offset:54272
	ds_read_b128 v[182:185], v8 offset:55296
	ds_read_b128 v[186:189], v8 offset:56320
	global_load_lds_dwordx4 v[14:15], off
	v_lshl_add_u64 v[14:15], v[232:233], 0, s[56:57]
	s_mov_b32 m0, s40
	s_nop 0
	global_load_lds_dwordx4 v[14:15], off
	s_barrier
; #define PG8_STAGE(bufoff, gbase, voff) do { _Pragma("unroll") for (int _i = 0; _i < 2; ++_i) \
;         __builtin_amdgcn_global_load_lds((const unsigned*)((const char*)(gbase) + (voff)[_i]), (LAS unsigned*)(lds + (bufoff) + ldsw + _i * 8192), 16, 0, 0); } while (0)
; #define PG8_LDA(dst, b, h) do { _Pragma("unroll") for (int m = 0; m < 4; ++m) _Pragma("unroll") for (int k = 0; k < 2; ++k) dst[m][k] = *(const LAS bf16x8*)(lds + PG8_SA(b, h) + aoff + m * 2048 + k * 1024); } while (0)
; #define PG8_LDB(dst, b, h) do { _Pragma("unroll") for (int n = 0; n < 2; ++n) _Pragma("unroll") for (int k = 0; k < 2; ++k) dst[n][k] = *(const LAS bf16x8*)(lds + PG8_SB(b, h) + boff + n * 2048 + k * 1024); } while (0)
; #define PG8_MMA(ai, bj, At, Bt) do { __builtin_amdgcn_s_setprio(1); _Pragma("unroll") for (int m = 0; m < 4; ++m) _Pragma("unroll") for (int n = 0; n < 2; ++n) _Pragma("unroll") for (int k = 0; k < 2; ++k) \
;         acc[ai][bj][m][n] = __builtin_amdgcn_mfma_f32_16x16x32_bf16(Bt[n][k], At[m][k], acc[ai][bj][m][n], 0, 0, 0); __builtin_amdgcn_s_setprio(0); } while (0)
; #define PG8_WAIT_V(n) asm volatile("s_waitcnt vmcnt(" #n ")" ::: "memory")
; #define PG8_WAIT_L(n) asm volatile("s_waitcnt lgkmcnt(" #n ")" ::: "memory")
; #define PG8_BAR __builtin_amdgcn_s_barrier()
; #define PG8_SCHED __builtin_amdgcn_sched_barrier(0)
; template <class Epi>
; DI void gemm_phase(LAS unsigned char* lds, const Gemm g, const StaticOrder& S, const Epi& E) {
;     ...
;             PG8_WAIT_V(6); PG8_BAR; PG8_MMA(1, 1, At, B1); PG8_BAR;
;             PG8_LDB(B0, 1, 0); PG8_SCHED; PG8_LDA(At, 1, 0); PG8_STAGE(PG8_SA(0, 1), a2 + hstepA, voffA);
;             PG8_WAIT_L(8); PG8_BAR; PG8_WAIT_L(0); PG8_MMA(0, 0, At, B0); PG8_BAR; PG8_SCHED;
;             PG8_LDB(B1, 1, 1); PG8_STAGE(PG8_SB(1, 0), b3, voffB);
;             PG8_BAR; PG8_WAIT_L(0); PG8_MMA(0, 1, At, B1); PG8_BAR;
;             PG8_LDA(At, 1, 1); PG8_STAGE(PG8_SA(1, 0), a3, voffA);
;             PG8_BAR; PG8_WAIT_L(0); PG8_MMA(1, 0, At, B0); PG8_BAR; PG8_SCHED;
	s_waitcnt lgkmcnt(0)
	s_nop 0
	s_waitcnt lgkmcnt(0)
	v_mfma_f32_16x16x32_bf16 v[142:145], v[102:105], v[134:137], v[142:145]
	v_mfma_f32_16x16x32_bf16 v[146:149], v[126:129], v[134:137], v[146:149]
	v_mfma_f32_16x16x32_bf16 v[150:153], v[102:105], v[166:169], v[150:153]
	v_mfma_f32_16x16x32_bf16 v[154:157], v[126:129], v[166:169], v[154:157]
	v_mfma_f32_16x16x32_bf16 v[158:161], v[102:105], v[174:177], v[158:161]
	v_mfma_f32_16x16x32_bf16 v[162:165], v[126:129], v[174:177], v[162:165]
	v_mfma_f32_16x16x32_bf16 v[10:13], v[102:105], v[182:185], v[10:13]
	v_mfma_f32_16x16x32_bf16 v[18:21], v[126:129], v[182:185], v[18:21]
	v_mfma_f32_16x16x32_bf16 v[142:145], v[106:109], v[138:141], v[142:145]
	v_mfma_f32_16x16x32_bf16 v[146:149], v[130:133], v[138:141], v[146:149]
	v_mfma_f32_16x16x32_bf16 v[150:153], v[106:109], v[170:173], v[150:153]
	v_mfma_f32_16x16x32_bf16 v[154:157], v[130:133], v[170:173], v[154:157]
	v_mfma_f32_16x16x32_bf16 v[158:161], v[106:109], v[178:181], v[158:161]
	v_mfma_f32_16x16x32_bf16 v[162:165], v[130:133], v[178:181], v[162:165]
	v_mfma_f32_16x16x32_bf16 v[10:13], v[106:109], v[186:189], v[10:13]
	v_mfma_f32_16x16x32_bf16 v[18:21], v[130:133], v[186:189], v[18:21]
	s_nop 0
	s_barrier
	s_add_u32 s52, s20, 0x10180
	s_addc_u32 s53, s21, 0
	s_add_i32 s21, s54, s35
	v_lshl_add_u64 v[14:15], s[52:53], 0, v[0:1]
	s_mov_b32 m0, s21
	s_add_i32 s20, s21, 0x2000
	global_load_lds_dwordx4 v[14:15], off
	v_lshl_add_u64 v[14:15], s[52:53], 0, v[2:3]
	s_mov_b32 m0, s20
	s_nop 0
	global_load_lds_dwordx4 v[14:15], off
	s_waitcnt vmcnt(6)
	s_barrier
	s_nop 0
	v_mfma_f32_16x16x32_bf16 v[22:25], v[190:193], v[134:137], v[22:25]
	v_mfma_f32_16x16x32_bf16 v[26:29], v[220:223], v[134:137], v[26:29]
	v_mfma_f32_16x16x32_bf16 v[58:61], v[190:193], v[166:169], v[58:61]
	v_mfma_f32_16x16x32_bf16 v[102:105], v[220:223], v[166:169], v[114:117]
	v_mfma_f32_16x16x32_bf16 v[106:109], v[190:193], v[174:177], v[118:121]
	v_mfma_f32_16x16x32_bf16 v[114:117], v[220:223], v[174:177], v[122:125]
	v_mfma_f32_16x16x32_bf16 v[94:97], v[190:193], v[182:185], v[94:97]
	v_mfma_f32_16x16x32_bf16 v[98:101], v[220:223], v[182:185], v[98:101]
	v_mfma_f32_16x16x32_bf16 v[22:25], v[216:219], v[138:141], v[22:25]
	v_mfma_f32_16x16x32_bf16 v[26:29], v[224:227], v[138:141], v[26:29]
	v_mfma_f32_16x16x32_bf16 v[58:61], v[216:219], v[170:173], v[58:61]
	v_mfma_f32_16x16x32_bf16 v[102:105], v[224:227], v[170:173], v[102:105]
	v_mfma_f32_16x16x32_bf16 v[106:109], v[216:219], v[178:181], v[106:109]
	v_mfma_f32_16x16x32_bf16 v[114:117], v[224:227], v[178:181], v[114:117]
	v_mfma_f32_16x16x32_bf16 v[94:97], v[216:219], v[186:189], v[94:97]
	v_mfma_f32_16x16x32_bf16 v[98:101], v[224:227], v[186:189], v[98:101]
	s_nop 0
	s_barrier
	ds_read_b128 v[118:121], v9
	ds_read_b128 v[122:125], v9 offset:1024
	ds_read_b128 v[126:129], v9 offset:2048
	ds_read_b128 v[130:133], v9 offset:3072
	s_add_u32 s18, s18, 0x10180
	s_addc_u32 s19, s19, 0
	s_mov_b32 m0, s48
	v_lshl_add_u64 v[14:15], s[18:19], 0, v[6:7]
	ds_read_b128 v[134:137], v8
	ds_read_b128 v[138:141], v8 offset:1024
	ds_read_b128 v[166:169], v8 offset:2048
	ds_read_b128 v[170:173], v8 offset:3072
	ds_read_b128 v[174:177], v8 offset:4096
	ds_read_b128 v[178:181], v8 offset:5120
	ds_read_b128 v[182:185], v8 offset:6144
	ds_read_b128 v[186:189], v8 offset:7168
	global_load_lds_dwordx4 v[14:15], off
	v_lshl_add_u64 v[14:15], s[18:19], 0, v[4:5]
	s_mov_b32 m0, s11
	s_nop 0
	global_load_lds_dwordx4 v[14:15], off
	s_waitcnt lgkmcnt(8)
	s_barrier
	s_waitcnt lgkmcnt(0)
	s_nop 0
	s_waitcnt lgkmcnt(0)
	v_mfma_f32_16x16x32_bf16 v[62:65], v[118:121], v[134:137], v[62:65]
	v_mfma_f32_16x16x32_bf16 v[66:69], v[126:129], v[134:137], v[66:69]
	v_mfma_f32_16x16x32_bf16 v[70:73], v[118:121], v[166:169], v[70:73]
	v_mfma_f32_16x16x32_bf16 v[74:77], v[126:129], v[166:169], v[74:77]
	v_mfma_f32_16x16x32_bf16 v[78:81], v[118:121], v[174:177], v[78:81]
	v_mfma_f32_16x16x32_bf16 v[82:85], v[126:129], v[174:177], v[82:85]
	v_mfma_f32_16x16x32_bf16 v[86:89], v[118:121], v[182:185], v[86:89]
	v_mfma_f32_16x16x32_bf16 v[90:93], v[126:129], v[182:185], v[90:93]
	v_mfma_f32_16x16x32_bf16 v[62:65], v[122:125], v[138:141], v[62:65]
	v_mfma_f32_16x16x32_bf16 v[66:69], v[130:133], v[138:141], v[66:69]
	v_mfma_f32_16x16x32_bf16 v[70:73], v[122:125], v[170:173], v[70:73]
	v_mfma_f32_16x16x32_bf16 v[74:77], v[130:133], v[170:173], v[74:77]
	v_mfma_f32_16x16x32_bf16 v[78:81], v[122:125], v[178:181], v[78:81]
	v_mfma_f32_16x16x32_bf16 v[82:85], v[130:133], v[178:181], v[82:85]
	v_mfma_f32_16x16x32_bf16 v[86:89], v[122:125], v[186:189], v[86:89]
	v_mfma_f32_16x16x32_bf16 v[90:93], v[130:133], v[186:189], v[90:93]
	s_nop 0
	s_barrier
	s_mov_b32 m0, s47
	v_lshl_add_u64 v[14:15], s[4:5], 0, v[0:1]
	ds_read_b128 v[190:193], v17
	ds_read_b128 v[216:219], v17 offset:1024
	ds_read_b128 v[220:223], v17 offset:2048
	ds_read_b128 v[224:227], v17 offset:3072
	global_load_lds_dwordx4 v[14:15], off
	v_lshl_add_u64 v[228:229], s[4:5], 0, v[2:3]
	s_mov_b32 m0, s13
	s_nop 0
	global_load_lds_dwordx4 v[228:229], off
	s_barrier
; #define PG8_STAGE(bufoff, gbase, voff) do { _Pragma("unroll") for (int _i = 0; _i < 2; ++_i) \
;         __builtin_amdgcn_global_load_lds((const unsigned*)((const char*)(gbase) + (voff)[_i]), (LAS unsigned*)(lds + (bufoff) + ldsw + _i * 8192), 16, 0, 0); } while (0)
; #define PG8_LDA(dst, b, h) do { _Pragma("unroll") for (int m = 0; m < 4; ++m) _Pragma("unroll") for (int k = 0; k < 2; ++k) dst[m][k] = *(const LAS bf16x8*)(lds + PG8_SA(b, h) + aoff + m * 2048 + k * 1024); } while (0)
; #define PG8_LDB(dst, b, h) do { _Pragma("unroll") for (int n = 0; n < 2; ++n) _Pragma("unroll") for (int k = 0; k < 2; ++k) dst[n][k] = *(const LAS bf16x8*)(lds + PG8_SB(b, h) + boff + n * 2048 + k * 1024); } while (0)
; #define PG8_MMA(ai, bj, At, Bt) do { __builtin_amdgcn_s_setprio(1); _Pragma("unroll") for (int m = 0; m < 4; ++m) _Pragma("unroll") for (int n = 0; n < 2; ++n) _Pragma("unroll") for (int k = 0; k < 2; ++k) \
;         acc[ai][bj][m][n] = __builtin_amdgcn_mfma_f32_16x16x32_bf16(Bt[n][k], At[m][k], acc[ai][bj][m][n], 0, 0, 0); __builtin_amdgcn_s_setprio(0); } while (0)
; #define PG8_WAIT_V(n) asm volatile("s_waitcnt vmcnt(" #n ")" ::: "memory")
; #define PG8_WAIT_L(n) asm volatile("s_waitcnt lgkmcnt(" #n ")" ::: "memory")
; #define PG8_BAR __builtin_amdgcn_s_barrier()
; #define PG8_SCHED __builtin_amdgcn_sched_barrier(0)
; template <class Epi>
; DI void gemm_phase(LAS unsigned char* lds, const Gemm g, const StaticOrder& S, const Epi& E) {
;     ...
;             PG8_WAIT_L(8); PG8_BAR; PG8_WAIT_L(0); PG8_MMA(0, 0, At, B0); PG8_BAR; PG8_SCHED;
;             PG8_LDB(B1, 1, 1); PG8_STAGE(PG8_SB(1, 0), b3, voffB);
;             PG8_BAR; PG8_WAIT_L(0); PG8_MMA(0, 1, At, B1); PG8_BAR;
;             PG8_LDA(At, 1, 1); PG8_STAGE(PG8_SA(1, 0), a3, voffA);
;             PG8_BAR; PG8_WAIT_L(0); PG8_MMA(1, 0, At, B0); PG8_BAR; PG8_SCHED;
;             PG8_STAGE(PG8_SB(1, 1), b3 + hstepB, voffB);
;             PG8_WAIT_V(6); PG8_BAR; PG8_MMA(1, 1, At, B1); PG8_BAR;
	s_waitcnt lgkmcnt(0)
	s_nop 0
	s_waitcnt lgkmcnt(0)
	v_mfma_f32_16x16x32_bf16 v[110:113], v[190:193], v[134:137], v[110:113]
	v_mfma_f32_16x16x32_bf16 v[30:33], v[220:223], v[134:137], v[30:33]
	v_mfma_f32_16x16x32_bf16 v[34:37], v[190:193], v[166:169], v[34:37]
	v_mfma_f32_16x16x32_bf16 v[38:41], v[220:223], v[166:169], v[38:41]
	v_mfma_f32_16x16x32_bf16 v[42:45], v[190:193], v[174:177], v[42:45]
	v_mfma_f32_16x16x32_bf16 v[46:49], v[220:223], v[174:177], v[46:49]
	v_mfma_f32_16x16x32_bf16 v[50:53], v[190:193], v[182:185], v[50:53]
	v_mfma_f32_16x16x32_bf16 v[54:57], v[220:223], v[182:185], v[54:57]
	v_mfma_f32_16x16x32_bf16 v[110:113], v[216:219], v[138:141], v[110:113]
	v_mfma_f32_16x16x32_bf16 v[30:33], v[224:227], v[138:141], v[30:33]
	v_mfma_f32_16x16x32_bf16 v[34:37], v[216:219], v[170:173], v[34:37]
	v_mfma_f32_16x16x32_bf16 v[38:41], v[224:227], v[170:173], v[38:41]
	v_mfma_f32_16x16x32_bf16 v[42:45], v[216:219], v[178:181], v[42:45]
	v_mfma_f32_16x16x32_bf16 v[46:49], v[224:227], v[178:181], v[46:49]
	v_mfma_f32_16x16x32_bf16 v[50:53], v[216:219], v[186:189], v[50:53]
	v_mfma_f32_16x16x32_bf16 v[54:57], v[224:227], v[186:189], v[54:57]
	s_nop 0
	s_mov_b32 m0, s9
	v_lshl_add_u64 v[230:231], s[22:23], 0, v[6:7]
	s_barrier
	ds_read_b128 v[134:137], v8 offset:16384
	ds_read_b128 v[138:141], v8 offset:17408
	ds_read_b128 v[166:169], v8 offset:18432
	ds_read_b128 v[170:173], v8 offset:19456
	ds_read_b128 v[174:177], v8 offset:20480
	ds_read_b128 v[178:181], v8 offset:21504
	ds_read_b128 v[182:185], v8 offset:22528
	ds_read_b128 v[186:189], v8 offset:23552
	global_load_lds_dwordx4 v[230:231], off
	v_lshl_add_u64 v[232:233], s[22:23], 0, v[4:5]
	s_mov_b32 m0, s36
	s_nop 0
	global_load_lds_dwordx4 v[232:233], off
	s_barrier
	s_waitcnt lgkmcnt(0)
	s_nop 0
	s_waitcnt lgkmcnt(0)
	v_mfma_f32_16x16x32_bf16 v[142:145], v[118:121], v[134:137], v[142:145]
	v_mfma_f32_16x16x32_bf16 v[146:149], v[126:129], v[134:137], v[146:149]
	v_mfma_f32_16x16x32_bf16 v[150:153], v[118:121], v[166:169], v[150:153]
	v_mfma_f32_16x16x32_bf16 v[154:157], v[126:129], v[166:169], v[154:157]
	v_mfma_f32_16x16x32_bf16 v[158:161], v[118:121], v[174:177], v[158:161]
	v_mfma_f32_16x16x32_bf16 v[162:165], v[126:129], v[174:177], v[162:165]
	v_mfma_f32_16x16x32_bf16 v[10:13], v[118:121], v[182:185], v[10:13]
	v_mfma_f32_16x16x32_bf16 v[18:21], v[126:129], v[182:185], v[18:21]
	v_mfma_f32_16x16x32_bf16 v[142:145], v[122:125], v[138:141], v[142:145]
	v_mfma_f32_16x16x32_bf16 v[146:149], v[130:133], v[138:141], v[146:149]
	v_mfma_f32_16x16x32_bf16 v[150:153], v[122:125], v[170:173], v[150:153]
	v_mfma_f32_16x16x32_bf16 v[154:157], v[130:133], v[170:173], v[154:157]
	v_mfma_f32_16x16x32_bf16 v[158:161], v[122:125], v[178:181], v[158:161]
	v_mfma_f32_16x16x32_bf16 v[162:165], v[130:133], v[178:181], v[162:165]
	v_mfma_f32_16x16x32_bf16 v[10:13], v[122:125], v[186:189], v[10:13]
	v_mfma_f32_16x16x32_bf16 v[18:21], v[130:133], v[186:189], v[18:21]
	s_nop 0
	s_barrier
	s_add_u32 s18, s4, 0x10000
	s_addc_u32 s19, s5, 0
	s_mov_b32 m0, s49
	v_lshl_add_u64 v[118:119], s[18:19], 0, v[0:1]
	global_load_lds_dwordx4 v[118:119], off
	v_lshl_add_u64 v[118:119], s[18:19], 0, v[2:3]
	s_mov_b32 m0, s46
	s_nop 0
	global_load_lds_dwordx4 v[118:119], off
	s_waitcnt vmcnt(6)
	s_barrier
	s_nop 0
	v_mfma_f32_16x16x32_bf16 v[22:25], v[190:193], v[134:137], v[22:25]
	v_mfma_f32_16x16x32_bf16 v[26:29], v[220:223], v[134:137], v[26:29]
	v_mfma_f32_16x16x32_bf16 v[58:61], v[190:193], v[166:169], v[58:61]
	v_mfma_f32_16x16x32_bf16 v[102:105], v[220:223], v[166:169], v[102:105]
	v_mfma_f32_16x16x32_bf16 v[106:109], v[190:193], v[174:177], v[106:109]
	v_mfma_f32_16x16x32_bf16 v[114:117], v[220:223], v[174:177], v[114:117]
	v_mfma_f32_16x16x32_bf16 v[94:97], v[190:193], v[182:185], v[94:97]
	v_mfma_f32_16x16x32_bf16 v[98:101], v[220:223], v[182:185], v[98:101]
	v_mfma_f32_16x16x32_bf16 v[22:25], v[216:219], v[138:141], v[22:25]
	v_mfma_f32_16x16x32_bf16 v[26:29], v[224:227], v[138:141], v[26:29]
	v_mfma_f32_16x16x32_bf16 v[58:61], v[216:219], v[170:173], v[58:61]
	v_mfma_f32_16x16x32_bf16 v[102:105], v[224:227], v[170:173], v[102:105]
	v_mfma_f32_16x16x32_bf16 v[106:109], v[216:219], v[178:181], v[106:109]
	v_mfma_f32_16x16x32_bf16 v[114:117], v[224:227], v[178:181], v[114:117]
	v_mfma_f32_16x16x32_bf16 v[94:97], v[216:219], v[186:189], v[94:97]
	v_mfma_f32_16x16x32_bf16 v[98:101], v[224:227], v[186:189], v[98:101]
	s_nop 0
	s_barrier
	ds_read_b128 v[118:121], v200
	ds_read_b128 v[122:125], v200 offset:1024
	ds_read_b128 v[126:129], v200 offset:2048
	ds_read_b128 v[130:133], v200 offset:3072
	s_add_u32 s18, s22, 0x10000
	s_addc_u32 s19, s23, 0
	s_mov_b32 m0, s37
	v_lshl_add_u64 v[190:191], s[18:19], 0, v[6:7]
	ds_read_b128 v[134:137], v8 offset:32768
	ds_read_b128 v[138:141], v8 offset:33792
	ds_read_b128 v[166:169], v8 offset:34816
	ds_read_b128 v[170:173], v8 offset:35840
	ds_read_b128 v[174:177], v8 offset:36864
	ds_read_b128 v[178:181], v8 offset:37888
	ds_read_b128 v[182:185], v8 offset:38912
	ds_read_b128 v[186:189], v8 offset:39936
	global_load_lds_dwordx4 v[190:191], off
	v_lshl_add_u64 v[190:191], s[18:19], 0, v[4:5]
	s_mov_b32 m0, s38
	s_nop 0
	global_load_lds_dwordx4 v[190:191], off
	s_waitcnt lgkmcnt(8)
	s_barrier
; #define PG8_STAGE(bufoff, gbase, voff) do { _Pragma("unroll") for (int _i = 0; _i < 2; ++_i) \
;         __builtin_amdgcn_global_load_lds((const unsigned*)((const char*)(gbase) + (voff)[_i]), (LAS unsigned*)(lds + (bufoff) + ldsw + _i * 8192), 16, 0, 0); } while (0)
; #define PG8_LDA(dst, b, h) do { _Pragma("unroll") for (int m = 0; m < 4; ++m) _Pragma("unroll") for (int k = 0; k < 2; ++k) dst[m][k] = *(const LAS bf16x8*)(lds + PG8_SA(b, h) + aoff + m * 2048 + k * 1024); } while (0)
; #define PG8_LDB(dst, b, h) do { _Pragma("unroll") for (int n = 0; n < 2; ++n) _Pragma("unroll") for (int k = 0; k < 2; ++k) dst[n][k] = *(const LAS bf16x8*)(lds + PG8_SB(b, h) + boff + n * 2048 + k * 1024); } while (0)
; #define PG8_MMA(ai, bj, At, Bt) do { __builtin_amdgcn_s_setprio(1); _Pragma("unroll") for (int m = 0; m < 4; ++m) _Pragma("unroll") for (int n = 0; n < 2; ++n) _Pragma("unroll") for (int k = 0; k < 2; ++k) \
;         acc[ai][bj][m][n] = __builtin_amdgcn_mfma_f32_16x16x32_bf16(Bt[n][k], At[m][k], acc[ai][bj][m][n], 0, 0, 0); __builtin_amdgcn_s_setprio(0); } while (0)
; #define PG8_WAIT_V(n) asm volatile("s_waitcnt vmcnt(" #n ")" ::: "memory")
; #define PG8_WAIT_L(n) asm volatile("s_waitcnt lgkmcnt(" #n ")" ::: "memory")
; #define PG8_BAR __builtin_amdgcn_s_barrier()
; #define PG8_SCHED __builtin_amdgcn_sched_barrier(0)
; template <class Epi>
; DI void gemm_phase(LAS unsigned char* lds, const Gemm g, const StaticOrder& S, const Epi& E) {
;     ...
;             PG8_WAIT_L(8); PG8_BAR; PG8_WAIT_L(0); PG8_MMA(0, 0, At, B0); PG8_BAR; PG8_SCHED;
;             PG8_LDB(B1, 1, 1); PG8_STAGE(PG8_SB(1, 0), b3, voffB);
;             PG8_BAR; PG8_WAIT_L(0); PG8_MMA(0, 1, At, B1); PG8_BAR;
;             PG8_LDA(At, 1, 1); PG8_STAGE(PG8_SA(1, 0), a3, voffA);
;             PG8_BAR; PG8_WAIT_L(0); PG8_MMA(1, 0, At, B0); PG8_BAR; PG8_SCHED;
;             PG8_STAGE(PG8_SB(1, 1), b3 + hstepB, voffB);
;             PG8_WAIT_V(6); PG8_BAR; PG8_MMA(1, 1, At, B1); PG8_BAR;
	s_waitcnt lgkmcnt(0)
	s_nop 0
	s_waitcnt lgkmcnt(0)
	v_mfma_f32_16x16x32_bf16 v[62:65], v[118:121], v[134:137], v[62:65]
	v_mfma_f32_16x16x32_bf16 v[66:69], v[126:129], v[134:137], v[66:69]
	v_mfma_f32_16x16x32_bf16 v[70:73], v[118:121], v[166:169], v[70:73]
	v_mfma_f32_16x16x32_bf16 v[74:77], v[126:129], v[166:169], v[74:77]
	v_mfma_f32_16x16x32_bf16 v[78:81], v[118:121], v[174:177], v[78:81]
	v_mfma_f32_16x16x32_bf16 v[82:85], v[126:129], v[174:177], v[82:85]
	v_mfma_f32_16x16x32_bf16 v[86:89], v[118:121], v[182:185], v[86:89]
	v_mfma_f32_16x16x32_bf16 v[90:93], v[126:129], v[182:185], v[90:93]
	v_mfma_f32_16x16x32_bf16 v[62:65], v[122:125], v[138:141], v[62:65]
	v_mfma_f32_16x16x32_bf16 v[66:69], v[130:133], v[138:141], v[66:69]
	v_mfma_f32_16x16x32_bf16 v[70:73], v[122:125], v[170:173], v[70:73]
	v_mfma_f32_16x16x32_bf16 v[74:77], v[130:133], v[170:173], v[74:77]
	v_mfma_f32_16x16x32_bf16 v[78:81], v[122:125], v[178:181], v[78:81]
	v_mfma_f32_16x16x32_bf16 v[82:85], v[130:133], v[178:181], v[82:85]
	v_mfma_f32_16x16x32_bf16 v[86:89], v[122:125], v[186:189], v[86:89]
	v_mfma_f32_16x16x32_bf16 v[90:93], v[130:133], v[186:189], v[90:93]
	s_nop 0
	s_barrier
	s_mov_b32 m0, s51
	v_lshl_add_u64 v[14:15], v[14:15], 0, s[2:3]
	ds_read_b128 v[190:193], v201
	ds_read_b128 v[216:219], v201 offset:1024
	ds_read_b128 v[220:223], v201 offset:2048
	ds_read_b128 v[224:227], v201 offset:3072
	global_load_lds_dwordx4 v[14:15], off
	v_lshl_add_u64 v[14:15], v[228:229], 0, s[2:3]
	s_mov_b32 m0, s50
	s_nop 0
	global_load_lds_dwordx4 v[14:15], off
	s_barrier
	s_waitcnt lgkmcnt(0)
	s_nop 0
	s_waitcnt lgkmcnt(0)
	v_mfma_f32_16x16x32_bf16 v[110:113], v[190:193], v[134:137], v[110:113]
	v_mfma_f32_16x16x32_bf16 v[30:33], v[220:223], v[134:137], v[30:33]
	v_mfma_f32_16x16x32_bf16 v[34:37], v[190:193], v[166:169], v[34:37]
	v_mfma_f32_16x16x32_bf16 v[38:41], v[220:223], v[166:169], v[38:41]
	v_mfma_f32_16x16x32_bf16 v[42:45], v[190:193], v[174:177], v[42:45]
	v_mfma_f32_16x16x32_bf16 v[46:49], v[220:223], v[174:177], v[46:49]
	v_mfma_f32_16x16x32_bf16 v[50:53], v[190:193], v[182:185], v[50:53]
	v_mfma_f32_16x16x32_bf16 v[54:57], v[220:223], v[182:185], v[54:57]
	v_mfma_f32_16x16x32_bf16 v[110:113], v[216:219], v[138:141], v[110:113]
	v_mfma_f32_16x16x32_bf16 v[30:33], v[224:227], v[138:141], v[30:33]
	v_mfma_f32_16x16x32_bf16 v[34:37], v[216:219], v[170:173], v[34:37]
	v_mfma_f32_16x16x32_bf16 v[38:41], v[224:227], v[170:173], v[38:41]
	v_mfma_f32_16x16x32_bf16 v[42:45], v[216:219], v[178:181], v[42:45]
	v_mfma_f32_16x16x32_bf16 v[46:49], v[224:227], v[178:181], v[46:49]
	v_mfma_f32_16x16x32_bf16 v[50:53], v[216:219], v[186:189], v[50:53]
	v_mfma_f32_16x16x32_bf16 v[54:57], v[224:227], v[186:189], v[54:57]
	s_nop 0
	s_mov_b32 m0, s39
	v_lshl_add_u64 v[14:15], v[230:231], 0, s[2:3]
	s_barrier
	ds_read_b128 v[134:137], v8 offset:49152
	ds_read_b128 v[138:141], v8 offset:50176
	ds_read_b128 v[166:169], v8 offset:51200
	ds_read_b128 v[170:173], v8 offset:52224
	ds_read_b128 v[174:177], v8 offset:53248
	ds_read_b128 v[178:181], v8 offset:54272
	ds_read_b128 v[182:185], v8 offset:55296
	ds_read_b128 v[186:189], v8 offset:56320
	global_load_lds_dwordx4 v[14:15], off
	v_lshl_add_u64 v[14:15], v[232:233], 0, s[2:3]
	s_mov_b32 m0, s40
	s_nop 0
	global_load_lds_dwordx4 v[14:15], off
	s_barrier
	s_waitcnt lgkmcnt(0)
	s_nop 0
	s_waitcnt lgkmcnt(0)
	v_mfma_f32_16x16x32_bf16 v[142:145], v[118:121], v[134:137], v[142:145]
	v_mfma_f32_16x16x32_bf16 v[146:149], v[126:129], v[134:137], v[146:149]
	v_mfma_f32_16x16x32_bf16 v[150:153], v[118:121], v[166:169], v[150:153]
	v_mfma_f32_16x16x32_bf16 v[154:157], v[126:129], v[166:169], v[154:157]
	v_mfma_f32_16x16x32_bf16 v[158:161], v[118:121], v[174:177], v[158:161]
	v_mfma_f32_16x16x32_bf16 v[162:165], v[126:129], v[174:177], v[162:165]
	v_mfma_f32_16x16x32_bf16 v[10:13], v[118:121], v[182:185], v[10:13]
	v_mfma_f32_16x16x32_bf16 v[18:21], v[126:129], v[182:185], v[18:21]
	v_mfma_f32_16x16x32_bf16 v[142:145], v[122:125], v[138:141], v[142:145]
	v_mfma_f32_16x16x32_bf16 v[146:149], v[130:133], v[138:141], v[146:149]
	v_mfma_f32_16x16x32_bf16 v[150:153], v[122:125], v[170:173], v[150:153]
	v_mfma_f32_16x16x32_bf16 v[154:157], v[130:133], v[170:173], v[154:157]
	v_mfma_f32_16x16x32_bf16 v[158:161], v[122:125], v[178:181], v[158:161]
	v_mfma_f32_16x16x32_bf16 v[162:165], v[130:133], v[178:181], v[162:165]
	v_mfma_f32_16x16x32_bf16 v[10:13], v[122:125], v[186:189], v[10:13]
	v_mfma_f32_16x16x32_bf16 v[18:21], v[130:133], v[186:189], v[18:21]
	s_nop 0
	s_barrier
	s_add_u32 s4, s4, 0x10080
	s_addc_u32 s5, s5, 0
	s_mov_b32 m0, s21
	v_lshl_add_u64 v[14:15], s[4:5], 0, v[0:1]
	global_load_lds_dwordx4 v[14:15], off
	v_lshl_add_u64 v[14:15], s[4:5], 0, v[2:3]
	s_mov_b32 m0, s20
	s_nop 0
	global_load_lds_dwordx4 v[14:15], off
	s_waitcnt vmcnt(6)
	s_barrier
	s_nop 0
	v_mfma_f32_16x16x32_bf16 v[22:25], v[190:193], v[134:137], v[22:25]
	v_mfma_f32_16x16x32_bf16 v[26:29], v[220:223], v[134:137], v[26:29]
	v_mfma_f32_16x16x32_bf16 v[58:61], v[190:193], v[166:169], v[58:61]
	v_mfma_f32_16x16x32_bf16 v[102:105], v[220:223], v[166:169], v[102:105]
	v_mfma_f32_16x16x32_bf16 v[106:109], v[190:193], v[174:177], v[106:109]
	v_mfma_f32_16x16x32_bf16 v[114:117], v[220:223], v[174:177], v[114:117]
	v_mfma_f32_16x16x32_bf16 v[94:97], v[190:193], v[182:185], v[94:97]
	v_mfma_f32_16x16x32_bf16 v[98:101], v[220:223], v[182:185], v[98:101]
	v_mfma_f32_16x16x32_bf16 v[22:25], v[216:219], v[138:141], v[22:25]
	v_mfma_f32_16x16x32_bf16 v[26:29], v[224:227], v[138:141], v[26:29]
	v_mfma_f32_16x16x32_bf16 v[58:61], v[216:219], v[170:173], v[58:61]
	v_mfma_f32_16x16x32_bf16 v[102:105], v[224:227], v[170:173], v[102:105]
	v_mfma_f32_16x16x32_bf16 v[106:109], v[216:219], v[178:181], v[106:109]
	v_mfma_f32_16x16x32_bf16 v[114:117], v[224:227], v[178:181], v[114:117]
	v_mfma_f32_16x16x32_bf16 v[94:97], v[216:219], v[186:189], v[94:97]
	v_mfma_f32_16x16x32_bf16 v[98:101], v[224:227], v[186:189], v[98:101]
	s_nop 0
	v_mov_b32_e32 v9, v238
	s_barrier
	s_lshl_b32 s8, s8, 8
	s_cmp_gt_i32 s44, 3
	v_ashrrev_i32_e32 v14, 2, v9
	v_and_b32_e32 v15, 0xffffffc0, v14
	v_lshrrev_b32_e32 v14, 1, v9
	v_and_or_b32 v9, v9, 15, s8
	v_readlane_b32 s4, v254, 52
	v_and_b32_e32 v14, 0x78, v14
	v_add_u32_e32 v118, v9, v15
	v_readlane_b32 s5, v254, 53
	v_lshl_or_b32 v14, s44, 8, v14
	v_ashrrev_i32_e32 v119, 31, v118
	s_cselect_b32 s8, 9, 10
	s_cselect_b32 s5, s42, s5
	s_cselect_b32 s4, s41, s4
	v_lshlrev_b64 v[120:121], s8, v[118:119]
	v_ashrrev_i32_e32 v15, 31, v14
	v_lshl_add_u64 v[120:121], v[120:121], 1, s[4:5]
	v_lshlrev_b64 v[14:15], 1, v[14:15]
	v_cvt_pk_bf16_f32 v62, v62, v63
	v_cvt_pk_bf16_f32 v63, v64, v65
	v_cvt_pk_bf16_f32 v64, v66, v67
	v_cvt_pk_bf16_f32 v65, v68, v69
	v_lshl_add_u64 v[66:67], v[120:121], 0, v[14:15]
	global_store_dwordx4 v[66:67], v[62:65], off
	v_cvt_pk_bf16_f32 v22, v22, v23
	v_cvt_pk_bf16_f32 v23, v24, v25
	v_cvt_pk_bf16_f32 v64, v30, v31
	v_or_b32_e32 v30, 16, v118
	v_ashrrev_i32_e32 v31, 31, v30
	v_cvt_pk_bf16_f32 v62, v110, v111
	v_cvt_pk_bf16_f32 v63, v112, v113
	v_cvt_pk_bf16_f32 v65, v32, v33
	v_lshlrev_b64 v[30:31], s8, v[30:31]
	global_store_dwordx4 v[66:67], v[62:65], off offset:256
	v_cvt_pk_bf16_f32 v32, v74, v75
	v_cvt_pk_bf16_f32 v33, v76, v77
	v_lshl_add_u64 v[62:63], v[30:31], 1, s[4:5]
	v_cvt_pk_bf16_f32 v30, v70, v71
	v_cvt_pk_bf16_f32 v31, v72, v73
	v_lshl_add_u64 v[62:63], v[62:63], 0, v[14:15]
	global_store_dwordx4 v[62:63], v[30:33], off
	v_cvt_pk_bf16_f32 v24, v26, v27
	v_cvt_pk_bf16_f32 v25, v28, v29
	v_cvt_pk_bf16_f32 v30, v34, v35
	v_cvt_pk_bf16_f32 v31, v36, v37
	v_cvt_pk_bf16_f32 v32, v38, v39
	v_cvt_pk_bf16_f32 v33, v40, v41
	global_store_dwordx4 v[62:63], v[30:33], off offset:256
	v_cvt_pk_bf16_f32 v10, v10, v11
	v_cvt_pk_bf16_f32 v11, v12, v13
	v_or_b32_e32 v30, 32, v118
	v_ashrrev_i32_e32 v31, 31, v30
	v_lshlrev_b64 v[30:31], s8, v[30:31]
	v_lshl_add_u64 v[34:35], v[30:31], 1, s[4:5]
	v_cvt_pk_bf16_f32 v30, v78, v79
	v_cvt_pk_bf16_f32 v31, v80, v81
	v_cvt_pk_bf16_f32 v32, v82, v83
	v_cvt_pk_bf16_f32 v33, v84, v85
	v_lshl_add_u64 v[34:35], v[34:35], 0, v[14:15]
	global_store_dwordx4 v[34:35], v[30:33], off
	v_cvt_pk_bf16_f32 v12, v18, v19
	v_cvt_pk_bf16_f32 v13, v20, v21
	v_cvt_pk_bf16_f32 v30, v42, v43
	v_cvt_pk_bf16_f32 v31, v44, v45
	v_cvt_pk_bf16_f32 v32, v46, v47
	v_cvt_pk_bf16_f32 v33, v48, v49
	global_store_dwordx4 v[34:35], v[30:33], off offset:256
	s_add_i32 s43, s43, s24
	s_andn2_b64 vcc, exec, s[0:1]
	v_or_b32_e32 v30, 48, v118
	v_ashrrev_i32_e32 v31, 31, v30
	v_lshlrev_b64 v[30:31], s8, v[30:31]
	v_lshl_add_u64 v[34:35], v[30:31], 1, s[4:5]
	v_cvt_pk_bf16_f32 v30, v86, v87
	v_cvt_pk_bf16_f32 v31, v88, v89
	v_cvt_pk_bf16_f32 v32, v90, v91
	v_cvt_pk_bf16_f32 v33, v92, v93
	v_lshl_add_u64 v[34:35], v[34:35], 0, v[14:15]
	global_store_dwordx4 v[34:35], v[30:33], off
	s_mov_b32 s44, s10
	s_mov_b64 s[20:21], s[16:17]
	v_cvt_pk_bf16_f32 v30, v50, v51
	v_cvt_pk_bf16_f32 v31, v52, v53
	v_cvt_pk_bf16_f32 v32, v54, v55
	v_cvt_pk_bf16_f32 v33, v56, v57
	global_store_dwordx4 v[34:35], v[30:33], off offset:256
	s_mov_b64 s[18:19], s[14:15]
	s_nop 0
	v_add_u32_e32 v30, 0x80, v118
	v_ashrrev_i32_e32 v31, 31, v30
	v_lshlrev_b64 v[30:31], s8, v[30:31]
	v_lshl_add_u64 v[34:35], v[30:31], 1, s[4:5]
	v_lshl_add_u64 v[34:35], v[34:35], 0, v[14:15]
	global_store_dwordx4 v[34:35], v[22:25], off offset:256
	v_cvt_pk_bf16_f32 v30, v142, v143
	v_cvt_pk_bf16_f32 v31, v144, v145
	v_add_u32_e32 v22, 0x90, v118
	v_ashrrev_i32_e32 v23, 31, v22
	v_lshlrev_b64 v[22:23], s8, v[22:23]
	v_lshl_add_u64 v[26:27], v[22:23], 1, s[4:5]
	v_cvt_pk_bf16_f32 v32, v146, v147
	v_cvt_pk_bf16_f32 v33, v148, v149
	v_cvt_pk_bf16_f32 v22, v150, v151
	v_cvt_pk_bf16_f32 v23, v152, v153
	v_cvt_pk_bf16_f32 v24, v154, v155
	v_cvt_pk_bf16_f32 v25, v156, v157
	v_lshl_add_u64 v[26:27], v[26:27], 0, v[14:15]
	global_store_dwordx4 v[34:35], v[30:33], off
	global_store_dwordx4 v[26:27], v[22:25], off
	s_nop 1
	v_cvt_pk_bf16_f32 v22, v58, v59
	v_cvt_pk_bf16_f32 v23, v60, v61
	v_cvt_pk_bf16_f32 v24, v102, v103
	v_cvt_pk_bf16_f32 v25, v104, v105
	global_store_dwordx4 v[26:27], v[22:25], off offset:256
	s_nop 1
	v_add_u32_e32 v22, 0xa0, v118
	v_ashrrev_i32_e32 v23, 31, v22
	v_lshlrev_b64 v[22:23], s8, v[22:23]
	v_lshl_add_u64 v[26:27], v[22:23], 1, s[4:5]
	v_cvt_pk_bf16_f32 v22, v158, v159
	v_cvt_pk_bf16_f32 v23, v160, v161
	v_cvt_pk_bf16_f32 v24, v162, v163
	v_cvt_pk_bf16_f32 v25, v164, v165
	v_lshl_add_u64 v[26:27], v[26:27], 0, v[14:15]
	global_store_dwordx4 v[26:27], v[22:25], off
	s_nop 1
	v_cvt_pk_bf16_f32 v22, v106, v107
	v_cvt_pk_bf16_f32 v23, v108, v109
	v_cvt_pk_bf16_f32 v24, v114, v115
	v_cvt_pk_bf16_f32 v25, v116, v117
	global_store_dwordx4 v[26:27], v[22:25], off offset:256
	s_nop 1
	v_add_u32_e32 v22, 0xb0, v118
	v_ashrrev_i32_e32 v23, 31, v22
	v_lshlrev_b64 v[22:23], s8, v[22:23]
	v_lshl_add_u64 v[22:23], v[22:23], 1, s[4:5]
	v_lshl_add_u64 v[14:15], v[22:23], 0, v[14:15]
	global_store_dwordx4 v[14:15], v[10:13], off
	s_mov_b32 s8, s12
	s_nop 0
	v_cvt_pk_bf16_f32 v10, v94, v95
	v_cvt_pk_bf16_f32 v11, v96, v97
	v_cvt_pk_bf16_f32 v12, v98, v99
	v_cvt_pk_bf16_f32 v13, v100, v101
	global_store_dwordx4 v[14:15], v[10:13], off offset:256
	s_cbranch_vccz .LBB0_817

; #define PG8_STAGE(bufoff, gbase, voff) do { _Pragma("unroll") for (int _i = 0; _i < 2; ++_i) \
;         __builtin_amdgcn_global_load_lds((const unsigned*)((const char*)(gbase) + (voff)[_i]), (LAS unsigned*)(lds + (bufoff) + ldsw + _i * 8192), 16, 0, 0); } while (0)
; #define PG8_LDA(dst, b, h) do { _Pragma("unroll") for (int m = 0; m < 4; ++m) _Pragma("unroll") for (int k = 0; k < 2; ++k) dst[m][k] = *(const LAS bf16x8*)(lds + PG8_SA(b, h) + aoff + m * 2048 + k * 1024); } while (0)
; #define PG8_LDB(dst, b, h) do { _Pragma("unroll") for (int n = 0; n < 2; ++n) _Pragma("unroll") for (int k = 0; k < 2; ++k) dst[n][k] = *(const LAS bf16x8*)(lds + PG8_SB(b, h) + boff + n * 2048 + k * 1024); } while (0)
; #define PG8_MMA(ai, bj, At, Bt) do { __builtin_amdgcn_s_setprio(1); _Pragma("unroll") for (int m = 0; m < 4; ++m) _Pragma("unroll") for (int n = 0; n < 2; ++n) _Pragma("unroll") for (int k = 0; k < 2; ++k) \
;         acc[ai][bj][m][n] = __builtin_amdgcn_mfma_f32_16x16x32_bf16(Bt[n][k], At[m][k], acc[ai][bj][m][n], 0, 0, 0); __builtin_amdgcn_s_setprio(0); } while (0)
; template <class Epi>
; DI void gemm_phase(LAS unsigned char* lds, const Gemm g, const StaticOrder& S, const Epi& E) {
;     ...
;         for (int t = 0; t < nt; t += 2) {
;             const bool last = (t == nt - 2);
;             const char* a1 = cA + (size_t)(t + 1) * kstep;
;             const char* a2 = last ? nA : cA + (size_t)(t + 2) * kstep; const char* b2 = last ? nB : cB + (size_t)(t + 2) * kstep;
;             const char* a3 = a2 + kstep; const char* b3 = b2 + kstep;
;             PG8_LDB(B0, 0, 0); PG8_SCHED; PG8_LDA(At, 0, 0); PG8_STAGE(PG8_SA(1, 1), a1 + hstepA, voffA);
;             PG8_WAIT_L(8); PG8_BAR; PG8_WAIT_L(0); PG8_MMA(0, 0, At, B0); PG8_BAR; PG8_SCHED;
;             PG8_LDB(B1, 0, 1); PG8_STAGE(PG8_SB(0, 0), b2, voffB);
;             PG8_BAR; PG8_WAIT_L(0); PG8_MMA(0, 1, At, B1); PG8_BAR;
;             PG8_LDA(At, 0, 1); PG8_STAGE(PG8_SA(0, 0), a2, voffA);
;             PG8_BAR; PG8_WAIT_L(0); PG8_MMA(1, 0, At, B0); PG8_BAR; PG8_SCHED;
;             PG8_STAGE(PG8_SB(0, 1), b2 + hstepB, voffB);
;             PG8_WAIT_V(6); PG8_BAR; PG8_MMA(1, 1, At, B1); PG8_BAR;
;             PG8_LDB(B0, 1, 0); PG8_SCHED; PG8_LDA(At, 1, 0); PG8_STAGE(PG8_SA(0, 1), a2 + hstepA, voffA);
;             PG8_WAIT_L(8); PG8_BAR; PG8_WAIT_L(0); PG8_MMA(0, 0, At, B0); PG8_BAR; PG8_SCHED;
.LBB0_841:
	s_add_u32 s22, s20, 0xfffc0080
	s_addc_u32 s23, s21, -1
	s_add_i32 s57, 0, 0x10000
	v_add_u32_e32 v150, s57, v136
	ds_read_b128 v[138:141], v150
	ds_read_b128 v[142:145], v150 offset:1024
	ds_read_b128 v[146:149], v150 offset:2048
	ds_read_b128 v[150:153], v150 offset:3072
	s_cmp_eq_u32 s56, 12
	s_cselect_b32 s29, s15, s23
	s_cselect_b32 s28, s52, s22
	s_cselect_b32 s23, s13, s55
	s_cselect_b32 s22, s53, s54
	v_lshl_add_u64 v[186:187], s[20:21], 0, v[134:135]
	s_add_i32 m0, s9, 0xc000
	ds_read_b128 v[154:157], v137
	ds_read_b128 v[158:161], v137 offset:1024
	ds_read_b128 v[162:165], v137 offset:2048
	ds_read_b128 v[166:169], v137 offset:3072
	ds_read_b128 v[170:173], v137 offset:4096
	ds_read_b128 v[174:177], v137 offset:5120
	ds_read_b128 v[178:181], v137 offset:6144
	ds_read_b128 v[182:185], v137 offset:7168
	global_load_lds_dwordx4 v[186:187], off
	v_lshl_add_u64 v[186:187], s[20:21], 0, v[132:133]
	s_add_i32 m0, s9, 0xe000
	s_nop 0
	global_load_lds_dwordx4 v[186:187], off
	s_waitcnt lgkmcnt(8)
	s_barrier
	s_waitcnt lgkmcnt(0)
	s_nop 0
	s_waitcnt lgkmcnt(0)
	v_mfma_f32_16x16x32_bf16 v[126:129], v[138:141], v[154:157], v[126:129]
	v_mfma_f32_16x16x32_bf16 v[122:125], v[146:149], v[154:157], v[122:125]
	v_mfma_f32_16x16x32_bf16 v[118:121], v[138:141], v[162:165], v[118:121]
	v_mfma_f32_16x16x32_bf16 v[114:117], v[146:149], v[162:165], v[114:117]
	v_mfma_f32_16x16x32_bf16 v[106:109], v[138:141], v[170:173], v[106:109]
	v_mfma_f32_16x16x32_bf16 v[98:101], v[146:149], v[170:173], v[98:101]
	v_mfma_f32_16x16x32_bf16 v[90:93], v[138:141], v[178:181], v[90:93]
	v_mfma_f32_16x16x32_bf16 v[82:85], v[146:149], v[178:181], v[82:85]
	v_mfma_f32_16x16x32_bf16 v[126:129], v[142:145], v[158:161], v[126:129]
	v_mfma_f32_16x16x32_bf16 v[122:125], v[150:153], v[158:161], v[122:125]
	v_mfma_f32_16x16x32_bf16 v[118:121], v[142:145], v[166:169], v[118:121]
	v_mfma_f32_16x16x32_bf16 v[114:117], v[150:153], v[166:169], v[114:117]
	v_mfma_f32_16x16x32_bf16 v[106:109], v[142:145], v[174:177], v[106:109]
	v_mfma_f32_16x16x32_bf16 v[98:101], v[150:153], v[174:177], v[98:101]
	v_mfma_f32_16x16x32_bf16 v[90:93], v[142:145], v[182:185], v[90:93]
	v_mfma_f32_16x16x32_bf16 v[82:85], v[150:153], v[182:185], v[82:85]
	s_nop 0
	s_barrier
	s_add_i32 s60, 0, 0x14000
	s_add_i32 s57, s57, s43
	v_add_u32_e32 v200, s60, v136
	v_lshl_add_u64 v[224:225], s[22:23], 0, v[0:1]
	s_mov_b32 m0, s57
	ds_read_b128 v[186:189], v200
	ds_read_b128 v[190:193], v200 offset:1024
	ds_read_b128 v[216:219], v200 offset:2048
	ds_read_b128 v[220:223], v200 offset:3072
	global_load_lds_dwordx4 v[224:225], off
	v_lshl_add_u64 v[226:227], s[22:23], 0, v[130:131]
	s_add_i32 m0, s57, 0x2000
	s_nop 0
	global_load_lds_dwordx4 v[226:227], off
	s_barrier
	s_waitcnt lgkmcnt(0)
	s_nop 0
	s_waitcnt lgkmcnt(0)
	v_mfma_f32_16x16x32_bf16 v[110:113], v[186:189], v[154:157], v[110:113]
	v_mfma_f32_16x16x32_bf16 v[102:105], v[216:219], v[154:157], v[102:105]
	v_mfma_f32_16x16x32_bf16 v[94:97], v[186:189], v[162:165], v[94:97]
	v_mfma_f32_16x16x32_bf16 v[86:89], v[216:219], v[162:165], v[86:89]
	v_mfma_f32_16x16x32_bf16 v[78:81], v[186:189], v[170:173], v[78:81]
	v_mfma_f32_16x16x32_bf16 v[74:77], v[216:219], v[170:173], v[74:77]
	v_mfma_f32_16x16x32_bf16 v[70:73], v[186:189], v[178:181], v[70:73]
	v_mfma_f32_16x16x32_bf16 v[66:69], v[216:219], v[178:181], v[66:69]
	v_mfma_f32_16x16x32_bf16 v[110:113], v[190:193], v[158:161], v[110:113]
	v_mfma_f32_16x16x32_bf16 v[102:105], v[220:223], v[158:161], v[102:105]
	v_mfma_f32_16x16x32_bf16 v[94:97], v[190:193], v[166:169], v[94:97]
	v_mfma_f32_16x16x32_bf16 v[86:89], v[220:223], v[166:169], v[86:89]
	v_mfma_f32_16x16x32_bf16 v[78:81], v[190:193], v[174:177], v[78:81]
	v_mfma_f32_16x16x32_bf16 v[74:77], v[220:223], v[174:177], v[74:77]
	v_mfma_f32_16x16x32_bf16 v[70:73], v[190:193], v[182:185], v[70:73]
	v_mfma_f32_16x16x32_bf16 v[66:69], v[220:223], v[182:185], v[66:69]
	s_nop 0
	s_mov_b32 m0, s9
	v_lshl_add_u64 v[228:229], s[28:29], 0, v[0:1]
	s_barrier
	ds_read_b128 v[154:157], v137 offset:16384
	ds_read_b128 v[158:161], v137 offset:17408
	ds_read_b128 v[162:165], v137 offset:18432
	ds_read_b128 v[166:169], v137 offset:19456
	ds_read_b128 v[170:173], v137 offset:20480
	ds_read_b128 v[174:177], v137 offset:21504
	ds_read_b128 v[178:181], v137 offset:22528
	ds_read_b128 v[182:185], v137 offset:23552
	global_load_lds_dwordx4 v[228:229], off
	v_lshl_add_u64 v[230:231], s[28:29], 0, v[130:131]
	s_mov_b32 m0, s44
	s_nop 0
	global_load_lds_dwordx4 v[230:231], off
	s_barrier
	s_waitcnt lgkmcnt(0)
	s_nop 0
	s_waitcnt lgkmcnt(0)
	v_mfma_f32_16x16x32_bf16 v[62:65], v[138:141], v[154:157], v[62:65]
	v_mfma_f32_16x16x32_bf16 v[58:61], v[146:149], v[154:157], v[58:61]
	v_mfma_f32_16x16x32_bf16 v[54:57], v[138:141], v[162:165], v[54:57]
	v_mfma_f32_16x16x32_bf16 v[50:53], v[146:149], v[162:165], v[50:53]
	v_mfma_f32_16x16x32_bf16 v[38:41], v[138:141], v[170:173], v[38:41]
	v_mfma_f32_16x16x32_bf16 v[34:37], v[146:149], v[170:173], v[34:37]
	v_mfma_f32_16x16x32_bf16 v[22:25], v[138:141], v[178:181], v[22:25]
	v_mfma_f32_16x16x32_bf16 v[18:21], v[146:149], v[178:181], v[18:21]
	v_mfma_f32_16x16x32_bf16 v[62:65], v[142:145], v[158:161], v[62:65]
	v_mfma_f32_16x16x32_bf16 v[58:61], v[150:153], v[158:161], v[58:61]
	v_mfma_f32_16x16x32_bf16 v[54:57], v[142:145], v[166:169], v[54:57]
	v_mfma_f32_16x16x32_bf16 v[50:53], v[150:153], v[166:169], v[50:53]
	v_mfma_f32_16x16x32_bf16 v[38:41], v[142:145], v[174:177], v[38:41]
	v_mfma_f32_16x16x32_bf16 v[34:37], v[150:153], v[174:177], v[34:37]
	v_mfma_f32_16x16x32_bf16 v[22:25], v[142:145], v[182:185], v[22:25]
	v_mfma_f32_16x16x32_bf16 v[18:21], v[150:153], v[182:185], v[18:21]
	s_nop 0
	s_barrier
; #define PG8_STAGE(bufoff, gbase, voff) do { _Pragma("unroll") for (int _i = 0; _i < 2; ++_i) \
;         __builtin_amdgcn_global_load_lds((const unsigned*)((const char*)(gbase) + (voff)[_i]), (LAS unsigned*)(lds + (bufoff) + ldsw + _i * 8192), 16, 0, 0); } while (0)
; #define PG8_LDA(dst, b, h) do { _Pragma("unroll") for (int m = 0; m < 4; ++m) _Pragma("unroll") for (int k = 0; k < 2; ++k) dst[m][k] = *(const LAS bf16x8*)(lds + PG8_SA(b, h) + aoff + m * 2048 + k * 1024); } while (0)
; #define PG8_LDB(dst, b, h) do { _Pragma("unroll") for (int n = 0; n < 2; ++n) _Pragma("unroll") for (int k = 0; k < 2; ++k) dst[n][k] = *(const LAS bf16x8*)(lds + PG8_SB(b, h) + boff + n * 2048 + k * 1024); } while (0)
; #define PG8_MMA(ai, bj, At, Bt) do { __builtin_amdgcn_s_setprio(1); _Pragma("unroll") for (int m = 0; m < 4; ++m) _Pragma("unroll") for (int n = 0; n < 2; ++n) _Pragma("unroll") for (int k = 0; k < 2; ++k) \
;         acc[ai][bj][m][n] = __builtin_amdgcn_mfma_f32_16x16x32_bf16(Bt[n][k], At[m][k], acc[ai][bj][m][n], 0, 0, 0); __builtin_amdgcn_s_setprio(0); } while (0)
; #define PG8_WAIT_V(n) asm volatile("s_waitcnt vmcnt(" #n ")" ::: "memory")
; #define PG8_WAIT_L(n) asm volatile("s_waitcnt lgkmcnt(" #n ")" ::: "memory")
; #define PG8_BAR __builtin_amdgcn_s_barrier()
; #define PG8_SCHED __builtin_amdgcn_sched_barrier(0)
; template <class Epi>
; DI void gemm_phase(LAS unsigned char* lds, const Gemm g, const StaticOrder& S, const Epi& E) {
;     ...
;             PG8_BAR; PG8_WAIT_L(0); PG8_MMA(0, 1, At, B1); PG8_BAR;
;             PG8_LDA(At, 0, 1); PG8_STAGE(PG8_SA(0, 0), a2, voffA);
;             PG8_BAR; PG8_WAIT_L(0); PG8_MMA(1, 0, At, B0); PG8_BAR; PG8_SCHED;
;             PG8_STAGE(PG8_SB(0, 1), b2 + hstepB, voffB);
;             PG8_WAIT_V(6); PG8_BAR; PG8_MMA(1, 1, At, B1); PG8_BAR;
;             PG8_LDB(B0, 1, 0); PG8_SCHED; PG8_LDA(At, 1, 0); PG8_STAGE(PG8_SA(0, 1), a2 + hstepA, voffA);
;             PG8_WAIT_L(8); PG8_BAR; PG8_WAIT_L(0); PG8_MMA(0, 0, At, B0); PG8_BAR; PG8_SCHED;
;             PG8_LDB(B1, 1, 1); PG8_STAGE(PG8_SB(1, 0), b3, voffB);
;             PG8_BAR; PG8_WAIT_L(0); PG8_MMA(0, 1, At, B1); PG8_BAR;
;             PG8_LDA(At, 1, 1); PG8_STAGE(PG8_SA(1, 0), a3, voffA);
;             PG8_BAR; PG8_WAIT_L(0); PG8_MMA(1, 0, At, B0); PG8_BAR; PG8_SCHED;
	s_add_u32 s58, s22, 0x40000
	s_addc_u32 s59, s23, 0
	s_add_i32 s57, s60, s43
	v_lshl_add_u64 v[138:139], s[58:59], 0, v[0:1]
	s_mov_b32 m0, s57
	s_nop 0
	global_load_lds_dwordx4 v[138:139], off
	v_lshl_add_u64 v[138:139], s[58:59], 0, v[130:131]
	s_add_i32 m0, s57, 0x2000
	s_nop 0
	global_load_lds_dwordx4 v[138:139], off
	s_waitcnt vmcnt(6)
	s_barrier
	s_nop 0
	v_mfma_f32_16x16x32_bf16 v[46:49], v[186:189], v[154:157], v[46:49]
	v_mfma_f32_16x16x32_bf16 v[42:45], v[216:219], v[154:157], v[42:45]
	v_mfma_f32_16x16x32_bf16 v[30:33], v[186:189], v[162:165], v[30:33]
	v_mfma_f32_16x16x32_bf16 v[26:29], v[216:219], v[162:165], v[26:29]
	v_mfma_f32_16x16x32_bf16 v[14:17], v[186:189], v[170:173], v[14:17]
	v_mfma_f32_16x16x32_bf16 v[10:13], v[216:219], v[170:173], v[10:13]
	v_mfma_f32_16x16x32_bf16 v[6:9], v[186:189], v[178:181], v[6:9]
	v_mfma_f32_16x16x32_bf16 v[2:5], v[216:219], v[178:181], v[2:5]
	v_mfma_f32_16x16x32_bf16 v[46:49], v[190:193], v[158:161], v[46:49]
	v_mfma_f32_16x16x32_bf16 v[42:45], v[220:223], v[158:161], v[42:45]
	v_mfma_f32_16x16x32_bf16 v[30:33], v[190:193], v[166:169], v[30:33]
	v_mfma_f32_16x16x32_bf16 v[26:29], v[220:223], v[166:169], v[26:29]
	v_mfma_f32_16x16x32_bf16 v[14:17], v[190:193], v[174:177], v[14:17]
	v_mfma_f32_16x16x32_bf16 v[10:13], v[220:223], v[174:177], v[10:13]
	v_mfma_f32_16x16x32_bf16 v[6:9], v[190:193], v[182:185], v[6:9]
	v_mfma_f32_16x16x32_bf16 v[2:5], v[220:223], v[182:185], v[2:5]
	s_nop 0
	s_add_i32 s57, 0, 0x18000
	v_add_u32_e32 v150, s57, v136
	s_barrier
	ds_read_b128 v[138:141], v150
	ds_read_b128 v[142:145], v150 offset:1024
	ds_read_b128 v[146:149], v150 offset:2048
	ds_read_b128 v[150:153], v150 offset:3072
	s_add_u32 s28, s28, 0x40000
	s_addc_u32 s29, s29, 0
	s_mov_b32 m0, s46
	v_lshl_add_u64 v[186:187], s[28:29], 0, v[0:1]
	ds_read_b128 v[154:157], v137 offset:32768
	ds_read_b128 v[158:161], v137 offset:33792
	ds_read_b128 v[162:165], v137 offset:34816
	ds_read_b128 v[166:169], v137 offset:35840
	ds_read_b128 v[170:173], v137 offset:36864
	ds_read_b128 v[174:177], v137 offset:37888
	ds_read_b128 v[178:181], v137 offset:38912
	ds_read_b128 v[182:185], v137 offset:39936
	global_load_lds_dwordx4 v[186:187], off
	v_lshl_add_u64 v[186:187], s[28:29], 0, v[130:131]
	s_mov_b32 m0, s47
	s_nop 0
	global_load_lds_dwordx4 v[186:187], off
	s_waitcnt lgkmcnt(8)
	s_barrier
	s_waitcnt lgkmcnt(0)
	s_nop 0
	s_waitcnt lgkmcnt(0)
	v_mfma_f32_16x16x32_bf16 v[126:129], v[138:141], v[154:157], v[126:129]
	v_mfma_f32_16x16x32_bf16 v[122:125], v[146:149], v[154:157], v[122:125]
	v_mfma_f32_16x16x32_bf16 v[118:121], v[138:141], v[162:165], v[118:121]
	v_mfma_f32_16x16x32_bf16 v[114:117], v[146:149], v[162:165], v[114:117]
	v_mfma_f32_16x16x32_bf16 v[106:109], v[138:141], v[170:173], v[106:109]
	v_mfma_f32_16x16x32_bf16 v[98:101], v[146:149], v[170:173], v[98:101]
	v_mfma_f32_16x16x32_bf16 v[90:93], v[138:141], v[178:181], v[90:93]
	v_mfma_f32_16x16x32_bf16 v[82:85], v[146:149], v[178:181], v[82:85]
	v_mfma_f32_16x16x32_bf16 v[126:129], v[142:145], v[158:161], v[126:129]
	v_mfma_f32_16x16x32_bf16 v[122:125], v[150:153], v[158:161], v[122:125]
	v_mfma_f32_16x16x32_bf16 v[118:121], v[142:145], v[166:169], v[118:121]
	v_mfma_f32_16x16x32_bf16 v[114:117], v[150:153], v[166:169], v[114:117]
	v_mfma_f32_16x16x32_bf16 v[106:109], v[142:145], v[174:177], v[106:109]
	v_mfma_f32_16x16x32_bf16 v[98:101], v[150:153], v[174:177], v[98:101]
	v_mfma_f32_16x16x32_bf16 v[90:93], v[142:145], v[182:185], v[90:93]
	v_mfma_f32_16x16x32_bf16 v[82:85], v[150:153], v[182:185], v[82:85]
	s_nop 0
	s_barrier
	s_add_i32 s28, 0, 0x1c000
	s_add_i32 s29, s57, s43
	v_add_u32_e32 v200, s28, v136
	v_lshl_add_u64 v[224:225], v[224:225], 0, s[2:3]
	s_mov_b32 m0, s29
	ds_read_b128 v[186:189], v200
	ds_read_b128 v[190:193], v200 offset:1024
	ds_read_b128 v[216:219], v200 offset:2048
	ds_read_b128 v[220:223], v200 offset:3072
	global_load_lds_dwordx4 v[224:225], off
	v_lshl_add_u64 v[224:225], v[226:227], 0, s[2:3]
	s_add_i32 m0, s29, 0x2000
	s_nop 0
	global_load_lds_dwordx4 v[224:225], off
	s_barrier
	s_waitcnt lgkmcnt(0)
	s_nop 0
	s_waitcnt lgkmcnt(0)
	v_mfma_f32_16x16x32_bf16 v[110:113], v[186:189], v[154:157], v[110:113]
	v_mfma_f32_16x16x32_bf16 v[102:105], v[216:219], v[154:157], v[102:105]
	v_mfma_f32_16x16x32_bf16 v[94:97], v[186:189], v[162:165], v[94:97]
	v_mfma_f32_16x16x32_bf16 v[86:89], v[216:219], v[162:165], v[86:89]
	v_mfma_f32_16x16x32_bf16 v[78:81], v[186:189], v[170:173], v[78:81]
	v_mfma_f32_16x16x32_bf16 v[74:77], v[216:219], v[170:173], v[74:77]
	v_mfma_f32_16x16x32_bf16 v[70:73], v[186:189], v[178:181], v[70:73]
	v_mfma_f32_16x16x32_bf16 v[66:69], v[216:219], v[178:181], v[66:69]
	v_mfma_f32_16x16x32_bf16 v[110:113], v[190:193], v[158:161], v[110:113]
	v_mfma_f32_16x16x32_bf16 v[102:105], v[220:223], v[158:161], v[102:105]
	v_mfma_f32_16x16x32_bf16 v[94:97], v[190:193], v[166:169], v[94:97]
	v_mfma_f32_16x16x32_bf16 v[86:89], v[220:223], v[166:169], v[86:89]
	v_mfma_f32_16x16x32_bf16 v[78:81], v[190:193], v[174:177], v[78:81]
	v_mfma_f32_16x16x32_bf16 v[74:77], v[220:223], v[174:177], v[74:77]
	v_mfma_f32_16x16x32_bf16 v[70:73], v[190:193], v[182:185], v[70:73]
	v_mfma_f32_16x16x32_bf16 v[66:69], v[220:223], v[182:185], v[66:69]
	s_nop 0
	s_mov_b32 m0, s48
	v_lshl_add_u64 v[224:225], v[228:229], 0, s[2:3]
	s_barrier
	ds_read_b128 v[154:157], v137 offset:49152
	ds_read_b128 v[158:161], v137 offset:50176
	ds_read_b128 v[162:165], v137 offset:51200
	ds_read_b128 v[166:169], v137 offset:52224
	ds_read_b128 v[170:173], v137 offset:53248
	ds_read_b128 v[174:177], v137 offset:54272
	ds_read_b128 v[178:181], v137 offset:55296
	ds_read_b128 v[182:185], v137 offset:56320
	global_load_lds_dwordx4 v[224:225], off
	v_lshl_add_u64 v[224:225], v[230:231], 0, s[2:3]
	s_mov_b32 m0, s49
	s_nop 0
	global_load_lds_dwordx4 v[224:225], off
	s_barrier
; #define PG8_STAGE(bufoff, gbase, voff) do { _Pragma("unroll") for (int _i = 0; _i < 2; ++_i) \
;         __builtin_amdgcn_global_load_lds((const unsigned*)((const char*)(gbase) + (voff)[_i]), (LAS unsigned*)(lds + (bufoff) + ldsw + _i * 8192), 16, 0, 0); } while (0)
; #define PG8_LDA(dst, b, h) do { _Pragma("unroll") for (int m = 0; m < 4; ++m) _Pragma("unroll") for (int k = 0; k < 2; ++k) dst[m][k] = *(const LAS bf16x8*)(lds + PG8_SA(b, h) + aoff + m * 2048 + k * 1024); } while (0)
; #define PG8_MMA(ai, bj, At, Bt) do { __builtin_amdgcn_s_setprio(1); _Pragma("unroll") for (int m = 0; m < 4; ++m) _Pragma("unroll") for (int n = 0; n < 2; ++n) _Pragma("unroll") for (int k = 0; k < 2; ++k) \
;         acc[ai][bj][m][n] = __builtin_amdgcn_mfma_f32_16x16x32_bf16(Bt[n][k], At[m][k], acc[ai][bj][m][n], 0, 0, 0); __builtin_amdgcn_s_setprio(0); } while (0)
; #define PG8_WAIT_V(n) asm volatile("s_waitcnt vmcnt(" #n ")" ::: "memory")
; #define PG8_WAIT_L(n) asm volatile("s_waitcnt lgkmcnt(" #n ")" ::: "memory")
; #define PG8_BAR __builtin_amdgcn_s_barrier()
; #define PG8_SCHED __builtin_amdgcn_sched_barrier(0)
; template <class Epi>
; DI void gemm_phase(LAS unsigned char* lds, const Gemm g, const StaticOrder& S, const Epi& E) {
;     ...
;             PG8_BAR; PG8_WAIT_L(0); PG8_MMA(0, 1, At, B1); PG8_BAR;
;             PG8_LDA(At, 1, 1); PG8_STAGE(PG8_SA(1, 0), a3, voffA);
;             PG8_BAR; PG8_WAIT_L(0); PG8_MMA(1, 0, At, B0); PG8_BAR; PG8_SCHED;
;             PG8_STAGE(PG8_SB(1, 1), b3 + hstepB, voffB);
;             PG8_WAIT_V(6); PG8_BAR; PG8_MMA(1, 1, At, B1); PG8_BAR;
;         }
;         E(acc, cur, wr, wc, fr, fq);
;     ...
;     PG8_WAIT_V(0);
;     if (wr == 0) PG8_BAR;
;     PG8_BAR;
	s_waitcnt lgkmcnt(0)
	s_nop 0
	s_waitcnt lgkmcnt(0)
	v_mfma_f32_16x16x32_bf16 v[62:65], v[138:141], v[154:157], v[62:65]
	v_mfma_f32_16x16x32_bf16 v[58:61], v[146:149], v[154:157], v[58:61]
	v_mfma_f32_16x16x32_bf16 v[54:57], v[138:141], v[162:165], v[54:57]
	v_mfma_f32_16x16x32_bf16 v[50:53], v[146:149], v[162:165], v[50:53]
	v_mfma_f32_16x16x32_bf16 v[38:41], v[138:141], v[170:173], v[38:41]
	v_mfma_f32_16x16x32_bf16 v[34:37], v[146:149], v[170:173], v[34:37]
	v_mfma_f32_16x16x32_bf16 v[22:25], v[138:141], v[178:181], v[22:25]
	v_mfma_f32_16x16x32_bf16 v[18:21], v[146:149], v[178:181], v[18:21]
	v_mfma_f32_16x16x32_bf16 v[62:65], v[142:145], v[158:161], v[62:65]
	v_mfma_f32_16x16x32_bf16 v[58:61], v[150:153], v[158:161], v[58:61]
	v_mfma_f32_16x16x32_bf16 v[54:57], v[142:145], v[166:169], v[54:57]
	v_mfma_f32_16x16x32_bf16 v[50:53], v[150:153], v[166:169], v[50:53]
	v_mfma_f32_16x16x32_bf16 v[38:41], v[142:145], v[174:177], v[38:41]
	v_mfma_f32_16x16x32_bf16 v[34:37], v[150:153], v[174:177], v[34:37]
	v_mfma_f32_16x16x32_bf16 v[22:25], v[142:145], v[182:185], v[22:25]
	v_mfma_f32_16x16x32_bf16 v[18:21], v[150:153], v[182:185], v[18:21]
	s_nop 0
	s_barrier
	s_add_u32 s22, s22, 0x40080
	s_addc_u32 s23, s23, 0
	s_add_i32 s28, s28, s43
	v_lshl_add_u64 v[138:139], s[22:23], 0, v[0:1]
	s_mov_b32 m0, s28
	s_nop 0
	global_load_lds_dwordx4 v[138:139], off
	v_lshl_add_u64 v[138:139], s[22:23], 0, v[130:131]
	s_add_i32 m0, s28, 0x2000
	s_nop 0
	global_load_lds_dwordx4 v[138:139], off
	s_waitcnt vmcnt(6)
	s_barrier
	s_nop 0
	v_mfma_f32_16x16x32_bf16 v[46:49], v[186:189], v[154:157], v[46:49]
	v_mfma_f32_16x16x32_bf16 v[42:45], v[216:219], v[154:157], v[42:45]
	v_mfma_f32_16x16x32_bf16 v[30:33], v[186:189], v[162:165], v[30:33]
	v_mfma_f32_16x16x32_bf16 v[26:29], v[216:219], v[162:165], v[26:29]
	v_mfma_f32_16x16x32_bf16 v[14:17], v[186:189], v[170:173], v[14:17]
	v_mfma_f32_16x16x32_bf16 v[10:13], v[216:219], v[170:173], v[10:13]
	v_mfma_f32_16x16x32_bf16 v[6:9], v[186:189], v[178:181], v[6:9]
	v_mfma_f32_16x16x32_bf16 v[2:5], v[216:219], v[178:181], v[2:5]
	v_mfma_f32_16x16x32_bf16 v[46:49], v[190:193], v[158:161], v[46:49]
	v_mfma_f32_16x16x32_bf16 v[42:45], v[220:223], v[158:161], v[42:45]
	v_mfma_f32_16x16x32_bf16 v[30:33], v[190:193], v[166:169], v[30:33]
	v_mfma_f32_16x16x32_bf16 v[26:29], v[220:223], v[166:169], v[26:29]
	v_mfma_f32_16x16x32_bf16 v[14:17], v[190:193], v[174:177], v[14:17]
	v_mfma_f32_16x16x32_bf16 v[10:13], v[220:223], v[174:177], v[10:13]
	v_mfma_f32_16x16x32_bf16 v[6:9], v[190:193], v[182:185], v[6:9]
	v_mfma_f32_16x16x32_bf16 v[2:5], v[220:223], v[182:185], v[2:5]
	s_nop 0
	s_add_i32 s56, s56, 2
	s_add_u32 s54, s54, 0x100
	s_addc_u32 s55, s55, 0
	s_add_u32 s20, s20, 0x100
	s_addc_u32 s21, s21, 0
	s_cmp_gt_u32 s56, 13
	s_barrier
	s_cbranch_scc0 .LBB0_841
	v_mov_b32_e32 v139, v238
	s_lshl_b32 s8, s8, 8
	v_ashrrev_i32_e32 v138, 2, v139
	v_and_b32_e32 v140, 0xffffffc0, v138
	v_lshrrev_b32_e32 v138, 1, v139
	v_lshrrev_b32_e32 v141, 2, v139
	v_and_or_b32 v139, v139, 15, s8
	s_lshl_b32 s13, s51, 8
	v_and_b32_e32 v138, 0x60, v138
	v_and_b32_e32 v141, 12, v141
	v_add_u32_e32 v140, v139, v140
	v_or3_b32 v138, v138, s13, v141
	v_ashrrev_i32_e32 v141, 31, v140
	v_lshlrev_b64 v[142:143], 10, v[140:141]
	v_ashrrev_i32_e32 v139, 31, v138
	v_lshl_add_u64 v[142:143], s[6:7], 0, v[142:143]
	v_lshlrev_b64 v[138:139], 2, v[138:139]
	v_lshl_add_u64 v[142:143], v[142:143], 0, v[138:139]
	global_store_dwordx4 v[142:143], v[126:129], off
	global_store_dwordx4 v[142:143], v[122:125], off offset:64
	global_store_dwordx4 v[142:143], v[110:113], off offset:512
	global_store_dwordx4 v[142:143], v[102:105], off offset:576
	s_mov_b32 s8, 0x20000
	s_mov_b64 s[20:21], 0x20000
	v_or_b32_e32 v102, 16, v140
	v_ashrrev_i32_e32 v103, 31, v102
	v_lshlrev_b64 v[102:103], 10, v[102:103]
	v_lshl_add_u64 v[102:103], s[6:7], 0, v[102:103]
	v_lshl_add_u64 v[102:103], v[102:103], 0, v[138:139]
	global_store_dwordx4 v[102:103], v[118:121], off
	global_store_dwordx4 v[102:103], v[114:117], off offset:64
	global_store_dwordx4 v[102:103], v[94:97], off offset:512
	global_store_dwordx4 v[102:103], v[86:89], off offset:576
	s_mov_b32 s51, s12
	s_mov_b64 s[22:23], s[18:19]
	v_or_b32_e32 v86, 32, v140
	v_ashrrev_i32_e32 v87, 31, v86
	v_lshlrev_b64 v[86:87], 10, v[86:87]
	v_lshl_add_u64 v[86:87], s[6:7], 0, v[86:87]
	v_lshl_add_u64 v[86:87], v[86:87], 0, v[138:139]
	global_store_dwordx4 v[86:87], v[106:109], off
	global_store_dwordx4 v[86:87], v[98:101], off offset:64
	global_store_dwordx4 v[86:87], v[78:81], off offset:512
	global_store_dwordx4 v[86:87], v[74:77], off offset:576
	s_nop 1
	v_or_b32_e32 v74, 48, v140
	v_ashrrev_i32_e32 v75, 31, v74
	v_lshlrev_b64 v[74:75], 10, v[74:75]
	v_lshl_add_u64 v[74:75], s[6:7], 0, v[74:75]
	v_lshl_add_u64 v[74:75], v[74:75], 0, v[138:139]
	global_store_dwordx4 v[74:75], v[90:93], off
	global_store_dwordx4 v[74:75], v[82:85], off offset:64
	global_store_dwordx4 v[74:75], v[70:73], off offset:512
	global_store_dwordx4 v[74:75], v[66:69], off offset:576
	s_nop 1
	v_add_co_u32_e32 v68, vcc, s8, v142
	s_mov_b32 s8, 0x24000
	s_nop 0
	v_addc_co_u32_e32 v69, vcc, 0, v143, vcc
	v_lshl_add_u64 v[66:67], v[142:143], 0, s[20:21]
	global_store_dwordx4 v[68:69], v[62:65], off
	global_store_dwordx4 v[66:67], v[58:61], off offset:64
	global_store_dwordx4 v[66:67], v[46:49], off offset:512
	global_store_dwordx4 v[66:67], v[42:45], off offset:576
	s_mov_b64 s[20:21], 0x24000
	s_nop 0
	v_add_co_u32_e32 v44, vcc, s8, v142
	s_mov_b32 s8, 0x28000
	s_nop 0
	v_addc_co_u32_e32 v45, vcc, 0, v143, vcc
	v_lshl_add_u64 v[42:43], v[142:143], 0, s[20:21]
	global_store_dwordx4 v[44:45], v[54:57], off
	global_store_dwordx4 v[42:43], v[50:53], off offset:64
	global_store_dwordx4 v[42:43], v[30:33], off offset:512
	global_store_dwordx4 v[42:43], v[26:29], off offset:576
	s_mov_b64 s[20:21], 0x28000
	s_nop 0
	v_add_co_u32_e32 v28, vcc, s8, v142
	v_lshl_add_u64 v[26:27], v[142:143], 0, s[20:21]
	s_nop 0
	v_addc_co_u32_e32 v29, vcc, 0, v143, vcc
	global_store_dwordx4 v[28:29], v[38:41], off
	global_store_dwordx4 v[26:27], v[34:37], off offset:64
	global_store_dwordx4 v[26:27], v[14:17], off offset:512
	global_store_dwordx4 v[26:27], v[10:13], off offset:576
	s_mov_b64 s[20:21], 0x2c000
	s_mov_b32 s8, s14
	v_add_co_u32_e32 v12, vcc, 0x2c000, v142
	v_lshl_add_u64 v[10:11], v[142:143], 0, s[20:21]
	s_nop 0
	v_addc_co_u32_e32 v13, vcc, 0, v143, vcc
	s_and_b64 vcc, exec, s[10:11]
	s_mov_b64 s[20:21], s[16:17]
	global_store_dwordx4 v[12:13], v[22:25], off
	global_store_dwordx4 v[10:11], v[18:21], off offset:64
	global_store_dwordx4 v[10:11], v[6:9], off offset:512
	global_store_dwordx4 v[10:11], v[2:5], off offset:576
	s_cbranch_vccz .LBB0_834
	s_waitcnt vmcnt(0)
	s_cmpk_gt_u32 s39, 0xff
	s_cbranch_scc1 .LBB0_824
	s_barrier
	s_branch .LBB0_824

; #define PG8_STAGE(bufoff, gbase, voff) do { _Pragma("unroll") for (int _i = 0; _i < 2; ++_i) \
;         __builtin_amdgcn_global_load_lds((const unsigned*)((const char*)(gbase) + (voff)[_i]), (LAS unsigned*)(lds + (bufoff) + ldsw + _i * 8192), 16, 0, 0); } while (0)
; #define PG8_LDA(dst, b, h) do { _Pragma("unroll") for (int m = 0; m < 4; ++m) _Pragma("unroll") for (int k = 0; k < 2; ++k) dst[m][k] = *(const LAS bf16x8*)(lds + PG8_SA(b, h) + aoff + m * 2048 + k * 1024); } while (0)
; #define PG8_LDB(dst, b, h) do { _Pragma("unroll") for (int n = 0; n < 2; ++n) _Pragma("unroll") for (int k = 0; k < 2; ++k) dst[n][k] = *(const LAS bf16x8*)(lds + PG8_SB(b, h) + boff + n * 2048 + k * 1024); } while (0)
; #define PG8_MMA(ai, bj, At, Bt) do { __builtin_amdgcn_s_setprio(1); _Pragma("unroll") for (int m = 0; m < 4; ++m) _Pragma("unroll") for (int n = 0; n < 2; ++n) _Pragma("unroll") for (int k = 0; k < 2; ++k) \
;         acc[ai][bj][m][n] = __builtin_amdgcn_mfma_f32_16x16x32_bf16(Bt[n][k], At[m][k], acc[ai][bj][m][n], 0, 0, 0); __builtin_amdgcn_s_setprio(0); } while (0)
; template <class Epi>
; DI void gemm_phase(LAS unsigned char* lds, const Gemm g, const StaticOrder& S, const Epi& E) {
;     ...
;         for (int t = 0; t < nt; t += 2) {
;             const bool last = (t == nt - 2);
;             const char* a1 = cA + (size_t)(t + 1) * kstep;
;             const char* a2 = last ? nA : cA + (size_t)(t + 2) * kstep; const char* b2 = last ? nB : cB + (size_t)(t + 2) * kstep;
;             const char* a3 = a2 + kstep; const char* b3 = b2 + kstep;
;             PG8_LDB(B0, 0, 0); PG8_SCHED; PG8_LDA(At, 0, 0); PG8_STAGE(PG8_SA(1, 1), a1 + hstepA, voffA);
;             PG8_WAIT_L(8); PG8_BAR; PG8_WAIT_L(0); PG8_MMA(0, 0, At, B0); PG8_BAR; PG8_SCHED;
;             PG8_LDB(B1, 0, 1); PG8_STAGE(PG8_SB(0, 0), b2, voffB);
;             PG8_BAR; PG8_WAIT_L(0); PG8_MMA(0, 1, At, B1); PG8_BAR;
;             PG8_LDA(At, 0, 1); PG8_STAGE(PG8_SA(0, 0), a2, voffA);
;             PG8_BAR; PG8_WAIT_L(0); PG8_MMA(1, 0, At, B0); PG8_BAR; PG8_SCHED;
;             PG8_STAGE(PG8_SB(0, 1), b2 + hstepB, voffB);
;             PG8_WAIT_V(6); PG8_BAR; PG8_MMA(1, 1, At, B1); PG8_BAR;
;             PG8_LDB(B0, 1, 0); PG8_SCHED; PG8_LDA(At, 1, 0); PG8_STAGE(PG8_SA(0, 1), a2 + hstepA, voffA);
;             PG8_WAIT_L(8); PG8_BAR; PG8_WAIT_L(0); PG8_MMA(0, 0, At, B0); PG8_BAR; PG8_SCHED;
.LBB0_860:
	s_add_u32 s20, s18, 0xfffc0080
	s_addc_u32 s21, s19, -1
	s_add_i32 s49, 0, 0x10000
	v_add_u32_e32 v154, s49, v140
	ds_read_b128 v[142:145], v154
	ds_read_b128 v[146:149], v154 offset:1024
	ds_read_b128 v[150:153], v154 offset:2048
	ds_read_b128 v[154:157], v154 offset:3072
	s_cmp_eq_u32 s48, 12
	s_cselect_b32 s23, s13, s21
	s_cselect_b32 s22, s43, s20
	s_cselect_b32 s21, s11, s47
	s_cselect_b32 s20, s44, s46
	v_lshl_add_u64 v[190:191], s[18:19], 0, v[138:139]
	s_add_i32 m0, s9, 0xc000
	ds_read_b128 v[158:161], v141
	ds_read_b128 v[162:165], v141 offset:1024
	ds_read_b128 v[166:169], v141 offset:2048
	ds_read_b128 v[170:173], v141 offset:3072
	ds_read_b128 v[174:177], v141 offset:4096
	ds_read_b128 v[178:181], v141 offset:5120
	ds_read_b128 v[182:185], v141 offset:6144
	ds_read_b128 v[186:189], v141 offset:7168
	global_load_lds_dwordx4 v[190:191], off
	v_lshl_add_u64 v[190:191], s[18:19], 0, v[136:137]
	s_add_i32 m0, s9, 0xe000
	s_nop 0
	global_load_lds_dwordx4 v[190:191], off
	s_waitcnt lgkmcnt(8)
	s_barrier
	s_waitcnt lgkmcnt(0)
	s_nop 0
	s_waitcnt lgkmcnt(0)
	v_mfma_f32_16x16x32_bf16 v[126:129], v[142:145], v[158:161], v[126:129]
	v_mfma_f32_16x16x32_bf16 v[122:125], v[150:153], v[158:161], v[122:125]
	v_mfma_f32_16x16x32_bf16 v[118:121], v[142:145], v[166:169], v[118:121]
	v_mfma_f32_16x16x32_bf16 v[114:117], v[150:153], v[166:169], v[114:117]
	v_mfma_f32_16x16x32_bf16 v[102:105], v[142:145], v[174:177], v[102:105]
	v_mfma_f32_16x16x32_bf16 v[98:101], v[150:153], v[174:177], v[98:101]
	v_mfma_f32_16x16x32_bf16 v[86:89], v[142:145], v[182:185], v[86:89]
	v_mfma_f32_16x16x32_bf16 v[82:85], v[150:153], v[182:185], v[82:85]
	v_mfma_f32_16x16x32_bf16 v[126:129], v[146:149], v[162:165], v[126:129]
	v_mfma_f32_16x16x32_bf16 v[122:125], v[154:157], v[162:165], v[122:125]
	v_mfma_f32_16x16x32_bf16 v[118:121], v[146:149], v[170:173], v[118:121]
	v_mfma_f32_16x16x32_bf16 v[114:117], v[154:157], v[170:173], v[114:117]
	v_mfma_f32_16x16x32_bf16 v[102:105], v[146:149], v[178:181], v[102:105]
	v_mfma_f32_16x16x32_bf16 v[98:101], v[154:157], v[178:181], v[98:101]
	v_mfma_f32_16x16x32_bf16 v[86:89], v[146:149], v[186:189], v[86:89]
	v_mfma_f32_16x16x32_bf16 v[82:85], v[154:157], v[186:189], v[82:85]
	s_nop 0
	s_barrier
	s_add_i32 s52, 0, 0x14000
	s_add_i32 s49, s49, s35
	v_add_u32_e32 v200, s52, v140
	v_lshl_add_u64 v[228:229], s[20:21], 0, v[130:131]
	s_mov_b32 m0, s49
	ds_read_b128 v[190:193], v200
	ds_read_b128 v[216:219], v200 offset:1024
	ds_read_b128 v[220:223], v200 offset:2048
	ds_read_b128 v[224:227], v200 offset:3072
	global_load_lds_dwordx4 v[228:229], off
	v_lshl_add_u64 v[230:231], s[20:21], 0, v[134:135]
	s_add_i32 m0, s49, 0x2000
	s_nop 0
	global_load_lds_dwordx4 v[230:231], off
	s_barrier
	s_waitcnt lgkmcnt(0)
	s_nop 0
	s_waitcnt lgkmcnt(0)
	v_mfma_f32_16x16x32_bf16 v[110:113], v[190:193], v[158:161], v[110:113]
	v_mfma_f32_16x16x32_bf16 v[106:109], v[220:223], v[158:161], v[106:109]
	v_mfma_f32_16x16x32_bf16 v[94:97], v[190:193], v[166:169], v[94:97]
	v_mfma_f32_16x16x32_bf16 v[90:93], v[220:223], v[166:169], v[90:93]
	v_mfma_f32_16x16x32_bf16 v[78:81], v[190:193], v[174:177], v[78:81]
	v_mfma_f32_16x16x32_bf16 v[74:77], v[220:223], v[174:177], v[74:77]
	v_mfma_f32_16x16x32_bf16 v[70:73], v[190:193], v[182:185], v[70:73]
	v_mfma_f32_16x16x32_bf16 v[66:69], v[220:223], v[182:185], v[66:69]
	v_mfma_f32_16x16x32_bf16 v[110:113], v[216:219], v[162:165], v[110:113]
	v_mfma_f32_16x16x32_bf16 v[106:109], v[224:227], v[162:165], v[106:109]
	v_mfma_f32_16x16x32_bf16 v[94:97], v[216:219], v[170:173], v[94:97]
	v_mfma_f32_16x16x32_bf16 v[90:93], v[224:227], v[170:173], v[90:93]
	v_mfma_f32_16x16x32_bf16 v[78:81], v[216:219], v[178:181], v[78:81]
	v_mfma_f32_16x16x32_bf16 v[74:77], v[224:227], v[178:181], v[74:77]
	v_mfma_f32_16x16x32_bf16 v[70:73], v[216:219], v[186:189], v[70:73]
	v_mfma_f32_16x16x32_bf16 v[66:69], v[224:227], v[186:189], v[66:69]
	s_nop 0
	s_mov_b32 m0, s9
	v_lshl_add_u64 v[232:233], s[22:23], 0, v[0:1]
	s_barrier
	ds_read_b128 v[158:161], v141 offset:16384
	ds_read_b128 v[162:165], v141 offset:17408
	ds_read_b128 v[166:169], v141 offset:18432
	ds_read_b128 v[170:173], v141 offset:19456
	ds_read_b128 v[174:177], v141 offset:20480
	ds_read_b128 v[178:181], v141 offset:21504
	ds_read_b128 v[182:185], v141 offset:22528
	ds_read_b128 v[186:189], v141 offset:23552
	global_load_lds_dwordx4 v[232:233], off
	v_lshl_add_u64 v[234:235], s[22:23], 0, v[132:133]
	s_mov_b32 m0, s36
	s_nop 0
	global_load_lds_dwordx4 v[234:235], off
	s_barrier
	s_waitcnt lgkmcnt(0)
	s_nop 0
	s_waitcnt lgkmcnt(0)
	v_mfma_f32_16x16x32_bf16 v[62:65], v[142:145], v[158:161], v[62:65]
	v_mfma_f32_16x16x32_bf16 v[58:61], v[150:153], v[158:161], v[58:61]
	v_mfma_f32_16x16x32_bf16 v[54:57], v[142:145], v[166:169], v[54:57]
	v_mfma_f32_16x16x32_bf16 v[50:53], v[150:153], v[166:169], v[50:53]
	v_mfma_f32_16x16x32_bf16 v[38:41], v[142:145], v[174:177], v[38:41]
	v_mfma_f32_16x16x32_bf16 v[34:37], v[150:153], v[174:177], v[34:37]
	v_mfma_f32_16x16x32_bf16 v[22:25], v[142:145], v[182:185], v[22:25]
	v_mfma_f32_16x16x32_bf16 v[18:21], v[150:153], v[182:185], v[18:21]
	v_mfma_f32_16x16x32_bf16 v[62:65], v[146:149], v[162:165], v[62:65]
	v_mfma_f32_16x16x32_bf16 v[58:61], v[154:157], v[162:165], v[58:61]
	v_mfma_f32_16x16x32_bf16 v[54:57], v[146:149], v[170:173], v[54:57]
	v_mfma_f32_16x16x32_bf16 v[50:53], v[154:157], v[170:173], v[50:53]
	v_mfma_f32_16x16x32_bf16 v[38:41], v[146:149], v[178:181], v[38:41]
	v_mfma_f32_16x16x32_bf16 v[34:37], v[154:157], v[178:181], v[34:37]
	v_mfma_f32_16x16x32_bf16 v[22:25], v[146:149], v[186:189], v[22:25]
	v_mfma_f32_16x16x32_bf16 v[18:21], v[154:157], v[186:189], v[18:21]
	s_nop 0
	s_barrier
; #define PG8_STAGE(bufoff, gbase, voff) do { _Pragma("unroll") for (int _i = 0; _i < 2; ++_i) \
;         __builtin_amdgcn_global_load_lds((const unsigned*)((const char*)(gbase) + (voff)[_i]), (LAS unsigned*)(lds + (bufoff) + ldsw + _i * 8192), 16, 0, 0); } while (0)
; #define PG8_LDA(dst, b, h) do { _Pragma("unroll") for (int m = 0; m < 4; ++m) _Pragma("unroll") for (int k = 0; k < 2; ++k) dst[m][k] = *(const LAS bf16x8*)(lds + PG8_SA(b, h) + aoff + m * 2048 + k * 1024); } while (0)
; #define PG8_LDB(dst, b, h) do { _Pragma("unroll") for (int n = 0; n < 2; ++n) _Pragma("unroll") for (int k = 0; k < 2; ++k) dst[n][k] = *(const LAS bf16x8*)(lds + PG8_SB(b, h) + boff + n * 2048 + k * 1024); } while (0)
; #define PG8_MMA(ai, bj, At, Bt) do { __builtin_amdgcn_s_setprio(1); _Pragma("unroll") for (int m = 0; m < 4; ++m) _Pragma("unroll") for (int n = 0; n < 2; ++n) _Pragma("unroll") for (int k = 0; k < 2; ++k) \
;         acc[ai][bj][m][n] = __builtin_amdgcn_mfma_f32_16x16x32_bf16(Bt[n][k], At[m][k], acc[ai][bj][m][n], 0, 0, 0); __builtin_amdgcn_s_setprio(0); } while (0)
; #define PG8_WAIT_V(n) asm volatile("s_waitcnt vmcnt(" #n ")" ::: "memory")
; #define PG8_WAIT_L(n) asm volatile("s_waitcnt lgkmcnt(" #n ")" ::: "memory")
; #define PG8_BAR __builtin_amdgcn_s_barrier()
; #define PG8_SCHED __builtin_amdgcn_sched_barrier(0)
; template <class Epi>
; DI void gemm_phase(LAS unsigned char* lds, const Gemm g, const StaticOrder& S, const Epi& E) {
;     ...
;             PG8_BAR; PG8_WAIT_L(0); PG8_MMA(0, 1, At, B1); PG8_BAR;
;             PG8_LDA(At, 0, 1); PG8_STAGE(PG8_SA(0, 0), a2, voffA);
;             PG8_BAR; PG8_WAIT_L(0); PG8_MMA(1, 0, At, B0); PG8_BAR; PG8_SCHED;
;             PG8_STAGE(PG8_SB(0, 1), b2 + hstepB, voffB);
;             PG8_WAIT_V(6); PG8_BAR; PG8_MMA(1, 1, At, B1); PG8_BAR;
;             PG8_LDB(B0, 1, 0); PG8_SCHED; PG8_LDA(At, 1, 0); PG8_STAGE(PG8_SA(0, 1), a2 + hstepA, voffA);
;             PG8_WAIT_L(8); PG8_BAR; PG8_WAIT_L(0); PG8_MMA(0, 0, At, B0); PG8_BAR; PG8_SCHED;
;             PG8_LDB(B1, 1, 1); PG8_STAGE(PG8_SB(1, 0), b3, voffB);
;             PG8_BAR; PG8_WAIT_L(0); PG8_MMA(0, 1, At, B1); PG8_BAR;
;             PG8_LDA(At, 1, 1); PG8_STAGE(PG8_SA(1, 0), a3, voffA);
;             PG8_BAR; PG8_WAIT_L(0); PG8_MMA(1, 0, At, B0); PG8_BAR; PG8_SCHED;
	s_add_u32 s50, s20, 0x40000
	s_addc_u32 s51, s21, 0
	s_add_i32 s49, s52, s35
	v_lshl_add_u64 v[142:143], s[50:51], 0, v[130:131]
	s_mov_b32 m0, s49
	s_nop 0
	global_load_lds_dwordx4 v[142:143], off
	v_lshl_add_u64 v[142:143], s[50:51], 0, v[134:135]
	s_add_i32 m0, s49, 0x2000
	s_nop 0
	global_load_lds_dwordx4 v[142:143], off
	s_waitcnt vmcnt(6)
	s_barrier
	s_nop 0
	v_mfma_f32_16x16x32_bf16 v[46:49], v[190:193], v[158:161], v[46:49]
	v_mfma_f32_16x16x32_bf16 v[42:45], v[220:223], v[158:161], v[42:45]
	v_mfma_f32_16x16x32_bf16 v[30:33], v[190:193], v[166:169], v[30:33]
	v_mfma_f32_16x16x32_bf16 v[26:29], v[220:223], v[166:169], v[26:29]
	v_mfma_f32_16x16x32_bf16 v[14:17], v[190:193], v[174:177], v[14:17]
	v_mfma_f32_16x16x32_bf16 v[10:13], v[220:223], v[174:177], v[10:13]
	v_mfma_f32_16x16x32_bf16 v[6:9], v[190:193], v[182:185], v[6:9]
	v_mfma_f32_16x16x32_bf16 v[2:5], v[220:223], v[182:185], v[2:5]
	v_mfma_f32_16x16x32_bf16 v[46:49], v[216:219], v[162:165], v[46:49]
	v_mfma_f32_16x16x32_bf16 v[42:45], v[224:227], v[162:165], v[42:45]
	v_mfma_f32_16x16x32_bf16 v[30:33], v[216:219], v[170:173], v[30:33]
	v_mfma_f32_16x16x32_bf16 v[26:29], v[224:227], v[170:173], v[26:29]
	v_mfma_f32_16x16x32_bf16 v[14:17], v[216:219], v[178:181], v[14:17]
	v_mfma_f32_16x16x32_bf16 v[10:13], v[224:227], v[178:181], v[10:13]
	v_mfma_f32_16x16x32_bf16 v[6:9], v[216:219], v[186:189], v[6:9]
	v_mfma_f32_16x16x32_bf16 v[2:5], v[224:227], v[186:189], v[2:5]
	s_nop 0
	s_add_i32 s49, 0, 0x18000
	v_add_u32_e32 v154, s49, v140
	s_barrier
	ds_read_b128 v[142:145], v154
	ds_read_b128 v[146:149], v154 offset:1024
	ds_read_b128 v[150:153], v154 offset:2048
	ds_read_b128 v[154:157], v154 offset:3072
	s_add_u32 s22, s22, 0x40000
	s_addc_u32 s23, s23, 0
	s_mov_b32 m0, s37
	v_lshl_add_u64 v[190:191], s[22:23], 0, v[0:1]
	ds_read_b128 v[158:161], v141 offset:32768
	ds_read_b128 v[162:165], v141 offset:33792
	ds_read_b128 v[166:169], v141 offset:34816
	ds_read_b128 v[170:173], v141 offset:35840
	ds_read_b128 v[174:177], v141 offset:36864
	ds_read_b128 v[178:181], v141 offset:37888
	ds_read_b128 v[182:185], v141 offset:38912
	ds_read_b128 v[186:189], v141 offset:39936
	global_load_lds_dwordx4 v[190:191], off
	v_lshl_add_u64 v[190:191], s[22:23], 0, v[132:133]
	s_mov_b32 m0, s38
	s_nop 0
	global_load_lds_dwordx4 v[190:191], off
	s_waitcnt lgkmcnt(8)
	s_barrier
	s_waitcnt lgkmcnt(0)
	s_nop 0
	s_waitcnt lgkmcnt(0)
	v_mfma_f32_16x16x32_bf16 v[126:129], v[142:145], v[158:161], v[126:129]
	v_mfma_f32_16x16x32_bf16 v[122:125], v[150:153], v[158:161], v[122:125]
	v_mfma_f32_16x16x32_bf16 v[118:121], v[142:145], v[166:169], v[118:121]
	v_mfma_f32_16x16x32_bf16 v[114:117], v[150:153], v[166:169], v[114:117]
	v_mfma_f32_16x16x32_bf16 v[102:105], v[142:145], v[174:177], v[102:105]
	v_mfma_f32_16x16x32_bf16 v[98:101], v[150:153], v[174:177], v[98:101]
	v_mfma_f32_16x16x32_bf16 v[86:89], v[142:145], v[182:185], v[86:89]
	v_mfma_f32_16x16x32_bf16 v[82:85], v[150:153], v[182:185], v[82:85]
	v_mfma_f32_16x16x32_bf16 v[126:129], v[146:149], v[162:165], v[126:129]
	v_mfma_f32_16x16x32_bf16 v[122:125], v[154:157], v[162:165], v[122:125]
	v_mfma_f32_16x16x32_bf16 v[118:121], v[146:149], v[170:173], v[118:121]
	v_mfma_f32_16x16x32_bf16 v[114:117], v[154:157], v[170:173], v[114:117]
	v_mfma_f32_16x16x32_bf16 v[102:105], v[146:149], v[178:181], v[102:105]
	v_mfma_f32_16x16x32_bf16 v[98:101], v[154:157], v[178:181], v[98:101]
	v_mfma_f32_16x16x32_bf16 v[86:89], v[146:149], v[186:189], v[86:89]
	v_mfma_f32_16x16x32_bf16 v[82:85], v[154:157], v[186:189], v[82:85]
	s_nop 0
	s_barrier
	s_add_i32 s22, 0, 0x1c000
	s_add_i32 s23, s49, s35
	v_add_u32_e32 v200, s22, v140
	v_lshl_add_u64 v[228:229], v[228:229], 0, s[2:3]
	s_mov_b32 m0, s23
	ds_read_b128 v[190:193], v200
	ds_read_b128 v[216:219], v200 offset:1024
	ds_read_b128 v[220:223], v200 offset:2048
	ds_read_b128 v[224:227], v200 offset:3072
	global_load_lds_dwordx4 v[228:229], off
	v_lshl_add_u64 v[228:229], v[230:231], 0, s[2:3]
	s_add_i32 m0, s23, 0x2000
	s_nop 0
	global_load_lds_dwordx4 v[228:229], off
	s_barrier
	s_waitcnt lgkmcnt(0)
	s_nop 0
	s_waitcnt lgkmcnt(0)
	v_mfma_f32_16x16x32_bf16 v[110:113], v[190:193], v[158:161], v[110:113]
	v_mfma_f32_16x16x32_bf16 v[106:109], v[220:223], v[158:161], v[106:109]
	v_mfma_f32_16x16x32_bf16 v[94:97], v[190:193], v[166:169], v[94:97]
	v_mfma_f32_16x16x32_bf16 v[90:93], v[220:223], v[166:169], v[90:93]
	v_mfma_f32_16x16x32_bf16 v[78:81], v[190:193], v[174:177], v[78:81]
	v_mfma_f32_16x16x32_bf16 v[74:77], v[220:223], v[174:177], v[74:77]
	v_mfma_f32_16x16x32_bf16 v[70:73], v[190:193], v[182:185], v[70:73]
	v_mfma_f32_16x16x32_bf16 v[66:69], v[220:223], v[182:185], v[66:69]
	v_mfma_f32_16x16x32_bf16 v[110:113], v[216:219], v[162:165], v[110:113]
	v_mfma_f32_16x16x32_bf16 v[106:109], v[224:227], v[162:165], v[106:109]
	v_mfma_f32_16x16x32_bf16 v[94:97], v[216:219], v[170:173], v[94:97]
	v_mfma_f32_16x16x32_bf16 v[90:93], v[224:227], v[170:173], v[90:93]
	v_mfma_f32_16x16x32_bf16 v[78:81], v[216:219], v[178:181], v[78:81]
	v_mfma_f32_16x16x32_bf16 v[74:77], v[224:227], v[178:181], v[74:77]
	v_mfma_f32_16x16x32_bf16 v[70:73], v[216:219], v[186:189], v[70:73]
	v_mfma_f32_16x16x32_bf16 v[66:69], v[224:227], v[186:189], v[66:69]
	s_nop 0
	s_mov_b32 m0, s39
	v_lshl_add_u64 v[228:229], v[232:233], 0, s[2:3]
	s_barrier
	ds_read_b128 v[158:161], v141 offset:49152
	ds_read_b128 v[162:165], v141 offset:50176
	ds_read_b128 v[166:169], v141 offset:51200
	ds_read_b128 v[170:173], v141 offset:52224
	ds_read_b128 v[174:177], v141 offset:53248
	ds_read_b128 v[178:181], v141 offset:54272
	ds_read_b128 v[182:185], v141 offset:55296
	ds_read_b128 v[186:189], v141 offset:56320
	global_load_lds_dwordx4 v[228:229], off
	v_lshl_add_u64 v[228:229], v[234:235], 0, s[2:3]
	s_mov_b32 m0, s40
	s_nop 0
	global_load_lds_dwordx4 v[228:229], off
	s_barrier
; #define PG8_STAGE(bufoff, gbase, voff) do { _Pragma("unroll") for (int _i = 0; _i < 2; ++_i) \
;         __builtin_amdgcn_global_load_lds((const unsigned*)((const char*)(gbase) + (voff)[_i]), (LAS unsigned*)(lds + (bufoff) + ldsw + _i * 8192), 16, 0, 0); } while (0)
; #define PG8_LDA(dst, b, h) do { _Pragma("unroll") for (int m = 0; m < 4; ++m) _Pragma("unroll") for (int k = 0; k < 2; ++k) dst[m][k] = *(const LAS bf16x8*)(lds + PG8_SA(b, h) + aoff + m * 2048 + k * 1024); } while (0)
; #define PG8_MMA(ai, bj, At, Bt) do { __builtin_amdgcn_s_setprio(1); _Pragma("unroll") for (int m = 0; m < 4; ++m) _Pragma("unroll") for (int n = 0; n < 2; ++n) _Pragma("unroll") for (int k = 0; k < 2; ++k) \
;         acc[ai][bj][m][n] = __builtin_amdgcn_mfma_f32_16x16x32_bf16(Bt[n][k], At[m][k], acc[ai][bj][m][n], 0, 0, 0); __builtin_amdgcn_s_setprio(0); } while (0)
; #define PG8_WAIT_V(n) asm volatile("s_waitcnt vmcnt(" #n ")" ::: "memory")
; #define PG8_WAIT_L(n) asm volatile("s_waitcnt lgkmcnt(" #n ")" ::: "memory")
; #define PG8_BAR __builtin_amdgcn_s_barrier()
; #define PG8_SCHED __builtin_amdgcn_sched_barrier(0)
; template <class Epi>
; DI void gemm_phase(LAS unsigned char* lds, const Gemm g, const StaticOrder& S, const Epi& E) {
;     ...
;             PG8_BAR; PG8_WAIT_L(0); PG8_MMA(0, 1, At, B1); PG8_BAR;
;             PG8_LDA(At, 1, 1); PG8_STAGE(PG8_SA(1, 0), a3, voffA);
;             PG8_BAR; PG8_WAIT_L(0); PG8_MMA(1, 0, At, B0); PG8_BAR; PG8_SCHED;
;             PG8_STAGE(PG8_SB(1, 1), b3 + hstepB, voffB);
;             PG8_WAIT_V(6); PG8_BAR; PG8_MMA(1, 1, At, B1); PG8_BAR;
	s_waitcnt lgkmcnt(0)
	s_nop 0
	s_waitcnt lgkmcnt(0)
	v_mfma_f32_16x16x32_bf16 v[62:65], v[142:145], v[158:161], v[62:65]
	v_mfma_f32_16x16x32_bf16 v[58:61], v[150:153], v[158:161], v[58:61]
	v_mfma_f32_16x16x32_bf16 v[54:57], v[142:145], v[166:169], v[54:57]
	v_mfma_f32_16x16x32_bf16 v[50:53], v[150:153], v[166:169], v[50:53]
	v_mfma_f32_16x16x32_bf16 v[38:41], v[142:145], v[174:177], v[38:41]
	v_mfma_f32_16x16x32_bf16 v[34:37], v[150:153], v[174:177], v[34:37]
	v_mfma_f32_16x16x32_bf16 v[22:25], v[142:145], v[182:185], v[22:25]
	v_mfma_f32_16x16x32_bf16 v[18:21], v[150:153], v[182:185], v[18:21]
	v_mfma_f32_16x16x32_bf16 v[62:65], v[146:149], v[162:165], v[62:65]
	v_mfma_f32_16x16x32_bf16 v[58:61], v[154:157], v[162:165], v[58:61]
	v_mfma_f32_16x16x32_bf16 v[54:57], v[146:149], v[170:173], v[54:57]
	v_mfma_f32_16x16x32_bf16 v[50:53], v[154:157], v[170:173], v[50:53]
	v_mfma_f32_16x16x32_bf16 v[38:41], v[146:149], v[178:181], v[38:41]
	v_mfma_f32_16x16x32_bf16 v[34:37], v[154:157], v[178:181], v[34:37]
	v_mfma_f32_16x16x32_bf16 v[22:25], v[146:149], v[186:189], v[22:25]
	v_mfma_f32_16x16x32_bf16 v[18:21], v[154:157], v[186:189], v[18:21]
	s_nop 0
	s_barrier
	s_add_u32 s20, s20, 0x40080
	s_addc_u32 s21, s21, 0
	s_add_i32 s22, s22, s35
	v_lshl_add_u64 v[142:143], s[20:21], 0, v[130:131]
	s_mov_b32 m0, s22
	s_nop 0
	global_load_lds_dwordx4 v[142:143], off
	v_lshl_add_u64 v[142:143], s[20:21], 0, v[134:135]
	s_add_i32 m0, s22, 0x2000
	s_nop 0
	global_load_lds_dwordx4 v[142:143], off
	s_waitcnt vmcnt(6)
	s_barrier
	s_nop 0
	v_mfma_f32_16x16x32_bf16 v[46:49], v[190:193], v[158:161], v[46:49]
	v_mfma_f32_16x16x32_bf16 v[42:45], v[220:223], v[158:161], v[42:45]
	v_mfma_f32_16x16x32_bf16 v[30:33], v[190:193], v[166:169], v[30:33]
	v_mfma_f32_16x16x32_bf16 v[26:29], v[220:223], v[166:169], v[26:29]
	v_mfma_f32_16x16x32_bf16 v[14:17], v[190:193], v[174:177], v[14:17]
	v_mfma_f32_16x16x32_bf16 v[10:13], v[220:223], v[174:177], v[10:13]
	v_mfma_f32_16x16x32_bf16 v[6:9], v[190:193], v[182:185], v[6:9]
	v_mfma_f32_16x16x32_bf16 v[2:5], v[220:223], v[182:185], v[2:5]
	v_mfma_f32_16x16x32_bf16 v[46:49], v[216:219], v[162:165], v[46:49]
	v_mfma_f32_16x16x32_bf16 v[42:45], v[224:227], v[162:165], v[42:45]
	v_mfma_f32_16x16x32_bf16 v[30:33], v[216:219], v[170:173], v[30:33]
	v_mfma_f32_16x16x32_bf16 v[26:29], v[224:227], v[170:173], v[26:29]
	v_mfma_f32_16x16x32_bf16 v[14:17], v[216:219], v[178:181], v[14:17]
	v_mfma_f32_16x16x32_bf16 v[10:13], v[224:227], v[178:181], v[10:13]
	v_mfma_f32_16x16x32_bf16 v[6:9], v[216:219], v[186:189], v[6:9]
	v_mfma_f32_16x16x32_bf16 v[2:5], v[224:227], v[186:189], v[2:5]
	s_nop 0
	s_add_i32 s48, s48, 2
	s_add_u32 s46, s46, 0x100
	s_addc_u32 s47, s47, 0
	s_add_u32 s18, s18, 0x100
	s_addc_u32 s19, s19, 0
	s_cmp_gt_u32 s48, 13
	s_barrier
	s_cbranch_scc0 .LBB0_860
	v_mov_b32_e32 v143, v238
	s_lshl_b32 s8, s8, 8
	v_ashrrev_i32_e32 v142, 2, v143
	v_and_b32_e32 v144, 0xffffffc0, v142
	v_lshrrev_b32_e32 v142, 1, v143
	v_and_b32_e32 v142, 0x78, v142
	v_and_or_b32 v143, v143, 15, s8
	v_lshl_or_b32 v142, s42, 8, v142
	v_add_u32_e32 v144, v143, v144
	v_cvt_pk_bf16_f32 v126, v126, v127
	v_cvt_pk_bf16_f32 v127, v128, v129
	v_cvt_pk_bf16_f32 v128, v122, v123
	v_mov_b64_e32 v[122:123], s[6:7]
	v_ashrrev_i32_e32 v143, 31, v142
	v_cvt_pk_bf16_f32 v70, v70, v71
	v_cvt_pk_bf16_f32 v71, v72, v73
	v_cvt_pk_bf16_f32 v72, v66, v67
	v_add_u32_e32 v66, 0x80, v144
	v_cvt_pk_bf16_f32 v129, v124, v125
	v_mad_i64_i32 v[124:125], s[18:19], v144, s65, v[122:123]
	v_lshlrev_b64 v[142:143], 1, v[142:143]
	v_cvt_pk_bf16_f32 v62, v62, v63
	v_cvt_pk_bf16_f32 v63, v64, v65
	v_cvt_pk_bf16_f32 v64, v58, v59
	v_mad_i64_i32 v[58:59], s[18:19], v66, s65, v[122:123]
	v_lshl_add_u64 v[124:125], v[124:125], 0, v[142:143]
	v_cvt_pk_bf16_f32 v110, v110, v111
	v_cvt_pk_bf16_f32 v111, v112, v113
	v_cvt_pk_bf16_f32 v112, v106, v107
	v_cvt_pk_bf16_f32 v113, v108, v109
	v_lshl_add_u64 v[58:59], v[58:59], 0, v[142:143]
	v_cvt_pk_bf16_f32 v46, v46, v47
	v_cvt_pk_bf16_f32 v47, v48, v49
	v_cvt_pk_bf16_f32 v48, v42, v43
	v_cvt_pk_bf16_f32 v49, v44, v45
	global_store_dwordx4 v[124:125], v[110:113], off offset:256
	global_store_dwordx4 v[58:59], v[46:49], off offset:256
	v_cvt_pk_bf16_f32 v94, v94, v95
	v_or_b32_e32 v110, 16, v144
	v_add_u32_e32 v46, 0x90, v144
	v_mad_i64_i32 v[110:111], s[18:19], v110, s65, v[122:123]
	v_mad_i64_i32 v[46:47], s[18:19], v46, s65, v[122:123]
	v_lshl_add_u64 v[110:111], v[110:111], 0, v[142:143]
	v_cvt_pk_bf16_f32 v95, v96, v97
	v_cvt_pk_bf16_f32 v96, v90, v91
	v_cvt_pk_bf16_f32 v97, v92, v93
	v_lshl_add_u64 v[46:47], v[46:47], 0, v[142:143]
	v_cvt_pk_bf16_f32 v30, v30, v31
	v_cvt_pk_bf16_f32 v31, v32, v33
	v_cvt_pk_bf16_f32 v32, v26, v27
	v_cvt_pk_bf16_f32 v33, v28, v29
	global_store_dwordx4 v[110:111], v[94:97], off offset:256
	global_store_dwordx4 v[46:47], v[30:33], off offset:256
	v_cvt_pk_bf16_f32 v78, v78, v79
	v_or_b32_e32 v94, 32, v144
	v_add_u32_e32 v30, 0xa0, v144
	v_mad_i64_i32 v[94:95], s[18:19], v94, s65, v[122:123]
	v_mad_i64_i32 v[30:31], s[18:19], v30, s65, v[122:123]
	v_lshl_add_u64 v[94:95], v[94:95], 0, v[142:143]
	v_cvt_pk_bf16_f32 v79, v80, v81
	v_cvt_pk_bf16_f32 v80, v74, v75
	v_cvt_pk_bf16_f32 v81, v76, v77
	v_lshl_add_u64 v[30:31], v[30:31], 0, v[142:143]
	v_cvt_pk_bf16_f32 v14, v14, v15
	v_cvt_pk_bf16_f32 v15, v16, v17
	v_cvt_pk_bf16_f32 v16, v10, v11
	v_cvt_pk_bf16_f32 v17, v12, v13
	global_store_dwordx4 v[94:95], v[78:81], off offset:256
	global_store_dwordx4 v[30:31], v[14:17], off offset:256
	v_cvt_pk_bf16_f32 v106, v118, v119
	v_or_b32_e32 v78, 48, v144
	v_add_u32_e32 v14, 0xb0, v144
	v_mad_i64_i32 v[78:79], s[18:19], v78, s65, v[122:123]
	v_mad_i64_i32 v[14:15], s[18:19], v14, s65, v[122:123]
	v_cvt_pk_bf16_f32 v107, v120, v121
	v_cvt_pk_bf16_f32 v108, v114, v115
	v_cvt_pk_bf16_f32 v109, v116, v117
	v_cvt_pk_bf16_f32 v90, v102, v103
	v_cvt_pk_bf16_f32 v91, v104, v105
	v_cvt_pk_bf16_f32 v92, v98, v99
	v_cvt_pk_bf16_f32 v93, v100, v101
	v_cvt_pk_bf16_f32 v74, v86, v87
	v_cvt_pk_bf16_f32 v75, v88, v89
	v_cvt_pk_bf16_f32 v76, v82, v83
	v_cvt_pk_bf16_f32 v77, v84, v85
	v_lshl_add_u64 v[78:79], v[78:79], 0, v[142:143]
	v_cvt_pk_bf16_f32 v73, v68, v69
	v_cvt_pk_bf16_f32 v65, v60, v61
	v_cvt_pk_bf16_f32 v42, v54, v55
	v_cvt_pk_bf16_f32 v43, v56, v57
	v_cvt_pk_bf16_f32 v44, v50, v51
	v_cvt_pk_bf16_f32 v45, v52, v53
	v_cvt_pk_bf16_f32 v26, v38, v39
	v_cvt_pk_bf16_f32 v27, v40, v41
	v_cvt_pk_bf16_f32 v28, v34, v35
	v_cvt_pk_bf16_f32 v29, v36, v37
	v_cvt_pk_bf16_f32 v10, v22, v23
	v_cvt_pk_bf16_f32 v11, v24, v25
	v_cvt_pk_bf16_f32 v12, v18, v19
	v_cvt_pk_bf16_f32 v13, v20, v21
	v_lshl_add_u64 v[14:15], v[14:15], 0, v[142:143]
	v_cvt_pk_bf16_f32 v6, v6, v7
	v_cvt_pk_bf16_f32 v7, v8, v9
	v_cvt_pk_bf16_f32 v8, v2, v3
	v_cvt_pk_bf16_f32 v9, v4, v5
	s_and_b64 vcc, exec, s[0:1]
	s_mov_b32 s42, s10
	s_mov_b32 s8, s12
	s_mov_b64 s[20:21], s[16:17]
	s_mov_b64 s[18:19], s[14:15]
	global_store_dwordx4 v[124:125], v[126:129], off
	global_store_dwordx4 v[110:111], v[106:109], off
	global_store_dwordx4 v[94:95], v[90:93], off
	global_store_dwordx4 v[78:79], v[74:77], off
	global_store_dwordx4 v[78:79], v[70:73], off offset:256
	global_store_dwordx4 v[58:59], v[62:65], off
	global_store_dwordx4 v[46:47], v[42:45], off
	global_store_dwordx4 v[30:31], v[26:29], off
	global_store_dwordx4 v[14:15], v[10:13], off
	global_store_dwordx4 v[14:15], v[6:9], off offset:256
	s_cbranch_vccz .LBB0_853
	s_waitcnt vmcnt(0)
	s_cmpk_gt_u32 s29, 0xff
	s_cbranch_scc1 .LBB0_864
	s_barrier
